# all 7 norm phases hand-written (deep row prefetch): phase1 f32 src, 5 adaLN norms, final f32-out
# speedup vs baseline: 1.0029x; 1.0029x over previous
.LBB0_267:
	v_mov_b32_e32 v1, 0x2416c
	ds_read_b32 v2, v1
	ds_read_b32 v1, v1 offset:4
	s_waitcnt lgkmcnt(0)
	v_readfirstlane_b32 s2, v2
	v_readfirstlane_b32 s3, v1
	s_cmp_lt_i32 s2, 1
	s_cbranch_scc1 .Lnorm_fb_p1
	v_and_b32_e32 v1, 63, v0
	v_lshlrev_b32_e32 v2, 5, v1
	v_add_u32_e32 v3, 0x1000, v2
	v_lshlrev_b32_e32 v1, 4, v1
	v_readfirstlane_b32 s0, v0
	s_lshr_b32 s1, s0, 6
	s_add_i32 s2, s2, -1
	s_lshl_b32 s18, s2, 8
	s_lshl_b32 s19, s3, 3
	s_add_i32 s18, s18, s19
	s_add_i32 s18, s18, s1
	s_lshr_b32 s19, s2, 4
	s_lshl_b32 s20, s18, 12
	s_lshl_b32 s21, s18, 13
	s_add_u32 s6, s40, 0x0
	s_addc_u32 s7, s41, 0
	s_add_u32 s6, s6, s21
	s_addc_u32 s7, s7, 0
	s_add_u32 s10, s88, 0x13e00000
	s_addc_u32 s11, s89, 0
	s_add_u32 s10, s10, s20
	s_addc_u32 s11, s11, 0
	s_add_u32 s16, s44, 0x0
	s_addc_u32 s17, s45, 0
	s_mul_i32 s22, s19, 0x12000
	s_add_u32 s24, s88, 0x100000
	s_addc_u32 s25, s89, 0
	s_add_u32 s24, s24, s22
	s_addc_u32 s25, s25, 0
	s_mul_i32 s22, s19, 0x12000
	s_add_u32 s26, s88, 0x102000
	s_addc_u32 s27, s89, 0
	s_add_u32 s26, s26, s22
	s_addc_u32 s27, s27, 0
	global_load_dwordx4 v[200:203], v2, s[16:17] offset:0
	global_load_dwordx4 v[204:207], v2, s[16:17] offset:16
	global_load_dwordx4 v[208:211], v2, s[16:17] offset:2048
	global_load_dwordx4 v[212:215], v2, s[16:17] offset:2064
	global_load_dwordx4 v[216:219], v3, s[16:17] offset:0
	global_load_dwordx4 v[220:223], v3, s[16:17] offset:16
	global_load_dwordx4 v[224:227], v3, s[16:17] offset:2048
	global_load_dwordx4 v[228:231], v3, s[16:17] offset:2064
	global_load_dwordx4 v[8:11], v2, s[26:27] offset:0
	global_load_dwordx4 v[12:15], v2, s[26:27] offset:16
	global_load_dwordx4 v[16:19], v2, s[26:27] offset:2048
	global_load_dwordx4 v[20:23], v2, s[26:27] offset:2064
	global_load_dwordx4 v[24:27], v3, s[26:27] offset:0
	global_load_dwordx4 v[28:31], v3, s[26:27] offset:16
	global_load_dwordx4 v[32:35], v3, s[26:27] offset:2048
	global_load_dwordx4 v[36:39], v3, s[26:27] offset:2064
	global_load_dwordx4 v[40:43], v2, s[24:25] offset:0
	global_load_dwordx4 v[44:47], v2, s[24:25] offset:16
	global_load_dwordx4 v[48:51], v2, s[24:25] offset:2048
	global_load_dwordx4 v[52:55], v2, s[24:25] offset:2064
	global_load_dwordx4 v[56:59], v3, s[24:25] offset:0
	global_load_dwordx4 v[60:63], v3, s[24:25] offset:16
	global_load_dwordx4 v[64:67], v3, s[24:25] offset:2048
	global_load_dwordx4 v[68:71], v3, s[24:25] offset:2064
	s_add_u32 s8, s6, 0x0
	s_addc_u32 s9, s7, 0
	global_load_dwordx4 v[72:75], v2, s[8:9] offset:0 nt
	global_load_dwordx4 v[76:79], v2, s[8:9] offset:16 nt
	global_load_dwordx4 v[80:83], v2, s[8:9] offset:2048 nt
	global_load_dwordx4 v[84:87], v2, s[8:9] offset:2064 nt
	global_load_dwordx4 v[88:91], v3, s[8:9] offset:0 nt
	global_load_dwordx4 v[92:95], v3, s[8:9] offset:16 nt
	global_load_dwordx4 v[96:99], v3, s[8:9] offset:2048 nt
	global_load_dwordx4 v[100:103], v3, s[8:9] offset:2064 nt
	s_add_u32 s8, s6, 0x40000
	s_addc_u32 s9, s7, 0
	global_load_dwordx4 v[104:107], v2, s[8:9] offset:0 nt
	global_load_dwordx4 v[108:111], v2, s[8:9] offset:16 nt
	global_load_dwordx4 v[112:115], v2, s[8:9] offset:2048 nt
	global_load_dwordx4 v[116:119], v2, s[8:9] offset:2064 nt
	global_load_dwordx4 v[120:123], v3, s[8:9] offset:0 nt
	global_load_dwordx4 v[124:127], v3, s[8:9] offset:16 nt
	global_load_dwordx4 v[128:131], v3, s[8:9] offset:2048 nt
	global_load_dwordx4 v[132:135], v3, s[8:9] offset:2064 nt
	s_add_u32 s8, s6, 0x80000
	s_addc_u32 s9, s7, 0
	global_load_dwordx4 v[136:139], v2, s[8:9] offset:0 nt
	global_load_dwordx4 v[140:143], v2, s[8:9] offset:16 nt
	global_load_dwordx4 v[144:147], v2, s[8:9] offset:2048 nt
	global_load_dwordx4 v[148:151], v2, s[8:9] offset:2064 nt
	global_load_dwordx4 v[152:155], v3, s[8:9] offset:0 nt
	global_load_dwordx4 v[156:159], v3, s[8:9] offset:16 nt
	global_load_dwordx4 v[160:163], v3, s[8:9] offset:2048 nt
	global_load_dwordx4 v[164:167], v3, s[8:9] offset:2064 nt
	s_add_u32 s8, s6, 0xc0000
	s_addc_u32 s9, s7, 0
	global_load_dwordx4 v[168:171], v2, s[8:9] offset:0 nt
	global_load_dwordx4 v[172:175], v2, s[8:9] offset:16 nt
	global_load_dwordx4 v[176:179], v2, s[8:9] offset:2048 nt
	global_load_dwordx4 v[180:183], v2, s[8:9] offset:2064 nt
	global_load_dwordx4 v[184:187], v3, s[8:9] offset:0 nt
	global_load_dwordx4 v[188:191], v3, s[8:9] offset:16 nt
	global_load_dwordx4 v[192:195], v3, s[8:9] offset:2048 nt
	global_load_dwordx4 v[196:199], v3, s[8:9] offset:2064 nt
	s_waitcnt vmcnt(32)
	v_pk_add_f32 v[8:9], v[8:9], 1.0 op_sel_hi:[1,0]
	v_pk_add_f32 v[10:11], v[10:11], 1.0 op_sel_hi:[1,0]
	v_pk_add_f32 v[12:13], v[12:13], 1.0 op_sel_hi:[1,0]
	v_pk_add_f32 v[14:15], v[14:15], 1.0 op_sel_hi:[1,0]
	v_pk_add_f32 v[16:17], v[16:17], 1.0 op_sel_hi:[1,0]
	v_pk_add_f32 v[18:19], v[18:19], 1.0 op_sel_hi:[1,0]
	v_pk_add_f32 v[20:21], v[20:21], 1.0 op_sel_hi:[1,0]
	v_pk_add_f32 v[22:23], v[22:23], 1.0 op_sel_hi:[1,0]
	v_pk_add_f32 v[24:25], v[24:25], 1.0 op_sel_hi:[1,0]
	v_pk_add_f32 v[26:27], v[26:27], 1.0 op_sel_hi:[1,0]
	v_pk_add_f32 v[28:29], v[28:29], 1.0 op_sel_hi:[1,0]
	v_pk_add_f32 v[30:31], v[30:31], 1.0 op_sel_hi:[1,0]
	v_pk_add_f32 v[32:33], v[32:33], 1.0 op_sel_hi:[1,0]
	v_pk_add_f32 v[34:35], v[34:35], 1.0 op_sel_hi:[1,0]
	v_pk_add_f32 v[36:37], v[36:37], 1.0 op_sel_hi:[1,0]
	v_pk_add_f32 v[38:39], v[38:39], 1.0 op_sel_hi:[1,0]
	v_pk_mul_f32 v[8:9], v[200:201], v[8:9]
	v_pk_mul_f32 v[10:11], v[202:203], v[10:11]
	v_pk_mul_f32 v[12:13], v[204:205], v[12:13]
	v_pk_mul_f32 v[14:15], v[206:207], v[14:15]
	v_pk_mul_f32 v[16:17], v[208:209], v[16:17]
	v_pk_mul_f32 v[18:19], v[210:211], v[18:19]
	v_pk_mul_f32 v[20:21], v[212:213], v[20:21]
	v_pk_mul_f32 v[22:23], v[214:215], v[22:23]
	v_pk_mul_f32 v[24:25], v[216:217], v[24:25]
	v_pk_mul_f32 v[26:27], v[218:219], v[26:27]
	v_pk_mul_f32 v[28:29], v[220:221], v[28:29]
	v_pk_mul_f32 v[30:31], v[222:223], v[30:31]
	v_pk_mul_f32 v[32:33], v[224:225], v[32:33]
	v_pk_mul_f32 v[34:35], v[226:227], v[34:35]
	v_pk_mul_f32 v[36:37], v[228:229], v[36:37]
	v_pk_mul_f32 v[38:39], v[230:231], v[38:39]
	s_nop 1
	s_add_u32 s8, s6, 0x100000
	s_addc_u32 s9, s7, 0
	global_load_dwordx4 v[200:203], v2, s[8:9] offset:0 nt
	global_load_dwordx4 v[204:207], v2, s[8:9] offset:16 nt
	global_load_dwordx4 v[208:211], v2, s[8:9] offset:2048 nt
	global_load_dwordx4 v[212:215], v2, s[8:9] offset:2064 nt
	global_load_dwordx4 v[216:219], v3, s[8:9] offset:0 nt
	global_load_dwordx4 v[220:223], v3, s[8:9] offset:16 nt
	global_load_dwordx4 v[224:227], v3, s[8:9] offset:2048 nt
	global_load_dwordx4 v[228:231], v3, s[8:9] offset:2064 nt
	v_mov_b32_e32 v248, 0x260
	s_waitcnt vmcnt(32)
	v_pk_mul_f32 v[232:233], v[72:73], v[72:73]
	v_pk_mul_f32 v[234:235], v[74:75], v[74:75]
	v_pk_mul_f32 v[236:237], v[76:77], v[76:77]
	v_pk_mul_f32 v[238:239], v[78:79], v[78:79]
	v_pk_fma_f32 v[232:233], v[80:81], v[80:81], v[232:233]
	v_pk_fma_f32 v[234:235], v[82:83], v[82:83], v[234:235]
	v_pk_fma_f32 v[236:237], v[84:85], v[84:85], v[236:237]
	v_pk_fma_f32 v[238:239], v[86:87], v[86:87], v[238:239]
	v_pk_fma_f32 v[232:233], v[88:89], v[88:89], v[232:233]
	v_pk_fma_f32 v[234:235], v[90:91], v[90:91], v[234:235]
	v_pk_fma_f32 v[236:237], v[92:93], v[92:93], v[236:237]
	v_pk_fma_f32 v[238:239], v[94:95], v[94:95], v[238:239]
	v_pk_fma_f32 v[232:233], v[96:97], v[96:97], v[232:233]
	v_pk_fma_f32 v[234:235], v[98:99], v[98:99], v[234:235]
	v_pk_fma_f32 v[236:237], v[100:101], v[100:101], v[236:237]
	v_pk_fma_f32 v[238:239], v[102:103], v[102:103], v[238:239]
	v_pk_add_f32 v[232:233], v[232:233], v[234:235]
	v_pk_add_f32 v[236:237], v[236:237], v[238:239]
	v_pk_add_f32 v[232:233], v[232:233], v[236:237]
	v_add_f32_e32 v240, v232, v233
	s_nop 1
	v_add_f32_dpp v240, v240, v240 quad_perm:[1,0,3,2] row_mask:0xf bank_mask:0xf
	s_nop 1
	v_add_f32_dpp v240, v240, v240 quad_perm:[2,3,0,1] row_mask:0xf bank_mask:0xf
	s_nop 1
	v_add_f32_dpp v240, v240, v240 row_half_mirror row_mask:0xf bank_mask:0xf
	s_nop 1
	v_add_f32_dpp v240, v240, v240 row_mirror row_mask:0xf bank_mask:0xf
	s_nop 1
	v_readlane_b32 s0, v240, 0
	v_readlane_b32 s1, v240, 16
	v_readlane_b32 s2, v240, 32
	v_readlane_b32 s3, v240, 48
	v_mov_b32_e32 v249, 0x358637bd
	s_nop 1
	v_mov_b32_e32 v240, s0
	v_add_f32_e32 v240, s1, v240
	v_add_f32_e32 v240, s2, v240
	v_add_f32_e32 v240, s3, v240
	v_fmamk_f32 v240, v240, 0x3a000000, v249
	s_mov_b32 s0, 0xf800000
	v_mul_f32_e32 v241, 0x4f800000, v240
	v_cmp_gt_f32_e32 vcc, s0, v240
	s_nop 1
	v_cndmask_b32_e32 v240, v240, v241, vcc
	v_sqrt_f32_e32 v241, v240
	s_nop 0
	v_add_u32_e32 v242, -1, v241
	v_fma_f32 v243, -v242, v241, v240
	v_cmp_ge_f32_e64 s[0:1], 0, v243
	v_add_u32_e32 v243, 1, v241
	s_nop 0
	v_cndmask_b32_e64 v242, v241, v242, s[0:1]
	v_fma_f32 v241, -v243, v241, v240
	v_cmp_lt_f32_e64 s[0:1], 0, v241
	s_nop 1
	v_cndmask_b32_e64 v241, v242, v243, s[0:1]
	v_mul_f32_e32 v242, 0x37800000, v241
	v_cndmask_b32_e32 v241, v241, v242, vcc
	v_cmp_class_f32_e32 vcc, v240, v248
	s_nop 1
	v_cndmask_b32_e32 v240, v241, v240, vcc
	v_div_scale_f32 v241, s[0:1], v240, v240, 1.0
	v_rcp_f32_e32 v242, v241
	s_nop 0
	v_fma_f32 v243, -v241, v242, 1.0
	v_fmac_f32_e32 v242, v243, v242
	v_div_scale_f32 v243, vcc, 1.0, v240, 1.0
	v_mul_f32_e32 v244, v243, v242
	v_fma_f32 v247, -v241, v244, v243
	v_fmac_f32_e32 v244, v247, v242
	v_fma_f32 v241, -v241, v244, v243
	s_nop 1
	v_div_fmas_f32 v241, v241, v242, v244
	v_div_fixup_f32 v246, v241, v240, 1.0
	v_pk_mul_f32 v[72:73], v[72:73], v[246:247] op_sel_hi:[1,0]
	v_pk_mul_f32 v[74:75], v[74:75], v[246:247] op_sel_hi:[1,0]
	v_pk_mul_f32 v[76:77], v[76:77], v[246:247] op_sel_hi:[1,0]
	v_pk_mul_f32 v[78:79], v[78:79], v[246:247] op_sel_hi:[1,0]
	v_pk_mul_f32 v[80:81], v[80:81], v[246:247] op_sel_hi:[1,0]
	v_pk_mul_f32 v[82:83], v[82:83], v[246:247] op_sel_hi:[1,0]
	v_pk_mul_f32 v[84:85], v[84:85], v[246:247] op_sel_hi:[1,0]
	v_pk_mul_f32 v[86:87], v[86:87], v[246:247] op_sel_hi:[1,0]
	v_pk_mul_f32 v[88:89], v[88:89], v[246:247] op_sel_hi:[1,0]
	v_pk_mul_f32 v[90:91], v[90:91], v[246:247] op_sel_hi:[1,0]
	v_pk_mul_f32 v[92:93], v[92:93], v[246:247] op_sel_hi:[1,0]
	v_pk_mul_f32 v[94:95], v[94:95], v[246:247] op_sel_hi:[1,0]
	v_pk_mul_f32 v[96:97], v[96:97], v[246:247] op_sel_hi:[1,0]
	v_pk_mul_f32 v[98:99], v[98:99], v[246:247] op_sel_hi:[1,0]
	v_pk_mul_f32 v[100:101], v[100:101], v[246:247] op_sel_hi:[1,0]
	v_pk_mul_f32 v[102:103], v[102:103], v[246:247] op_sel_hi:[1,0]
	s_add_u32 s8, s10, 0x0
	s_addc_u32 s9, s11, 0
	v_pk_fma_f32 v[72:73], v[8:9], v[72:73], v[40:41]
	v_cvt_pk_bf16_f32 v232, v72, v73
	v_pk_fma_f32 v[74:75], v[10:11], v[74:75], v[42:43]
	v_cvt_pk_bf16_f32 v233, v74, v75
	v_pk_fma_f32 v[76:77], v[12:13], v[76:77], v[44:45]
	v_cvt_pk_bf16_f32 v234, v76, v77
	v_pk_fma_f32 v[78:79], v[14:15], v[78:79], v[46:47]
	v_cvt_pk_bf16_f32 v235, v78, v79
	global_store_dwordx4 v1, v[232:235], s[8:9] offset:0
	v_pk_fma_f32 v[80:81], v[16:17], v[80:81], v[48:49]
	v_cvt_pk_bf16_f32 v236, v80, v81
	v_pk_fma_f32 v[82:83], v[18:19], v[82:83], v[50:51]
	v_cvt_pk_bf16_f32 v237, v82, v83
	v_pk_fma_f32 v[84:85], v[20:21], v[84:85], v[52:53]
	v_cvt_pk_bf16_f32 v238, v84, v85
	v_pk_fma_f32 v[86:87], v[22:23], v[86:87], v[54:55]
	v_cvt_pk_bf16_f32 v239, v86, v87
	global_store_dwordx4 v1, v[236:239], s[8:9] offset:1024
	v_pk_fma_f32 v[88:89], v[24:25], v[88:89], v[56:57]
	v_cvt_pk_bf16_f32 v232, v88, v89
	v_pk_fma_f32 v[90:91], v[26:27], v[90:91], v[58:59]
	v_cvt_pk_bf16_f32 v233, v90, v91
	v_pk_fma_f32 v[92:93], v[28:29], v[92:93], v[60:61]
	v_cvt_pk_bf16_f32 v234, v92, v93
	v_pk_fma_f32 v[94:95], v[30:31], v[94:95], v[62:63]
	v_cvt_pk_bf16_f32 v235, v94, v95
	global_store_dwordx4 v1, v[232:235], s[8:9] offset:2048
	v_pk_fma_f32 v[96:97], v[32:33], v[96:97], v[64:65]
	v_cvt_pk_bf16_f32 v236, v96, v97
	v_pk_fma_f32 v[98:99], v[34:35], v[98:99], v[66:67]
	v_cvt_pk_bf16_f32 v237, v98, v99
	v_pk_fma_f32 v[100:101], v[36:37], v[100:101], v[68:69]
	v_cvt_pk_bf16_f32 v238, v100, v101
	v_pk_fma_f32 v[102:103], v[38:39], v[102:103], v[70:71]
	v_cvt_pk_bf16_f32 v239, v102, v103
	global_store_dwordx4 v1, v[236:239], s[8:9] offset:3072
	s_nop 1
	s_add_u32 s8, s6, 0x140000
	s_addc_u32 s9, s7, 0
	global_load_dwordx4 v[72:75], v2, s[8:9] offset:0 nt
	global_load_dwordx4 v[76:79], v2, s[8:9] offset:16 nt
	global_load_dwordx4 v[80:83], v2, s[8:9] offset:2048 nt
	global_load_dwordx4 v[84:87], v2, s[8:9] offset:2064 nt
	global_load_dwordx4 v[88:91], v3, s[8:9] offset:0 nt
	global_load_dwordx4 v[92:95], v3, s[8:9] offset:16 nt
	global_load_dwordx4 v[96:99], v3, s[8:9] offset:2048 nt
	global_load_dwordx4 v[100:103], v3, s[8:9] offset:2064 nt
	s_waitcnt vmcnt(36)
	v_pk_mul_f32 v[232:233], v[104:105], v[104:105]
	v_pk_mul_f32 v[234:235], v[106:107], v[106:107]
	v_pk_mul_f32 v[236:237], v[108:109], v[108:109]
	v_pk_mul_f32 v[238:239], v[110:111], v[110:111]
	v_pk_fma_f32 v[232:233], v[112:113], v[112:113], v[232:233]
	v_pk_fma_f32 v[234:235], v[114:115], v[114:115], v[234:235]
	v_pk_fma_f32 v[236:237], v[116:117], v[116:117], v[236:237]
	v_pk_fma_f32 v[238:239], v[118:119], v[118:119], v[238:239]
	v_pk_fma_f32 v[232:233], v[120:121], v[120:121], v[232:233]
	v_pk_fma_f32 v[234:235], v[122:123], v[122:123], v[234:235]
	v_pk_fma_f32 v[236:237], v[124:125], v[124:125], v[236:237]
	v_pk_fma_f32 v[238:239], v[126:127], v[126:127], v[238:239]
	v_pk_fma_f32 v[232:233], v[128:129], v[128:129], v[232:233]
	v_pk_fma_f32 v[234:235], v[130:131], v[130:131], v[234:235]
	v_pk_fma_f32 v[236:237], v[132:133], v[132:133], v[236:237]
	v_pk_fma_f32 v[238:239], v[134:135], v[134:135], v[238:239]
	v_pk_add_f32 v[232:233], v[232:233], v[234:235]
	v_pk_add_f32 v[236:237], v[236:237], v[238:239]
	v_pk_add_f32 v[232:233], v[232:233], v[236:237]
	v_add_f32_e32 v240, v232, v233
	s_nop 1
	v_add_f32_dpp v240, v240, v240 quad_perm:[1,0,3,2] row_mask:0xf bank_mask:0xf
	s_nop 1
	v_add_f32_dpp v240, v240, v240 quad_perm:[2,3,0,1] row_mask:0xf bank_mask:0xf
	s_nop 1
	v_add_f32_dpp v240, v240, v240 row_half_mirror row_mask:0xf bank_mask:0xf
	s_nop 1
	v_add_f32_dpp v240, v240, v240 row_mirror row_mask:0xf bank_mask:0xf
	s_nop 1
	v_readlane_b32 s0, v240, 0
	v_readlane_b32 s1, v240, 16
	v_readlane_b32 s2, v240, 32
	v_readlane_b32 s3, v240, 48
	v_mov_b32_e32 v249, 0x358637bd
	s_nop 1
	v_mov_b32_e32 v240, s0
	v_add_f32_e32 v240, s1, v240
	v_add_f32_e32 v240, s2, v240
	v_add_f32_e32 v240, s3, v240
	v_fmamk_f32 v240, v240, 0x3a000000, v249
	s_mov_b32 s0, 0xf800000
	v_mul_f32_e32 v241, 0x4f800000, v240
	v_cmp_gt_f32_e32 vcc, s0, v240
	s_nop 1
	v_cndmask_b32_e32 v240, v240, v241, vcc
	v_sqrt_f32_e32 v241, v240
	s_nop 0
	v_add_u32_e32 v242, -1, v241
	v_fma_f32 v243, -v242, v241, v240
	v_cmp_ge_f32_e64 s[0:1], 0, v243
	v_add_u32_e32 v243, 1, v241
	s_nop 0
	v_cndmask_b32_e64 v242, v241, v242, s[0:1]
	v_fma_f32 v241, -v243, v241, v240
	v_cmp_lt_f32_e64 s[0:1], 0, v241
	s_nop 1
	v_cndmask_b32_e64 v241, v242, v243, s[0:1]
	v_mul_f32_e32 v242, 0x37800000, v241
	v_cndmask_b32_e32 v241, v241, v242, vcc
	v_cmp_class_f32_e32 vcc, v240, v248
	s_nop 1
	v_cndmask_b32_e32 v240, v241, v240, vcc
	v_div_scale_f32 v241, s[0:1], v240, v240, 1.0
	v_rcp_f32_e32 v242, v241
	s_nop 0
	v_fma_f32 v243, -v241, v242, 1.0
	v_fmac_f32_e32 v242, v243, v242
	v_div_scale_f32 v243, vcc, 1.0, v240, 1.0
	v_mul_f32_e32 v244, v243, v242
	v_fma_f32 v247, -v241, v244, v243
	v_fmac_f32_e32 v244, v247, v242
	v_fma_f32 v241, -v241, v244, v243
	s_nop 1
	v_div_fmas_f32 v241, v241, v242, v244
	v_div_fixup_f32 v246, v241, v240, 1.0
	v_pk_mul_f32 v[104:105], v[104:105], v[246:247] op_sel_hi:[1,0]
	v_pk_mul_f32 v[106:107], v[106:107], v[246:247] op_sel_hi:[1,0]
	v_pk_mul_f32 v[108:109], v[108:109], v[246:247] op_sel_hi:[1,0]
	v_pk_mul_f32 v[110:111], v[110:111], v[246:247] op_sel_hi:[1,0]
	v_pk_mul_f32 v[112:113], v[112:113], v[246:247] op_sel_hi:[1,0]
	v_pk_mul_f32 v[114:115], v[114:115], v[246:247] op_sel_hi:[1,0]
	v_pk_mul_f32 v[116:117], v[116:117], v[246:247] op_sel_hi:[1,0]
	v_pk_mul_f32 v[118:119], v[118:119], v[246:247] op_sel_hi:[1,0]
	v_pk_mul_f32 v[120:121], v[120:121], v[246:247] op_sel_hi:[1,0]
	v_pk_mul_f32 v[122:123], v[122:123], v[246:247] op_sel_hi:[1,0]
	v_pk_mul_f32 v[124:125], v[124:125], v[246:247] op_sel_hi:[1,0]
	v_pk_mul_f32 v[126:127], v[126:127], v[246:247] op_sel_hi:[1,0]
	v_pk_mul_f32 v[128:129], v[128:129], v[246:247] op_sel_hi:[1,0]
	v_pk_mul_f32 v[130:131], v[130:131], v[246:247] op_sel_hi:[1,0]
	v_pk_mul_f32 v[132:133], v[132:133], v[246:247] op_sel_hi:[1,0]
	v_pk_mul_f32 v[134:135], v[134:135], v[246:247] op_sel_hi:[1,0]
	s_add_u32 s8, s10, 0x20000
	s_addc_u32 s9, s11, 0
	v_pk_fma_f32 v[104:105], v[8:9], v[104:105], v[40:41]
	v_cvt_pk_bf16_f32 v232, v104, v105
	v_pk_fma_f32 v[106:107], v[10:11], v[106:107], v[42:43]
	v_cvt_pk_bf16_f32 v233, v106, v107
	v_pk_fma_f32 v[108:109], v[12:13], v[108:109], v[44:45]
	v_cvt_pk_bf16_f32 v234, v108, v109
	v_pk_fma_f32 v[110:111], v[14:15], v[110:111], v[46:47]
	v_cvt_pk_bf16_f32 v235, v110, v111
	global_store_dwordx4 v1, v[232:235], s[8:9] offset:0
	v_pk_fma_f32 v[112:113], v[16:17], v[112:113], v[48:49]
	v_cvt_pk_bf16_f32 v236, v112, v113
	v_pk_fma_f32 v[114:115], v[18:19], v[114:115], v[50:51]
	v_cvt_pk_bf16_f32 v237, v114, v115
	v_pk_fma_f32 v[116:117], v[20:21], v[116:117], v[52:53]
	v_cvt_pk_bf16_f32 v238, v116, v117
	v_pk_fma_f32 v[118:119], v[22:23], v[118:119], v[54:55]
	v_cvt_pk_bf16_f32 v239, v118, v119
	global_store_dwordx4 v1, v[236:239], s[8:9] offset:1024
	v_pk_fma_f32 v[120:121], v[24:25], v[120:121], v[56:57]
	v_cvt_pk_bf16_f32 v232, v120, v121
	v_pk_fma_f32 v[122:123], v[26:27], v[122:123], v[58:59]
	v_cvt_pk_bf16_f32 v233, v122, v123
	v_pk_fma_f32 v[124:125], v[28:29], v[124:125], v[60:61]
	v_cvt_pk_bf16_f32 v234, v124, v125
	v_pk_fma_f32 v[126:127], v[30:31], v[126:127], v[62:63]
	v_cvt_pk_bf16_f32 v235, v126, v127
	global_store_dwordx4 v1, v[232:235], s[8:9] offset:2048
	v_pk_fma_f32 v[128:129], v[32:33], v[128:129], v[64:65]
	v_cvt_pk_bf16_f32 v236, v128, v129
	v_pk_fma_f32 v[130:131], v[34:35], v[130:131], v[66:67]
	v_cvt_pk_bf16_f32 v237, v130, v131
	v_pk_fma_f32 v[132:133], v[36:37], v[132:133], v[68:69]
	v_cvt_pk_bf16_f32 v238, v132, v133
	v_pk_fma_f32 v[134:135], v[38:39], v[134:135], v[70:71]
	v_cvt_pk_bf16_f32 v239, v134, v135
	global_store_dwordx4 v1, v[236:239], s[8:9] offset:3072
	s_nop 1
	s_add_u32 s8, s6, 0x180000
	s_addc_u32 s9, s7, 0
	global_load_dwordx4 v[104:107], v2, s[8:9] offset:0 nt
	global_load_dwordx4 v[108:111], v2, s[8:9] offset:16 nt
	global_load_dwordx4 v[112:115], v2, s[8:9] offset:2048 nt
	global_load_dwordx4 v[116:119], v2, s[8:9] offset:2064 nt
	global_load_dwordx4 v[120:123], v3, s[8:9] offset:0 nt
	global_load_dwordx4 v[124:127], v3, s[8:9] offset:16 nt
	global_load_dwordx4 v[128:131], v3, s[8:9] offset:2048 nt
	global_load_dwordx4 v[132:135], v3, s[8:9] offset:2064 nt
	s_waitcnt vmcnt(40)
	v_pk_mul_f32 v[232:233], v[136:137], v[136:137]
	v_pk_mul_f32 v[234:235], v[138:139], v[138:139]
	v_pk_mul_f32 v[236:237], v[140:141], v[140:141]
	v_pk_mul_f32 v[238:239], v[142:143], v[142:143]
	v_pk_fma_f32 v[232:233], v[144:145], v[144:145], v[232:233]
	v_pk_fma_f32 v[234:235], v[146:147], v[146:147], v[234:235]
	v_pk_fma_f32 v[236:237], v[148:149], v[148:149], v[236:237]
	v_pk_fma_f32 v[238:239], v[150:151], v[150:151], v[238:239]
	v_pk_fma_f32 v[232:233], v[152:153], v[152:153], v[232:233]
	v_pk_fma_f32 v[234:235], v[154:155], v[154:155], v[234:235]
	v_pk_fma_f32 v[236:237], v[156:157], v[156:157], v[236:237]
	v_pk_fma_f32 v[238:239], v[158:159], v[158:159], v[238:239]
	v_pk_fma_f32 v[232:233], v[160:161], v[160:161], v[232:233]
	v_pk_fma_f32 v[234:235], v[162:163], v[162:163], v[234:235]
	v_pk_fma_f32 v[236:237], v[164:165], v[164:165], v[236:237]
	v_pk_fma_f32 v[238:239], v[166:167], v[166:167], v[238:239]
	v_pk_add_f32 v[232:233], v[232:233], v[234:235]
	v_pk_add_f32 v[236:237], v[236:237], v[238:239]
	v_pk_add_f32 v[232:233], v[232:233], v[236:237]
	v_add_f32_e32 v240, v232, v233
	s_nop 1
	v_add_f32_dpp v240, v240, v240 quad_perm:[1,0,3,2] row_mask:0xf bank_mask:0xf
	s_nop 1
	v_add_f32_dpp v240, v240, v240 quad_perm:[2,3,0,1] row_mask:0xf bank_mask:0xf
	s_nop 1
	v_add_f32_dpp v240, v240, v240 row_half_mirror row_mask:0xf bank_mask:0xf
	s_nop 1
	v_add_f32_dpp v240, v240, v240 row_mirror row_mask:0xf bank_mask:0xf
	s_nop 1
	v_readlane_b32 s0, v240, 0
	v_readlane_b32 s1, v240, 16
	v_readlane_b32 s2, v240, 32
	v_readlane_b32 s3, v240, 48
	v_mov_b32_e32 v249, 0x358637bd
	s_nop 1
	v_mov_b32_e32 v240, s0
	v_add_f32_e32 v240, s1, v240
	v_add_f32_e32 v240, s2, v240
	v_add_f32_e32 v240, s3, v240
	v_fmamk_f32 v240, v240, 0x3a000000, v249
	s_mov_b32 s0, 0xf800000
	v_mul_f32_e32 v241, 0x4f800000, v240
	v_cmp_gt_f32_e32 vcc, s0, v240
	s_nop 1
	v_cndmask_b32_e32 v240, v240, v241, vcc
	v_sqrt_f32_e32 v241, v240
	s_nop 0
	v_add_u32_e32 v242, -1, v241
	v_fma_f32 v243, -v242, v241, v240
	v_cmp_ge_f32_e64 s[0:1], 0, v243
	v_add_u32_e32 v243, 1, v241
	s_nop 0
	v_cndmask_b32_e64 v242, v241, v242, s[0:1]
	v_fma_f32 v241, -v243, v241, v240
	v_cmp_lt_f32_e64 s[0:1], 0, v241
	s_nop 1
	v_cndmask_b32_e64 v241, v242, v243, s[0:1]
	v_mul_f32_e32 v242, 0x37800000, v241
	v_cndmask_b32_e32 v241, v241, v242, vcc
	v_cmp_class_f32_e32 vcc, v240, v248
	s_nop 1
	v_cndmask_b32_e32 v240, v241, v240, vcc
	v_div_scale_f32 v241, s[0:1], v240, v240, 1.0
	v_rcp_f32_e32 v242, v241
	s_nop 0
	v_fma_f32 v243, -v241, v242, 1.0
	v_fmac_f32_e32 v242, v243, v242
	v_div_scale_f32 v243, vcc, 1.0, v240, 1.0
	v_mul_f32_e32 v244, v243, v242
	v_fma_f32 v247, -v241, v244, v243
	v_fmac_f32_e32 v244, v247, v242
	v_fma_f32 v241, -v241, v244, v243
	s_nop 1
	v_div_fmas_f32 v241, v241, v242, v244
	v_div_fixup_f32 v246, v241, v240, 1.0
	v_pk_mul_f32 v[136:137], v[136:137], v[246:247] op_sel_hi:[1,0]
	v_pk_mul_f32 v[138:139], v[138:139], v[246:247] op_sel_hi:[1,0]
	v_pk_mul_f32 v[140:141], v[140:141], v[246:247] op_sel_hi:[1,0]
	v_pk_mul_f32 v[142:143], v[142:143], v[246:247] op_sel_hi:[1,0]
	v_pk_mul_f32 v[144:145], v[144:145], v[246:247] op_sel_hi:[1,0]
	v_pk_mul_f32 v[146:147], v[146:147], v[246:247] op_sel_hi:[1,0]
	v_pk_mul_f32 v[148:149], v[148:149], v[246:247] op_sel_hi:[1,0]
	v_pk_mul_f32 v[150:151], v[150:151], v[246:247] op_sel_hi:[1,0]
	v_pk_mul_f32 v[152:153], v[152:153], v[246:247] op_sel_hi:[1,0]
	v_pk_mul_f32 v[154:155], v[154:155], v[246:247] op_sel_hi:[1,0]
	v_pk_mul_f32 v[156:157], v[156:157], v[246:247] op_sel_hi:[1,0]
	v_pk_mul_f32 v[158:159], v[158:159], v[246:247] op_sel_hi:[1,0]
	v_pk_mul_f32 v[160:161], v[160:161], v[246:247] op_sel_hi:[1,0]
	v_pk_mul_f32 v[162:163], v[162:163], v[246:247] op_sel_hi:[1,0]
	v_pk_mul_f32 v[164:165], v[164:165], v[246:247] op_sel_hi:[1,0]
	v_pk_mul_f32 v[166:167], v[166:167], v[246:247] op_sel_hi:[1,0]
	s_add_u32 s8, s10, 0x40000
	s_addc_u32 s9, s11, 0
	v_pk_fma_f32 v[136:137], v[8:9], v[136:137], v[40:41]
	v_cvt_pk_bf16_f32 v232, v136, v137
	v_pk_fma_f32 v[138:139], v[10:11], v[138:139], v[42:43]
	v_cvt_pk_bf16_f32 v233, v138, v139
	v_pk_fma_f32 v[140:141], v[12:13], v[140:141], v[44:45]
	v_cvt_pk_bf16_f32 v234, v140, v141
	v_pk_fma_f32 v[142:143], v[14:15], v[142:143], v[46:47]
	v_cvt_pk_bf16_f32 v235, v142, v143
	global_store_dwordx4 v1, v[232:235], s[8:9] offset:0
	v_pk_fma_f32 v[144:145], v[16:17], v[144:145], v[48:49]
	v_cvt_pk_bf16_f32 v236, v144, v145
	v_pk_fma_f32 v[146:147], v[18:19], v[146:147], v[50:51]
	v_cvt_pk_bf16_f32 v237, v146, v147
	v_pk_fma_f32 v[148:149], v[20:21], v[148:149], v[52:53]
	v_cvt_pk_bf16_f32 v238, v148, v149
	v_pk_fma_f32 v[150:151], v[22:23], v[150:151], v[54:55]
	v_cvt_pk_bf16_f32 v239, v150, v151
	global_store_dwordx4 v1, v[236:239], s[8:9] offset:1024
	v_pk_fma_f32 v[152:153], v[24:25], v[152:153], v[56:57]
	v_cvt_pk_bf16_f32 v232, v152, v153
	v_pk_fma_f32 v[154:155], v[26:27], v[154:155], v[58:59]
	v_cvt_pk_bf16_f32 v233, v154, v155
	v_pk_fma_f32 v[156:157], v[28:29], v[156:157], v[60:61]
	v_cvt_pk_bf16_f32 v234, v156, v157
	v_pk_fma_f32 v[158:159], v[30:31], v[158:159], v[62:63]
	v_cvt_pk_bf16_f32 v235, v158, v159
	global_store_dwordx4 v1, v[232:235], s[8:9] offset:2048
	v_pk_fma_f32 v[160:161], v[32:33], v[160:161], v[64:65]
	v_cvt_pk_bf16_f32 v236, v160, v161
	v_pk_fma_f32 v[162:163], v[34:35], v[162:163], v[66:67]
	v_cvt_pk_bf16_f32 v237, v162, v163
	v_pk_fma_f32 v[164:165], v[36:37], v[164:165], v[68:69]
	v_cvt_pk_bf16_f32 v238, v164, v165
	v_pk_fma_f32 v[166:167], v[38:39], v[166:167], v[70:71]
	v_cvt_pk_bf16_f32 v239, v166, v167
	global_store_dwordx4 v1, v[236:239], s[8:9] offset:3072
	s_nop 1
	s_add_u32 s8, s6, 0x1c0000
	s_addc_u32 s9, s7, 0
	global_load_dwordx4 v[136:139], v2, s[8:9] offset:0 nt
	global_load_dwordx4 v[140:143], v2, s[8:9] offset:16 nt
	global_load_dwordx4 v[144:147], v2, s[8:9] offset:2048 nt
	global_load_dwordx4 v[148:151], v2, s[8:9] offset:2064 nt
	global_load_dwordx4 v[152:155], v3, s[8:9] offset:0 nt
	global_load_dwordx4 v[156:159], v3, s[8:9] offset:16 nt
	global_load_dwordx4 v[160:163], v3, s[8:9] offset:2048 nt
	global_load_dwordx4 v[164:167], v3, s[8:9] offset:2064 nt
	s_waitcnt vmcnt(44)
	v_pk_mul_f32 v[232:233], v[168:169], v[168:169]
	v_pk_mul_f32 v[234:235], v[170:171], v[170:171]
	v_pk_mul_f32 v[236:237], v[172:173], v[172:173]
	v_pk_mul_f32 v[238:239], v[174:175], v[174:175]
	v_pk_fma_f32 v[232:233], v[176:177], v[176:177], v[232:233]
	v_pk_fma_f32 v[234:235], v[178:179], v[178:179], v[234:235]
	v_pk_fma_f32 v[236:237], v[180:181], v[180:181], v[236:237]
	v_pk_fma_f32 v[238:239], v[182:183], v[182:183], v[238:239]
	v_pk_fma_f32 v[232:233], v[184:185], v[184:185], v[232:233]
	v_pk_fma_f32 v[234:235], v[186:187], v[186:187], v[234:235]
	v_pk_fma_f32 v[236:237], v[188:189], v[188:189], v[236:237]
	v_pk_fma_f32 v[238:239], v[190:191], v[190:191], v[238:239]
	v_pk_fma_f32 v[232:233], v[192:193], v[192:193], v[232:233]
	v_pk_fma_f32 v[234:235], v[194:195], v[194:195], v[234:235]
	v_pk_fma_f32 v[236:237], v[196:197], v[196:197], v[236:237]
	v_pk_fma_f32 v[238:239], v[198:199], v[198:199], v[238:239]
	v_pk_add_f32 v[232:233], v[232:233], v[234:235]
	v_pk_add_f32 v[236:237], v[236:237], v[238:239]
	v_pk_add_f32 v[232:233], v[232:233], v[236:237]
	v_add_f32_e32 v240, v232, v233
	s_nop 1
	v_add_f32_dpp v240, v240, v240 quad_perm:[1,0,3,2] row_mask:0xf bank_mask:0xf
	s_nop 1
	v_add_f32_dpp v240, v240, v240 quad_perm:[2,3,0,1] row_mask:0xf bank_mask:0xf
	s_nop 1
	v_add_f32_dpp v240, v240, v240 row_half_mirror row_mask:0xf bank_mask:0xf
	s_nop 1
	v_add_f32_dpp v240, v240, v240 row_mirror row_mask:0xf bank_mask:0xf
	s_nop 1
	v_readlane_b32 s0, v240, 0
	v_readlane_b32 s1, v240, 16
	v_readlane_b32 s2, v240, 32
	v_readlane_b32 s3, v240, 48
	v_mov_b32_e32 v249, 0x358637bd
	s_nop 1
	v_mov_b32_e32 v240, s0
	v_add_f32_e32 v240, s1, v240
	v_add_f32_e32 v240, s2, v240
	v_add_f32_e32 v240, s3, v240
	v_fmamk_f32 v240, v240, 0x3a000000, v249
	s_mov_b32 s0, 0xf800000
	v_mul_f32_e32 v241, 0x4f800000, v240
	v_cmp_gt_f32_e32 vcc, s0, v240
	s_nop 1
	v_cndmask_b32_e32 v240, v240, v241, vcc
	v_sqrt_f32_e32 v241, v240
	s_nop 0
	v_add_u32_e32 v242, -1, v241
	v_fma_f32 v243, -v242, v241, v240
	v_cmp_ge_f32_e64 s[0:1], 0, v243
	v_add_u32_e32 v243, 1, v241
	s_nop 0
	v_cndmask_b32_e64 v242, v241, v242, s[0:1]
	v_fma_f32 v241, -v243, v241, v240
	v_cmp_lt_f32_e64 s[0:1], 0, v241
	s_nop 1
	v_cndmask_b32_e64 v241, v242, v243, s[0:1]
	v_mul_f32_e32 v242, 0x37800000, v241
	v_cndmask_b32_e32 v241, v241, v242, vcc
	v_cmp_class_f32_e32 vcc, v240, v248
	s_nop 1
	v_cndmask_b32_e32 v240, v241, v240, vcc
	v_div_scale_f32 v241, s[0:1], v240, v240, 1.0
	v_rcp_f32_e32 v242, v241
	s_nop 0
	v_fma_f32 v243, -v241, v242, 1.0
	v_fmac_f32_e32 v242, v243, v242
	v_div_scale_f32 v243, vcc, 1.0, v240, 1.0
	v_mul_f32_e32 v244, v243, v242
	v_fma_f32 v247, -v241, v244, v243
	v_fmac_f32_e32 v244, v247, v242
	v_fma_f32 v241, -v241, v244, v243
	s_nop 1
	v_div_fmas_f32 v241, v241, v242, v244
	v_div_fixup_f32 v246, v241, v240, 1.0
	v_pk_mul_f32 v[168:169], v[168:169], v[246:247] op_sel_hi:[1,0]
	v_pk_mul_f32 v[170:171], v[170:171], v[246:247] op_sel_hi:[1,0]
	v_pk_mul_f32 v[172:173], v[172:173], v[246:247] op_sel_hi:[1,0]
	v_pk_mul_f32 v[174:175], v[174:175], v[246:247] op_sel_hi:[1,0]
	v_pk_mul_f32 v[176:177], v[176:177], v[246:247] op_sel_hi:[1,0]
	v_pk_mul_f32 v[178:179], v[178:179], v[246:247] op_sel_hi:[1,0]
	v_pk_mul_f32 v[180:181], v[180:181], v[246:247] op_sel_hi:[1,0]
	v_pk_mul_f32 v[182:183], v[182:183], v[246:247] op_sel_hi:[1,0]
	v_pk_mul_f32 v[184:185], v[184:185], v[246:247] op_sel_hi:[1,0]
	v_pk_mul_f32 v[186:187], v[186:187], v[246:247] op_sel_hi:[1,0]
	v_pk_mul_f32 v[188:189], v[188:189], v[246:247] op_sel_hi:[1,0]
	v_pk_mul_f32 v[190:191], v[190:191], v[246:247] op_sel_hi:[1,0]
	v_pk_mul_f32 v[192:193], v[192:193], v[246:247] op_sel_hi:[1,0]
	v_pk_mul_f32 v[194:195], v[194:195], v[246:247] op_sel_hi:[1,0]
	v_pk_mul_f32 v[196:197], v[196:197], v[246:247] op_sel_hi:[1,0]
	v_pk_mul_f32 v[198:199], v[198:199], v[246:247] op_sel_hi:[1,0]
	s_add_u32 s8, s10, 0x60000
	s_addc_u32 s9, s11, 0
	v_pk_fma_f32 v[168:169], v[8:9], v[168:169], v[40:41]
	v_cvt_pk_bf16_f32 v232, v168, v169
	v_pk_fma_f32 v[170:171], v[10:11], v[170:171], v[42:43]
	v_cvt_pk_bf16_f32 v233, v170, v171
	v_pk_fma_f32 v[172:173], v[12:13], v[172:173], v[44:45]
	v_cvt_pk_bf16_f32 v234, v172, v173
	v_pk_fma_f32 v[174:175], v[14:15], v[174:175], v[46:47]
	v_cvt_pk_bf16_f32 v235, v174, v175
	global_store_dwordx4 v1, v[232:235], s[8:9] offset:0
	v_pk_fma_f32 v[176:177], v[16:17], v[176:177], v[48:49]
	v_cvt_pk_bf16_f32 v236, v176, v177
	v_pk_fma_f32 v[178:179], v[18:19], v[178:179], v[50:51]
	v_cvt_pk_bf16_f32 v237, v178, v179
	v_pk_fma_f32 v[180:181], v[20:21], v[180:181], v[52:53]
	v_cvt_pk_bf16_f32 v238, v180, v181
	v_pk_fma_f32 v[182:183], v[22:23], v[182:183], v[54:55]
	v_cvt_pk_bf16_f32 v239, v182, v183
	global_store_dwordx4 v1, v[236:239], s[8:9] offset:1024
	v_pk_fma_f32 v[184:185], v[24:25], v[184:185], v[56:57]
	v_cvt_pk_bf16_f32 v232, v184, v185
	v_pk_fma_f32 v[186:187], v[26:27], v[186:187], v[58:59]
	v_cvt_pk_bf16_f32 v233, v186, v187
	v_pk_fma_f32 v[188:189], v[28:29], v[188:189], v[60:61]
	v_cvt_pk_bf16_f32 v234, v188, v189
	v_pk_fma_f32 v[190:191], v[30:31], v[190:191], v[62:63]
	v_cvt_pk_bf16_f32 v235, v190, v191
	global_store_dwordx4 v1, v[232:235], s[8:9] offset:2048
	v_pk_fma_f32 v[192:193], v[32:33], v[192:193], v[64:65]
	v_cvt_pk_bf16_f32 v236, v192, v193
	v_pk_fma_f32 v[194:195], v[34:35], v[194:195], v[66:67]
	v_cvt_pk_bf16_f32 v237, v194, v195
	v_pk_fma_f32 v[196:197], v[36:37], v[196:197], v[68:69]
	v_cvt_pk_bf16_f32 v238, v196, v197
	v_pk_fma_f32 v[198:199], v[38:39], v[198:199], v[70:71]
	v_cvt_pk_bf16_f32 v239, v198, v199
	global_store_dwordx4 v1, v[236:239], s[8:9] offset:3072
	s_waitcnt vmcnt(40)
	v_pk_mul_f32 v[232:233], v[200:201], v[200:201]
	v_pk_mul_f32 v[234:235], v[202:203], v[202:203]
	v_pk_mul_f32 v[236:237], v[204:205], v[204:205]
	v_pk_mul_f32 v[238:239], v[206:207], v[206:207]
	v_pk_fma_f32 v[232:233], v[208:209], v[208:209], v[232:233]
	v_pk_fma_f32 v[234:235], v[210:211], v[210:211], v[234:235]
	v_pk_fma_f32 v[236:237], v[212:213], v[212:213], v[236:237]
	v_pk_fma_f32 v[238:239], v[214:215], v[214:215], v[238:239]
	v_pk_fma_f32 v[232:233], v[216:217], v[216:217], v[232:233]
	v_pk_fma_f32 v[234:235], v[218:219], v[218:219], v[234:235]
	v_pk_fma_f32 v[236:237], v[220:221], v[220:221], v[236:237]
	v_pk_fma_f32 v[238:239], v[222:223], v[222:223], v[238:239]
	v_pk_fma_f32 v[232:233], v[224:225], v[224:225], v[232:233]
	v_pk_fma_f32 v[234:235], v[226:227], v[226:227], v[234:235]
	v_pk_fma_f32 v[236:237], v[228:229], v[228:229], v[236:237]
	v_pk_fma_f32 v[238:239], v[230:231], v[230:231], v[238:239]
	v_pk_add_f32 v[232:233], v[232:233], v[234:235]
	v_pk_add_f32 v[236:237], v[236:237], v[238:239]
	v_pk_add_f32 v[232:233], v[232:233], v[236:237]
	v_add_f32_e32 v240, v232, v233
	s_nop 1
	v_add_f32_dpp v240, v240, v240 quad_perm:[1,0,3,2] row_mask:0xf bank_mask:0xf
	s_nop 1
	v_add_f32_dpp v240, v240, v240 quad_perm:[2,3,0,1] row_mask:0xf bank_mask:0xf
	s_nop 1
	v_add_f32_dpp v240, v240, v240 row_half_mirror row_mask:0xf bank_mask:0xf
	s_nop 1
	v_add_f32_dpp v240, v240, v240 row_mirror row_mask:0xf bank_mask:0xf
	s_nop 1
	v_readlane_b32 s0, v240, 0
	v_readlane_b32 s1, v240, 16
	v_readlane_b32 s2, v240, 32
	v_readlane_b32 s3, v240, 48
	v_mov_b32_e32 v249, 0x358637bd
	s_nop 1
	v_mov_b32_e32 v240, s0
	v_add_f32_e32 v240, s1, v240
	v_add_f32_e32 v240, s2, v240
	v_add_f32_e32 v240, s3, v240
	v_fmamk_f32 v240, v240, 0x3a000000, v249
	s_mov_b32 s0, 0xf800000
	v_mul_f32_e32 v241, 0x4f800000, v240
	v_cmp_gt_f32_e32 vcc, s0, v240
	s_nop 1
	v_cndmask_b32_e32 v240, v240, v241, vcc
	v_sqrt_f32_e32 v241, v240
	s_nop 0
	v_add_u32_e32 v242, -1, v241
	v_fma_f32 v243, -v242, v241, v240
	v_cmp_ge_f32_e64 s[0:1], 0, v243
	v_add_u32_e32 v243, 1, v241
	s_nop 0
	v_cndmask_b32_e64 v242, v241, v242, s[0:1]
	v_fma_f32 v241, -v243, v241, v240
	v_cmp_lt_f32_e64 s[0:1], 0, v241
	s_nop 1
	v_cndmask_b32_e64 v241, v242, v243, s[0:1]
	v_mul_f32_e32 v242, 0x37800000, v241
	v_cndmask_b32_e32 v241, v241, v242, vcc
	v_cmp_class_f32_e32 vcc, v240, v248
	s_nop 1
	v_cndmask_b32_e32 v240, v241, v240, vcc
	v_div_scale_f32 v241, s[0:1], v240, v240, 1.0
	v_rcp_f32_e32 v242, v241
	s_nop 0
	v_fma_f32 v243, -v241, v242, 1.0
	v_fmac_f32_e32 v242, v243, v242
	v_div_scale_f32 v243, vcc, 1.0, v240, 1.0
	v_mul_f32_e32 v244, v243, v242
	v_fma_f32 v247, -v241, v244, v243
	v_fmac_f32_e32 v244, v247, v242
	v_fma_f32 v241, -v241, v244, v243
	s_nop 1
	v_div_fmas_f32 v241, v241, v242, v244
	v_div_fixup_f32 v246, v241, v240, 1.0
	v_pk_mul_f32 v[200:201], v[200:201], v[246:247] op_sel_hi:[1,0]
	v_pk_mul_f32 v[202:203], v[202:203], v[246:247] op_sel_hi:[1,0]
	v_pk_mul_f32 v[204:205], v[204:205], v[246:247] op_sel_hi:[1,0]
	v_pk_mul_f32 v[206:207], v[206:207], v[246:247] op_sel_hi:[1,0]
	v_pk_mul_f32 v[208:209], v[208:209], v[246:247] op_sel_hi:[1,0]
	v_pk_mul_f32 v[210:211], v[210:211], v[246:247] op_sel_hi:[1,0]
	v_pk_mul_f32 v[212:213], v[212:213], v[246:247] op_sel_hi:[1,0]
	v_pk_mul_f32 v[214:215], v[214:215], v[246:247] op_sel_hi:[1,0]
	v_pk_mul_f32 v[216:217], v[216:217], v[246:247] op_sel_hi:[1,0]
	v_pk_mul_f32 v[218:219], v[218:219], v[246:247] op_sel_hi:[1,0]
	v_pk_mul_f32 v[220:221], v[220:221], v[246:247] op_sel_hi:[1,0]
	v_pk_mul_f32 v[222:223], v[222:223], v[246:247] op_sel_hi:[1,0]
	v_pk_mul_f32 v[224:225], v[224:225], v[246:247] op_sel_hi:[1,0]
	v_pk_mul_f32 v[226:227], v[226:227], v[246:247] op_sel_hi:[1,0]
	v_pk_mul_f32 v[228:229], v[228:229], v[246:247] op_sel_hi:[1,0]
	v_pk_mul_f32 v[230:231], v[230:231], v[246:247] op_sel_hi:[1,0]
	s_add_u32 s8, s10, 0x80000
	s_addc_u32 s9, s11, 0
	v_pk_fma_f32 v[200:201], v[8:9], v[200:201], v[40:41]
	v_cvt_pk_bf16_f32 v232, v200, v201
	v_pk_fma_f32 v[202:203], v[10:11], v[202:203], v[42:43]
	v_cvt_pk_bf16_f32 v233, v202, v203
	v_pk_fma_f32 v[204:205], v[12:13], v[204:205], v[44:45]
	v_cvt_pk_bf16_f32 v234, v204, v205
	v_pk_fma_f32 v[206:207], v[14:15], v[206:207], v[46:47]
	v_cvt_pk_bf16_f32 v235, v206, v207
	global_store_dwordx4 v1, v[232:235], s[8:9] offset:0
	v_pk_fma_f32 v[208:209], v[16:17], v[208:209], v[48:49]
	v_cvt_pk_bf16_f32 v236, v208, v209
	v_pk_fma_f32 v[210:211], v[18:19], v[210:211], v[50:51]
	v_cvt_pk_bf16_f32 v237, v210, v211
	v_pk_fma_f32 v[212:213], v[20:21], v[212:213], v[52:53]
	v_cvt_pk_bf16_f32 v238, v212, v213
	v_pk_fma_f32 v[214:215], v[22:23], v[214:215], v[54:55]
	v_cvt_pk_bf16_f32 v239, v214, v215
	global_store_dwordx4 v1, v[236:239], s[8:9] offset:1024
	v_pk_fma_f32 v[216:217], v[24:25], v[216:217], v[56:57]
	v_cvt_pk_bf16_f32 v232, v216, v217
	v_pk_fma_f32 v[218:219], v[26:27], v[218:219], v[58:59]
	v_cvt_pk_bf16_f32 v233, v218, v219
	v_pk_fma_f32 v[220:221], v[28:29], v[220:221], v[60:61]
	v_cvt_pk_bf16_f32 v234, v220, v221
	v_pk_fma_f32 v[222:223], v[30:31], v[222:223], v[62:63]
	v_cvt_pk_bf16_f32 v235, v222, v223
	global_store_dwordx4 v1, v[232:235], s[8:9] offset:2048
	v_pk_fma_f32 v[224:225], v[32:33], v[224:225], v[64:65]
	v_cvt_pk_bf16_f32 v236, v224, v225
	v_pk_fma_f32 v[226:227], v[34:35], v[226:227], v[66:67]
	v_cvt_pk_bf16_f32 v237, v226, v227
	v_pk_fma_f32 v[228:229], v[36:37], v[228:229], v[68:69]
	v_cvt_pk_bf16_f32 v238, v228, v229
	v_pk_fma_f32 v[230:231], v[38:39], v[230:231], v[70:71]
	v_cvt_pk_bf16_f32 v239, v230, v231
	global_store_dwordx4 v1, v[236:239], s[8:9] offset:3072
	s_waitcnt vmcnt(32)
	v_pk_mul_f32 v[232:233], v[72:73], v[72:73]
	v_pk_mul_f32 v[234:235], v[74:75], v[74:75]
	v_pk_mul_f32 v[236:237], v[76:77], v[76:77]
	v_pk_mul_f32 v[238:239], v[78:79], v[78:79]
	v_pk_fma_f32 v[232:233], v[80:81], v[80:81], v[232:233]
	v_pk_fma_f32 v[234:235], v[82:83], v[82:83], v[234:235]
	v_pk_fma_f32 v[236:237], v[84:85], v[84:85], v[236:237]
	v_pk_fma_f32 v[238:239], v[86:87], v[86:87], v[238:239]
	v_pk_fma_f32 v[232:233], v[88:89], v[88:89], v[232:233]
	v_pk_fma_f32 v[234:235], v[90:91], v[90:91], v[234:235]
	v_pk_fma_f32 v[236:237], v[92:93], v[92:93], v[236:237]
	v_pk_fma_f32 v[238:239], v[94:95], v[94:95], v[238:239]
	v_pk_fma_f32 v[232:233], v[96:97], v[96:97], v[232:233]
	v_pk_fma_f32 v[234:235], v[98:99], v[98:99], v[234:235]
	v_pk_fma_f32 v[236:237], v[100:101], v[100:101], v[236:237]
	v_pk_fma_f32 v[238:239], v[102:103], v[102:103], v[238:239]
	v_pk_add_f32 v[232:233], v[232:233], v[234:235]
	v_pk_add_f32 v[236:237], v[236:237], v[238:239]
	v_pk_add_f32 v[232:233], v[232:233], v[236:237]
	v_add_f32_e32 v240, v232, v233
	s_nop 1
	v_add_f32_dpp v240, v240, v240 quad_perm:[1,0,3,2] row_mask:0xf bank_mask:0xf
	s_nop 1
	v_add_f32_dpp v240, v240, v240 quad_perm:[2,3,0,1] row_mask:0xf bank_mask:0xf
	s_nop 1
	v_add_f32_dpp v240, v240, v240 row_half_mirror row_mask:0xf bank_mask:0xf
	s_nop 1
	v_add_f32_dpp v240, v240, v240 row_mirror row_mask:0xf bank_mask:0xf
	s_nop 1
	v_readlane_b32 s0, v240, 0
	v_readlane_b32 s1, v240, 16
	v_readlane_b32 s2, v240, 32
	v_readlane_b32 s3, v240, 48
	v_mov_b32_e32 v249, 0x358637bd
	s_nop 1
	v_mov_b32_e32 v240, s0
	v_add_f32_e32 v240, s1, v240
	v_add_f32_e32 v240, s2, v240
	v_add_f32_e32 v240, s3, v240
	v_fmamk_f32 v240, v240, 0x3a000000, v249
	s_mov_b32 s0, 0xf800000
	v_mul_f32_e32 v241, 0x4f800000, v240
	v_cmp_gt_f32_e32 vcc, s0, v240
	s_nop 1
	v_cndmask_b32_e32 v240, v240, v241, vcc
	v_sqrt_f32_e32 v241, v240
	s_nop 0
	v_add_u32_e32 v242, -1, v241
	v_fma_f32 v243, -v242, v241, v240
	v_cmp_ge_f32_e64 s[0:1], 0, v243
	v_add_u32_e32 v243, 1, v241
	s_nop 0
	v_cndmask_b32_e64 v242, v241, v242, s[0:1]
	v_fma_f32 v241, -v243, v241, v240
	v_cmp_lt_f32_e64 s[0:1], 0, v241
	s_nop 1
	v_cndmask_b32_e64 v241, v242, v243, s[0:1]
	v_mul_f32_e32 v242, 0x37800000, v241
	v_cndmask_b32_e32 v241, v241, v242, vcc
	v_cmp_class_f32_e32 vcc, v240, v248
	s_nop 1
	v_cndmask_b32_e32 v240, v241, v240, vcc
	v_div_scale_f32 v241, s[0:1], v240, v240, 1.0
	v_rcp_f32_e32 v242, v241
	s_nop 0
	v_fma_f32 v243, -v241, v242, 1.0
	v_fmac_f32_e32 v242, v243, v242
	v_div_scale_f32 v243, vcc, 1.0, v240, 1.0
	v_mul_f32_e32 v244, v243, v242
	v_fma_f32 v247, -v241, v244, v243
	v_fmac_f32_e32 v244, v247, v242
	v_fma_f32 v241, -v241, v244, v243
	s_nop 1
	v_div_fmas_f32 v241, v241, v242, v244
	v_div_fixup_f32 v246, v241, v240, 1.0
	v_pk_mul_f32 v[72:73], v[72:73], v[246:247] op_sel_hi:[1,0]
	v_pk_mul_f32 v[74:75], v[74:75], v[246:247] op_sel_hi:[1,0]
	v_pk_mul_f32 v[76:77], v[76:77], v[246:247] op_sel_hi:[1,0]
	v_pk_mul_f32 v[78:79], v[78:79], v[246:247] op_sel_hi:[1,0]
	v_pk_mul_f32 v[80:81], v[80:81], v[246:247] op_sel_hi:[1,0]
	v_pk_mul_f32 v[82:83], v[82:83], v[246:247] op_sel_hi:[1,0]
	v_pk_mul_f32 v[84:85], v[84:85], v[246:247] op_sel_hi:[1,0]
	v_pk_mul_f32 v[86:87], v[86:87], v[246:247] op_sel_hi:[1,0]
	v_pk_mul_f32 v[88:89], v[88:89], v[246:247] op_sel_hi:[1,0]
	v_pk_mul_f32 v[90:91], v[90:91], v[246:247] op_sel_hi:[1,0]
	v_pk_mul_f32 v[92:93], v[92:93], v[246:247] op_sel_hi:[1,0]
	v_pk_mul_f32 v[94:95], v[94:95], v[246:247] op_sel_hi:[1,0]
	v_pk_mul_f32 v[96:97], v[96:97], v[246:247] op_sel_hi:[1,0]
	v_pk_mul_f32 v[98:99], v[98:99], v[246:247] op_sel_hi:[1,0]
	v_pk_mul_f32 v[100:101], v[100:101], v[246:247] op_sel_hi:[1,0]
	v_pk_mul_f32 v[102:103], v[102:103], v[246:247] op_sel_hi:[1,0]
	s_add_u32 s8, s10, 0xa0000
	s_addc_u32 s9, s11, 0
	v_pk_fma_f32 v[72:73], v[8:9], v[72:73], v[40:41]
	v_cvt_pk_bf16_f32 v232, v72, v73
	v_pk_fma_f32 v[74:75], v[10:11], v[74:75], v[42:43]
	v_cvt_pk_bf16_f32 v233, v74, v75
	v_pk_fma_f32 v[76:77], v[12:13], v[76:77], v[44:45]
	v_cvt_pk_bf16_f32 v234, v76, v77
	v_pk_fma_f32 v[78:79], v[14:15], v[78:79], v[46:47]
	v_cvt_pk_bf16_f32 v235, v78, v79
	global_store_dwordx4 v1, v[232:235], s[8:9] offset:0
	v_pk_fma_f32 v[80:81], v[16:17], v[80:81], v[48:49]
	v_cvt_pk_bf16_f32 v236, v80, v81
	v_pk_fma_f32 v[82:83], v[18:19], v[82:83], v[50:51]
	v_cvt_pk_bf16_f32 v237, v82, v83
	v_pk_fma_f32 v[84:85], v[20:21], v[84:85], v[52:53]
	v_cvt_pk_bf16_f32 v238, v84, v85
	v_pk_fma_f32 v[86:87], v[22:23], v[86:87], v[54:55]
	v_cvt_pk_bf16_f32 v239, v86, v87
	global_store_dwordx4 v1, v[236:239], s[8:9] offset:1024
	v_pk_fma_f32 v[88:89], v[24:25], v[88:89], v[56:57]
	v_cvt_pk_bf16_f32 v232, v88, v89
	v_pk_fma_f32 v[90:91], v[26:27], v[90:91], v[58:59]
	v_cvt_pk_bf16_f32 v233, v90, v91
	v_pk_fma_f32 v[92:93], v[28:29], v[92:93], v[60:61]
	v_cvt_pk_bf16_f32 v234, v92, v93
	v_pk_fma_f32 v[94:95], v[30:31], v[94:95], v[62:63]
	v_cvt_pk_bf16_f32 v235, v94, v95
	global_store_dwordx4 v1, v[232:235], s[8:9] offset:2048
	v_pk_fma_f32 v[96:97], v[32:33], v[96:97], v[64:65]
	v_cvt_pk_bf16_f32 v236, v96, v97
	v_pk_fma_f32 v[98:99], v[34:35], v[98:99], v[66:67]
	v_cvt_pk_bf16_f32 v237, v98, v99
	v_pk_fma_f32 v[100:101], v[36:37], v[100:101], v[68:69]
	v_cvt_pk_bf16_f32 v238, v100, v101
	v_pk_fma_f32 v[102:103], v[38:39], v[102:103], v[70:71]
	v_cvt_pk_bf16_f32 v239, v102, v103
	global_store_dwordx4 v1, v[236:239], s[8:9] offset:3072
	s_waitcnt vmcnt(24)
	v_pk_mul_f32 v[232:233], v[104:105], v[104:105]
	v_pk_mul_f32 v[234:235], v[106:107], v[106:107]
	v_pk_mul_f32 v[236:237], v[108:109], v[108:109]
	v_pk_mul_f32 v[238:239], v[110:111], v[110:111]
	v_pk_fma_f32 v[232:233], v[112:113], v[112:113], v[232:233]
	v_pk_fma_f32 v[234:235], v[114:115], v[114:115], v[234:235]
	v_pk_fma_f32 v[236:237], v[116:117], v[116:117], v[236:237]
	v_pk_fma_f32 v[238:239], v[118:119], v[118:119], v[238:239]
	v_pk_fma_f32 v[232:233], v[120:121], v[120:121], v[232:233]
	v_pk_fma_f32 v[234:235], v[122:123], v[122:123], v[234:235]
	v_pk_fma_f32 v[236:237], v[124:125], v[124:125], v[236:237]
	v_pk_fma_f32 v[238:239], v[126:127], v[126:127], v[238:239]
	v_pk_fma_f32 v[232:233], v[128:129], v[128:129], v[232:233]
	v_pk_fma_f32 v[234:235], v[130:131], v[130:131], v[234:235]
	v_pk_fma_f32 v[236:237], v[132:133], v[132:133], v[236:237]
	v_pk_fma_f32 v[238:239], v[134:135], v[134:135], v[238:239]
	v_pk_add_f32 v[232:233], v[232:233], v[234:235]
	v_pk_add_f32 v[236:237], v[236:237], v[238:239]
	v_pk_add_f32 v[232:233], v[232:233], v[236:237]
	v_add_f32_e32 v240, v232, v233
	s_nop 1
	v_add_f32_dpp v240, v240, v240 quad_perm:[1,0,3,2] row_mask:0xf bank_mask:0xf
	s_nop 1
	v_add_f32_dpp v240, v240, v240 quad_perm:[2,3,0,1] row_mask:0xf bank_mask:0xf
	s_nop 1
	v_add_f32_dpp v240, v240, v240 row_half_mirror row_mask:0xf bank_mask:0xf
	s_nop 1
	v_add_f32_dpp v240, v240, v240 row_mirror row_mask:0xf bank_mask:0xf
	s_nop 1
	v_readlane_b32 s0, v240, 0
	v_readlane_b32 s1, v240, 16
	v_readlane_b32 s2, v240, 32
	v_readlane_b32 s3, v240, 48
	v_mov_b32_e32 v249, 0x358637bd
	s_nop 1
	v_mov_b32_e32 v240, s0
	v_add_f32_e32 v240, s1, v240
	v_add_f32_e32 v240, s2, v240
	v_add_f32_e32 v240, s3, v240
	v_fmamk_f32 v240, v240, 0x3a000000, v249
	s_mov_b32 s0, 0xf800000
	v_mul_f32_e32 v241, 0x4f800000, v240
	v_cmp_gt_f32_e32 vcc, s0, v240
	s_nop 1
	v_cndmask_b32_e32 v240, v240, v241, vcc
	v_sqrt_f32_e32 v241, v240
	s_nop 0
	v_add_u32_e32 v242, -1, v241
	v_fma_f32 v243, -v242, v241, v240
	v_cmp_ge_f32_e64 s[0:1], 0, v243
	v_add_u32_e32 v243, 1, v241
	s_nop 0
	v_cndmask_b32_e64 v242, v241, v242, s[0:1]
	v_fma_f32 v241, -v243, v241, v240
	v_cmp_lt_f32_e64 s[0:1], 0, v241
	s_nop 1
	v_cndmask_b32_e64 v241, v242, v243, s[0:1]
	v_mul_f32_e32 v242, 0x37800000, v241
	v_cndmask_b32_e32 v241, v241, v242, vcc
	v_cmp_class_f32_e32 vcc, v240, v248
	s_nop 1
	v_cndmask_b32_e32 v240, v241, v240, vcc
	v_div_scale_f32 v241, s[0:1], v240, v240, 1.0
	v_rcp_f32_e32 v242, v241
	s_nop 0
	v_fma_f32 v243, -v241, v242, 1.0
	v_fmac_f32_e32 v242, v243, v242
	v_div_scale_f32 v243, vcc, 1.0, v240, 1.0
	v_mul_f32_e32 v244, v243, v242
	v_fma_f32 v247, -v241, v244, v243
	v_fmac_f32_e32 v244, v247, v242
	v_fma_f32 v241, -v241, v244, v243
	s_nop 1
	v_div_fmas_f32 v241, v241, v242, v244
	v_div_fixup_f32 v246, v241, v240, 1.0
	v_pk_mul_f32 v[104:105], v[104:105], v[246:247] op_sel_hi:[1,0]
	v_pk_mul_f32 v[106:107], v[106:107], v[246:247] op_sel_hi:[1,0]
	v_pk_mul_f32 v[108:109], v[108:109], v[246:247] op_sel_hi:[1,0]
	v_pk_mul_f32 v[110:111], v[110:111], v[246:247] op_sel_hi:[1,0]
	v_pk_mul_f32 v[112:113], v[112:113], v[246:247] op_sel_hi:[1,0]
	v_pk_mul_f32 v[114:115], v[114:115], v[246:247] op_sel_hi:[1,0]
	v_pk_mul_f32 v[116:117], v[116:117], v[246:247] op_sel_hi:[1,0]
	v_pk_mul_f32 v[118:119], v[118:119], v[246:247] op_sel_hi:[1,0]
	v_pk_mul_f32 v[120:121], v[120:121], v[246:247] op_sel_hi:[1,0]
	v_pk_mul_f32 v[122:123], v[122:123], v[246:247] op_sel_hi:[1,0]
	v_pk_mul_f32 v[124:125], v[124:125], v[246:247] op_sel_hi:[1,0]
	v_pk_mul_f32 v[126:127], v[126:127], v[246:247] op_sel_hi:[1,0]
	v_pk_mul_f32 v[128:129], v[128:129], v[246:247] op_sel_hi:[1,0]
	v_pk_mul_f32 v[130:131], v[130:131], v[246:247] op_sel_hi:[1,0]
	v_pk_mul_f32 v[132:133], v[132:133], v[246:247] op_sel_hi:[1,0]
	v_pk_mul_f32 v[134:135], v[134:135], v[246:247] op_sel_hi:[1,0]
	s_add_u32 s8, s10, 0xc0000
	s_addc_u32 s9, s11, 0
	v_pk_fma_f32 v[104:105], v[8:9], v[104:105], v[40:41]
	v_cvt_pk_bf16_f32 v232, v104, v105
	v_pk_fma_f32 v[106:107], v[10:11], v[106:107], v[42:43]
	v_cvt_pk_bf16_f32 v233, v106, v107
	v_pk_fma_f32 v[108:109], v[12:13], v[108:109], v[44:45]
	v_cvt_pk_bf16_f32 v234, v108, v109
	v_pk_fma_f32 v[110:111], v[14:15], v[110:111], v[46:47]
	v_cvt_pk_bf16_f32 v235, v110, v111
	global_store_dwordx4 v1, v[232:235], s[8:9] offset:0
	v_pk_fma_f32 v[112:113], v[16:17], v[112:113], v[48:49]
	v_cvt_pk_bf16_f32 v236, v112, v113
	v_pk_fma_f32 v[114:115], v[18:19], v[114:115], v[50:51]
	v_cvt_pk_bf16_f32 v237, v114, v115
	v_pk_fma_f32 v[116:117], v[20:21], v[116:117], v[52:53]
	v_cvt_pk_bf16_f32 v238, v116, v117
	v_pk_fma_f32 v[118:119], v[22:23], v[118:119], v[54:55]
	v_cvt_pk_bf16_f32 v239, v118, v119
	global_store_dwordx4 v1, v[236:239], s[8:9] offset:1024
	v_pk_fma_f32 v[120:121], v[24:25], v[120:121], v[56:57]
	v_cvt_pk_bf16_f32 v232, v120, v121
	v_pk_fma_f32 v[122:123], v[26:27], v[122:123], v[58:59]
	v_cvt_pk_bf16_f32 v233, v122, v123
	v_pk_fma_f32 v[124:125], v[28:29], v[124:125], v[60:61]
	v_cvt_pk_bf16_f32 v234, v124, v125
	v_pk_fma_f32 v[126:127], v[30:31], v[126:127], v[62:63]
	v_cvt_pk_bf16_f32 v235, v126, v127
	global_store_dwordx4 v1, v[232:235], s[8:9] offset:2048
	v_pk_fma_f32 v[128:129], v[32:33], v[128:129], v[64:65]
	v_cvt_pk_bf16_f32 v236, v128, v129
	v_pk_fma_f32 v[130:131], v[34:35], v[130:131], v[66:67]
	v_cvt_pk_bf16_f32 v237, v130, v131
	v_pk_fma_f32 v[132:133], v[36:37], v[132:133], v[68:69]
	v_cvt_pk_bf16_f32 v238, v132, v133
	v_pk_fma_f32 v[134:135], v[38:39], v[134:135], v[70:71]
	v_cvt_pk_bf16_f32 v239, v134, v135
	global_store_dwordx4 v1, v[236:239], s[8:9] offset:3072
	s_waitcnt vmcnt(16)
	v_pk_mul_f32 v[232:233], v[136:137], v[136:137]
	v_pk_mul_f32 v[234:235], v[138:139], v[138:139]
	v_pk_mul_f32 v[236:237], v[140:141], v[140:141]
	v_pk_mul_f32 v[238:239], v[142:143], v[142:143]
	v_pk_fma_f32 v[232:233], v[144:145], v[144:145], v[232:233]
	v_pk_fma_f32 v[234:235], v[146:147], v[146:147], v[234:235]
	v_pk_fma_f32 v[236:237], v[148:149], v[148:149], v[236:237]
	v_pk_fma_f32 v[238:239], v[150:151], v[150:151], v[238:239]
	v_pk_fma_f32 v[232:233], v[152:153], v[152:153], v[232:233]
	v_pk_fma_f32 v[234:235], v[154:155], v[154:155], v[234:235]
	v_pk_fma_f32 v[236:237], v[156:157], v[156:157], v[236:237]
	v_pk_fma_f32 v[238:239], v[158:159], v[158:159], v[238:239]
	v_pk_fma_f32 v[232:233], v[160:161], v[160:161], v[232:233]
	v_pk_fma_f32 v[234:235], v[162:163], v[162:163], v[234:235]
	v_pk_fma_f32 v[236:237], v[164:165], v[164:165], v[236:237]
	v_pk_fma_f32 v[238:239], v[166:167], v[166:167], v[238:239]
	v_pk_add_f32 v[232:233], v[232:233], v[234:235]
	v_pk_add_f32 v[236:237], v[236:237], v[238:239]
	v_pk_add_f32 v[232:233], v[232:233], v[236:237]
	v_add_f32_e32 v240, v232, v233
	s_nop 1
	v_add_f32_dpp v240, v240, v240 quad_perm:[1,0,3,2] row_mask:0xf bank_mask:0xf
	s_nop 1
	v_add_f32_dpp v240, v240, v240 quad_perm:[2,3,0,1] row_mask:0xf bank_mask:0xf
	s_nop 1
	v_add_f32_dpp v240, v240, v240 row_half_mirror row_mask:0xf bank_mask:0xf
	s_nop 1
	v_add_f32_dpp v240, v240, v240 row_mirror row_mask:0xf bank_mask:0xf
	s_nop 1
	v_readlane_b32 s0, v240, 0
	v_readlane_b32 s1, v240, 16
	v_readlane_b32 s2, v240, 32
	v_readlane_b32 s3, v240, 48
	v_mov_b32_e32 v249, 0x358637bd
	s_nop 1
	v_mov_b32_e32 v240, s0
	v_add_f32_e32 v240, s1, v240
	v_add_f32_e32 v240, s2, v240
	v_add_f32_e32 v240, s3, v240
	v_fmamk_f32 v240, v240, 0x3a000000, v249
	s_mov_b32 s0, 0xf800000
	v_mul_f32_e32 v241, 0x4f800000, v240
	v_cmp_gt_f32_e32 vcc, s0, v240
	s_nop 1
	v_cndmask_b32_e32 v240, v240, v241, vcc
	v_sqrt_f32_e32 v241, v240
	s_nop 0
	v_add_u32_e32 v242, -1, v241
	v_fma_f32 v243, -v242, v241, v240
	v_cmp_ge_f32_e64 s[0:1], 0, v243
	v_add_u32_e32 v243, 1, v241
	s_nop 0
	v_cndmask_b32_e64 v242, v241, v242, s[0:1]
	v_fma_f32 v241, -v243, v241, v240
	v_cmp_lt_f32_e64 s[0:1], 0, v241
	s_nop 1
	v_cndmask_b32_e64 v241, v242, v243, s[0:1]
	v_mul_f32_e32 v242, 0x37800000, v241
	v_cndmask_b32_e32 v241, v241, v242, vcc
	v_cmp_class_f32_e32 vcc, v240, v248
	s_nop 1
	v_cndmask_b32_e32 v240, v241, v240, vcc
	v_div_scale_f32 v241, s[0:1], v240, v240, 1.0
	v_rcp_f32_e32 v242, v241
	s_nop 0
	v_fma_f32 v243, -v241, v242, 1.0
	v_fmac_f32_e32 v242, v243, v242
	v_div_scale_f32 v243, vcc, 1.0, v240, 1.0
	v_mul_f32_e32 v244, v243, v242
	v_fma_f32 v247, -v241, v244, v243
	v_fmac_f32_e32 v244, v247, v242
	v_fma_f32 v241, -v241, v244, v243
	s_nop 1
	v_div_fmas_f32 v241, v241, v242, v244
	v_div_fixup_f32 v246, v241, v240, 1.0
	v_pk_mul_f32 v[136:137], v[136:137], v[246:247] op_sel_hi:[1,0]
	v_pk_mul_f32 v[138:139], v[138:139], v[246:247] op_sel_hi:[1,0]
	v_pk_mul_f32 v[140:141], v[140:141], v[246:247] op_sel_hi:[1,0]
	v_pk_mul_f32 v[142:143], v[142:143], v[246:247] op_sel_hi:[1,0]
	v_pk_mul_f32 v[144:145], v[144:145], v[246:247] op_sel_hi:[1,0]
	v_pk_mul_f32 v[146:147], v[146:147], v[246:247] op_sel_hi:[1,0]
	v_pk_mul_f32 v[148:149], v[148:149], v[246:247] op_sel_hi:[1,0]
	v_pk_mul_f32 v[150:151], v[150:151], v[246:247] op_sel_hi:[1,0]
	v_pk_mul_f32 v[152:153], v[152:153], v[246:247] op_sel_hi:[1,0]
	v_pk_mul_f32 v[154:155], v[154:155], v[246:247] op_sel_hi:[1,0]
	v_pk_mul_f32 v[156:157], v[156:157], v[246:247] op_sel_hi:[1,0]
	v_pk_mul_f32 v[158:159], v[158:159], v[246:247] op_sel_hi:[1,0]
	v_pk_mul_f32 v[160:161], v[160:161], v[246:247] op_sel_hi:[1,0]
	v_pk_mul_f32 v[162:163], v[162:163], v[246:247] op_sel_hi:[1,0]
	v_pk_mul_f32 v[164:165], v[164:165], v[246:247] op_sel_hi:[1,0]
	v_pk_mul_f32 v[166:167], v[166:167], v[246:247] op_sel_hi:[1,0]
	s_add_u32 s8, s10, 0xe0000
	s_addc_u32 s9, s11, 0
	v_pk_fma_f32 v[136:137], v[8:9], v[136:137], v[40:41]
	v_cvt_pk_bf16_f32 v232, v136, v137
	v_pk_fma_f32 v[138:139], v[10:11], v[138:139], v[42:43]
	v_cvt_pk_bf16_f32 v233, v138, v139
	v_pk_fma_f32 v[140:141], v[12:13], v[140:141], v[44:45]
	v_cvt_pk_bf16_f32 v234, v140, v141
	v_pk_fma_f32 v[142:143], v[14:15], v[142:143], v[46:47]
	v_cvt_pk_bf16_f32 v235, v142, v143
	global_store_dwordx4 v1, v[232:235], s[8:9] offset:0
	v_pk_fma_f32 v[144:145], v[16:17], v[144:145], v[48:49]
	v_cvt_pk_bf16_f32 v236, v144, v145
	v_pk_fma_f32 v[146:147], v[18:19], v[146:147], v[50:51]
	v_cvt_pk_bf16_f32 v237, v146, v147
	v_pk_fma_f32 v[148:149], v[20:21], v[148:149], v[52:53]
	v_cvt_pk_bf16_f32 v238, v148, v149
	v_pk_fma_f32 v[150:151], v[22:23], v[150:151], v[54:55]
	v_cvt_pk_bf16_f32 v239, v150, v151
	global_store_dwordx4 v1, v[236:239], s[8:9] offset:1024
	v_pk_fma_f32 v[152:153], v[24:25], v[152:153], v[56:57]
	v_cvt_pk_bf16_f32 v232, v152, v153
	v_pk_fma_f32 v[154:155], v[26:27], v[154:155], v[58:59]
	v_cvt_pk_bf16_f32 v233, v154, v155
	v_pk_fma_f32 v[156:157], v[28:29], v[156:157], v[60:61]
	v_cvt_pk_bf16_f32 v234, v156, v157
	v_pk_fma_f32 v[158:159], v[30:31], v[158:159], v[62:63]
	v_cvt_pk_bf16_f32 v235, v158, v159
	global_store_dwordx4 v1, v[232:235], s[8:9] offset:2048
	v_pk_fma_f32 v[160:161], v[32:33], v[160:161], v[64:65]
	v_cvt_pk_bf16_f32 v236, v160, v161
	v_pk_fma_f32 v[162:163], v[34:35], v[162:163], v[66:67]
	v_cvt_pk_bf16_f32 v237, v162, v163
	v_pk_fma_f32 v[164:165], v[36:37], v[164:165], v[68:69]
	v_cvt_pk_bf16_f32 v238, v164, v165
	v_pk_fma_f32 v[166:167], v[38:39], v[166:167], v[70:71]
	v_cvt_pk_bf16_f32 v239, v166, v167
	global_store_dwordx4 v1, v[236:239], s[8:9] offset:3072
	s_branch .LBB0_278

.LBB0_551:
	v_readlane_b32 s4, v250, 12
	s_cmp_lt_i32 s4, 5
	s_cselect_b64 s[0:1], -1, 0
	s_and_b64 s[2:3], s[0:1], s[2:3]
	s_andn2_b64 vcc, exec, s[2:3]
	v_readlane_b32 s5, v250, 13
	v_readlane_b32 s6, v250, 14
	v_readlane_b32 s7, v250, 15
	s_cbranch_vccnz .LBB0_563
	v_mov_b32_e32 v1, 0x2416c
	ds_read_b32 v2, v1
	ds_read_b32 v1, v1 offset:4
	s_waitcnt lgkmcnt(0)
	v_readfirstlane_b32 s4, v2
	v_readfirstlane_b32 s5, v1
	s_cmp_lt_i32 s4, 1
	s_cbranch_scc1 .Lnorm_fb_0
	v_and_b32_e32 v1, 63, v0
	v_lshlrev_b32_e32 v2, 5, v1
	v_add_u32_e32 v3, 0x1000, v2
	v_lshlrev_b32_e32 v1, 4, v1
	v_readfirstlane_b32 s0, v0
	s_lshr_b32 s1, s0, 6
	s_add_i32 s4, s4, -1
	s_lshl_b32 s18, s4, 8
	s_lshl_b32 s19, s5, 3
	s_add_i32 s18, s18, s19
	s_add_i32 s18, s18, s1
	s_lshr_b32 s19, s4, 4
	s_lshl_b32 s20, s18, 12
	s_lshl_b32 s21, s18, 13
	s_add_u32 s6, s88, 0x45c00000
	s_addc_u32 s7, s89, 0
	s_add_u32 s6, s6, s20
	s_addc_u32 s7, s7, 0
	s_add_u32 s10, s88, 0x13e00000
	s_addc_u32 s11, s89, 0
	s_add_u32 s10, s10, s20
	s_addc_u32 s11, s11, 0
	s_add_u32 s16, s44, 0x2000
	s_addc_u32 s17, s45, 0
	s_mul_i32 s22, s19, 0x12000
	s_add_u32 s24, s88, 0x106000
	s_addc_u32 s25, s89, 0
	s_add_u32 s24, s24, s22
	s_addc_u32 s25, s25, 0
	s_mul_i32 s22, s19, 0x12000
	s_add_u32 s26, s88, 0x108000
	s_addc_u32 s27, s89, 0
	s_add_u32 s26, s26, s22
	s_addc_u32 s27, s27, 0
	global_load_dwordx4 v[72:75], v2, s[16:17] offset:0
	global_load_dwordx4 v[76:79], v2, s[16:17] offset:16
	global_load_dwordx4 v[80:83], v2, s[16:17] offset:2048
	global_load_dwordx4 v[84:87], v2, s[16:17] offset:2064
	global_load_dwordx4 v[88:91], v3, s[16:17] offset:0
	global_load_dwordx4 v[92:95], v3, s[16:17] offset:16
	global_load_dwordx4 v[96:99], v3, s[16:17] offset:2048
	global_load_dwordx4 v[100:103], v3, s[16:17] offset:2064
	global_load_dwordx4 v[8:11], v2, s[26:27] offset:0
	global_load_dwordx4 v[12:15], v2, s[26:27] offset:16
	global_load_dwordx4 v[16:19], v2, s[26:27] offset:2048
	global_load_dwordx4 v[20:23], v2, s[26:27] offset:2064
	global_load_dwordx4 v[24:27], v3, s[26:27] offset:0
	global_load_dwordx4 v[28:31], v3, s[26:27] offset:16
	global_load_dwordx4 v[32:35], v3, s[26:27] offset:2048
	global_load_dwordx4 v[36:39], v3, s[26:27] offset:2064
	global_load_dwordx4 v[40:43], v2, s[24:25] offset:0
	global_load_dwordx4 v[44:47], v2, s[24:25] offset:16
	global_load_dwordx4 v[48:51], v2, s[24:25] offset:2048
	global_load_dwordx4 v[52:55], v2, s[24:25] offset:2064
	global_load_dwordx4 v[56:59], v3, s[24:25] offset:0
	global_load_dwordx4 v[60:63], v3, s[24:25] offset:16
	global_load_dwordx4 v[64:67], v3, s[24:25] offset:2048
	global_load_dwordx4 v[68:71], v3, s[24:25] offset:2064
	s_add_u32 s8, s6, 0x0
	s_addc_u32 s9, s7, 0
	global_load_dwordx4 v[104:107], v1, s[8:9] offset:0 nt
	global_load_dwordx4 v[108:111], v1, s[8:9] offset:1024 nt
	global_load_dwordx4 v[112:115], v1, s[8:9] offset:2048 nt
	global_load_dwordx4 v[116:119], v1, s[8:9] offset:3072 nt
	s_add_u32 s8, s6, 0x20000
	s_addc_u32 s9, s7, 0
	global_load_dwordx4 v[120:123], v1, s[8:9] offset:0 nt
	global_load_dwordx4 v[124:127], v1, s[8:9] offset:1024 nt
	global_load_dwordx4 v[128:131], v1, s[8:9] offset:2048 nt
	global_load_dwordx4 v[132:135], v1, s[8:9] offset:3072 nt
	s_add_u32 s8, s6, 0x40000
	s_addc_u32 s9, s7, 0
	global_load_dwordx4 v[136:139], v1, s[8:9] offset:0 nt
	global_load_dwordx4 v[140:143], v1, s[8:9] offset:1024 nt
	global_load_dwordx4 v[144:147], v1, s[8:9] offset:2048 nt
	global_load_dwordx4 v[148:151], v1, s[8:9] offset:3072 nt
	s_add_u32 s8, s6, 0x60000
	s_addc_u32 s9, s7, 0
	global_load_dwordx4 v[152:155], v1, s[8:9] offset:0 nt
	global_load_dwordx4 v[156:159], v1, s[8:9] offset:1024 nt
	global_load_dwordx4 v[160:163], v1, s[8:9] offset:2048 nt
	global_load_dwordx4 v[164:167], v1, s[8:9] offset:3072 nt
	s_add_u32 s8, s6, 0x80000
	s_addc_u32 s9, s7, 0
	global_load_dwordx4 v[168:171], v1, s[8:9] offset:0 nt
	global_load_dwordx4 v[172:175], v1, s[8:9] offset:1024 nt
	global_load_dwordx4 v[176:179], v1, s[8:9] offset:2048 nt
	global_load_dwordx4 v[180:183], v1, s[8:9] offset:3072 nt
	s_add_u32 s8, s6, 0xa0000
	s_addc_u32 s9, s7, 0
	global_load_dwordx4 v[184:187], v1, s[8:9] offset:0 nt
	global_load_dwordx4 v[188:191], v1, s[8:9] offset:1024 nt
	global_load_dwordx4 v[192:195], v1, s[8:9] offset:2048 nt
	global_load_dwordx4 v[196:199], v1, s[8:9] offset:3072 nt
	s_add_u32 s8, s6, 0xc0000
	s_addc_u32 s9, s7, 0
	global_load_dwordx4 v[200:203], v1, s[8:9] offset:0 nt
	global_load_dwordx4 v[204:207], v1, s[8:9] offset:1024 nt
	global_load_dwordx4 v[208:211], v1, s[8:9] offset:2048 nt
	global_load_dwordx4 v[212:215], v1, s[8:9] offset:3072 nt
	s_add_u32 s8, s6, 0xe0000
	s_addc_u32 s9, s7, 0
	global_load_dwordx4 v[216:219], v1, s[8:9] offset:0 nt
	global_load_dwordx4 v[220:223], v1, s[8:9] offset:1024 nt
	global_load_dwordx4 v[224:227], v1, s[8:9] offset:2048 nt
	global_load_dwordx4 v[228:231], v1, s[8:9] offset:3072 nt
	s_waitcnt vmcnt(32)
	v_pk_add_f32 v[8:9], v[8:9], 1.0 op_sel_hi:[1,0]
	v_pk_add_f32 v[10:11], v[10:11], 1.0 op_sel_hi:[1,0]
	v_pk_add_f32 v[12:13], v[12:13], 1.0 op_sel_hi:[1,0]
	v_pk_add_f32 v[14:15], v[14:15], 1.0 op_sel_hi:[1,0]
	v_pk_add_f32 v[16:17], v[16:17], 1.0 op_sel_hi:[1,0]
	v_pk_add_f32 v[18:19], v[18:19], 1.0 op_sel_hi:[1,0]
	v_pk_add_f32 v[20:21], v[20:21], 1.0 op_sel_hi:[1,0]
	v_pk_add_f32 v[22:23], v[22:23], 1.0 op_sel_hi:[1,0]
	v_pk_add_f32 v[24:25], v[24:25], 1.0 op_sel_hi:[1,0]
	v_pk_add_f32 v[26:27], v[26:27], 1.0 op_sel_hi:[1,0]
	v_pk_add_f32 v[28:29], v[28:29], 1.0 op_sel_hi:[1,0]
	v_pk_add_f32 v[30:31], v[30:31], 1.0 op_sel_hi:[1,0]
	v_pk_add_f32 v[32:33], v[32:33], 1.0 op_sel_hi:[1,0]
	v_pk_add_f32 v[34:35], v[34:35], 1.0 op_sel_hi:[1,0]
	v_pk_add_f32 v[36:37], v[36:37], 1.0 op_sel_hi:[1,0]
	v_pk_add_f32 v[38:39], v[38:39], 1.0 op_sel_hi:[1,0]
	v_pk_mul_f32 v[8:9], v[72:73], v[8:9]
	v_pk_mul_f32 v[10:11], v[74:75], v[10:11]
	v_pk_mul_f32 v[12:13], v[76:77], v[12:13]
	v_pk_mul_f32 v[14:15], v[78:79], v[14:15]
	v_pk_mul_f32 v[16:17], v[80:81], v[16:17]
	v_pk_mul_f32 v[18:19], v[82:83], v[18:19]
	v_pk_mul_f32 v[20:21], v[84:85], v[20:21]
	v_pk_mul_f32 v[22:23], v[86:87], v[22:23]
	v_pk_mul_f32 v[24:25], v[88:89], v[24:25]
	v_pk_mul_f32 v[26:27], v[90:91], v[26:27]
	v_pk_mul_f32 v[28:29], v[92:93], v[28:29]
	v_pk_mul_f32 v[30:31], v[94:95], v[30:31]
	v_pk_mul_f32 v[32:33], v[96:97], v[32:33]
	v_pk_mul_f32 v[34:35], v[98:99], v[34:35]
	v_pk_mul_f32 v[36:37], v[100:101], v[36:37]
	v_pk_mul_f32 v[38:39], v[102:103], v[38:39]
	v_mov_b32_e32 v248, 0x260
	s_waitcnt vmcnt(28)
	v_cvt_f32_f16_e32 v72, v104
	v_cvt_f32_f16_sdwa v73, v104 dst_sel:DWORD dst_unused:UNUSED_PAD src0_sel:WORD_1
	v_cvt_f32_f16_e32 v74, v105
	v_cvt_f32_f16_sdwa v75, v105 dst_sel:DWORD dst_unused:UNUSED_PAD src0_sel:WORD_1
	v_cvt_f32_f16_e32 v76, v106
	v_cvt_f32_f16_sdwa v77, v106 dst_sel:DWORD dst_unused:UNUSED_PAD src0_sel:WORD_1
	v_cvt_f32_f16_e32 v78, v107
	v_cvt_f32_f16_sdwa v79, v107 dst_sel:DWORD dst_unused:UNUSED_PAD src0_sel:WORD_1
	v_cvt_f32_f16_e32 v80, v108
	v_cvt_f32_f16_sdwa v81, v108 dst_sel:DWORD dst_unused:UNUSED_PAD src0_sel:WORD_1
	v_cvt_f32_f16_e32 v82, v109
	v_cvt_f32_f16_sdwa v83, v109 dst_sel:DWORD dst_unused:UNUSED_PAD src0_sel:WORD_1
	v_cvt_f32_f16_e32 v84, v110
	v_cvt_f32_f16_sdwa v85, v110 dst_sel:DWORD dst_unused:UNUSED_PAD src0_sel:WORD_1
	v_cvt_f32_f16_e32 v86, v111
	v_cvt_f32_f16_sdwa v87, v111 dst_sel:DWORD dst_unused:UNUSED_PAD src0_sel:WORD_1
	v_cvt_f32_f16_e32 v88, v112
	v_cvt_f32_f16_sdwa v89, v112 dst_sel:DWORD dst_unused:UNUSED_PAD src0_sel:WORD_1
	v_cvt_f32_f16_e32 v90, v113
	v_cvt_f32_f16_sdwa v91, v113 dst_sel:DWORD dst_unused:UNUSED_PAD src0_sel:WORD_1
	v_cvt_f32_f16_e32 v92, v114
	v_cvt_f32_f16_sdwa v93, v114 dst_sel:DWORD dst_unused:UNUSED_PAD src0_sel:WORD_1
	v_cvt_f32_f16_e32 v94, v115
	v_cvt_f32_f16_sdwa v95, v115 dst_sel:DWORD dst_unused:UNUSED_PAD src0_sel:WORD_1
	v_cvt_f32_f16_e32 v96, v116
	v_cvt_f32_f16_sdwa v97, v116 dst_sel:DWORD dst_unused:UNUSED_PAD src0_sel:WORD_1
	v_cvt_f32_f16_e32 v98, v117
	v_cvt_f32_f16_sdwa v99, v117 dst_sel:DWORD dst_unused:UNUSED_PAD src0_sel:WORD_1
	v_cvt_f32_f16_e32 v100, v118
	v_cvt_f32_f16_sdwa v101, v118 dst_sel:DWORD dst_unused:UNUSED_PAD src0_sel:WORD_1
	v_cvt_f32_f16_e32 v102, v119
	v_cvt_f32_f16_sdwa v103, v119 dst_sel:DWORD dst_unused:UNUSED_PAD src0_sel:WORD_1
	v_pk_mul_f32 v[232:233], v[72:73], v[72:73]
	v_pk_mul_f32 v[234:235], v[74:75], v[74:75]
	v_pk_mul_f32 v[236:237], v[76:77], v[76:77]
	v_pk_mul_f32 v[238:239], v[78:79], v[78:79]
	v_pk_fma_f32 v[232:233], v[80:81], v[80:81], v[232:233]
	v_pk_fma_f32 v[234:235], v[82:83], v[82:83], v[234:235]
	v_pk_fma_f32 v[236:237], v[84:85], v[84:85], v[236:237]
	v_pk_fma_f32 v[238:239], v[86:87], v[86:87], v[238:239]
	v_pk_fma_f32 v[232:233], v[88:89], v[88:89], v[232:233]
	v_pk_fma_f32 v[234:235], v[90:91], v[90:91], v[234:235]
	v_pk_fma_f32 v[236:237], v[92:93], v[92:93], v[236:237]
	v_pk_fma_f32 v[238:239], v[94:95], v[94:95], v[238:239]
	v_pk_fma_f32 v[232:233], v[96:97], v[96:97], v[232:233]
	v_pk_fma_f32 v[234:235], v[98:99], v[98:99], v[234:235]
	v_pk_fma_f32 v[236:237], v[100:101], v[100:101], v[236:237]
	v_pk_fma_f32 v[238:239], v[102:103], v[102:103], v[238:239]
	v_pk_add_f32 v[232:233], v[232:233], v[234:235]
	v_pk_add_f32 v[236:237], v[236:237], v[238:239]
	v_pk_add_f32 v[232:233], v[232:233], v[236:237]
	v_add_f32_e32 v240, v232, v233
	s_nop 1
	v_add_f32_dpp v240, v240, v240 quad_perm:[1,0,3,2] row_mask:0xf bank_mask:0xf
	s_nop 1
	v_add_f32_dpp v240, v240, v240 quad_perm:[2,3,0,1] row_mask:0xf bank_mask:0xf
	s_nop 1
	v_add_f32_dpp v240, v240, v240 row_half_mirror row_mask:0xf bank_mask:0xf
	s_nop 1
	v_add_f32_dpp v240, v240, v240 row_mirror row_mask:0xf bank_mask:0xf
	s_nop 1
	v_readlane_b32 s0, v240, 0
	v_readlane_b32 s1, v240, 16
	v_readlane_b32 s4, v240, 32
	v_readlane_b32 s5, v240, 48
	v_mov_b32_e32 v249, 0x358637bd
	s_nop 1
	v_mov_b32_e32 v240, s0
	v_add_f32_e32 v240, s1, v240
	v_add_f32_e32 v240, s4, v240
	v_add_f32_e32 v240, s5, v240
	v_fmamk_f32 v240, v240, 0x3a000000, v249
	s_mov_b32 s0, 0xf800000
	v_mul_f32_e32 v241, 0x4f800000, v240
	v_cmp_gt_f32_e32 vcc, s0, v240
	s_nop 1
	v_cndmask_b32_e32 v240, v240, v241, vcc
	v_sqrt_f32_e32 v241, v240
	s_nop 0
	v_add_u32_e32 v242, -1, v241
	v_fma_f32 v243, -v242, v241, v240
	v_cmp_ge_f32_e64 s[0:1], 0, v243
	v_add_u32_e32 v243, 1, v241
	s_nop 0
	v_cndmask_b32_e64 v242, v241, v242, s[0:1]
	v_fma_f32 v241, -v243, v241, v240
	v_cmp_lt_f32_e64 s[0:1], 0, v241
	s_nop 1
	v_cndmask_b32_e64 v241, v242, v243, s[0:1]
	v_mul_f32_e32 v242, 0x37800000, v241
	v_cndmask_b32_e32 v241, v241, v242, vcc
	v_cmp_class_f32_e32 vcc, v240, v248
	s_nop 1
	v_cndmask_b32_e32 v240, v241, v240, vcc
	v_div_scale_f32 v241, s[0:1], v240, v240, 1.0
	v_rcp_f32_e32 v242, v241
	s_nop 0
	v_fma_f32 v243, -v241, v242, 1.0
	v_fmac_f32_e32 v242, v243, v242
	v_div_scale_f32 v243, vcc, 1.0, v240, 1.0
	v_mul_f32_e32 v244, v243, v242
	v_fma_f32 v247, -v241, v244, v243
	v_fmac_f32_e32 v244, v247, v242
	v_fma_f32 v241, -v241, v244, v243
	s_nop 1
	v_div_fmas_f32 v241, v241, v242, v244
	v_div_fixup_f32 v246, v241, v240, 1.0
	v_pk_mul_f32 v[72:73], v[72:73], v[246:247] op_sel_hi:[1,0]
	v_pk_mul_f32 v[74:75], v[74:75], v[246:247] op_sel_hi:[1,0]
	v_pk_mul_f32 v[76:77], v[76:77], v[246:247] op_sel_hi:[1,0]
	v_pk_mul_f32 v[78:79], v[78:79], v[246:247] op_sel_hi:[1,0]
	v_pk_mul_f32 v[80:81], v[80:81], v[246:247] op_sel_hi:[1,0]
	v_pk_mul_f32 v[82:83], v[82:83], v[246:247] op_sel_hi:[1,0]
	v_pk_mul_f32 v[84:85], v[84:85], v[246:247] op_sel_hi:[1,0]
	v_pk_mul_f32 v[86:87], v[86:87], v[246:247] op_sel_hi:[1,0]
	v_pk_mul_f32 v[88:89], v[88:89], v[246:247] op_sel_hi:[1,0]
	v_pk_mul_f32 v[90:91], v[90:91], v[246:247] op_sel_hi:[1,0]
	v_pk_mul_f32 v[92:93], v[92:93], v[246:247] op_sel_hi:[1,0]
	v_pk_mul_f32 v[94:95], v[94:95], v[246:247] op_sel_hi:[1,0]
	v_pk_mul_f32 v[96:97], v[96:97], v[246:247] op_sel_hi:[1,0]
	v_pk_mul_f32 v[98:99], v[98:99], v[246:247] op_sel_hi:[1,0]
	v_pk_mul_f32 v[100:101], v[100:101], v[246:247] op_sel_hi:[1,0]
	v_pk_mul_f32 v[102:103], v[102:103], v[246:247] op_sel_hi:[1,0]
	s_add_u32 s8, s10, 0x0
	s_addc_u32 s9, s11, 0
	v_pk_fma_f32 v[72:73], v[8:9], v[72:73], v[40:41]
	v_cvt_pk_bf16_f32 v232, v72, v73
	v_pk_fma_f32 v[74:75], v[10:11], v[74:75], v[42:43]
	v_cvt_pk_bf16_f32 v233, v74, v75
	v_pk_fma_f32 v[76:77], v[12:13], v[76:77], v[44:45]
	v_cvt_pk_bf16_f32 v234, v76, v77
	v_pk_fma_f32 v[78:79], v[14:15], v[78:79], v[46:47]
	v_cvt_pk_bf16_f32 v235, v78, v79
	global_store_dwordx4 v1, v[232:235], s[8:9] offset:0
	v_pk_fma_f32 v[80:81], v[16:17], v[80:81], v[48:49]
	v_cvt_pk_bf16_f32 v236, v80, v81
	v_pk_fma_f32 v[82:83], v[18:19], v[82:83], v[50:51]
	v_cvt_pk_bf16_f32 v237, v82, v83
	v_pk_fma_f32 v[84:85], v[20:21], v[84:85], v[52:53]
	v_cvt_pk_bf16_f32 v238, v84, v85
	v_pk_fma_f32 v[86:87], v[22:23], v[86:87], v[54:55]
	v_cvt_pk_bf16_f32 v239, v86, v87
	global_store_dwordx4 v1, v[236:239], s[8:9] offset:1024
	v_pk_fma_f32 v[88:89], v[24:25], v[88:89], v[56:57]
	v_cvt_pk_bf16_f32 v232, v88, v89
	v_pk_fma_f32 v[90:91], v[26:27], v[90:91], v[58:59]
	v_cvt_pk_bf16_f32 v233, v90, v91
	v_pk_fma_f32 v[92:93], v[28:29], v[92:93], v[60:61]
	v_cvt_pk_bf16_f32 v234, v92, v93
	v_pk_fma_f32 v[94:95], v[30:31], v[94:95], v[62:63]
	v_cvt_pk_bf16_f32 v235, v94, v95
	global_store_dwordx4 v1, v[232:235], s[8:9] offset:2048
	v_pk_fma_f32 v[96:97], v[32:33], v[96:97], v[64:65]
	v_cvt_pk_bf16_f32 v236, v96, v97
	v_pk_fma_f32 v[98:99], v[34:35], v[98:99], v[66:67]
	v_cvt_pk_bf16_f32 v237, v98, v99
	v_pk_fma_f32 v[100:101], v[36:37], v[100:101], v[68:69]
	v_cvt_pk_bf16_f32 v238, v100, v101
	v_pk_fma_f32 v[102:103], v[38:39], v[102:103], v[70:71]
	v_cvt_pk_bf16_f32 v239, v102, v103
	global_store_dwordx4 v1, v[236:239], s[8:9] offset:3072
	s_waitcnt vmcnt(28)
	v_cvt_f32_f16_e32 v72, v120
	v_cvt_f32_f16_sdwa v73, v120 dst_sel:DWORD dst_unused:UNUSED_PAD src0_sel:WORD_1
	v_cvt_f32_f16_e32 v74, v121
	v_cvt_f32_f16_sdwa v75, v121 dst_sel:DWORD dst_unused:UNUSED_PAD src0_sel:WORD_1
	v_cvt_f32_f16_e32 v76, v122
	v_cvt_f32_f16_sdwa v77, v122 dst_sel:DWORD dst_unused:UNUSED_PAD src0_sel:WORD_1
	v_cvt_f32_f16_e32 v78, v123
	v_cvt_f32_f16_sdwa v79, v123 dst_sel:DWORD dst_unused:UNUSED_PAD src0_sel:WORD_1
	v_cvt_f32_f16_e32 v80, v124
	v_cvt_f32_f16_sdwa v81, v124 dst_sel:DWORD dst_unused:UNUSED_PAD src0_sel:WORD_1
	v_cvt_f32_f16_e32 v82, v125
	v_cvt_f32_f16_sdwa v83, v125 dst_sel:DWORD dst_unused:UNUSED_PAD src0_sel:WORD_1
	v_cvt_f32_f16_e32 v84, v126
	v_cvt_f32_f16_sdwa v85, v126 dst_sel:DWORD dst_unused:UNUSED_PAD src0_sel:WORD_1
	v_cvt_f32_f16_e32 v86, v127
	v_cvt_f32_f16_sdwa v87, v127 dst_sel:DWORD dst_unused:UNUSED_PAD src0_sel:WORD_1
	v_cvt_f32_f16_e32 v88, v128
	v_cvt_f32_f16_sdwa v89, v128 dst_sel:DWORD dst_unused:UNUSED_PAD src0_sel:WORD_1
	v_cvt_f32_f16_e32 v90, v129
	v_cvt_f32_f16_sdwa v91, v129 dst_sel:DWORD dst_unused:UNUSED_PAD src0_sel:WORD_1
	v_cvt_f32_f16_e32 v92, v130
	v_cvt_f32_f16_sdwa v93, v130 dst_sel:DWORD dst_unused:UNUSED_PAD src0_sel:WORD_1
	v_cvt_f32_f16_e32 v94, v131
	v_cvt_f32_f16_sdwa v95, v131 dst_sel:DWORD dst_unused:UNUSED_PAD src0_sel:WORD_1
	v_cvt_f32_f16_e32 v96, v132
	v_cvt_f32_f16_sdwa v97, v132 dst_sel:DWORD dst_unused:UNUSED_PAD src0_sel:WORD_1
	v_cvt_f32_f16_e32 v98, v133
	v_cvt_f32_f16_sdwa v99, v133 dst_sel:DWORD dst_unused:UNUSED_PAD src0_sel:WORD_1
	v_cvt_f32_f16_e32 v100, v134
	v_cvt_f32_f16_sdwa v101, v134 dst_sel:DWORD dst_unused:UNUSED_PAD src0_sel:WORD_1
	v_cvt_f32_f16_e32 v102, v135
	v_cvt_f32_f16_sdwa v103, v135 dst_sel:DWORD dst_unused:UNUSED_PAD src0_sel:WORD_1
	v_pk_mul_f32 v[232:233], v[72:73], v[72:73]
	v_pk_mul_f32 v[234:235], v[74:75], v[74:75]
	v_pk_mul_f32 v[236:237], v[76:77], v[76:77]
	v_pk_mul_f32 v[238:239], v[78:79], v[78:79]
	v_pk_fma_f32 v[232:233], v[80:81], v[80:81], v[232:233]
	v_pk_fma_f32 v[234:235], v[82:83], v[82:83], v[234:235]
	v_pk_fma_f32 v[236:237], v[84:85], v[84:85], v[236:237]
	v_pk_fma_f32 v[238:239], v[86:87], v[86:87], v[238:239]
	v_pk_fma_f32 v[232:233], v[88:89], v[88:89], v[232:233]
	v_pk_fma_f32 v[234:235], v[90:91], v[90:91], v[234:235]
	v_pk_fma_f32 v[236:237], v[92:93], v[92:93], v[236:237]
	v_pk_fma_f32 v[238:239], v[94:95], v[94:95], v[238:239]
	v_pk_fma_f32 v[232:233], v[96:97], v[96:97], v[232:233]
	v_pk_fma_f32 v[234:235], v[98:99], v[98:99], v[234:235]
	v_pk_fma_f32 v[236:237], v[100:101], v[100:101], v[236:237]
	v_pk_fma_f32 v[238:239], v[102:103], v[102:103], v[238:239]
	v_pk_add_f32 v[232:233], v[232:233], v[234:235]
	v_pk_add_f32 v[236:237], v[236:237], v[238:239]
	v_pk_add_f32 v[232:233], v[232:233], v[236:237]
	v_add_f32_e32 v240, v232, v233
	s_nop 1
	v_add_f32_dpp v240, v240, v240 quad_perm:[1,0,3,2] row_mask:0xf bank_mask:0xf
	s_nop 1
	v_add_f32_dpp v240, v240, v240 quad_perm:[2,3,0,1] row_mask:0xf bank_mask:0xf
	s_nop 1
	v_add_f32_dpp v240, v240, v240 row_half_mirror row_mask:0xf bank_mask:0xf
	s_nop 1
	v_add_f32_dpp v240, v240, v240 row_mirror row_mask:0xf bank_mask:0xf
	s_nop 1
	v_readlane_b32 s0, v240, 0
	v_readlane_b32 s1, v240, 16
	v_readlane_b32 s4, v240, 32
	v_readlane_b32 s5, v240, 48
	v_mov_b32_e32 v249, 0x358637bd
	s_nop 1
	v_mov_b32_e32 v240, s0
	v_add_f32_e32 v240, s1, v240
	v_add_f32_e32 v240, s4, v240
	v_add_f32_e32 v240, s5, v240
	v_fmamk_f32 v240, v240, 0x3a000000, v249
	s_mov_b32 s0, 0xf800000
	v_mul_f32_e32 v241, 0x4f800000, v240
	v_cmp_gt_f32_e32 vcc, s0, v240
	s_nop 1
	v_cndmask_b32_e32 v240, v240, v241, vcc
	v_sqrt_f32_e32 v241, v240
	s_nop 0
	v_add_u32_e32 v242, -1, v241
	v_fma_f32 v243, -v242, v241, v240
	v_cmp_ge_f32_e64 s[0:1], 0, v243
	v_add_u32_e32 v243, 1, v241
	s_nop 0
	v_cndmask_b32_e64 v242, v241, v242, s[0:1]
	v_fma_f32 v241, -v243, v241, v240
	v_cmp_lt_f32_e64 s[0:1], 0, v241
	s_nop 1
	v_cndmask_b32_e64 v241, v242, v243, s[0:1]
	v_mul_f32_e32 v242, 0x37800000, v241
	v_cndmask_b32_e32 v241, v241, v242, vcc
	v_cmp_class_f32_e32 vcc, v240, v248
	s_nop 1
	v_cndmask_b32_e32 v240, v241, v240, vcc
	v_div_scale_f32 v241, s[0:1], v240, v240, 1.0
	v_rcp_f32_e32 v242, v241
	s_nop 0
	v_fma_f32 v243, -v241, v242, 1.0
	v_fmac_f32_e32 v242, v243, v242
	v_div_scale_f32 v243, vcc, 1.0, v240, 1.0
	v_mul_f32_e32 v244, v243, v242
	v_fma_f32 v247, -v241, v244, v243
	v_fmac_f32_e32 v244, v247, v242
	v_fma_f32 v241, -v241, v244, v243
	s_nop 1
	v_div_fmas_f32 v241, v241, v242, v244
	v_div_fixup_f32 v246, v241, v240, 1.0
	v_pk_mul_f32 v[72:73], v[72:73], v[246:247] op_sel_hi:[1,0]
	v_pk_mul_f32 v[74:75], v[74:75], v[246:247] op_sel_hi:[1,0]
	v_pk_mul_f32 v[76:77], v[76:77], v[246:247] op_sel_hi:[1,0]
	v_pk_mul_f32 v[78:79], v[78:79], v[246:247] op_sel_hi:[1,0]
	v_pk_mul_f32 v[80:81], v[80:81], v[246:247] op_sel_hi:[1,0]
	v_pk_mul_f32 v[82:83], v[82:83], v[246:247] op_sel_hi:[1,0]
	v_pk_mul_f32 v[84:85], v[84:85], v[246:247] op_sel_hi:[1,0]
	v_pk_mul_f32 v[86:87], v[86:87], v[246:247] op_sel_hi:[1,0]
	v_pk_mul_f32 v[88:89], v[88:89], v[246:247] op_sel_hi:[1,0]
	v_pk_mul_f32 v[90:91], v[90:91], v[246:247] op_sel_hi:[1,0]
	v_pk_mul_f32 v[92:93], v[92:93], v[246:247] op_sel_hi:[1,0]
	v_pk_mul_f32 v[94:95], v[94:95], v[246:247] op_sel_hi:[1,0]
	v_pk_mul_f32 v[96:97], v[96:97], v[246:247] op_sel_hi:[1,0]
	v_pk_mul_f32 v[98:99], v[98:99], v[246:247] op_sel_hi:[1,0]
	v_pk_mul_f32 v[100:101], v[100:101], v[246:247] op_sel_hi:[1,0]
	v_pk_mul_f32 v[102:103], v[102:103], v[246:247] op_sel_hi:[1,0]
	s_add_u32 s8, s10, 0x20000
	s_addc_u32 s9, s11, 0
	v_pk_fma_f32 v[72:73], v[8:9], v[72:73], v[40:41]
	v_cvt_pk_bf16_f32 v232, v72, v73
	v_pk_fma_f32 v[74:75], v[10:11], v[74:75], v[42:43]
	v_cvt_pk_bf16_f32 v233, v74, v75
	v_pk_fma_f32 v[76:77], v[12:13], v[76:77], v[44:45]
	v_cvt_pk_bf16_f32 v234, v76, v77
	v_pk_fma_f32 v[78:79], v[14:15], v[78:79], v[46:47]
	v_cvt_pk_bf16_f32 v235, v78, v79
	global_store_dwordx4 v1, v[232:235], s[8:9] offset:0
	v_pk_fma_f32 v[80:81], v[16:17], v[80:81], v[48:49]
	v_cvt_pk_bf16_f32 v236, v80, v81
	v_pk_fma_f32 v[82:83], v[18:19], v[82:83], v[50:51]
	v_cvt_pk_bf16_f32 v237, v82, v83
	v_pk_fma_f32 v[84:85], v[20:21], v[84:85], v[52:53]
	v_cvt_pk_bf16_f32 v238, v84, v85
	v_pk_fma_f32 v[86:87], v[22:23], v[86:87], v[54:55]
	v_cvt_pk_bf16_f32 v239, v86, v87
	global_store_dwordx4 v1, v[236:239], s[8:9] offset:1024
	v_pk_fma_f32 v[88:89], v[24:25], v[88:89], v[56:57]
	v_cvt_pk_bf16_f32 v232, v88, v89
	v_pk_fma_f32 v[90:91], v[26:27], v[90:91], v[58:59]
	v_cvt_pk_bf16_f32 v233, v90, v91
	v_pk_fma_f32 v[92:93], v[28:29], v[92:93], v[60:61]
	v_cvt_pk_bf16_f32 v234, v92, v93
	v_pk_fma_f32 v[94:95], v[30:31], v[94:95], v[62:63]
	v_cvt_pk_bf16_f32 v235, v94, v95
	global_store_dwordx4 v1, v[232:235], s[8:9] offset:2048
	v_pk_fma_f32 v[96:97], v[32:33], v[96:97], v[64:65]
	v_cvt_pk_bf16_f32 v236, v96, v97
	v_pk_fma_f32 v[98:99], v[34:35], v[98:99], v[66:67]
	v_cvt_pk_bf16_f32 v237, v98, v99
	v_pk_fma_f32 v[100:101], v[36:37], v[100:101], v[68:69]
	v_cvt_pk_bf16_f32 v238, v100, v101
	v_pk_fma_f32 v[102:103], v[38:39], v[102:103], v[70:71]
	v_cvt_pk_bf16_f32 v239, v102, v103
	global_store_dwordx4 v1, v[236:239], s[8:9] offset:3072
	s_waitcnt vmcnt(28)
	v_cvt_f32_f16_e32 v72, v136
	v_cvt_f32_f16_sdwa v73, v136 dst_sel:DWORD dst_unused:UNUSED_PAD src0_sel:WORD_1
	v_cvt_f32_f16_e32 v74, v137
	v_cvt_f32_f16_sdwa v75, v137 dst_sel:DWORD dst_unused:UNUSED_PAD src0_sel:WORD_1
	v_cvt_f32_f16_e32 v76, v138
	v_cvt_f32_f16_sdwa v77, v138 dst_sel:DWORD dst_unused:UNUSED_PAD src0_sel:WORD_1
	v_cvt_f32_f16_e32 v78, v139
	v_cvt_f32_f16_sdwa v79, v139 dst_sel:DWORD dst_unused:UNUSED_PAD src0_sel:WORD_1
	v_cvt_f32_f16_e32 v80, v140
	v_cvt_f32_f16_sdwa v81, v140 dst_sel:DWORD dst_unused:UNUSED_PAD src0_sel:WORD_1
	v_cvt_f32_f16_e32 v82, v141
	v_cvt_f32_f16_sdwa v83, v141 dst_sel:DWORD dst_unused:UNUSED_PAD src0_sel:WORD_1
	v_cvt_f32_f16_e32 v84, v142
	v_cvt_f32_f16_sdwa v85, v142 dst_sel:DWORD dst_unused:UNUSED_PAD src0_sel:WORD_1
	v_cvt_f32_f16_e32 v86, v143
	v_cvt_f32_f16_sdwa v87, v143 dst_sel:DWORD dst_unused:UNUSED_PAD src0_sel:WORD_1
	v_cvt_f32_f16_e32 v88, v144
	v_cvt_f32_f16_sdwa v89, v144 dst_sel:DWORD dst_unused:UNUSED_PAD src0_sel:WORD_1
	v_cvt_f32_f16_e32 v90, v145
	v_cvt_f32_f16_sdwa v91, v145 dst_sel:DWORD dst_unused:UNUSED_PAD src0_sel:WORD_1
	v_cvt_f32_f16_e32 v92, v146
	v_cvt_f32_f16_sdwa v93, v146 dst_sel:DWORD dst_unused:UNUSED_PAD src0_sel:WORD_1
	v_cvt_f32_f16_e32 v94, v147
	v_cvt_f32_f16_sdwa v95, v147 dst_sel:DWORD dst_unused:UNUSED_PAD src0_sel:WORD_1
	v_cvt_f32_f16_e32 v96, v148
	v_cvt_f32_f16_sdwa v97, v148 dst_sel:DWORD dst_unused:UNUSED_PAD src0_sel:WORD_1
	v_cvt_f32_f16_e32 v98, v149
	v_cvt_f32_f16_sdwa v99, v149 dst_sel:DWORD dst_unused:UNUSED_PAD src0_sel:WORD_1
	v_cvt_f32_f16_e32 v100, v150
	v_cvt_f32_f16_sdwa v101, v150 dst_sel:DWORD dst_unused:UNUSED_PAD src0_sel:WORD_1
	v_cvt_f32_f16_e32 v102, v151
	v_cvt_f32_f16_sdwa v103, v151 dst_sel:DWORD dst_unused:UNUSED_PAD src0_sel:WORD_1
	v_pk_mul_f32 v[232:233], v[72:73], v[72:73]
	v_pk_mul_f32 v[234:235], v[74:75], v[74:75]
	v_pk_mul_f32 v[236:237], v[76:77], v[76:77]
	v_pk_mul_f32 v[238:239], v[78:79], v[78:79]
	v_pk_fma_f32 v[232:233], v[80:81], v[80:81], v[232:233]
	v_pk_fma_f32 v[234:235], v[82:83], v[82:83], v[234:235]
	v_pk_fma_f32 v[236:237], v[84:85], v[84:85], v[236:237]
	v_pk_fma_f32 v[238:239], v[86:87], v[86:87], v[238:239]
	v_pk_fma_f32 v[232:233], v[88:89], v[88:89], v[232:233]
	v_pk_fma_f32 v[234:235], v[90:91], v[90:91], v[234:235]
	v_pk_fma_f32 v[236:237], v[92:93], v[92:93], v[236:237]
	v_pk_fma_f32 v[238:239], v[94:95], v[94:95], v[238:239]
	v_pk_fma_f32 v[232:233], v[96:97], v[96:97], v[232:233]
	v_pk_fma_f32 v[234:235], v[98:99], v[98:99], v[234:235]
	v_pk_fma_f32 v[236:237], v[100:101], v[100:101], v[236:237]
	v_pk_fma_f32 v[238:239], v[102:103], v[102:103], v[238:239]
	v_pk_add_f32 v[232:233], v[232:233], v[234:235]
	v_pk_add_f32 v[236:237], v[236:237], v[238:239]
	v_pk_add_f32 v[232:233], v[232:233], v[236:237]
	v_add_f32_e32 v240, v232, v233
	s_nop 1
	v_add_f32_dpp v240, v240, v240 quad_perm:[1,0,3,2] row_mask:0xf bank_mask:0xf
	s_nop 1
	v_add_f32_dpp v240, v240, v240 quad_perm:[2,3,0,1] row_mask:0xf bank_mask:0xf
	s_nop 1
	v_add_f32_dpp v240, v240, v240 row_half_mirror row_mask:0xf bank_mask:0xf
	s_nop 1
	v_add_f32_dpp v240, v240, v240 row_mirror row_mask:0xf bank_mask:0xf
	s_nop 1
	v_readlane_b32 s0, v240, 0
	v_readlane_b32 s1, v240, 16
	v_readlane_b32 s4, v240, 32
	v_readlane_b32 s5, v240, 48
	v_mov_b32_e32 v249, 0x358637bd
	s_nop 1
	v_mov_b32_e32 v240, s0
	v_add_f32_e32 v240, s1, v240
	v_add_f32_e32 v240, s4, v240
	v_add_f32_e32 v240, s5, v240
	v_fmamk_f32 v240, v240, 0x3a000000, v249
	s_mov_b32 s0, 0xf800000
	v_mul_f32_e32 v241, 0x4f800000, v240
	v_cmp_gt_f32_e32 vcc, s0, v240
	s_nop 1
	v_cndmask_b32_e32 v240, v240, v241, vcc
	v_sqrt_f32_e32 v241, v240
	s_nop 0
	v_add_u32_e32 v242, -1, v241
	v_fma_f32 v243, -v242, v241, v240
	v_cmp_ge_f32_e64 s[0:1], 0, v243
	v_add_u32_e32 v243, 1, v241
	s_nop 0
	v_cndmask_b32_e64 v242, v241, v242, s[0:1]
	v_fma_f32 v241, -v243, v241, v240
	v_cmp_lt_f32_e64 s[0:1], 0, v241
	s_nop 1
	v_cndmask_b32_e64 v241, v242, v243, s[0:1]
	v_mul_f32_e32 v242, 0x37800000, v241
	v_cndmask_b32_e32 v241, v241, v242, vcc
	v_cmp_class_f32_e32 vcc, v240, v248
	s_nop 1
	v_cndmask_b32_e32 v240, v241, v240, vcc
	v_div_scale_f32 v241, s[0:1], v240, v240, 1.0
	v_rcp_f32_e32 v242, v241
	s_nop 0
	v_fma_f32 v243, -v241, v242, 1.0
	v_fmac_f32_e32 v242, v243, v242
	v_div_scale_f32 v243, vcc, 1.0, v240, 1.0
	v_mul_f32_e32 v244, v243, v242
	v_fma_f32 v247, -v241, v244, v243
	v_fmac_f32_e32 v244, v247, v242
	v_fma_f32 v241, -v241, v244, v243
	s_nop 1
	v_div_fmas_f32 v241, v241, v242, v244
	v_div_fixup_f32 v246, v241, v240, 1.0
	v_pk_mul_f32 v[72:73], v[72:73], v[246:247] op_sel_hi:[1,0]
	v_pk_mul_f32 v[74:75], v[74:75], v[246:247] op_sel_hi:[1,0]
	v_pk_mul_f32 v[76:77], v[76:77], v[246:247] op_sel_hi:[1,0]
	v_pk_mul_f32 v[78:79], v[78:79], v[246:247] op_sel_hi:[1,0]
	v_pk_mul_f32 v[80:81], v[80:81], v[246:247] op_sel_hi:[1,0]
	v_pk_mul_f32 v[82:83], v[82:83], v[246:247] op_sel_hi:[1,0]
	v_pk_mul_f32 v[84:85], v[84:85], v[246:247] op_sel_hi:[1,0]
	v_pk_mul_f32 v[86:87], v[86:87], v[246:247] op_sel_hi:[1,0]
	v_pk_mul_f32 v[88:89], v[88:89], v[246:247] op_sel_hi:[1,0]
	v_pk_mul_f32 v[90:91], v[90:91], v[246:247] op_sel_hi:[1,0]
	v_pk_mul_f32 v[92:93], v[92:93], v[246:247] op_sel_hi:[1,0]
	v_pk_mul_f32 v[94:95], v[94:95], v[246:247] op_sel_hi:[1,0]
	v_pk_mul_f32 v[96:97], v[96:97], v[246:247] op_sel_hi:[1,0]
	v_pk_mul_f32 v[98:99], v[98:99], v[246:247] op_sel_hi:[1,0]
	v_pk_mul_f32 v[100:101], v[100:101], v[246:247] op_sel_hi:[1,0]
	v_pk_mul_f32 v[102:103], v[102:103], v[246:247] op_sel_hi:[1,0]
	s_add_u32 s8, s10, 0x40000
	s_addc_u32 s9, s11, 0
	v_pk_fma_f32 v[72:73], v[8:9], v[72:73], v[40:41]
	v_cvt_pk_bf16_f32 v232, v72, v73
	v_pk_fma_f32 v[74:75], v[10:11], v[74:75], v[42:43]
	v_cvt_pk_bf16_f32 v233, v74, v75
	v_pk_fma_f32 v[76:77], v[12:13], v[76:77], v[44:45]
	v_cvt_pk_bf16_f32 v234, v76, v77
	v_pk_fma_f32 v[78:79], v[14:15], v[78:79], v[46:47]
	v_cvt_pk_bf16_f32 v235, v78, v79
	global_store_dwordx4 v1, v[232:235], s[8:9] offset:0
	v_pk_fma_f32 v[80:81], v[16:17], v[80:81], v[48:49]
	v_cvt_pk_bf16_f32 v236, v80, v81
	v_pk_fma_f32 v[82:83], v[18:19], v[82:83], v[50:51]
	v_cvt_pk_bf16_f32 v237, v82, v83
	v_pk_fma_f32 v[84:85], v[20:21], v[84:85], v[52:53]
	v_cvt_pk_bf16_f32 v238, v84, v85
	v_pk_fma_f32 v[86:87], v[22:23], v[86:87], v[54:55]
	v_cvt_pk_bf16_f32 v239, v86, v87
	global_store_dwordx4 v1, v[236:239], s[8:9] offset:1024
	v_pk_fma_f32 v[88:89], v[24:25], v[88:89], v[56:57]
	v_cvt_pk_bf16_f32 v232, v88, v89
	v_pk_fma_f32 v[90:91], v[26:27], v[90:91], v[58:59]
	v_cvt_pk_bf16_f32 v233, v90, v91
	v_pk_fma_f32 v[92:93], v[28:29], v[92:93], v[60:61]
	v_cvt_pk_bf16_f32 v234, v92, v93
	v_pk_fma_f32 v[94:95], v[30:31], v[94:95], v[62:63]
	v_cvt_pk_bf16_f32 v235, v94, v95
	global_store_dwordx4 v1, v[232:235], s[8:9] offset:2048
	v_pk_fma_f32 v[96:97], v[32:33], v[96:97], v[64:65]
	v_cvt_pk_bf16_f32 v236, v96, v97
	v_pk_fma_f32 v[98:99], v[34:35], v[98:99], v[66:67]
	v_cvt_pk_bf16_f32 v237, v98, v99
	v_pk_fma_f32 v[100:101], v[36:37], v[100:101], v[68:69]
	v_cvt_pk_bf16_f32 v238, v100, v101
	v_pk_fma_f32 v[102:103], v[38:39], v[102:103], v[70:71]
	v_cvt_pk_bf16_f32 v239, v102, v103
	global_store_dwordx4 v1, v[236:239], s[8:9] offset:3072
	s_waitcnt vmcnt(28)
	v_cvt_f32_f16_e32 v72, v152
	v_cvt_f32_f16_sdwa v73, v152 dst_sel:DWORD dst_unused:UNUSED_PAD src0_sel:WORD_1
	v_cvt_f32_f16_e32 v74, v153
	v_cvt_f32_f16_sdwa v75, v153 dst_sel:DWORD dst_unused:UNUSED_PAD src0_sel:WORD_1
	v_cvt_f32_f16_e32 v76, v154
	v_cvt_f32_f16_sdwa v77, v154 dst_sel:DWORD dst_unused:UNUSED_PAD src0_sel:WORD_1
	v_cvt_f32_f16_e32 v78, v155
	v_cvt_f32_f16_sdwa v79, v155 dst_sel:DWORD dst_unused:UNUSED_PAD src0_sel:WORD_1
	v_cvt_f32_f16_e32 v80, v156
	v_cvt_f32_f16_sdwa v81, v156 dst_sel:DWORD dst_unused:UNUSED_PAD src0_sel:WORD_1
	v_cvt_f32_f16_e32 v82, v157
	v_cvt_f32_f16_sdwa v83, v157 dst_sel:DWORD dst_unused:UNUSED_PAD src0_sel:WORD_1
	v_cvt_f32_f16_e32 v84, v158
	v_cvt_f32_f16_sdwa v85, v158 dst_sel:DWORD dst_unused:UNUSED_PAD src0_sel:WORD_1
	v_cvt_f32_f16_e32 v86, v159
	v_cvt_f32_f16_sdwa v87, v159 dst_sel:DWORD dst_unused:UNUSED_PAD src0_sel:WORD_1
	v_cvt_f32_f16_e32 v88, v160
	v_cvt_f32_f16_sdwa v89, v160 dst_sel:DWORD dst_unused:UNUSED_PAD src0_sel:WORD_1
	v_cvt_f32_f16_e32 v90, v161
	v_cvt_f32_f16_sdwa v91, v161 dst_sel:DWORD dst_unused:UNUSED_PAD src0_sel:WORD_1
	v_cvt_f32_f16_e32 v92, v162
	v_cvt_f32_f16_sdwa v93, v162 dst_sel:DWORD dst_unused:UNUSED_PAD src0_sel:WORD_1
	v_cvt_f32_f16_e32 v94, v163
	v_cvt_f32_f16_sdwa v95, v163 dst_sel:DWORD dst_unused:UNUSED_PAD src0_sel:WORD_1
	v_cvt_f32_f16_e32 v96, v164
	v_cvt_f32_f16_sdwa v97, v164 dst_sel:DWORD dst_unused:UNUSED_PAD src0_sel:WORD_1
	v_cvt_f32_f16_e32 v98, v165
	v_cvt_f32_f16_sdwa v99, v165 dst_sel:DWORD dst_unused:UNUSED_PAD src0_sel:WORD_1
	v_cvt_f32_f16_e32 v100, v166
	v_cvt_f32_f16_sdwa v101, v166 dst_sel:DWORD dst_unused:UNUSED_PAD src0_sel:WORD_1
	v_cvt_f32_f16_e32 v102, v167
	v_cvt_f32_f16_sdwa v103, v167 dst_sel:DWORD dst_unused:UNUSED_PAD src0_sel:WORD_1
	v_pk_mul_f32 v[232:233], v[72:73], v[72:73]
	v_pk_mul_f32 v[234:235], v[74:75], v[74:75]
	v_pk_mul_f32 v[236:237], v[76:77], v[76:77]
	v_pk_mul_f32 v[238:239], v[78:79], v[78:79]
	v_pk_fma_f32 v[232:233], v[80:81], v[80:81], v[232:233]
	v_pk_fma_f32 v[234:235], v[82:83], v[82:83], v[234:235]
	v_pk_fma_f32 v[236:237], v[84:85], v[84:85], v[236:237]
	v_pk_fma_f32 v[238:239], v[86:87], v[86:87], v[238:239]
	v_pk_fma_f32 v[232:233], v[88:89], v[88:89], v[232:233]
	v_pk_fma_f32 v[234:235], v[90:91], v[90:91], v[234:235]
	v_pk_fma_f32 v[236:237], v[92:93], v[92:93], v[236:237]
	v_pk_fma_f32 v[238:239], v[94:95], v[94:95], v[238:239]
	v_pk_fma_f32 v[232:233], v[96:97], v[96:97], v[232:233]
	v_pk_fma_f32 v[234:235], v[98:99], v[98:99], v[234:235]
	v_pk_fma_f32 v[236:237], v[100:101], v[100:101], v[236:237]
	v_pk_fma_f32 v[238:239], v[102:103], v[102:103], v[238:239]
	v_pk_add_f32 v[232:233], v[232:233], v[234:235]
	v_pk_add_f32 v[236:237], v[236:237], v[238:239]
	v_pk_add_f32 v[232:233], v[232:233], v[236:237]
	v_add_f32_e32 v240, v232, v233
	s_nop 1
	v_add_f32_dpp v240, v240, v240 quad_perm:[1,0,3,2] row_mask:0xf bank_mask:0xf
	s_nop 1
	v_add_f32_dpp v240, v240, v240 quad_perm:[2,3,0,1] row_mask:0xf bank_mask:0xf
	s_nop 1
	v_add_f32_dpp v240, v240, v240 row_half_mirror row_mask:0xf bank_mask:0xf
	s_nop 1
	v_add_f32_dpp v240, v240, v240 row_mirror row_mask:0xf bank_mask:0xf
	s_nop 1
	v_readlane_b32 s0, v240, 0
	v_readlane_b32 s1, v240, 16
	v_readlane_b32 s4, v240, 32
	v_readlane_b32 s5, v240, 48
	v_mov_b32_e32 v249, 0x358637bd
	s_nop 1
	v_mov_b32_e32 v240, s0
	v_add_f32_e32 v240, s1, v240
	v_add_f32_e32 v240, s4, v240
	v_add_f32_e32 v240, s5, v240
	v_fmamk_f32 v240, v240, 0x3a000000, v249
	s_mov_b32 s0, 0xf800000
	v_mul_f32_e32 v241, 0x4f800000, v240
	v_cmp_gt_f32_e32 vcc, s0, v240
	s_nop 1
	v_cndmask_b32_e32 v240, v240, v241, vcc
	v_sqrt_f32_e32 v241, v240
	s_nop 0
	v_add_u32_e32 v242, -1, v241
	v_fma_f32 v243, -v242, v241, v240
	v_cmp_ge_f32_e64 s[0:1], 0, v243
	v_add_u32_e32 v243, 1, v241
	s_nop 0
	v_cndmask_b32_e64 v242, v241, v242, s[0:1]
	v_fma_f32 v241, -v243, v241, v240
	v_cmp_lt_f32_e64 s[0:1], 0, v241
	s_nop 1
	v_cndmask_b32_e64 v241, v242, v243, s[0:1]
	v_mul_f32_e32 v242, 0x37800000, v241
	v_cndmask_b32_e32 v241, v241, v242, vcc
	v_cmp_class_f32_e32 vcc, v240, v248
	s_nop 1
	v_cndmask_b32_e32 v240, v241, v240, vcc
	v_div_scale_f32 v241, s[0:1], v240, v240, 1.0
	v_rcp_f32_e32 v242, v241
	s_nop 0
	v_fma_f32 v243, -v241, v242, 1.0
	v_fmac_f32_e32 v242, v243, v242
	v_div_scale_f32 v243, vcc, 1.0, v240, 1.0
	v_mul_f32_e32 v244, v243, v242
	v_fma_f32 v247, -v241, v244, v243
	v_fmac_f32_e32 v244, v247, v242
	v_fma_f32 v241, -v241, v244, v243
	s_nop 1
	v_div_fmas_f32 v241, v241, v242, v244
	v_div_fixup_f32 v246, v241, v240, 1.0
	v_pk_mul_f32 v[72:73], v[72:73], v[246:247] op_sel_hi:[1,0]
	v_pk_mul_f32 v[74:75], v[74:75], v[246:247] op_sel_hi:[1,0]
	v_pk_mul_f32 v[76:77], v[76:77], v[246:247] op_sel_hi:[1,0]
	v_pk_mul_f32 v[78:79], v[78:79], v[246:247] op_sel_hi:[1,0]
	v_pk_mul_f32 v[80:81], v[80:81], v[246:247] op_sel_hi:[1,0]
	v_pk_mul_f32 v[82:83], v[82:83], v[246:247] op_sel_hi:[1,0]
	v_pk_mul_f32 v[84:85], v[84:85], v[246:247] op_sel_hi:[1,0]
	v_pk_mul_f32 v[86:87], v[86:87], v[246:247] op_sel_hi:[1,0]
	v_pk_mul_f32 v[88:89], v[88:89], v[246:247] op_sel_hi:[1,0]
	v_pk_mul_f32 v[90:91], v[90:91], v[246:247] op_sel_hi:[1,0]
	v_pk_mul_f32 v[92:93], v[92:93], v[246:247] op_sel_hi:[1,0]
	v_pk_mul_f32 v[94:95], v[94:95], v[246:247] op_sel_hi:[1,0]
	v_pk_mul_f32 v[96:97], v[96:97], v[246:247] op_sel_hi:[1,0]
	v_pk_mul_f32 v[98:99], v[98:99], v[246:247] op_sel_hi:[1,0]
	v_pk_mul_f32 v[100:101], v[100:101], v[246:247] op_sel_hi:[1,0]
	v_pk_mul_f32 v[102:103], v[102:103], v[246:247] op_sel_hi:[1,0]
	s_add_u32 s8, s10, 0x60000
	s_addc_u32 s9, s11, 0
	v_pk_fma_f32 v[72:73], v[8:9], v[72:73], v[40:41]
	v_cvt_pk_bf16_f32 v232, v72, v73
	v_pk_fma_f32 v[74:75], v[10:11], v[74:75], v[42:43]
	v_cvt_pk_bf16_f32 v233, v74, v75
	v_pk_fma_f32 v[76:77], v[12:13], v[76:77], v[44:45]
	v_cvt_pk_bf16_f32 v234, v76, v77
	v_pk_fma_f32 v[78:79], v[14:15], v[78:79], v[46:47]
	v_cvt_pk_bf16_f32 v235, v78, v79
	global_store_dwordx4 v1, v[232:235], s[8:9] offset:0
	v_pk_fma_f32 v[80:81], v[16:17], v[80:81], v[48:49]
	v_cvt_pk_bf16_f32 v236, v80, v81
	v_pk_fma_f32 v[82:83], v[18:19], v[82:83], v[50:51]
	v_cvt_pk_bf16_f32 v237, v82, v83
	v_pk_fma_f32 v[84:85], v[20:21], v[84:85], v[52:53]
	v_cvt_pk_bf16_f32 v238, v84, v85
	v_pk_fma_f32 v[86:87], v[22:23], v[86:87], v[54:55]
	v_cvt_pk_bf16_f32 v239, v86, v87
	global_store_dwordx4 v1, v[236:239], s[8:9] offset:1024
	v_pk_fma_f32 v[88:89], v[24:25], v[88:89], v[56:57]
	v_cvt_pk_bf16_f32 v232, v88, v89
	v_pk_fma_f32 v[90:91], v[26:27], v[90:91], v[58:59]
	v_cvt_pk_bf16_f32 v233, v90, v91
	v_pk_fma_f32 v[92:93], v[28:29], v[92:93], v[60:61]
	v_cvt_pk_bf16_f32 v234, v92, v93
	v_pk_fma_f32 v[94:95], v[30:31], v[94:95], v[62:63]
	v_cvt_pk_bf16_f32 v235, v94, v95
	global_store_dwordx4 v1, v[232:235], s[8:9] offset:2048
	v_pk_fma_f32 v[96:97], v[32:33], v[96:97], v[64:65]
	v_cvt_pk_bf16_f32 v236, v96, v97
	v_pk_fma_f32 v[98:99], v[34:35], v[98:99], v[66:67]
	v_cvt_pk_bf16_f32 v237, v98, v99
	v_pk_fma_f32 v[100:101], v[36:37], v[100:101], v[68:69]
	v_cvt_pk_bf16_f32 v238, v100, v101
	v_pk_fma_f32 v[102:103], v[38:39], v[102:103], v[70:71]
	v_cvt_pk_bf16_f32 v239, v102, v103
	global_store_dwordx4 v1, v[236:239], s[8:9] offset:3072
	s_waitcnt vmcnt(28)
	v_cvt_f32_f16_e32 v72, v168
	v_cvt_f32_f16_sdwa v73, v168 dst_sel:DWORD dst_unused:UNUSED_PAD src0_sel:WORD_1
	v_cvt_f32_f16_e32 v74, v169
	v_cvt_f32_f16_sdwa v75, v169 dst_sel:DWORD dst_unused:UNUSED_PAD src0_sel:WORD_1
	v_cvt_f32_f16_e32 v76, v170
	v_cvt_f32_f16_sdwa v77, v170 dst_sel:DWORD dst_unused:UNUSED_PAD src0_sel:WORD_1
	v_cvt_f32_f16_e32 v78, v171
	v_cvt_f32_f16_sdwa v79, v171 dst_sel:DWORD dst_unused:UNUSED_PAD src0_sel:WORD_1
	v_cvt_f32_f16_e32 v80, v172
	v_cvt_f32_f16_sdwa v81, v172 dst_sel:DWORD dst_unused:UNUSED_PAD src0_sel:WORD_1
	v_cvt_f32_f16_e32 v82, v173
	v_cvt_f32_f16_sdwa v83, v173 dst_sel:DWORD dst_unused:UNUSED_PAD src0_sel:WORD_1
	v_cvt_f32_f16_e32 v84, v174
	v_cvt_f32_f16_sdwa v85, v174 dst_sel:DWORD dst_unused:UNUSED_PAD src0_sel:WORD_1
	v_cvt_f32_f16_e32 v86, v175
	v_cvt_f32_f16_sdwa v87, v175 dst_sel:DWORD dst_unused:UNUSED_PAD src0_sel:WORD_1
	v_cvt_f32_f16_e32 v88, v176
	v_cvt_f32_f16_sdwa v89, v176 dst_sel:DWORD dst_unused:UNUSED_PAD src0_sel:WORD_1
	v_cvt_f32_f16_e32 v90, v177
	v_cvt_f32_f16_sdwa v91, v177 dst_sel:DWORD dst_unused:UNUSED_PAD src0_sel:WORD_1
	v_cvt_f32_f16_e32 v92, v178
	v_cvt_f32_f16_sdwa v93, v178 dst_sel:DWORD dst_unused:UNUSED_PAD src0_sel:WORD_1
	v_cvt_f32_f16_e32 v94, v179
	v_cvt_f32_f16_sdwa v95, v179 dst_sel:DWORD dst_unused:UNUSED_PAD src0_sel:WORD_1
	v_cvt_f32_f16_e32 v96, v180
	v_cvt_f32_f16_sdwa v97, v180 dst_sel:DWORD dst_unused:UNUSED_PAD src0_sel:WORD_1
	v_cvt_f32_f16_e32 v98, v181
	v_cvt_f32_f16_sdwa v99, v181 dst_sel:DWORD dst_unused:UNUSED_PAD src0_sel:WORD_1
	v_cvt_f32_f16_e32 v100, v182
	v_cvt_f32_f16_sdwa v101, v182 dst_sel:DWORD dst_unused:UNUSED_PAD src0_sel:WORD_1
	v_cvt_f32_f16_e32 v102, v183
	v_cvt_f32_f16_sdwa v103, v183 dst_sel:DWORD dst_unused:UNUSED_PAD src0_sel:WORD_1
	v_pk_mul_f32 v[232:233], v[72:73], v[72:73]
	v_pk_mul_f32 v[234:235], v[74:75], v[74:75]
	v_pk_mul_f32 v[236:237], v[76:77], v[76:77]
	v_pk_mul_f32 v[238:239], v[78:79], v[78:79]
	v_pk_fma_f32 v[232:233], v[80:81], v[80:81], v[232:233]
	v_pk_fma_f32 v[234:235], v[82:83], v[82:83], v[234:235]
	v_pk_fma_f32 v[236:237], v[84:85], v[84:85], v[236:237]
	v_pk_fma_f32 v[238:239], v[86:87], v[86:87], v[238:239]
	v_pk_fma_f32 v[232:233], v[88:89], v[88:89], v[232:233]
	v_pk_fma_f32 v[234:235], v[90:91], v[90:91], v[234:235]
	v_pk_fma_f32 v[236:237], v[92:93], v[92:93], v[236:237]
	v_pk_fma_f32 v[238:239], v[94:95], v[94:95], v[238:239]
	v_pk_fma_f32 v[232:233], v[96:97], v[96:97], v[232:233]
	v_pk_fma_f32 v[234:235], v[98:99], v[98:99], v[234:235]
	v_pk_fma_f32 v[236:237], v[100:101], v[100:101], v[236:237]
	v_pk_fma_f32 v[238:239], v[102:103], v[102:103], v[238:239]
	v_pk_add_f32 v[232:233], v[232:233], v[234:235]
	v_pk_add_f32 v[236:237], v[236:237], v[238:239]
	v_pk_add_f32 v[232:233], v[232:233], v[236:237]
	v_add_f32_e32 v240, v232, v233
	s_nop 1
	v_add_f32_dpp v240, v240, v240 quad_perm:[1,0,3,2] row_mask:0xf bank_mask:0xf
	s_nop 1
	v_add_f32_dpp v240, v240, v240 quad_perm:[2,3,0,1] row_mask:0xf bank_mask:0xf
	s_nop 1
	v_add_f32_dpp v240, v240, v240 row_half_mirror row_mask:0xf bank_mask:0xf
	s_nop 1
	v_add_f32_dpp v240, v240, v240 row_mirror row_mask:0xf bank_mask:0xf
	s_nop 1
	v_readlane_b32 s0, v240, 0
	v_readlane_b32 s1, v240, 16
	v_readlane_b32 s4, v240, 32
	v_readlane_b32 s5, v240, 48
	v_mov_b32_e32 v249, 0x358637bd
	s_nop 1
	v_mov_b32_e32 v240, s0
	v_add_f32_e32 v240, s1, v240
	v_add_f32_e32 v240, s4, v240
	v_add_f32_e32 v240, s5, v240
	v_fmamk_f32 v240, v240, 0x3a000000, v249
	s_mov_b32 s0, 0xf800000
	v_mul_f32_e32 v241, 0x4f800000, v240
	v_cmp_gt_f32_e32 vcc, s0, v240
	s_nop 1
	v_cndmask_b32_e32 v240, v240, v241, vcc
	v_sqrt_f32_e32 v241, v240
	s_nop 0
	v_add_u32_e32 v242, -1, v241
	v_fma_f32 v243, -v242, v241, v240
	v_cmp_ge_f32_e64 s[0:1], 0, v243
	v_add_u32_e32 v243, 1, v241
	s_nop 0
	v_cndmask_b32_e64 v242, v241, v242, s[0:1]
	v_fma_f32 v241, -v243, v241, v240
	v_cmp_lt_f32_e64 s[0:1], 0, v241
	s_nop 1
	v_cndmask_b32_e64 v241, v242, v243, s[0:1]
	v_mul_f32_e32 v242, 0x37800000, v241
	v_cndmask_b32_e32 v241, v241, v242, vcc
	v_cmp_class_f32_e32 vcc, v240, v248
	s_nop 1
	v_cndmask_b32_e32 v240, v241, v240, vcc
	v_div_scale_f32 v241, s[0:1], v240, v240, 1.0
	v_rcp_f32_e32 v242, v241
	s_nop 0
	v_fma_f32 v243, -v241, v242, 1.0
	v_fmac_f32_e32 v242, v243, v242
	v_div_scale_f32 v243, vcc, 1.0, v240, 1.0
	v_mul_f32_e32 v244, v243, v242
	v_fma_f32 v247, -v241, v244, v243
	v_fmac_f32_e32 v244, v247, v242
	v_fma_f32 v241, -v241, v244, v243
	s_nop 1
	v_div_fmas_f32 v241, v241, v242, v244
	v_div_fixup_f32 v246, v241, v240, 1.0
	v_pk_mul_f32 v[72:73], v[72:73], v[246:247] op_sel_hi:[1,0]
	v_pk_mul_f32 v[74:75], v[74:75], v[246:247] op_sel_hi:[1,0]
	v_pk_mul_f32 v[76:77], v[76:77], v[246:247] op_sel_hi:[1,0]
	v_pk_mul_f32 v[78:79], v[78:79], v[246:247] op_sel_hi:[1,0]
	v_pk_mul_f32 v[80:81], v[80:81], v[246:247] op_sel_hi:[1,0]
	v_pk_mul_f32 v[82:83], v[82:83], v[246:247] op_sel_hi:[1,0]
	v_pk_mul_f32 v[84:85], v[84:85], v[246:247] op_sel_hi:[1,0]
	v_pk_mul_f32 v[86:87], v[86:87], v[246:247] op_sel_hi:[1,0]
	v_pk_mul_f32 v[88:89], v[88:89], v[246:247] op_sel_hi:[1,0]
	v_pk_mul_f32 v[90:91], v[90:91], v[246:247] op_sel_hi:[1,0]
	v_pk_mul_f32 v[92:93], v[92:93], v[246:247] op_sel_hi:[1,0]
	v_pk_mul_f32 v[94:95], v[94:95], v[246:247] op_sel_hi:[1,0]
	v_pk_mul_f32 v[96:97], v[96:97], v[246:247] op_sel_hi:[1,0]
	v_pk_mul_f32 v[98:99], v[98:99], v[246:247] op_sel_hi:[1,0]
	v_pk_mul_f32 v[100:101], v[100:101], v[246:247] op_sel_hi:[1,0]
	v_pk_mul_f32 v[102:103], v[102:103], v[246:247] op_sel_hi:[1,0]
	s_add_u32 s8, s10, 0x80000
	s_addc_u32 s9, s11, 0
	v_pk_fma_f32 v[72:73], v[8:9], v[72:73], v[40:41]
	v_cvt_pk_bf16_f32 v232, v72, v73
	v_pk_fma_f32 v[74:75], v[10:11], v[74:75], v[42:43]
	v_cvt_pk_bf16_f32 v233, v74, v75
	v_pk_fma_f32 v[76:77], v[12:13], v[76:77], v[44:45]
	v_cvt_pk_bf16_f32 v234, v76, v77
	v_pk_fma_f32 v[78:79], v[14:15], v[78:79], v[46:47]
	v_cvt_pk_bf16_f32 v235, v78, v79
	global_store_dwordx4 v1, v[232:235], s[8:9] offset:0
	v_pk_fma_f32 v[80:81], v[16:17], v[80:81], v[48:49]
	v_cvt_pk_bf16_f32 v236, v80, v81
	v_pk_fma_f32 v[82:83], v[18:19], v[82:83], v[50:51]
	v_cvt_pk_bf16_f32 v237, v82, v83
	v_pk_fma_f32 v[84:85], v[20:21], v[84:85], v[52:53]
	v_cvt_pk_bf16_f32 v238, v84, v85
	v_pk_fma_f32 v[86:87], v[22:23], v[86:87], v[54:55]
	v_cvt_pk_bf16_f32 v239, v86, v87
	global_store_dwordx4 v1, v[236:239], s[8:9] offset:1024
	v_pk_fma_f32 v[88:89], v[24:25], v[88:89], v[56:57]
	v_cvt_pk_bf16_f32 v232, v88, v89
	v_pk_fma_f32 v[90:91], v[26:27], v[90:91], v[58:59]
	v_cvt_pk_bf16_f32 v233, v90, v91
	v_pk_fma_f32 v[92:93], v[28:29], v[92:93], v[60:61]
	v_cvt_pk_bf16_f32 v234, v92, v93
	v_pk_fma_f32 v[94:95], v[30:31], v[94:95], v[62:63]
	v_cvt_pk_bf16_f32 v235, v94, v95
	global_store_dwordx4 v1, v[232:235], s[8:9] offset:2048
	v_pk_fma_f32 v[96:97], v[32:33], v[96:97], v[64:65]
	v_cvt_pk_bf16_f32 v236, v96, v97
	v_pk_fma_f32 v[98:99], v[34:35], v[98:99], v[66:67]
	v_cvt_pk_bf16_f32 v237, v98, v99
	v_pk_fma_f32 v[100:101], v[36:37], v[100:101], v[68:69]
	v_cvt_pk_bf16_f32 v238, v100, v101
	v_pk_fma_f32 v[102:103], v[38:39], v[102:103], v[70:71]
	v_cvt_pk_bf16_f32 v239, v102, v103
	global_store_dwordx4 v1, v[236:239], s[8:9] offset:3072
	s_waitcnt vmcnt(28)
	v_cvt_f32_f16_e32 v72, v184
	v_cvt_f32_f16_sdwa v73, v184 dst_sel:DWORD dst_unused:UNUSED_PAD src0_sel:WORD_1
	v_cvt_f32_f16_e32 v74, v185
	v_cvt_f32_f16_sdwa v75, v185 dst_sel:DWORD dst_unused:UNUSED_PAD src0_sel:WORD_1
	v_cvt_f32_f16_e32 v76, v186
	v_cvt_f32_f16_sdwa v77, v186 dst_sel:DWORD dst_unused:UNUSED_PAD src0_sel:WORD_1
	v_cvt_f32_f16_e32 v78, v187
	v_cvt_f32_f16_sdwa v79, v187 dst_sel:DWORD dst_unused:UNUSED_PAD src0_sel:WORD_1
	v_cvt_f32_f16_e32 v80, v188
	v_cvt_f32_f16_sdwa v81, v188 dst_sel:DWORD dst_unused:UNUSED_PAD src0_sel:WORD_1
	v_cvt_f32_f16_e32 v82, v189
	v_cvt_f32_f16_sdwa v83, v189 dst_sel:DWORD dst_unused:UNUSED_PAD src0_sel:WORD_1
	v_cvt_f32_f16_e32 v84, v190
	v_cvt_f32_f16_sdwa v85, v190 dst_sel:DWORD dst_unused:UNUSED_PAD src0_sel:WORD_1
	v_cvt_f32_f16_e32 v86, v191
	v_cvt_f32_f16_sdwa v87, v191 dst_sel:DWORD dst_unused:UNUSED_PAD src0_sel:WORD_1
	v_cvt_f32_f16_e32 v88, v192
	v_cvt_f32_f16_sdwa v89, v192 dst_sel:DWORD dst_unused:UNUSED_PAD src0_sel:WORD_1
	v_cvt_f32_f16_e32 v90, v193
	v_cvt_f32_f16_sdwa v91, v193 dst_sel:DWORD dst_unused:UNUSED_PAD src0_sel:WORD_1
	v_cvt_f32_f16_e32 v92, v194
	v_cvt_f32_f16_sdwa v93, v194 dst_sel:DWORD dst_unused:UNUSED_PAD src0_sel:WORD_1
	v_cvt_f32_f16_e32 v94, v195
	v_cvt_f32_f16_sdwa v95, v195 dst_sel:DWORD dst_unused:UNUSED_PAD src0_sel:WORD_1
	v_cvt_f32_f16_e32 v96, v196
	v_cvt_f32_f16_sdwa v97, v196 dst_sel:DWORD dst_unused:UNUSED_PAD src0_sel:WORD_1
	v_cvt_f32_f16_e32 v98, v197
	v_cvt_f32_f16_sdwa v99, v197 dst_sel:DWORD dst_unused:UNUSED_PAD src0_sel:WORD_1
	v_cvt_f32_f16_e32 v100, v198
	v_cvt_f32_f16_sdwa v101, v198 dst_sel:DWORD dst_unused:UNUSED_PAD src0_sel:WORD_1
	v_cvt_f32_f16_e32 v102, v199
	v_cvt_f32_f16_sdwa v103, v199 dst_sel:DWORD dst_unused:UNUSED_PAD src0_sel:WORD_1
	v_pk_mul_f32 v[232:233], v[72:73], v[72:73]
	v_pk_mul_f32 v[234:235], v[74:75], v[74:75]
	v_pk_mul_f32 v[236:237], v[76:77], v[76:77]
	v_pk_mul_f32 v[238:239], v[78:79], v[78:79]
	v_pk_fma_f32 v[232:233], v[80:81], v[80:81], v[232:233]
	v_pk_fma_f32 v[234:235], v[82:83], v[82:83], v[234:235]
	v_pk_fma_f32 v[236:237], v[84:85], v[84:85], v[236:237]
	v_pk_fma_f32 v[238:239], v[86:87], v[86:87], v[238:239]
	v_pk_fma_f32 v[232:233], v[88:89], v[88:89], v[232:233]
	v_pk_fma_f32 v[234:235], v[90:91], v[90:91], v[234:235]
	v_pk_fma_f32 v[236:237], v[92:93], v[92:93], v[236:237]
	v_pk_fma_f32 v[238:239], v[94:95], v[94:95], v[238:239]
	v_pk_fma_f32 v[232:233], v[96:97], v[96:97], v[232:233]
	v_pk_fma_f32 v[234:235], v[98:99], v[98:99], v[234:235]
	v_pk_fma_f32 v[236:237], v[100:101], v[100:101], v[236:237]
	v_pk_fma_f32 v[238:239], v[102:103], v[102:103], v[238:239]
	v_pk_add_f32 v[232:233], v[232:233], v[234:235]
	v_pk_add_f32 v[236:237], v[236:237], v[238:239]
	v_pk_add_f32 v[232:233], v[232:233], v[236:237]
	v_add_f32_e32 v240, v232, v233
	s_nop 1
	v_add_f32_dpp v240, v240, v240 quad_perm:[1,0,3,2] row_mask:0xf bank_mask:0xf
	s_nop 1
	v_add_f32_dpp v240, v240, v240 quad_perm:[2,3,0,1] row_mask:0xf bank_mask:0xf
	s_nop 1
	v_add_f32_dpp v240, v240, v240 row_half_mirror row_mask:0xf bank_mask:0xf
	s_nop 1
	v_add_f32_dpp v240, v240, v240 row_mirror row_mask:0xf bank_mask:0xf
	s_nop 1
	v_readlane_b32 s0, v240, 0
	v_readlane_b32 s1, v240, 16
	v_readlane_b32 s4, v240, 32
	v_readlane_b32 s5, v240, 48
	v_mov_b32_e32 v249, 0x358637bd
	s_nop 1
	v_mov_b32_e32 v240, s0
	v_add_f32_e32 v240, s1, v240
	v_add_f32_e32 v240, s4, v240
	v_add_f32_e32 v240, s5, v240
	v_fmamk_f32 v240, v240, 0x3a000000, v249
	s_mov_b32 s0, 0xf800000
	v_mul_f32_e32 v241, 0x4f800000, v240
	v_cmp_gt_f32_e32 vcc, s0, v240
	s_nop 1
	v_cndmask_b32_e32 v240, v240, v241, vcc
	v_sqrt_f32_e32 v241, v240
	s_nop 0
	v_add_u32_e32 v242, -1, v241
	v_fma_f32 v243, -v242, v241, v240
	v_cmp_ge_f32_e64 s[0:1], 0, v243
	v_add_u32_e32 v243, 1, v241
	s_nop 0
	v_cndmask_b32_e64 v242, v241, v242, s[0:1]
	v_fma_f32 v241, -v243, v241, v240
	v_cmp_lt_f32_e64 s[0:1], 0, v241
	s_nop 1
	v_cndmask_b32_e64 v241, v242, v243, s[0:1]
	v_mul_f32_e32 v242, 0x37800000, v241
	v_cndmask_b32_e32 v241, v241, v242, vcc
	v_cmp_class_f32_e32 vcc, v240, v248
	s_nop 1
	v_cndmask_b32_e32 v240, v241, v240, vcc
	v_div_scale_f32 v241, s[0:1], v240, v240, 1.0
	v_rcp_f32_e32 v242, v241
	s_nop 0
	v_fma_f32 v243, -v241, v242, 1.0
	v_fmac_f32_e32 v242, v243, v242
	v_div_scale_f32 v243, vcc, 1.0, v240, 1.0
	v_mul_f32_e32 v244, v243, v242
	v_fma_f32 v247, -v241, v244, v243
	v_fmac_f32_e32 v244, v247, v242
	v_fma_f32 v241, -v241, v244, v243
	s_nop 1
	v_div_fmas_f32 v241, v241, v242, v244
	v_div_fixup_f32 v246, v241, v240, 1.0
	v_pk_mul_f32 v[72:73], v[72:73], v[246:247] op_sel_hi:[1,0]
	v_pk_mul_f32 v[74:75], v[74:75], v[246:247] op_sel_hi:[1,0]
	v_pk_mul_f32 v[76:77], v[76:77], v[246:247] op_sel_hi:[1,0]
	v_pk_mul_f32 v[78:79], v[78:79], v[246:247] op_sel_hi:[1,0]
	v_pk_mul_f32 v[80:81], v[80:81], v[246:247] op_sel_hi:[1,0]
	v_pk_mul_f32 v[82:83], v[82:83], v[246:247] op_sel_hi:[1,0]
	v_pk_mul_f32 v[84:85], v[84:85], v[246:247] op_sel_hi:[1,0]
	v_pk_mul_f32 v[86:87], v[86:87], v[246:247] op_sel_hi:[1,0]
	v_pk_mul_f32 v[88:89], v[88:89], v[246:247] op_sel_hi:[1,0]
	v_pk_mul_f32 v[90:91], v[90:91], v[246:247] op_sel_hi:[1,0]
	v_pk_mul_f32 v[92:93], v[92:93], v[246:247] op_sel_hi:[1,0]
	v_pk_mul_f32 v[94:95], v[94:95], v[246:247] op_sel_hi:[1,0]
	v_pk_mul_f32 v[96:97], v[96:97], v[246:247] op_sel_hi:[1,0]
	v_pk_mul_f32 v[98:99], v[98:99], v[246:247] op_sel_hi:[1,0]
	v_pk_mul_f32 v[100:101], v[100:101], v[246:247] op_sel_hi:[1,0]
	v_pk_mul_f32 v[102:103], v[102:103], v[246:247] op_sel_hi:[1,0]
	s_add_u32 s8, s10, 0xa0000
	s_addc_u32 s9, s11, 0
	v_pk_fma_f32 v[72:73], v[8:9], v[72:73], v[40:41]
	v_cvt_pk_bf16_f32 v232, v72, v73
	v_pk_fma_f32 v[74:75], v[10:11], v[74:75], v[42:43]
	v_cvt_pk_bf16_f32 v233, v74, v75
	v_pk_fma_f32 v[76:77], v[12:13], v[76:77], v[44:45]
	v_cvt_pk_bf16_f32 v234, v76, v77
	v_pk_fma_f32 v[78:79], v[14:15], v[78:79], v[46:47]
	v_cvt_pk_bf16_f32 v235, v78, v79
	global_store_dwordx4 v1, v[232:235], s[8:9] offset:0
	v_pk_fma_f32 v[80:81], v[16:17], v[80:81], v[48:49]
	v_cvt_pk_bf16_f32 v236, v80, v81
	v_pk_fma_f32 v[82:83], v[18:19], v[82:83], v[50:51]
	v_cvt_pk_bf16_f32 v237, v82, v83
	v_pk_fma_f32 v[84:85], v[20:21], v[84:85], v[52:53]
	v_cvt_pk_bf16_f32 v238, v84, v85
	v_pk_fma_f32 v[86:87], v[22:23], v[86:87], v[54:55]
	v_cvt_pk_bf16_f32 v239, v86, v87
	global_store_dwordx4 v1, v[236:239], s[8:9] offset:1024
	v_pk_fma_f32 v[88:89], v[24:25], v[88:89], v[56:57]
	v_cvt_pk_bf16_f32 v232, v88, v89
	v_pk_fma_f32 v[90:91], v[26:27], v[90:91], v[58:59]
	v_cvt_pk_bf16_f32 v233, v90, v91
	v_pk_fma_f32 v[92:93], v[28:29], v[92:93], v[60:61]
	v_cvt_pk_bf16_f32 v234, v92, v93
	v_pk_fma_f32 v[94:95], v[30:31], v[94:95], v[62:63]
	v_cvt_pk_bf16_f32 v235, v94, v95
	global_store_dwordx4 v1, v[232:235], s[8:9] offset:2048
	v_pk_fma_f32 v[96:97], v[32:33], v[96:97], v[64:65]
	v_cvt_pk_bf16_f32 v236, v96, v97
	v_pk_fma_f32 v[98:99], v[34:35], v[98:99], v[66:67]
	v_cvt_pk_bf16_f32 v237, v98, v99
	v_pk_fma_f32 v[100:101], v[36:37], v[100:101], v[68:69]
	v_cvt_pk_bf16_f32 v238, v100, v101
	v_pk_fma_f32 v[102:103], v[38:39], v[102:103], v[70:71]
	v_cvt_pk_bf16_f32 v239, v102, v103
	global_store_dwordx4 v1, v[236:239], s[8:9] offset:3072
	s_waitcnt vmcnt(28)
	v_cvt_f32_f16_e32 v72, v200
	v_cvt_f32_f16_sdwa v73, v200 dst_sel:DWORD dst_unused:UNUSED_PAD src0_sel:WORD_1
	v_cvt_f32_f16_e32 v74, v201
	v_cvt_f32_f16_sdwa v75, v201 dst_sel:DWORD dst_unused:UNUSED_PAD src0_sel:WORD_1
	v_cvt_f32_f16_e32 v76, v202
	v_cvt_f32_f16_sdwa v77, v202 dst_sel:DWORD dst_unused:UNUSED_PAD src0_sel:WORD_1
	v_cvt_f32_f16_e32 v78, v203
	v_cvt_f32_f16_sdwa v79, v203 dst_sel:DWORD dst_unused:UNUSED_PAD src0_sel:WORD_1
	v_cvt_f32_f16_e32 v80, v204
	v_cvt_f32_f16_sdwa v81, v204 dst_sel:DWORD dst_unused:UNUSED_PAD src0_sel:WORD_1
	v_cvt_f32_f16_e32 v82, v205
	v_cvt_f32_f16_sdwa v83, v205 dst_sel:DWORD dst_unused:UNUSED_PAD src0_sel:WORD_1
	v_cvt_f32_f16_e32 v84, v206
	v_cvt_f32_f16_sdwa v85, v206 dst_sel:DWORD dst_unused:UNUSED_PAD src0_sel:WORD_1
	v_cvt_f32_f16_e32 v86, v207
	v_cvt_f32_f16_sdwa v87, v207 dst_sel:DWORD dst_unused:UNUSED_PAD src0_sel:WORD_1
	v_cvt_f32_f16_e32 v88, v208
	v_cvt_f32_f16_sdwa v89, v208 dst_sel:DWORD dst_unused:UNUSED_PAD src0_sel:WORD_1
	v_cvt_f32_f16_e32 v90, v209
	v_cvt_f32_f16_sdwa v91, v209 dst_sel:DWORD dst_unused:UNUSED_PAD src0_sel:WORD_1
	v_cvt_f32_f16_e32 v92, v210
	v_cvt_f32_f16_sdwa v93, v210 dst_sel:DWORD dst_unused:UNUSED_PAD src0_sel:WORD_1
	v_cvt_f32_f16_e32 v94, v211
	v_cvt_f32_f16_sdwa v95, v211 dst_sel:DWORD dst_unused:UNUSED_PAD src0_sel:WORD_1
	v_cvt_f32_f16_e32 v96, v212
	v_cvt_f32_f16_sdwa v97, v212 dst_sel:DWORD dst_unused:UNUSED_PAD src0_sel:WORD_1
	v_cvt_f32_f16_e32 v98, v213
	v_cvt_f32_f16_sdwa v99, v213 dst_sel:DWORD dst_unused:UNUSED_PAD src0_sel:WORD_1
	v_cvt_f32_f16_e32 v100, v214
	v_cvt_f32_f16_sdwa v101, v214 dst_sel:DWORD dst_unused:UNUSED_PAD src0_sel:WORD_1
	v_cvt_f32_f16_e32 v102, v215
	v_cvt_f32_f16_sdwa v103, v215 dst_sel:DWORD dst_unused:UNUSED_PAD src0_sel:WORD_1
	v_pk_mul_f32 v[232:233], v[72:73], v[72:73]
	v_pk_mul_f32 v[234:235], v[74:75], v[74:75]
	v_pk_mul_f32 v[236:237], v[76:77], v[76:77]
	v_pk_mul_f32 v[238:239], v[78:79], v[78:79]
	v_pk_fma_f32 v[232:233], v[80:81], v[80:81], v[232:233]
	v_pk_fma_f32 v[234:235], v[82:83], v[82:83], v[234:235]
	v_pk_fma_f32 v[236:237], v[84:85], v[84:85], v[236:237]
	v_pk_fma_f32 v[238:239], v[86:87], v[86:87], v[238:239]
	v_pk_fma_f32 v[232:233], v[88:89], v[88:89], v[232:233]
	v_pk_fma_f32 v[234:235], v[90:91], v[90:91], v[234:235]
	v_pk_fma_f32 v[236:237], v[92:93], v[92:93], v[236:237]
	v_pk_fma_f32 v[238:239], v[94:95], v[94:95], v[238:239]
	v_pk_fma_f32 v[232:233], v[96:97], v[96:97], v[232:233]
	v_pk_fma_f32 v[234:235], v[98:99], v[98:99], v[234:235]
	v_pk_fma_f32 v[236:237], v[100:101], v[100:101], v[236:237]
	v_pk_fma_f32 v[238:239], v[102:103], v[102:103], v[238:239]
	v_pk_add_f32 v[232:233], v[232:233], v[234:235]
	v_pk_add_f32 v[236:237], v[236:237], v[238:239]
	v_pk_add_f32 v[232:233], v[232:233], v[236:237]
	v_add_f32_e32 v240, v232, v233
	s_nop 1
	v_add_f32_dpp v240, v240, v240 quad_perm:[1,0,3,2] row_mask:0xf bank_mask:0xf
	s_nop 1
	v_add_f32_dpp v240, v240, v240 quad_perm:[2,3,0,1] row_mask:0xf bank_mask:0xf
	s_nop 1
	v_add_f32_dpp v240, v240, v240 row_half_mirror row_mask:0xf bank_mask:0xf
	s_nop 1
	v_add_f32_dpp v240, v240, v240 row_mirror row_mask:0xf bank_mask:0xf
	s_nop 1
	v_readlane_b32 s0, v240, 0
	v_readlane_b32 s1, v240, 16
	v_readlane_b32 s4, v240, 32
	v_readlane_b32 s5, v240, 48
	v_mov_b32_e32 v249, 0x358637bd
	s_nop 1
	v_mov_b32_e32 v240, s0
	v_add_f32_e32 v240, s1, v240
	v_add_f32_e32 v240, s4, v240
	v_add_f32_e32 v240, s5, v240
	v_fmamk_f32 v240, v240, 0x3a000000, v249
	s_mov_b32 s0, 0xf800000
	v_mul_f32_e32 v241, 0x4f800000, v240
	v_cmp_gt_f32_e32 vcc, s0, v240
	s_nop 1
	v_cndmask_b32_e32 v240, v240, v241, vcc
	v_sqrt_f32_e32 v241, v240
	s_nop 0
	v_add_u32_e32 v242, -1, v241
	v_fma_f32 v243, -v242, v241, v240
	v_cmp_ge_f32_e64 s[0:1], 0, v243
	v_add_u32_e32 v243, 1, v241
	s_nop 0
	v_cndmask_b32_e64 v242, v241, v242, s[0:1]
	v_fma_f32 v241, -v243, v241, v240
	v_cmp_lt_f32_e64 s[0:1], 0, v241
	s_nop 1
	v_cndmask_b32_e64 v241, v242, v243, s[0:1]
	v_mul_f32_e32 v242, 0x37800000, v241
	v_cndmask_b32_e32 v241, v241, v242, vcc
	v_cmp_class_f32_e32 vcc, v240, v248
	s_nop 1
	v_cndmask_b32_e32 v240, v241, v240, vcc
	v_div_scale_f32 v241, s[0:1], v240, v240, 1.0
	v_rcp_f32_e32 v242, v241
	s_nop 0
	v_fma_f32 v243, -v241, v242, 1.0
	v_fmac_f32_e32 v242, v243, v242
	v_div_scale_f32 v243, vcc, 1.0, v240, 1.0
	v_mul_f32_e32 v244, v243, v242
	v_fma_f32 v247, -v241, v244, v243
	v_fmac_f32_e32 v244, v247, v242
	v_fma_f32 v241, -v241, v244, v243
	s_nop 1
	v_div_fmas_f32 v241, v241, v242, v244
	v_div_fixup_f32 v246, v241, v240, 1.0
	v_pk_mul_f32 v[72:73], v[72:73], v[246:247] op_sel_hi:[1,0]
	v_pk_mul_f32 v[74:75], v[74:75], v[246:247] op_sel_hi:[1,0]
	v_pk_mul_f32 v[76:77], v[76:77], v[246:247] op_sel_hi:[1,0]
	v_pk_mul_f32 v[78:79], v[78:79], v[246:247] op_sel_hi:[1,0]
	v_pk_mul_f32 v[80:81], v[80:81], v[246:247] op_sel_hi:[1,0]
	v_pk_mul_f32 v[82:83], v[82:83], v[246:247] op_sel_hi:[1,0]
	v_pk_mul_f32 v[84:85], v[84:85], v[246:247] op_sel_hi:[1,0]
	v_pk_mul_f32 v[86:87], v[86:87], v[246:247] op_sel_hi:[1,0]
	v_pk_mul_f32 v[88:89], v[88:89], v[246:247] op_sel_hi:[1,0]
	v_pk_mul_f32 v[90:91], v[90:91], v[246:247] op_sel_hi:[1,0]
	v_pk_mul_f32 v[92:93], v[92:93], v[246:247] op_sel_hi:[1,0]
	v_pk_mul_f32 v[94:95], v[94:95], v[246:247] op_sel_hi:[1,0]
	v_pk_mul_f32 v[96:97], v[96:97], v[246:247] op_sel_hi:[1,0]
	v_pk_mul_f32 v[98:99], v[98:99], v[246:247] op_sel_hi:[1,0]
	v_pk_mul_f32 v[100:101], v[100:101], v[246:247] op_sel_hi:[1,0]
	v_pk_mul_f32 v[102:103], v[102:103], v[246:247] op_sel_hi:[1,0]
	s_add_u32 s8, s10, 0xc0000
	s_addc_u32 s9, s11, 0
	v_pk_fma_f32 v[72:73], v[8:9], v[72:73], v[40:41]
	v_cvt_pk_bf16_f32 v232, v72, v73
	v_pk_fma_f32 v[74:75], v[10:11], v[74:75], v[42:43]
	v_cvt_pk_bf16_f32 v233, v74, v75
	v_pk_fma_f32 v[76:77], v[12:13], v[76:77], v[44:45]
	v_cvt_pk_bf16_f32 v234, v76, v77
	v_pk_fma_f32 v[78:79], v[14:15], v[78:79], v[46:47]
	v_cvt_pk_bf16_f32 v235, v78, v79
	global_store_dwordx4 v1, v[232:235], s[8:9] offset:0
	v_pk_fma_f32 v[80:81], v[16:17], v[80:81], v[48:49]
	v_cvt_pk_bf16_f32 v236, v80, v81
	v_pk_fma_f32 v[82:83], v[18:19], v[82:83], v[50:51]
	v_cvt_pk_bf16_f32 v237, v82, v83
	v_pk_fma_f32 v[84:85], v[20:21], v[84:85], v[52:53]
	v_cvt_pk_bf16_f32 v238, v84, v85
	v_pk_fma_f32 v[86:87], v[22:23], v[86:87], v[54:55]
	v_cvt_pk_bf16_f32 v239, v86, v87
	global_store_dwordx4 v1, v[236:239], s[8:9] offset:1024
	v_pk_fma_f32 v[88:89], v[24:25], v[88:89], v[56:57]
	v_cvt_pk_bf16_f32 v232, v88, v89
	v_pk_fma_f32 v[90:91], v[26:27], v[90:91], v[58:59]
	v_cvt_pk_bf16_f32 v233, v90, v91
	v_pk_fma_f32 v[92:93], v[28:29], v[92:93], v[60:61]
	v_cvt_pk_bf16_f32 v234, v92, v93
	v_pk_fma_f32 v[94:95], v[30:31], v[94:95], v[62:63]
	v_cvt_pk_bf16_f32 v235, v94, v95
	global_store_dwordx4 v1, v[232:235], s[8:9] offset:2048
	v_pk_fma_f32 v[96:97], v[32:33], v[96:97], v[64:65]
	v_cvt_pk_bf16_f32 v236, v96, v97
	v_pk_fma_f32 v[98:99], v[34:35], v[98:99], v[66:67]
	v_cvt_pk_bf16_f32 v237, v98, v99
	v_pk_fma_f32 v[100:101], v[36:37], v[100:101], v[68:69]
	v_cvt_pk_bf16_f32 v238, v100, v101
	v_pk_fma_f32 v[102:103], v[38:39], v[102:103], v[70:71]
	v_cvt_pk_bf16_f32 v239, v102, v103
	global_store_dwordx4 v1, v[236:239], s[8:9] offset:3072
	s_waitcnt vmcnt(28)
	v_cvt_f32_f16_e32 v72, v216
	v_cvt_f32_f16_sdwa v73, v216 dst_sel:DWORD dst_unused:UNUSED_PAD src0_sel:WORD_1
	v_cvt_f32_f16_e32 v74, v217
	v_cvt_f32_f16_sdwa v75, v217 dst_sel:DWORD dst_unused:UNUSED_PAD src0_sel:WORD_1
	v_cvt_f32_f16_e32 v76, v218
	v_cvt_f32_f16_sdwa v77, v218 dst_sel:DWORD dst_unused:UNUSED_PAD src0_sel:WORD_1
	v_cvt_f32_f16_e32 v78, v219
	v_cvt_f32_f16_sdwa v79, v219 dst_sel:DWORD dst_unused:UNUSED_PAD src0_sel:WORD_1
	v_cvt_f32_f16_e32 v80, v220
	v_cvt_f32_f16_sdwa v81, v220 dst_sel:DWORD dst_unused:UNUSED_PAD src0_sel:WORD_1
	v_cvt_f32_f16_e32 v82, v221
	v_cvt_f32_f16_sdwa v83, v221 dst_sel:DWORD dst_unused:UNUSED_PAD src0_sel:WORD_1
	v_cvt_f32_f16_e32 v84, v222
	v_cvt_f32_f16_sdwa v85, v222 dst_sel:DWORD dst_unused:UNUSED_PAD src0_sel:WORD_1
	v_cvt_f32_f16_e32 v86, v223
	v_cvt_f32_f16_sdwa v87, v223 dst_sel:DWORD dst_unused:UNUSED_PAD src0_sel:WORD_1
	v_cvt_f32_f16_e32 v88, v224
	v_cvt_f32_f16_sdwa v89, v224 dst_sel:DWORD dst_unused:UNUSED_PAD src0_sel:WORD_1
	v_cvt_f32_f16_e32 v90, v225
	v_cvt_f32_f16_sdwa v91, v225 dst_sel:DWORD dst_unused:UNUSED_PAD src0_sel:WORD_1
	v_cvt_f32_f16_e32 v92, v226
	v_cvt_f32_f16_sdwa v93, v226 dst_sel:DWORD dst_unused:UNUSED_PAD src0_sel:WORD_1
	v_cvt_f32_f16_e32 v94, v227
	v_cvt_f32_f16_sdwa v95, v227 dst_sel:DWORD dst_unused:UNUSED_PAD src0_sel:WORD_1
	v_cvt_f32_f16_e32 v96, v228
	v_cvt_f32_f16_sdwa v97, v228 dst_sel:DWORD dst_unused:UNUSED_PAD src0_sel:WORD_1
	v_cvt_f32_f16_e32 v98, v229
	v_cvt_f32_f16_sdwa v99, v229 dst_sel:DWORD dst_unused:UNUSED_PAD src0_sel:WORD_1
	v_cvt_f32_f16_e32 v100, v230
	v_cvt_f32_f16_sdwa v101, v230 dst_sel:DWORD dst_unused:UNUSED_PAD src0_sel:WORD_1
	v_cvt_f32_f16_e32 v102, v231
	v_cvt_f32_f16_sdwa v103, v231 dst_sel:DWORD dst_unused:UNUSED_PAD src0_sel:WORD_1
	v_pk_mul_f32 v[232:233], v[72:73], v[72:73]
	v_pk_mul_f32 v[234:235], v[74:75], v[74:75]
	v_pk_mul_f32 v[236:237], v[76:77], v[76:77]
	v_pk_mul_f32 v[238:239], v[78:79], v[78:79]
	v_pk_fma_f32 v[232:233], v[80:81], v[80:81], v[232:233]
	v_pk_fma_f32 v[234:235], v[82:83], v[82:83], v[234:235]
	v_pk_fma_f32 v[236:237], v[84:85], v[84:85], v[236:237]
	v_pk_fma_f32 v[238:239], v[86:87], v[86:87], v[238:239]
	v_pk_fma_f32 v[232:233], v[88:89], v[88:89], v[232:233]
	v_pk_fma_f32 v[234:235], v[90:91], v[90:91], v[234:235]
	v_pk_fma_f32 v[236:237], v[92:93], v[92:93], v[236:237]
	v_pk_fma_f32 v[238:239], v[94:95], v[94:95], v[238:239]
	v_pk_fma_f32 v[232:233], v[96:97], v[96:97], v[232:233]
	v_pk_fma_f32 v[234:235], v[98:99], v[98:99], v[234:235]
	v_pk_fma_f32 v[236:237], v[100:101], v[100:101], v[236:237]
	v_pk_fma_f32 v[238:239], v[102:103], v[102:103], v[238:239]
	v_pk_add_f32 v[232:233], v[232:233], v[234:235]
	v_pk_add_f32 v[236:237], v[236:237], v[238:239]
	v_pk_add_f32 v[232:233], v[232:233], v[236:237]
	v_add_f32_e32 v240, v232, v233
	s_nop 1
	v_add_f32_dpp v240, v240, v240 quad_perm:[1,0,3,2] row_mask:0xf bank_mask:0xf
	s_nop 1
	v_add_f32_dpp v240, v240, v240 quad_perm:[2,3,0,1] row_mask:0xf bank_mask:0xf
	s_nop 1
	v_add_f32_dpp v240, v240, v240 row_half_mirror row_mask:0xf bank_mask:0xf
	s_nop 1
	v_add_f32_dpp v240, v240, v240 row_mirror row_mask:0xf bank_mask:0xf
	s_nop 1
	v_readlane_b32 s0, v240, 0
	v_readlane_b32 s1, v240, 16
	v_readlane_b32 s4, v240, 32
	v_readlane_b32 s5, v240, 48
	v_mov_b32_e32 v249, 0x358637bd
	s_nop 1
	v_mov_b32_e32 v240, s0
	v_add_f32_e32 v240, s1, v240
	v_add_f32_e32 v240, s4, v240
	v_add_f32_e32 v240, s5, v240
	v_fmamk_f32 v240, v240, 0x3a000000, v249
	s_mov_b32 s0, 0xf800000
	v_mul_f32_e32 v241, 0x4f800000, v240
	v_cmp_gt_f32_e32 vcc, s0, v240
	s_nop 1
	v_cndmask_b32_e32 v240, v240, v241, vcc
	v_sqrt_f32_e32 v241, v240
	s_nop 0
	v_add_u32_e32 v242, -1, v241
	v_fma_f32 v243, -v242, v241, v240
	v_cmp_ge_f32_e64 s[0:1], 0, v243
	v_add_u32_e32 v243, 1, v241
	s_nop 0
	v_cndmask_b32_e64 v242, v241, v242, s[0:1]
	v_fma_f32 v241, -v243, v241, v240
	v_cmp_lt_f32_e64 s[0:1], 0, v241
	s_nop 1
	v_cndmask_b32_e64 v241, v242, v243, s[0:1]
	v_mul_f32_e32 v242, 0x37800000, v241
	v_cndmask_b32_e32 v241, v241, v242, vcc
	v_cmp_class_f32_e32 vcc, v240, v248
	s_nop 1
	v_cndmask_b32_e32 v240, v241, v240, vcc
	v_div_scale_f32 v241, s[0:1], v240, v240, 1.0
	v_rcp_f32_e32 v242, v241
	s_nop 0
	v_fma_f32 v243, -v241, v242, 1.0
	v_fmac_f32_e32 v242, v243, v242
	v_div_scale_f32 v243, vcc, 1.0, v240, 1.0
	v_mul_f32_e32 v244, v243, v242
	v_fma_f32 v247, -v241, v244, v243
	v_fmac_f32_e32 v244, v247, v242
	v_fma_f32 v241, -v241, v244, v243
	s_nop 1
	v_div_fmas_f32 v241, v241, v242, v244
	v_div_fixup_f32 v246, v241, v240, 1.0
	v_pk_mul_f32 v[72:73], v[72:73], v[246:247] op_sel_hi:[1,0]
	v_pk_mul_f32 v[74:75], v[74:75], v[246:247] op_sel_hi:[1,0]
	v_pk_mul_f32 v[76:77], v[76:77], v[246:247] op_sel_hi:[1,0]
	v_pk_mul_f32 v[78:79], v[78:79], v[246:247] op_sel_hi:[1,0]
	v_pk_mul_f32 v[80:81], v[80:81], v[246:247] op_sel_hi:[1,0]
	v_pk_mul_f32 v[82:83], v[82:83], v[246:247] op_sel_hi:[1,0]
	v_pk_mul_f32 v[84:85], v[84:85], v[246:247] op_sel_hi:[1,0]
	v_pk_mul_f32 v[86:87], v[86:87], v[246:247] op_sel_hi:[1,0]
	v_pk_mul_f32 v[88:89], v[88:89], v[246:247] op_sel_hi:[1,0]
	v_pk_mul_f32 v[90:91], v[90:91], v[246:247] op_sel_hi:[1,0]
	v_pk_mul_f32 v[92:93], v[92:93], v[246:247] op_sel_hi:[1,0]
	v_pk_mul_f32 v[94:95], v[94:95], v[246:247] op_sel_hi:[1,0]
	v_pk_mul_f32 v[96:97], v[96:97], v[246:247] op_sel_hi:[1,0]
	v_pk_mul_f32 v[98:99], v[98:99], v[246:247] op_sel_hi:[1,0]
	v_pk_mul_f32 v[100:101], v[100:101], v[246:247] op_sel_hi:[1,0]
	v_pk_mul_f32 v[102:103], v[102:103], v[246:247] op_sel_hi:[1,0]
	s_add_u32 s8, s10, 0xe0000
	s_addc_u32 s9, s11, 0
	v_pk_fma_f32 v[72:73], v[8:9], v[72:73], v[40:41]
	v_cvt_pk_bf16_f32 v232, v72, v73
	v_pk_fma_f32 v[74:75], v[10:11], v[74:75], v[42:43]
	v_cvt_pk_bf16_f32 v233, v74, v75
	v_pk_fma_f32 v[76:77], v[12:13], v[76:77], v[44:45]
	v_cvt_pk_bf16_f32 v234, v76, v77
	v_pk_fma_f32 v[78:79], v[14:15], v[78:79], v[46:47]
	v_cvt_pk_bf16_f32 v235, v78, v79
	global_store_dwordx4 v1, v[232:235], s[8:9] offset:0
	v_pk_fma_f32 v[80:81], v[16:17], v[80:81], v[48:49]
	v_cvt_pk_bf16_f32 v236, v80, v81
	v_pk_fma_f32 v[82:83], v[18:19], v[82:83], v[50:51]
	v_cvt_pk_bf16_f32 v237, v82, v83
	v_pk_fma_f32 v[84:85], v[20:21], v[84:85], v[52:53]
	v_cvt_pk_bf16_f32 v238, v84, v85
	v_pk_fma_f32 v[86:87], v[22:23], v[86:87], v[54:55]
	v_cvt_pk_bf16_f32 v239, v86, v87
	global_store_dwordx4 v1, v[236:239], s[8:9] offset:1024
	v_pk_fma_f32 v[88:89], v[24:25], v[88:89], v[56:57]
	v_cvt_pk_bf16_f32 v232, v88, v89
	v_pk_fma_f32 v[90:91], v[26:27], v[90:91], v[58:59]
	v_cvt_pk_bf16_f32 v233, v90, v91
	v_pk_fma_f32 v[92:93], v[28:29], v[92:93], v[60:61]
	v_cvt_pk_bf16_f32 v234, v92, v93
	v_pk_fma_f32 v[94:95], v[30:31], v[94:95], v[62:63]
	v_cvt_pk_bf16_f32 v235, v94, v95
	global_store_dwordx4 v1, v[232:235], s[8:9] offset:2048
	v_pk_fma_f32 v[96:97], v[32:33], v[96:97], v[64:65]
	v_cvt_pk_bf16_f32 v236, v96, v97
	v_pk_fma_f32 v[98:99], v[34:35], v[98:99], v[66:67]
	v_cvt_pk_bf16_f32 v237, v98, v99
	v_pk_fma_f32 v[100:101], v[36:37], v[100:101], v[68:69]
	v_cvt_pk_bf16_f32 v238, v100, v101
	v_pk_fma_f32 v[102:103], v[38:39], v[102:103], v[70:71]
	v_cvt_pk_bf16_f32 v239, v102, v103
	global_store_dwordx4 v1, v[236:239], s[8:9] offset:3072
	s_branch .LBB0_563

.LBB0_1131:
	v_readlane_b32 s4, v250, 12
	s_cmp_lt_i32 s4, 10
	s_cselect_b64 s[0:1], -1, 0
	s_and_b64 s[2:3], s[0:1], s[2:3]
	s_andn2_b64 vcc, exec, s[2:3]
	v_readlane_b32 s5, v250, 13
	v_readlane_b32 s6, v250, 14
	v_readlane_b32 s7, v250, 15
	s_cbranch_vccnz .LBB0_1143
	v_mov_b32_e32 v1, 0x2416c
	ds_read_b32 v2, v1
	ds_read_b32 v1, v1 offset:4
	s_waitcnt lgkmcnt(0)
	v_readfirstlane_b32 s4, v2
	v_readfirstlane_b32 s5, v1
	s_cmp_lt_i32 s4, 1
	s_cbranch_scc1 .Lnorm_fb_1
	v_and_b32_e32 v1, 63, v0
	v_lshlrev_b32_e32 v2, 5, v1
	v_add_u32_e32 v3, 0x1000, v2
	v_lshlrev_b32_e32 v1, 4, v1
	v_readfirstlane_b32 s0, v0
	s_lshr_b32 s1, s0, 6
	s_add_i32 s4, s4, -1
	s_lshl_b32 s18, s4, 8
	s_lshl_b32 s19, s5, 3
	s_add_i32 s18, s18, s19
	s_add_i32 s18, s18, s1
	s_lshr_b32 s19, s4, 4
	s_lshl_b32 s20, s18, 12
	s_lshl_b32 s21, s18, 13
	s_add_u32 s6, s88, 0x45c00000
	s_addc_u32 s7, s89, 0
	s_add_u32 s6, s6, s20
	s_addc_u32 s7, s7, 0
	s_add_u32 s10, s88, 0x13e00000
	s_addc_u32 s11, s89, 0
	s_add_u32 s10, s10, s20
	s_addc_u32 s11, s11, 0
	s_add_u32 s16, s44, 0x4000
	s_addc_u32 s17, s45, 0
	s_mul_i32 s22, s19, 0x12000
	s_add_u32 s24, s88, 0x10c000
	s_addc_u32 s25, s89, 0
	s_add_u32 s24, s24, s22
	s_addc_u32 s25, s25, 0
	s_mul_i32 s22, s19, 0x12000
	s_add_u32 s26, s88, 0x10e000
	s_addc_u32 s27, s89, 0
	s_add_u32 s26, s26, s22
	s_addc_u32 s27, s27, 0
	global_load_dwordx4 v[72:75], v2, s[16:17] offset:0
	global_load_dwordx4 v[76:79], v2, s[16:17] offset:16
	global_load_dwordx4 v[80:83], v2, s[16:17] offset:2048
	global_load_dwordx4 v[84:87], v2, s[16:17] offset:2064
	global_load_dwordx4 v[88:91], v3, s[16:17] offset:0
	global_load_dwordx4 v[92:95], v3, s[16:17] offset:16
	global_load_dwordx4 v[96:99], v3, s[16:17] offset:2048
	global_load_dwordx4 v[100:103], v3, s[16:17] offset:2064
	global_load_dwordx4 v[8:11], v2, s[26:27] offset:0
	global_load_dwordx4 v[12:15], v2, s[26:27] offset:16
	global_load_dwordx4 v[16:19], v2, s[26:27] offset:2048
	global_load_dwordx4 v[20:23], v2, s[26:27] offset:2064
	global_load_dwordx4 v[24:27], v3, s[26:27] offset:0
	global_load_dwordx4 v[28:31], v3, s[26:27] offset:16
	global_load_dwordx4 v[32:35], v3, s[26:27] offset:2048
	global_load_dwordx4 v[36:39], v3, s[26:27] offset:2064
	global_load_dwordx4 v[40:43], v2, s[24:25] offset:0
	global_load_dwordx4 v[44:47], v2, s[24:25] offset:16
	global_load_dwordx4 v[48:51], v2, s[24:25] offset:2048
	global_load_dwordx4 v[52:55], v2, s[24:25] offset:2064
	global_load_dwordx4 v[56:59], v3, s[24:25] offset:0
	global_load_dwordx4 v[60:63], v3, s[24:25] offset:16
	global_load_dwordx4 v[64:67], v3, s[24:25] offset:2048
	global_load_dwordx4 v[68:71], v3, s[24:25] offset:2064
	s_add_u32 s8, s6, 0x0
	s_addc_u32 s9, s7, 0
	global_load_dwordx4 v[104:107], v1, s[8:9] offset:0 nt
	global_load_dwordx4 v[108:111], v1, s[8:9] offset:1024 nt
	global_load_dwordx4 v[112:115], v1, s[8:9] offset:2048 nt
	global_load_dwordx4 v[116:119], v1, s[8:9] offset:3072 nt
	s_add_u32 s8, s6, 0x20000
	s_addc_u32 s9, s7, 0
	global_load_dwordx4 v[120:123], v1, s[8:9] offset:0 nt
	global_load_dwordx4 v[124:127], v1, s[8:9] offset:1024 nt
	global_load_dwordx4 v[128:131], v1, s[8:9] offset:2048 nt
	global_load_dwordx4 v[132:135], v1, s[8:9] offset:3072 nt
	s_add_u32 s8, s6, 0x40000
	s_addc_u32 s9, s7, 0
	global_load_dwordx4 v[136:139], v1, s[8:9] offset:0 nt
	global_load_dwordx4 v[140:143], v1, s[8:9] offset:1024 nt
	global_load_dwordx4 v[144:147], v1, s[8:9] offset:2048 nt
	global_load_dwordx4 v[148:151], v1, s[8:9] offset:3072 nt
	s_add_u32 s8, s6, 0x60000
	s_addc_u32 s9, s7, 0
	global_load_dwordx4 v[152:155], v1, s[8:9] offset:0 nt
	global_load_dwordx4 v[156:159], v1, s[8:9] offset:1024 nt
	global_load_dwordx4 v[160:163], v1, s[8:9] offset:2048 nt
	global_load_dwordx4 v[164:167], v1, s[8:9] offset:3072 nt
	s_add_u32 s8, s6, 0x80000
	s_addc_u32 s9, s7, 0
	global_load_dwordx4 v[168:171], v1, s[8:9] offset:0 nt
	global_load_dwordx4 v[172:175], v1, s[8:9] offset:1024 nt
	global_load_dwordx4 v[176:179], v1, s[8:9] offset:2048 nt
	global_load_dwordx4 v[180:183], v1, s[8:9] offset:3072 nt
	s_add_u32 s8, s6, 0xa0000
	s_addc_u32 s9, s7, 0
	global_load_dwordx4 v[184:187], v1, s[8:9] offset:0 nt
	global_load_dwordx4 v[188:191], v1, s[8:9] offset:1024 nt
	global_load_dwordx4 v[192:195], v1, s[8:9] offset:2048 nt
	global_load_dwordx4 v[196:199], v1, s[8:9] offset:3072 nt
	s_add_u32 s8, s6, 0xc0000
	s_addc_u32 s9, s7, 0
	global_load_dwordx4 v[200:203], v1, s[8:9] offset:0 nt
	global_load_dwordx4 v[204:207], v1, s[8:9] offset:1024 nt
	global_load_dwordx4 v[208:211], v1, s[8:9] offset:2048 nt
	global_load_dwordx4 v[212:215], v1, s[8:9] offset:3072 nt
	s_add_u32 s8, s6, 0xe0000
	s_addc_u32 s9, s7, 0
	global_load_dwordx4 v[216:219], v1, s[8:9] offset:0 nt
	global_load_dwordx4 v[220:223], v1, s[8:9] offset:1024 nt
	global_load_dwordx4 v[224:227], v1, s[8:9] offset:2048 nt
	global_load_dwordx4 v[228:231], v1, s[8:9] offset:3072 nt
	s_waitcnt vmcnt(32)
	v_pk_add_f32 v[8:9], v[8:9], 1.0 op_sel_hi:[1,0]
	v_pk_add_f32 v[10:11], v[10:11], 1.0 op_sel_hi:[1,0]
	v_pk_add_f32 v[12:13], v[12:13], 1.0 op_sel_hi:[1,0]
	v_pk_add_f32 v[14:15], v[14:15], 1.0 op_sel_hi:[1,0]
	v_pk_add_f32 v[16:17], v[16:17], 1.0 op_sel_hi:[1,0]
	v_pk_add_f32 v[18:19], v[18:19], 1.0 op_sel_hi:[1,0]
	v_pk_add_f32 v[20:21], v[20:21], 1.0 op_sel_hi:[1,0]
	v_pk_add_f32 v[22:23], v[22:23], 1.0 op_sel_hi:[1,0]
	v_pk_add_f32 v[24:25], v[24:25], 1.0 op_sel_hi:[1,0]
	v_pk_add_f32 v[26:27], v[26:27], 1.0 op_sel_hi:[1,0]
	v_pk_add_f32 v[28:29], v[28:29], 1.0 op_sel_hi:[1,0]
	v_pk_add_f32 v[30:31], v[30:31], 1.0 op_sel_hi:[1,0]
	v_pk_add_f32 v[32:33], v[32:33], 1.0 op_sel_hi:[1,0]
	v_pk_add_f32 v[34:35], v[34:35], 1.0 op_sel_hi:[1,0]
	v_pk_add_f32 v[36:37], v[36:37], 1.0 op_sel_hi:[1,0]
	v_pk_add_f32 v[38:39], v[38:39], 1.0 op_sel_hi:[1,0]
	v_pk_mul_f32 v[8:9], v[72:73], v[8:9]
	v_pk_mul_f32 v[10:11], v[74:75], v[10:11]
	v_pk_mul_f32 v[12:13], v[76:77], v[12:13]
	v_pk_mul_f32 v[14:15], v[78:79], v[14:15]
	v_pk_mul_f32 v[16:17], v[80:81], v[16:17]
	v_pk_mul_f32 v[18:19], v[82:83], v[18:19]
	v_pk_mul_f32 v[20:21], v[84:85], v[20:21]
	v_pk_mul_f32 v[22:23], v[86:87], v[22:23]
	v_pk_mul_f32 v[24:25], v[88:89], v[24:25]
	v_pk_mul_f32 v[26:27], v[90:91], v[26:27]
	v_pk_mul_f32 v[28:29], v[92:93], v[28:29]
	v_pk_mul_f32 v[30:31], v[94:95], v[30:31]
	v_pk_mul_f32 v[32:33], v[96:97], v[32:33]
	v_pk_mul_f32 v[34:35], v[98:99], v[34:35]
	v_pk_mul_f32 v[36:37], v[100:101], v[36:37]
	v_pk_mul_f32 v[38:39], v[102:103], v[38:39]
	v_mov_b32_e32 v248, 0x260
	s_waitcnt vmcnt(28)
	v_cvt_f32_f16_e32 v72, v104
	v_cvt_f32_f16_sdwa v73, v104 dst_sel:DWORD dst_unused:UNUSED_PAD src0_sel:WORD_1
	v_cvt_f32_f16_e32 v74, v105
	v_cvt_f32_f16_sdwa v75, v105 dst_sel:DWORD dst_unused:UNUSED_PAD src0_sel:WORD_1
	v_cvt_f32_f16_e32 v76, v106
	v_cvt_f32_f16_sdwa v77, v106 dst_sel:DWORD dst_unused:UNUSED_PAD src0_sel:WORD_1
	v_cvt_f32_f16_e32 v78, v107
	v_cvt_f32_f16_sdwa v79, v107 dst_sel:DWORD dst_unused:UNUSED_PAD src0_sel:WORD_1
	v_cvt_f32_f16_e32 v80, v108
	v_cvt_f32_f16_sdwa v81, v108 dst_sel:DWORD dst_unused:UNUSED_PAD src0_sel:WORD_1
	v_cvt_f32_f16_e32 v82, v109
	v_cvt_f32_f16_sdwa v83, v109 dst_sel:DWORD dst_unused:UNUSED_PAD src0_sel:WORD_1
	v_cvt_f32_f16_e32 v84, v110
	v_cvt_f32_f16_sdwa v85, v110 dst_sel:DWORD dst_unused:UNUSED_PAD src0_sel:WORD_1
	v_cvt_f32_f16_e32 v86, v111
	v_cvt_f32_f16_sdwa v87, v111 dst_sel:DWORD dst_unused:UNUSED_PAD src0_sel:WORD_1
	v_cvt_f32_f16_e32 v88, v112
	v_cvt_f32_f16_sdwa v89, v112 dst_sel:DWORD dst_unused:UNUSED_PAD src0_sel:WORD_1
	v_cvt_f32_f16_e32 v90, v113
	v_cvt_f32_f16_sdwa v91, v113 dst_sel:DWORD dst_unused:UNUSED_PAD src0_sel:WORD_1
	v_cvt_f32_f16_e32 v92, v114
	v_cvt_f32_f16_sdwa v93, v114 dst_sel:DWORD dst_unused:UNUSED_PAD src0_sel:WORD_1
	v_cvt_f32_f16_e32 v94, v115
	v_cvt_f32_f16_sdwa v95, v115 dst_sel:DWORD dst_unused:UNUSED_PAD src0_sel:WORD_1
	v_cvt_f32_f16_e32 v96, v116
	v_cvt_f32_f16_sdwa v97, v116 dst_sel:DWORD dst_unused:UNUSED_PAD src0_sel:WORD_1
	v_cvt_f32_f16_e32 v98, v117
	v_cvt_f32_f16_sdwa v99, v117 dst_sel:DWORD dst_unused:UNUSED_PAD src0_sel:WORD_1
	v_cvt_f32_f16_e32 v100, v118
	v_cvt_f32_f16_sdwa v101, v118 dst_sel:DWORD dst_unused:UNUSED_PAD src0_sel:WORD_1
	v_cvt_f32_f16_e32 v102, v119
	v_cvt_f32_f16_sdwa v103, v119 dst_sel:DWORD dst_unused:UNUSED_PAD src0_sel:WORD_1
	v_pk_mul_f32 v[232:233], v[72:73], v[72:73]
	v_pk_mul_f32 v[234:235], v[74:75], v[74:75]
	v_pk_mul_f32 v[236:237], v[76:77], v[76:77]
	v_pk_mul_f32 v[238:239], v[78:79], v[78:79]
	v_pk_fma_f32 v[232:233], v[80:81], v[80:81], v[232:233]
	v_pk_fma_f32 v[234:235], v[82:83], v[82:83], v[234:235]
	v_pk_fma_f32 v[236:237], v[84:85], v[84:85], v[236:237]
	v_pk_fma_f32 v[238:239], v[86:87], v[86:87], v[238:239]
	v_pk_fma_f32 v[232:233], v[88:89], v[88:89], v[232:233]
	v_pk_fma_f32 v[234:235], v[90:91], v[90:91], v[234:235]
	v_pk_fma_f32 v[236:237], v[92:93], v[92:93], v[236:237]
	v_pk_fma_f32 v[238:239], v[94:95], v[94:95], v[238:239]
	v_pk_fma_f32 v[232:233], v[96:97], v[96:97], v[232:233]
	v_pk_fma_f32 v[234:235], v[98:99], v[98:99], v[234:235]
	v_pk_fma_f32 v[236:237], v[100:101], v[100:101], v[236:237]
	v_pk_fma_f32 v[238:239], v[102:103], v[102:103], v[238:239]
	v_pk_add_f32 v[232:233], v[232:233], v[234:235]
	v_pk_add_f32 v[236:237], v[236:237], v[238:239]
	v_pk_add_f32 v[232:233], v[232:233], v[236:237]
	v_add_f32_e32 v240, v232, v233
	s_nop 1
	v_add_f32_dpp v240, v240, v240 quad_perm:[1,0,3,2] row_mask:0xf bank_mask:0xf
	s_nop 1
	v_add_f32_dpp v240, v240, v240 quad_perm:[2,3,0,1] row_mask:0xf bank_mask:0xf
	s_nop 1
	v_add_f32_dpp v240, v240, v240 row_half_mirror row_mask:0xf bank_mask:0xf
	s_nop 1
	v_add_f32_dpp v240, v240, v240 row_mirror row_mask:0xf bank_mask:0xf
	s_nop 1
	v_readlane_b32 s0, v240, 0
	v_readlane_b32 s1, v240, 16
	v_readlane_b32 s4, v240, 32
	v_readlane_b32 s5, v240, 48
	v_mov_b32_e32 v249, 0x358637bd
	s_nop 1
	v_mov_b32_e32 v240, s0
	v_add_f32_e32 v240, s1, v240
	v_add_f32_e32 v240, s4, v240
	v_add_f32_e32 v240, s5, v240
	v_fmamk_f32 v240, v240, 0x3a000000, v249
	s_mov_b32 s0, 0xf800000
	v_mul_f32_e32 v241, 0x4f800000, v240
	v_cmp_gt_f32_e32 vcc, s0, v240
	s_nop 1
	v_cndmask_b32_e32 v240, v240, v241, vcc
	v_sqrt_f32_e32 v241, v240
	s_nop 0
	v_add_u32_e32 v242, -1, v241
	v_fma_f32 v243, -v242, v241, v240
	v_cmp_ge_f32_e64 s[0:1], 0, v243
	v_add_u32_e32 v243, 1, v241
	s_nop 0
	v_cndmask_b32_e64 v242, v241, v242, s[0:1]
	v_fma_f32 v241, -v243, v241, v240
	v_cmp_lt_f32_e64 s[0:1], 0, v241
	s_nop 1
	v_cndmask_b32_e64 v241, v242, v243, s[0:1]
	v_mul_f32_e32 v242, 0x37800000, v241
	v_cndmask_b32_e32 v241, v241, v242, vcc
	v_cmp_class_f32_e32 vcc, v240, v248
	s_nop 1
	v_cndmask_b32_e32 v240, v241, v240, vcc
	v_div_scale_f32 v241, s[0:1], v240, v240, 1.0
	v_rcp_f32_e32 v242, v241
	s_nop 0
	v_fma_f32 v243, -v241, v242, 1.0
	v_fmac_f32_e32 v242, v243, v242
	v_div_scale_f32 v243, vcc, 1.0, v240, 1.0
	v_mul_f32_e32 v244, v243, v242
	v_fma_f32 v247, -v241, v244, v243
	v_fmac_f32_e32 v244, v247, v242
	v_fma_f32 v241, -v241, v244, v243
	s_nop 1
	v_div_fmas_f32 v241, v241, v242, v244
	v_div_fixup_f32 v246, v241, v240, 1.0
	v_pk_mul_f32 v[72:73], v[72:73], v[246:247] op_sel_hi:[1,0]
	v_pk_mul_f32 v[74:75], v[74:75], v[246:247] op_sel_hi:[1,0]
	v_pk_mul_f32 v[76:77], v[76:77], v[246:247] op_sel_hi:[1,0]
	v_pk_mul_f32 v[78:79], v[78:79], v[246:247] op_sel_hi:[1,0]
	v_pk_mul_f32 v[80:81], v[80:81], v[246:247] op_sel_hi:[1,0]
	v_pk_mul_f32 v[82:83], v[82:83], v[246:247] op_sel_hi:[1,0]
	v_pk_mul_f32 v[84:85], v[84:85], v[246:247] op_sel_hi:[1,0]
	v_pk_mul_f32 v[86:87], v[86:87], v[246:247] op_sel_hi:[1,0]
	v_pk_mul_f32 v[88:89], v[88:89], v[246:247] op_sel_hi:[1,0]
	v_pk_mul_f32 v[90:91], v[90:91], v[246:247] op_sel_hi:[1,0]
	v_pk_mul_f32 v[92:93], v[92:93], v[246:247] op_sel_hi:[1,0]
	v_pk_mul_f32 v[94:95], v[94:95], v[246:247] op_sel_hi:[1,0]
	v_pk_mul_f32 v[96:97], v[96:97], v[246:247] op_sel_hi:[1,0]
	v_pk_mul_f32 v[98:99], v[98:99], v[246:247] op_sel_hi:[1,0]
	v_pk_mul_f32 v[100:101], v[100:101], v[246:247] op_sel_hi:[1,0]
	v_pk_mul_f32 v[102:103], v[102:103], v[246:247] op_sel_hi:[1,0]
	s_add_u32 s8, s10, 0x0
	s_addc_u32 s9, s11, 0
	v_pk_fma_f32 v[72:73], v[8:9], v[72:73], v[40:41]
	v_cvt_pk_bf16_f32 v232, v72, v73
	v_pk_fma_f32 v[74:75], v[10:11], v[74:75], v[42:43]
	v_cvt_pk_bf16_f32 v233, v74, v75
	v_pk_fma_f32 v[76:77], v[12:13], v[76:77], v[44:45]
	v_cvt_pk_bf16_f32 v234, v76, v77
	v_pk_fma_f32 v[78:79], v[14:15], v[78:79], v[46:47]
	v_cvt_pk_bf16_f32 v235, v78, v79
	global_store_dwordx4 v1, v[232:235], s[8:9] offset:0
	v_pk_fma_f32 v[80:81], v[16:17], v[80:81], v[48:49]
	v_cvt_pk_bf16_f32 v236, v80, v81
	v_pk_fma_f32 v[82:83], v[18:19], v[82:83], v[50:51]
	v_cvt_pk_bf16_f32 v237, v82, v83
	v_pk_fma_f32 v[84:85], v[20:21], v[84:85], v[52:53]
	v_cvt_pk_bf16_f32 v238, v84, v85
	v_pk_fma_f32 v[86:87], v[22:23], v[86:87], v[54:55]
	v_cvt_pk_bf16_f32 v239, v86, v87
	global_store_dwordx4 v1, v[236:239], s[8:9] offset:1024
	v_pk_fma_f32 v[88:89], v[24:25], v[88:89], v[56:57]
	v_cvt_pk_bf16_f32 v232, v88, v89
	v_pk_fma_f32 v[90:91], v[26:27], v[90:91], v[58:59]
	v_cvt_pk_bf16_f32 v233, v90, v91
	v_pk_fma_f32 v[92:93], v[28:29], v[92:93], v[60:61]
	v_cvt_pk_bf16_f32 v234, v92, v93
	v_pk_fma_f32 v[94:95], v[30:31], v[94:95], v[62:63]
	v_cvt_pk_bf16_f32 v235, v94, v95
	global_store_dwordx4 v1, v[232:235], s[8:9] offset:2048
	v_pk_fma_f32 v[96:97], v[32:33], v[96:97], v[64:65]
	v_cvt_pk_bf16_f32 v236, v96, v97
	v_pk_fma_f32 v[98:99], v[34:35], v[98:99], v[66:67]
	v_cvt_pk_bf16_f32 v237, v98, v99
	v_pk_fma_f32 v[100:101], v[36:37], v[100:101], v[68:69]
	v_cvt_pk_bf16_f32 v238, v100, v101
	v_pk_fma_f32 v[102:103], v[38:39], v[102:103], v[70:71]
	v_cvt_pk_bf16_f32 v239, v102, v103
	global_store_dwordx4 v1, v[236:239], s[8:9] offset:3072
	s_waitcnt vmcnt(28)
	v_cvt_f32_f16_e32 v72, v120
	v_cvt_f32_f16_sdwa v73, v120 dst_sel:DWORD dst_unused:UNUSED_PAD src0_sel:WORD_1
	v_cvt_f32_f16_e32 v74, v121
	v_cvt_f32_f16_sdwa v75, v121 dst_sel:DWORD dst_unused:UNUSED_PAD src0_sel:WORD_1
	v_cvt_f32_f16_e32 v76, v122
	v_cvt_f32_f16_sdwa v77, v122 dst_sel:DWORD dst_unused:UNUSED_PAD src0_sel:WORD_1
	v_cvt_f32_f16_e32 v78, v123
	v_cvt_f32_f16_sdwa v79, v123 dst_sel:DWORD dst_unused:UNUSED_PAD src0_sel:WORD_1
	v_cvt_f32_f16_e32 v80, v124
	v_cvt_f32_f16_sdwa v81, v124 dst_sel:DWORD dst_unused:UNUSED_PAD src0_sel:WORD_1
	v_cvt_f32_f16_e32 v82, v125
	v_cvt_f32_f16_sdwa v83, v125 dst_sel:DWORD dst_unused:UNUSED_PAD src0_sel:WORD_1
	v_cvt_f32_f16_e32 v84, v126
	v_cvt_f32_f16_sdwa v85, v126 dst_sel:DWORD dst_unused:UNUSED_PAD src0_sel:WORD_1
	v_cvt_f32_f16_e32 v86, v127
	v_cvt_f32_f16_sdwa v87, v127 dst_sel:DWORD dst_unused:UNUSED_PAD src0_sel:WORD_1
	v_cvt_f32_f16_e32 v88, v128
	v_cvt_f32_f16_sdwa v89, v128 dst_sel:DWORD dst_unused:UNUSED_PAD src0_sel:WORD_1
	v_cvt_f32_f16_e32 v90, v129
	v_cvt_f32_f16_sdwa v91, v129 dst_sel:DWORD dst_unused:UNUSED_PAD src0_sel:WORD_1
	v_cvt_f32_f16_e32 v92, v130
	v_cvt_f32_f16_sdwa v93, v130 dst_sel:DWORD dst_unused:UNUSED_PAD src0_sel:WORD_1
	v_cvt_f32_f16_e32 v94, v131
	v_cvt_f32_f16_sdwa v95, v131 dst_sel:DWORD dst_unused:UNUSED_PAD src0_sel:WORD_1
	v_cvt_f32_f16_e32 v96, v132
	v_cvt_f32_f16_sdwa v97, v132 dst_sel:DWORD dst_unused:UNUSED_PAD src0_sel:WORD_1
	v_cvt_f32_f16_e32 v98, v133
	v_cvt_f32_f16_sdwa v99, v133 dst_sel:DWORD dst_unused:UNUSED_PAD src0_sel:WORD_1
	v_cvt_f32_f16_e32 v100, v134
	v_cvt_f32_f16_sdwa v101, v134 dst_sel:DWORD dst_unused:UNUSED_PAD src0_sel:WORD_1
	v_cvt_f32_f16_e32 v102, v135
	v_cvt_f32_f16_sdwa v103, v135 dst_sel:DWORD dst_unused:UNUSED_PAD src0_sel:WORD_1
	v_pk_mul_f32 v[232:233], v[72:73], v[72:73]
	v_pk_mul_f32 v[234:235], v[74:75], v[74:75]
	v_pk_mul_f32 v[236:237], v[76:77], v[76:77]
	v_pk_mul_f32 v[238:239], v[78:79], v[78:79]
	v_pk_fma_f32 v[232:233], v[80:81], v[80:81], v[232:233]
	v_pk_fma_f32 v[234:235], v[82:83], v[82:83], v[234:235]
	v_pk_fma_f32 v[236:237], v[84:85], v[84:85], v[236:237]
	v_pk_fma_f32 v[238:239], v[86:87], v[86:87], v[238:239]
	v_pk_fma_f32 v[232:233], v[88:89], v[88:89], v[232:233]
	v_pk_fma_f32 v[234:235], v[90:91], v[90:91], v[234:235]
	v_pk_fma_f32 v[236:237], v[92:93], v[92:93], v[236:237]
	v_pk_fma_f32 v[238:239], v[94:95], v[94:95], v[238:239]
	v_pk_fma_f32 v[232:233], v[96:97], v[96:97], v[232:233]
	v_pk_fma_f32 v[234:235], v[98:99], v[98:99], v[234:235]
	v_pk_fma_f32 v[236:237], v[100:101], v[100:101], v[236:237]
	v_pk_fma_f32 v[238:239], v[102:103], v[102:103], v[238:239]
	v_pk_add_f32 v[232:233], v[232:233], v[234:235]
	v_pk_add_f32 v[236:237], v[236:237], v[238:239]
	v_pk_add_f32 v[232:233], v[232:233], v[236:237]
	v_add_f32_e32 v240, v232, v233
	s_nop 1
	v_add_f32_dpp v240, v240, v240 quad_perm:[1,0,3,2] row_mask:0xf bank_mask:0xf
	s_nop 1
	v_add_f32_dpp v240, v240, v240 quad_perm:[2,3,0,1] row_mask:0xf bank_mask:0xf
	s_nop 1
	v_add_f32_dpp v240, v240, v240 row_half_mirror row_mask:0xf bank_mask:0xf
	s_nop 1
	v_add_f32_dpp v240, v240, v240 row_mirror row_mask:0xf bank_mask:0xf
	s_nop 1
	v_readlane_b32 s0, v240, 0
	v_readlane_b32 s1, v240, 16
	v_readlane_b32 s4, v240, 32
	v_readlane_b32 s5, v240, 48
	v_mov_b32_e32 v249, 0x358637bd
	s_nop 1
	v_mov_b32_e32 v240, s0
	v_add_f32_e32 v240, s1, v240
	v_add_f32_e32 v240, s4, v240
	v_add_f32_e32 v240, s5, v240
	v_fmamk_f32 v240, v240, 0x3a000000, v249
	s_mov_b32 s0, 0xf800000
	v_mul_f32_e32 v241, 0x4f800000, v240
	v_cmp_gt_f32_e32 vcc, s0, v240
	s_nop 1
	v_cndmask_b32_e32 v240, v240, v241, vcc
	v_sqrt_f32_e32 v241, v240
	s_nop 0
	v_add_u32_e32 v242, -1, v241
	v_fma_f32 v243, -v242, v241, v240
	v_cmp_ge_f32_e64 s[0:1], 0, v243
	v_add_u32_e32 v243, 1, v241
	s_nop 0
	v_cndmask_b32_e64 v242, v241, v242, s[0:1]
	v_fma_f32 v241, -v243, v241, v240
	v_cmp_lt_f32_e64 s[0:1], 0, v241
	s_nop 1
	v_cndmask_b32_e64 v241, v242, v243, s[0:1]
	v_mul_f32_e32 v242, 0x37800000, v241
	v_cndmask_b32_e32 v241, v241, v242, vcc
	v_cmp_class_f32_e32 vcc, v240, v248
	s_nop 1
	v_cndmask_b32_e32 v240, v241, v240, vcc
	v_div_scale_f32 v241, s[0:1], v240, v240, 1.0
	v_rcp_f32_e32 v242, v241
	s_nop 0
	v_fma_f32 v243, -v241, v242, 1.0
	v_fmac_f32_e32 v242, v243, v242
	v_div_scale_f32 v243, vcc, 1.0, v240, 1.0
	v_mul_f32_e32 v244, v243, v242
	v_fma_f32 v247, -v241, v244, v243
	v_fmac_f32_e32 v244, v247, v242
	v_fma_f32 v241, -v241, v244, v243
	s_nop 1
	v_div_fmas_f32 v241, v241, v242, v244
	v_div_fixup_f32 v246, v241, v240, 1.0
	v_pk_mul_f32 v[72:73], v[72:73], v[246:247] op_sel_hi:[1,0]
	v_pk_mul_f32 v[74:75], v[74:75], v[246:247] op_sel_hi:[1,0]
	v_pk_mul_f32 v[76:77], v[76:77], v[246:247] op_sel_hi:[1,0]
	v_pk_mul_f32 v[78:79], v[78:79], v[246:247] op_sel_hi:[1,0]
	v_pk_mul_f32 v[80:81], v[80:81], v[246:247] op_sel_hi:[1,0]
	v_pk_mul_f32 v[82:83], v[82:83], v[246:247] op_sel_hi:[1,0]
	v_pk_mul_f32 v[84:85], v[84:85], v[246:247] op_sel_hi:[1,0]
	v_pk_mul_f32 v[86:87], v[86:87], v[246:247] op_sel_hi:[1,0]
	v_pk_mul_f32 v[88:89], v[88:89], v[246:247] op_sel_hi:[1,0]
	v_pk_mul_f32 v[90:91], v[90:91], v[246:247] op_sel_hi:[1,0]
	v_pk_mul_f32 v[92:93], v[92:93], v[246:247] op_sel_hi:[1,0]
	v_pk_mul_f32 v[94:95], v[94:95], v[246:247] op_sel_hi:[1,0]
	v_pk_mul_f32 v[96:97], v[96:97], v[246:247] op_sel_hi:[1,0]
	v_pk_mul_f32 v[98:99], v[98:99], v[246:247] op_sel_hi:[1,0]
	v_pk_mul_f32 v[100:101], v[100:101], v[246:247] op_sel_hi:[1,0]
	v_pk_mul_f32 v[102:103], v[102:103], v[246:247] op_sel_hi:[1,0]
	s_add_u32 s8, s10, 0x20000
	s_addc_u32 s9, s11, 0
	v_pk_fma_f32 v[72:73], v[8:9], v[72:73], v[40:41]
	v_cvt_pk_bf16_f32 v232, v72, v73
	v_pk_fma_f32 v[74:75], v[10:11], v[74:75], v[42:43]
	v_cvt_pk_bf16_f32 v233, v74, v75
	v_pk_fma_f32 v[76:77], v[12:13], v[76:77], v[44:45]
	v_cvt_pk_bf16_f32 v234, v76, v77
	v_pk_fma_f32 v[78:79], v[14:15], v[78:79], v[46:47]
	v_cvt_pk_bf16_f32 v235, v78, v79
	global_store_dwordx4 v1, v[232:235], s[8:9] offset:0
	v_pk_fma_f32 v[80:81], v[16:17], v[80:81], v[48:49]
	v_cvt_pk_bf16_f32 v236, v80, v81
	v_pk_fma_f32 v[82:83], v[18:19], v[82:83], v[50:51]
	v_cvt_pk_bf16_f32 v237, v82, v83
	v_pk_fma_f32 v[84:85], v[20:21], v[84:85], v[52:53]
	v_cvt_pk_bf16_f32 v238, v84, v85
	v_pk_fma_f32 v[86:87], v[22:23], v[86:87], v[54:55]
	v_cvt_pk_bf16_f32 v239, v86, v87
	global_store_dwordx4 v1, v[236:239], s[8:9] offset:1024
	v_pk_fma_f32 v[88:89], v[24:25], v[88:89], v[56:57]
	v_cvt_pk_bf16_f32 v232, v88, v89
	v_pk_fma_f32 v[90:91], v[26:27], v[90:91], v[58:59]
	v_cvt_pk_bf16_f32 v233, v90, v91
	v_pk_fma_f32 v[92:93], v[28:29], v[92:93], v[60:61]
	v_cvt_pk_bf16_f32 v234, v92, v93
	v_pk_fma_f32 v[94:95], v[30:31], v[94:95], v[62:63]
	v_cvt_pk_bf16_f32 v235, v94, v95
	global_store_dwordx4 v1, v[232:235], s[8:9] offset:2048
	v_pk_fma_f32 v[96:97], v[32:33], v[96:97], v[64:65]
	v_cvt_pk_bf16_f32 v236, v96, v97
	v_pk_fma_f32 v[98:99], v[34:35], v[98:99], v[66:67]
	v_cvt_pk_bf16_f32 v237, v98, v99
	v_pk_fma_f32 v[100:101], v[36:37], v[100:101], v[68:69]
	v_cvt_pk_bf16_f32 v238, v100, v101
	v_pk_fma_f32 v[102:103], v[38:39], v[102:103], v[70:71]
	v_cvt_pk_bf16_f32 v239, v102, v103
	global_store_dwordx4 v1, v[236:239], s[8:9] offset:3072
	s_waitcnt vmcnt(28)
	v_cvt_f32_f16_e32 v72, v136
	v_cvt_f32_f16_sdwa v73, v136 dst_sel:DWORD dst_unused:UNUSED_PAD src0_sel:WORD_1
	v_cvt_f32_f16_e32 v74, v137
	v_cvt_f32_f16_sdwa v75, v137 dst_sel:DWORD dst_unused:UNUSED_PAD src0_sel:WORD_1
	v_cvt_f32_f16_e32 v76, v138
	v_cvt_f32_f16_sdwa v77, v138 dst_sel:DWORD dst_unused:UNUSED_PAD src0_sel:WORD_1
	v_cvt_f32_f16_e32 v78, v139
	v_cvt_f32_f16_sdwa v79, v139 dst_sel:DWORD dst_unused:UNUSED_PAD src0_sel:WORD_1
	v_cvt_f32_f16_e32 v80, v140
	v_cvt_f32_f16_sdwa v81, v140 dst_sel:DWORD dst_unused:UNUSED_PAD src0_sel:WORD_1
	v_cvt_f32_f16_e32 v82, v141
	v_cvt_f32_f16_sdwa v83, v141 dst_sel:DWORD dst_unused:UNUSED_PAD src0_sel:WORD_1
	v_cvt_f32_f16_e32 v84, v142
	v_cvt_f32_f16_sdwa v85, v142 dst_sel:DWORD dst_unused:UNUSED_PAD src0_sel:WORD_1
	v_cvt_f32_f16_e32 v86, v143
	v_cvt_f32_f16_sdwa v87, v143 dst_sel:DWORD dst_unused:UNUSED_PAD src0_sel:WORD_1
	v_cvt_f32_f16_e32 v88, v144
	v_cvt_f32_f16_sdwa v89, v144 dst_sel:DWORD dst_unused:UNUSED_PAD src0_sel:WORD_1
	v_cvt_f32_f16_e32 v90, v145
	v_cvt_f32_f16_sdwa v91, v145 dst_sel:DWORD dst_unused:UNUSED_PAD src0_sel:WORD_1
	v_cvt_f32_f16_e32 v92, v146
	v_cvt_f32_f16_sdwa v93, v146 dst_sel:DWORD dst_unused:UNUSED_PAD src0_sel:WORD_1
	v_cvt_f32_f16_e32 v94, v147
	v_cvt_f32_f16_sdwa v95, v147 dst_sel:DWORD dst_unused:UNUSED_PAD src0_sel:WORD_1
	v_cvt_f32_f16_e32 v96, v148
	v_cvt_f32_f16_sdwa v97, v148 dst_sel:DWORD dst_unused:UNUSED_PAD src0_sel:WORD_1
	v_cvt_f32_f16_e32 v98, v149
	v_cvt_f32_f16_sdwa v99, v149 dst_sel:DWORD dst_unused:UNUSED_PAD src0_sel:WORD_1
	v_cvt_f32_f16_e32 v100, v150
	v_cvt_f32_f16_sdwa v101, v150 dst_sel:DWORD dst_unused:UNUSED_PAD src0_sel:WORD_1
	v_cvt_f32_f16_e32 v102, v151
	v_cvt_f32_f16_sdwa v103, v151 dst_sel:DWORD dst_unused:UNUSED_PAD src0_sel:WORD_1
	v_pk_mul_f32 v[232:233], v[72:73], v[72:73]
	v_pk_mul_f32 v[234:235], v[74:75], v[74:75]
	v_pk_mul_f32 v[236:237], v[76:77], v[76:77]
	v_pk_mul_f32 v[238:239], v[78:79], v[78:79]
	v_pk_fma_f32 v[232:233], v[80:81], v[80:81], v[232:233]
	v_pk_fma_f32 v[234:235], v[82:83], v[82:83], v[234:235]
	v_pk_fma_f32 v[236:237], v[84:85], v[84:85], v[236:237]
	v_pk_fma_f32 v[238:239], v[86:87], v[86:87], v[238:239]
	v_pk_fma_f32 v[232:233], v[88:89], v[88:89], v[232:233]
	v_pk_fma_f32 v[234:235], v[90:91], v[90:91], v[234:235]
	v_pk_fma_f32 v[236:237], v[92:93], v[92:93], v[236:237]
	v_pk_fma_f32 v[238:239], v[94:95], v[94:95], v[238:239]
	v_pk_fma_f32 v[232:233], v[96:97], v[96:97], v[232:233]
	v_pk_fma_f32 v[234:235], v[98:99], v[98:99], v[234:235]
	v_pk_fma_f32 v[236:237], v[100:101], v[100:101], v[236:237]
	v_pk_fma_f32 v[238:239], v[102:103], v[102:103], v[238:239]
	v_pk_add_f32 v[232:233], v[232:233], v[234:235]
	v_pk_add_f32 v[236:237], v[236:237], v[238:239]
	v_pk_add_f32 v[232:233], v[232:233], v[236:237]
	v_add_f32_e32 v240, v232, v233
	s_nop 1
	v_add_f32_dpp v240, v240, v240 quad_perm:[1,0,3,2] row_mask:0xf bank_mask:0xf
	s_nop 1
	v_add_f32_dpp v240, v240, v240 quad_perm:[2,3,0,1] row_mask:0xf bank_mask:0xf
	s_nop 1
	v_add_f32_dpp v240, v240, v240 row_half_mirror row_mask:0xf bank_mask:0xf
	s_nop 1
	v_add_f32_dpp v240, v240, v240 row_mirror row_mask:0xf bank_mask:0xf
	s_nop 1
	v_readlane_b32 s0, v240, 0
	v_readlane_b32 s1, v240, 16
	v_readlane_b32 s4, v240, 32
	v_readlane_b32 s5, v240, 48
	v_mov_b32_e32 v249, 0x358637bd
	s_nop 1
	v_mov_b32_e32 v240, s0
	v_add_f32_e32 v240, s1, v240
	v_add_f32_e32 v240, s4, v240
	v_add_f32_e32 v240, s5, v240
	v_fmamk_f32 v240, v240, 0x3a000000, v249
	s_mov_b32 s0, 0xf800000
	v_mul_f32_e32 v241, 0x4f800000, v240
	v_cmp_gt_f32_e32 vcc, s0, v240
	s_nop 1
	v_cndmask_b32_e32 v240, v240, v241, vcc
	v_sqrt_f32_e32 v241, v240
	s_nop 0
	v_add_u32_e32 v242, -1, v241
	v_fma_f32 v243, -v242, v241, v240
	v_cmp_ge_f32_e64 s[0:1], 0, v243
	v_add_u32_e32 v243, 1, v241
	s_nop 0
	v_cndmask_b32_e64 v242, v241, v242, s[0:1]
	v_fma_f32 v241, -v243, v241, v240
	v_cmp_lt_f32_e64 s[0:1], 0, v241
	s_nop 1
	v_cndmask_b32_e64 v241, v242, v243, s[0:1]
	v_mul_f32_e32 v242, 0x37800000, v241
	v_cndmask_b32_e32 v241, v241, v242, vcc
	v_cmp_class_f32_e32 vcc, v240, v248
	s_nop 1
	v_cndmask_b32_e32 v240, v241, v240, vcc
	v_div_scale_f32 v241, s[0:1], v240, v240, 1.0
	v_rcp_f32_e32 v242, v241
	s_nop 0
	v_fma_f32 v243, -v241, v242, 1.0
	v_fmac_f32_e32 v242, v243, v242
	v_div_scale_f32 v243, vcc, 1.0, v240, 1.0
	v_mul_f32_e32 v244, v243, v242
	v_fma_f32 v247, -v241, v244, v243
	v_fmac_f32_e32 v244, v247, v242
	v_fma_f32 v241, -v241, v244, v243
	s_nop 1
	v_div_fmas_f32 v241, v241, v242, v244
	v_div_fixup_f32 v246, v241, v240, 1.0
	v_pk_mul_f32 v[72:73], v[72:73], v[246:247] op_sel_hi:[1,0]
	v_pk_mul_f32 v[74:75], v[74:75], v[246:247] op_sel_hi:[1,0]
	v_pk_mul_f32 v[76:77], v[76:77], v[246:247] op_sel_hi:[1,0]
	v_pk_mul_f32 v[78:79], v[78:79], v[246:247] op_sel_hi:[1,0]
	v_pk_mul_f32 v[80:81], v[80:81], v[246:247] op_sel_hi:[1,0]
	v_pk_mul_f32 v[82:83], v[82:83], v[246:247] op_sel_hi:[1,0]
	v_pk_mul_f32 v[84:85], v[84:85], v[246:247] op_sel_hi:[1,0]
	v_pk_mul_f32 v[86:87], v[86:87], v[246:247] op_sel_hi:[1,0]
	v_pk_mul_f32 v[88:89], v[88:89], v[246:247] op_sel_hi:[1,0]
	v_pk_mul_f32 v[90:91], v[90:91], v[246:247] op_sel_hi:[1,0]
	v_pk_mul_f32 v[92:93], v[92:93], v[246:247] op_sel_hi:[1,0]
	v_pk_mul_f32 v[94:95], v[94:95], v[246:247] op_sel_hi:[1,0]
	v_pk_mul_f32 v[96:97], v[96:97], v[246:247] op_sel_hi:[1,0]
	v_pk_mul_f32 v[98:99], v[98:99], v[246:247] op_sel_hi:[1,0]
	v_pk_mul_f32 v[100:101], v[100:101], v[246:247] op_sel_hi:[1,0]
	v_pk_mul_f32 v[102:103], v[102:103], v[246:247] op_sel_hi:[1,0]
	s_add_u32 s8, s10, 0x40000
	s_addc_u32 s9, s11, 0
	v_pk_fma_f32 v[72:73], v[8:9], v[72:73], v[40:41]
	v_cvt_pk_bf16_f32 v232, v72, v73
	v_pk_fma_f32 v[74:75], v[10:11], v[74:75], v[42:43]
	v_cvt_pk_bf16_f32 v233, v74, v75
	v_pk_fma_f32 v[76:77], v[12:13], v[76:77], v[44:45]
	v_cvt_pk_bf16_f32 v234, v76, v77
	v_pk_fma_f32 v[78:79], v[14:15], v[78:79], v[46:47]
	v_cvt_pk_bf16_f32 v235, v78, v79
	global_store_dwordx4 v1, v[232:235], s[8:9] offset:0
	v_pk_fma_f32 v[80:81], v[16:17], v[80:81], v[48:49]
	v_cvt_pk_bf16_f32 v236, v80, v81
	v_pk_fma_f32 v[82:83], v[18:19], v[82:83], v[50:51]
	v_cvt_pk_bf16_f32 v237, v82, v83
	v_pk_fma_f32 v[84:85], v[20:21], v[84:85], v[52:53]
	v_cvt_pk_bf16_f32 v238, v84, v85
	v_pk_fma_f32 v[86:87], v[22:23], v[86:87], v[54:55]
	v_cvt_pk_bf16_f32 v239, v86, v87
	global_store_dwordx4 v1, v[236:239], s[8:9] offset:1024
	v_pk_fma_f32 v[88:89], v[24:25], v[88:89], v[56:57]
	v_cvt_pk_bf16_f32 v232, v88, v89
	v_pk_fma_f32 v[90:91], v[26:27], v[90:91], v[58:59]
	v_cvt_pk_bf16_f32 v233, v90, v91
	v_pk_fma_f32 v[92:93], v[28:29], v[92:93], v[60:61]
	v_cvt_pk_bf16_f32 v234, v92, v93
	v_pk_fma_f32 v[94:95], v[30:31], v[94:95], v[62:63]
	v_cvt_pk_bf16_f32 v235, v94, v95
	global_store_dwordx4 v1, v[232:235], s[8:9] offset:2048
	v_pk_fma_f32 v[96:97], v[32:33], v[96:97], v[64:65]
	v_cvt_pk_bf16_f32 v236, v96, v97
	v_pk_fma_f32 v[98:99], v[34:35], v[98:99], v[66:67]
	v_cvt_pk_bf16_f32 v237, v98, v99
	v_pk_fma_f32 v[100:101], v[36:37], v[100:101], v[68:69]
	v_cvt_pk_bf16_f32 v238, v100, v101
	v_pk_fma_f32 v[102:103], v[38:39], v[102:103], v[70:71]
	v_cvt_pk_bf16_f32 v239, v102, v103
	global_store_dwordx4 v1, v[236:239], s[8:9] offset:3072
	s_waitcnt vmcnt(28)
	v_cvt_f32_f16_e32 v72, v152
	v_cvt_f32_f16_sdwa v73, v152 dst_sel:DWORD dst_unused:UNUSED_PAD src0_sel:WORD_1
	v_cvt_f32_f16_e32 v74, v153
	v_cvt_f32_f16_sdwa v75, v153 dst_sel:DWORD dst_unused:UNUSED_PAD src0_sel:WORD_1
	v_cvt_f32_f16_e32 v76, v154
	v_cvt_f32_f16_sdwa v77, v154 dst_sel:DWORD dst_unused:UNUSED_PAD src0_sel:WORD_1
	v_cvt_f32_f16_e32 v78, v155
	v_cvt_f32_f16_sdwa v79, v155 dst_sel:DWORD dst_unused:UNUSED_PAD src0_sel:WORD_1
	v_cvt_f32_f16_e32 v80, v156
	v_cvt_f32_f16_sdwa v81, v156 dst_sel:DWORD dst_unused:UNUSED_PAD src0_sel:WORD_1
	v_cvt_f32_f16_e32 v82, v157
	v_cvt_f32_f16_sdwa v83, v157 dst_sel:DWORD dst_unused:UNUSED_PAD src0_sel:WORD_1
	v_cvt_f32_f16_e32 v84, v158
	v_cvt_f32_f16_sdwa v85, v158 dst_sel:DWORD dst_unused:UNUSED_PAD src0_sel:WORD_1
	v_cvt_f32_f16_e32 v86, v159
	v_cvt_f32_f16_sdwa v87, v159 dst_sel:DWORD dst_unused:UNUSED_PAD src0_sel:WORD_1
	v_cvt_f32_f16_e32 v88, v160
	v_cvt_f32_f16_sdwa v89, v160 dst_sel:DWORD dst_unused:UNUSED_PAD src0_sel:WORD_1
	v_cvt_f32_f16_e32 v90, v161
	v_cvt_f32_f16_sdwa v91, v161 dst_sel:DWORD dst_unused:UNUSED_PAD src0_sel:WORD_1
	v_cvt_f32_f16_e32 v92, v162
	v_cvt_f32_f16_sdwa v93, v162 dst_sel:DWORD dst_unused:UNUSED_PAD src0_sel:WORD_1
	v_cvt_f32_f16_e32 v94, v163
	v_cvt_f32_f16_sdwa v95, v163 dst_sel:DWORD dst_unused:UNUSED_PAD src0_sel:WORD_1
	v_cvt_f32_f16_e32 v96, v164
	v_cvt_f32_f16_sdwa v97, v164 dst_sel:DWORD dst_unused:UNUSED_PAD src0_sel:WORD_1
	v_cvt_f32_f16_e32 v98, v165
	v_cvt_f32_f16_sdwa v99, v165 dst_sel:DWORD dst_unused:UNUSED_PAD src0_sel:WORD_1
	v_cvt_f32_f16_e32 v100, v166
	v_cvt_f32_f16_sdwa v101, v166 dst_sel:DWORD dst_unused:UNUSED_PAD src0_sel:WORD_1
	v_cvt_f32_f16_e32 v102, v167
	v_cvt_f32_f16_sdwa v103, v167 dst_sel:DWORD dst_unused:UNUSED_PAD src0_sel:WORD_1
	v_pk_mul_f32 v[232:233], v[72:73], v[72:73]
	v_pk_mul_f32 v[234:235], v[74:75], v[74:75]
	v_pk_mul_f32 v[236:237], v[76:77], v[76:77]
	v_pk_mul_f32 v[238:239], v[78:79], v[78:79]
	v_pk_fma_f32 v[232:233], v[80:81], v[80:81], v[232:233]
	v_pk_fma_f32 v[234:235], v[82:83], v[82:83], v[234:235]
	v_pk_fma_f32 v[236:237], v[84:85], v[84:85], v[236:237]
	v_pk_fma_f32 v[238:239], v[86:87], v[86:87], v[238:239]
	v_pk_fma_f32 v[232:233], v[88:89], v[88:89], v[232:233]
	v_pk_fma_f32 v[234:235], v[90:91], v[90:91], v[234:235]
	v_pk_fma_f32 v[236:237], v[92:93], v[92:93], v[236:237]
	v_pk_fma_f32 v[238:239], v[94:95], v[94:95], v[238:239]
	v_pk_fma_f32 v[232:233], v[96:97], v[96:97], v[232:233]
	v_pk_fma_f32 v[234:235], v[98:99], v[98:99], v[234:235]
	v_pk_fma_f32 v[236:237], v[100:101], v[100:101], v[236:237]
	v_pk_fma_f32 v[238:239], v[102:103], v[102:103], v[238:239]
	v_pk_add_f32 v[232:233], v[232:233], v[234:235]
	v_pk_add_f32 v[236:237], v[236:237], v[238:239]
	v_pk_add_f32 v[232:233], v[232:233], v[236:237]
	v_add_f32_e32 v240, v232, v233
	s_nop 1
	v_add_f32_dpp v240, v240, v240 quad_perm:[1,0,3,2] row_mask:0xf bank_mask:0xf
	s_nop 1
	v_add_f32_dpp v240, v240, v240 quad_perm:[2,3,0,1] row_mask:0xf bank_mask:0xf
	s_nop 1
	v_add_f32_dpp v240, v240, v240 row_half_mirror row_mask:0xf bank_mask:0xf
	s_nop 1
	v_add_f32_dpp v240, v240, v240 row_mirror row_mask:0xf bank_mask:0xf
	s_nop 1
	v_readlane_b32 s0, v240, 0
	v_readlane_b32 s1, v240, 16
	v_readlane_b32 s4, v240, 32
	v_readlane_b32 s5, v240, 48
	v_mov_b32_e32 v249, 0x358637bd
	s_nop 1
	v_mov_b32_e32 v240, s0
	v_add_f32_e32 v240, s1, v240
	v_add_f32_e32 v240, s4, v240
	v_add_f32_e32 v240, s5, v240
	v_fmamk_f32 v240, v240, 0x3a000000, v249
	s_mov_b32 s0, 0xf800000
	v_mul_f32_e32 v241, 0x4f800000, v240
	v_cmp_gt_f32_e32 vcc, s0, v240
	s_nop 1
	v_cndmask_b32_e32 v240, v240, v241, vcc
	v_sqrt_f32_e32 v241, v240
	s_nop 0
	v_add_u32_e32 v242, -1, v241
	v_fma_f32 v243, -v242, v241, v240
	v_cmp_ge_f32_e64 s[0:1], 0, v243
	v_add_u32_e32 v243, 1, v241
	s_nop 0
	v_cndmask_b32_e64 v242, v241, v242, s[0:1]
	v_fma_f32 v241, -v243, v241, v240
	v_cmp_lt_f32_e64 s[0:1], 0, v241
	s_nop 1
	v_cndmask_b32_e64 v241, v242, v243, s[0:1]
	v_mul_f32_e32 v242, 0x37800000, v241
	v_cndmask_b32_e32 v241, v241, v242, vcc
	v_cmp_class_f32_e32 vcc, v240, v248
	s_nop 1
	v_cndmask_b32_e32 v240, v241, v240, vcc
	v_div_scale_f32 v241, s[0:1], v240, v240, 1.0
	v_rcp_f32_e32 v242, v241
	s_nop 0
	v_fma_f32 v243, -v241, v242, 1.0
	v_fmac_f32_e32 v242, v243, v242
	v_div_scale_f32 v243, vcc, 1.0, v240, 1.0
	v_mul_f32_e32 v244, v243, v242
	v_fma_f32 v247, -v241, v244, v243
	v_fmac_f32_e32 v244, v247, v242
	v_fma_f32 v241, -v241, v244, v243
	s_nop 1
	v_div_fmas_f32 v241, v241, v242, v244
	v_div_fixup_f32 v246, v241, v240, 1.0
	v_pk_mul_f32 v[72:73], v[72:73], v[246:247] op_sel_hi:[1,0]
	v_pk_mul_f32 v[74:75], v[74:75], v[246:247] op_sel_hi:[1,0]
	v_pk_mul_f32 v[76:77], v[76:77], v[246:247] op_sel_hi:[1,0]
	v_pk_mul_f32 v[78:79], v[78:79], v[246:247] op_sel_hi:[1,0]
	v_pk_mul_f32 v[80:81], v[80:81], v[246:247] op_sel_hi:[1,0]
	v_pk_mul_f32 v[82:83], v[82:83], v[246:247] op_sel_hi:[1,0]
	v_pk_mul_f32 v[84:85], v[84:85], v[246:247] op_sel_hi:[1,0]
	v_pk_mul_f32 v[86:87], v[86:87], v[246:247] op_sel_hi:[1,0]
	v_pk_mul_f32 v[88:89], v[88:89], v[246:247] op_sel_hi:[1,0]
	v_pk_mul_f32 v[90:91], v[90:91], v[246:247] op_sel_hi:[1,0]
	v_pk_mul_f32 v[92:93], v[92:93], v[246:247] op_sel_hi:[1,0]
	v_pk_mul_f32 v[94:95], v[94:95], v[246:247] op_sel_hi:[1,0]
	v_pk_mul_f32 v[96:97], v[96:97], v[246:247] op_sel_hi:[1,0]
	v_pk_mul_f32 v[98:99], v[98:99], v[246:247] op_sel_hi:[1,0]
	v_pk_mul_f32 v[100:101], v[100:101], v[246:247] op_sel_hi:[1,0]
	v_pk_mul_f32 v[102:103], v[102:103], v[246:247] op_sel_hi:[1,0]
	s_add_u32 s8, s10, 0x60000
	s_addc_u32 s9, s11, 0
	v_pk_fma_f32 v[72:73], v[8:9], v[72:73], v[40:41]
	v_cvt_pk_bf16_f32 v232, v72, v73
	v_pk_fma_f32 v[74:75], v[10:11], v[74:75], v[42:43]
	v_cvt_pk_bf16_f32 v233, v74, v75
	v_pk_fma_f32 v[76:77], v[12:13], v[76:77], v[44:45]
	v_cvt_pk_bf16_f32 v234, v76, v77
	v_pk_fma_f32 v[78:79], v[14:15], v[78:79], v[46:47]
	v_cvt_pk_bf16_f32 v235, v78, v79
	global_store_dwordx4 v1, v[232:235], s[8:9] offset:0
	v_pk_fma_f32 v[80:81], v[16:17], v[80:81], v[48:49]
	v_cvt_pk_bf16_f32 v236, v80, v81
	v_pk_fma_f32 v[82:83], v[18:19], v[82:83], v[50:51]
	v_cvt_pk_bf16_f32 v237, v82, v83
	v_pk_fma_f32 v[84:85], v[20:21], v[84:85], v[52:53]
	v_cvt_pk_bf16_f32 v238, v84, v85
	v_pk_fma_f32 v[86:87], v[22:23], v[86:87], v[54:55]
	v_cvt_pk_bf16_f32 v239, v86, v87
	global_store_dwordx4 v1, v[236:239], s[8:9] offset:1024
	v_pk_fma_f32 v[88:89], v[24:25], v[88:89], v[56:57]
	v_cvt_pk_bf16_f32 v232, v88, v89
	v_pk_fma_f32 v[90:91], v[26:27], v[90:91], v[58:59]
	v_cvt_pk_bf16_f32 v233, v90, v91
	v_pk_fma_f32 v[92:93], v[28:29], v[92:93], v[60:61]
	v_cvt_pk_bf16_f32 v234, v92, v93
	v_pk_fma_f32 v[94:95], v[30:31], v[94:95], v[62:63]
	v_cvt_pk_bf16_f32 v235, v94, v95
	global_store_dwordx4 v1, v[232:235], s[8:9] offset:2048
	v_pk_fma_f32 v[96:97], v[32:33], v[96:97], v[64:65]
	v_cvt_pk_bf16_f32 v236, v96, v97
	v_pk_fma_f32 v[98:99], v[34:35], v[98:99], v[66:67]
	v_cvt_pk_bf16_f32 v237, v98, v99
	v_pk_fma_f32 v[100:101], v[36:37], v[100:101], v[68:69]
	v_cvt_pk_bf16_f32 v238, v100, v101
	v_pk_fma_f32 v[102:103], v[38:39], v[102:103], v[70:71]
	v_cvt_pk_bf16_f32 v239, v102, v103
	global_store_dwordx4 v1, v[236:239], s[8:9] offset:3072
	s_waitcnt vmcnt(28)
	v_cvt_f32_f16_e32 v72, v168
	v_cvt_f32_f16_sdwa v73, v168 dst_sel:DWORD dst_unused:UNUSED_PAD src0_sel:WORD_1
	v_cvt_f32_f16_e32 v74, v169
	v_cvt_f32_f16_sdwa v75, v169 dst_sel:DWORD dst_unused:UNUSED_PAD src0_sel:WORD_1
	v_cvt_f32_f16_e32 v76, v170
	v_cvt_f32_f16_sdwa v77, v170 dst_sel:DWORD dst_unused:UNUSED_PAD src0_sel:WORD_1
	v_cvt_f32_f16_e32 v78, v171
	v_cvt_f32_f16_sdwa v79, v171 dst_sel:DWORD dst_unused:UNUSED_PAD src0_sel:WORD_1
	v_cvt_f32_f16_e32 v80, v172
	v_cvt_f32_f16_sdwa v81, v172 dst_sel:DWORD dst_unused:UNUSED_PAD src0_sel:WORD_1
	v_cvt_f32_f16_e32 v82, v173
	v_cvt_f32_f16_sdwa v83, v173 dst_sel:DWORD dst_unused:UNUSED_PAD src0_sel:WORD_1
	v_cvt_f32_f16_e32 v84, v174
	v_cvt_f32_f16_sdwa v85, v174 dst_sel:DWORD dst_unused:UNUSED_PAD src0_sel:WORD_1
	v_cvt_f32_f16_e32 v86, v175
	v_cvt_f32_f16_sdwa v87, v175 dst_sel:DWORD dst_unused:UNUSED_PAD src0_sel:WORD_1
	v_cvt_f32_f16_e32 v88, v176
	v_cvt_f32_f16_sdwa v89, v176 dst_sel:DWORD dst_unused:UNUSED_PAD src0_sel:WORD_1
	v_cvt_f32_f16_e32 v90, v177
	v_cvt_f32_f16_sdwa v91, v177 dst_sel:DWORD dst_unused:UNUSED_PAD src0_sel:WORD_1
	v_cvt_f32_f16_e32 v92, v178
	v_cvt_f32_f16_sdwa v93, v178 dst_sel:DWORD dst_unused:UNUSED_PAD src0_sel:WORD_1
	v_cvt_f32_f16_e32 v94, v179
	v_cvt_f32_f16_sdwa v95, v179 dst_sel:DWORD dst_unused:UNUSED_PAD src0_sel:WORD_1
	v_cvt_f32_f16_e32 v96, v180
	v_cvt_f32_f16_sdwa v97, v180 dst_sel:DWORD dst_unused:UNUSED_PAD src0_sel:WORD_1
	v_cvt_f32_f16_e32 v98, v181
	v_cvt_f32_f16_sdwa v99, v181 dst_sel:DWORD dst_unused:UNUSED_PAD src0_sel:WORD_1
	v_cvt_f32_f16_e32 v100, v182
	v_cvt_f32_f16_sdwa v101, v182 dst_sel:DWORD dst_unused:UNUSED_PAD src0_sel:WORD_1
	v_cvt_f32_f16_e32 v102, v183
	v_cvt_f32_f16_sdwa v103, v183 dst_sel:DWORD dst_unused:UNUSED_PAD src0_sel:WORD_1
	v_pk_mul_f32 v[232:233], v[72:73], v[72:73]
	v_pk_mul_f32 v[234:235], v[74:75], v[74:75]
	v_pk_mul_f32 v[236:237], v[76:77], v[76:77]
	v_pk_mul_f32 v[238:239], v[78:79], v[78:79]
	v_pk_fma_f32 v[232:233], v[80:81], v[80:81], v[232:233]
	v_pk_fma_f32 v[234:235], v[82:83], v[82:83], v[234:235]
	v_pk_fma_f32 v[236:237], v[84:85], v[84:85], v[236:237]
	v_pk_fma_f32 v[238:239], v[86:87], v[86:87], v[238:239]
	v_pk_fma_f32 v[232:233], v[88:89], v[88:89], v[232:233]
	v_pk_fma_f32 v[234:235], v[90:91], v[90:91], v[234:235]
	v_pk_fma_f32 v[236:237], v[92:93], v[92:93], v[236:237]
	v_pk_fma_f32 v[238:239], v[94:95], v[94:95], v[238:239]
	v_pk_fma_f32 v[232:233], v[96:97], v[96:97], v[232:233]
	v_pk_fma_f32 v[234:235], v[98:99], v[98:99], v[234:235]
	v_pk_fma_f32 v[236:237], v[100:101], v[100:101], v[236:237]
	v_pk_fma_f32 v[238:239], v[102:103], v[102:103], v[238:239]
	v_pk_add_f32 v[232:233], v[232:233], v[234:235]
	v_pk_add_f32 v[236:237], v[236:237], v[238:239]
	v_pk_add_f32 v[232:233], v[232:233], v[236:237]
	v_add_f32_e32 v240, v232, v233
	s_nop 1
	v_add_f32_dpp v240, v240, v240 quad_perm:[1,0,3,2] row_mask:0xf bank_mask:0xf
	s_nop 1
	v_add_f32_dpp v240, v240, v240 quad_perm:[2,3,0,1] row_mask:0xf bank_mask:0xf
	s_nop 1
	v_add_f32_dpp v240, v240, v240 row_half_mirror row_mask:0xf bank_mask:0xf
	s_nop 1
	v_add_f32_dpp v240, v240, v240 row_mirror row_mask:0xf bank_mask:0xf
	s_nop 1
	v_readlane_b32 s0, v240, 0
	v_readlane_b32 s1, v240, 16
	v_readlane_b32 s4, v240, 32
	v_readlane_b32 s5, v240, 48
	v_mov_b32_e32 v249, 0x358637bd
	s_nop 1
	v_mov_b32_e32 v240, s0
	v_add_f32_e32 v240, s1, v240
	v_add_f32_e32 v240, s4, v240
	v_add_f32_e32 v240, s5, v240
	v_fmamk_f32 v240, v240, 0x3a000000, v249
	s_mov_b32 s0, 0xf800000
	v_mul_f32_e32 v241, 0x4f800000, v240
	v_cmp_gt_f32_e32 vcc, s0, v240
	s_nop 1
	v_cndmask_b32_e32 v240, v240, v241, vcc
	v_sqrt_f32_e32 v241, v240
	s_nop 0
	v_add_u32_e32 v242, -1, v241
	v_fma_f32 v243, -v242, v241, v240
	v_cmp_ge_f32_e64 s[0:1], 0, v243
	v_add_u32_e32 v243, 1, v241
	s_nop 0
	v_cndmask_b32_e64 v242, v241, v242, s[0:1]
	v_fma_f32 v241, -v243, v241, v240
	v_cmp_lt_f32_e64 s[0:1], 0, v241
	s_nop 1
	v_cndmask_b32_e64 v241, v242, v243, s[0:1]
	v_mul_f32_e32 v242, 0x37800000, v241
	v_cndmask_b32_e32 v241, v241, v242, vcc
	v_cmp_class_f32_e32 vcc, v240, v248
	s_nop 1
	v_cndmask_b32_e32 v240, v241, v240, vcc
	v_div_scale_f32 v241, s[0:1], v240, v240, 1.0
	v_rcp_f32_e32 v242, v241
	s_nop 0
	v_fma_f32 v243, -v241, v242, 1.0
	v_fmac_f32_e32 v242, v243, v242
	v_div_scale_f32 v243, vcc, 1.0, v240, 1.0
	v_mul_f32_e32 v244, v243, v242
	v_fma_f32 v247, -v241, v244, v243
	v_fmac_f32_e32 v244, v247, v242
	v_fma_f32 v241, -v241, v244, v243
	s_nop 1
	v_div_fmas_f32 v241, v241, v242, v244
	v_div_fixup_f32 v246, v241, v240, 1.0
	v_pk_mul_f32 v[72:73], v[72:73], v[246:247] op_sel_hi:[1,0]
	v_pk_mul_f32 v[74:75], v[74:75], v[246:247] op_sel_hi:[1,0]
	v_pk_mul_f32 v[76:77], v[76:77], v[246:247] op_sel_hi:[1,0]
	v_pk_mul_f32 v[78:79], v[78:79], v[246:247] op_sel_hi:[1,0]
	v_pk_mul_f32 v[80:81], v[80:81], v[246:247] op_sel_hi:[1,0]
	v_pk_mul_f32 v[82:83], v[82:83], v[246:247] op_sel_hi:[1,0]
	v_pk_mul_f32 v[84:85], v[84:85], v[246:247] op_sel_hi:[1,0]
	v_pk_mul_f32 v[86:87], v[86:87], v[246:247] op_sel_hi:[1,0]
	v_pk_mul_f32 v[88:89], v[88:89], v[246:247] op_sel_hi:[1,0]
	v_pk_mul_f32 v[90:91], v[90:91], v[246:247] op_sel_hi:[1,0]
	v_pk_mul_f32 v[92:93], v[92:93], v[246:247] op_sel_hi:[1,0]
	v_pk_mul_f32 v[94:95], v[94:95], v[246:247] op_sel_hi:[1,0]
	v_pk_mul_f32 v[96:97], v[96:97], v[246:247] op_sel_hi:[1,0]
	v_pk_mul_f32 v[98:99], v[98:99], v[246:247] op_sel_hi:[1,0]
	v_pk_mul_f32 v[100:101], v[100:101], v[246:247] op_sel_hi:[1,0]
	v_pk_mul_f32 v[102:103], v[102:103], v[246:247] op_sel_hi:[1,0]
	s_add_u32 s8, s10, 0x80000
	s_addc_u32 s9, s11, 0
	v_pk_fma_f32 v[72:73], v[8:9], v[72:73], v[40:41]
	v_cvt_pk_bf16_f32 v232, v72, v73
	v_pk_fma_f32 v[74:75], v[10:11], v[74:75], v[42:43]
	v_cvt_pk_bf16_f32 v233, v74, v75
	v_pk_fma_f32 v[76:77], v[12:13], v[76:77], v[44:45]
	v_cvt_pk_bf16_f32 v234, v76, v77
	v_pk_fma_f32 v[78:79], v[14:15], v[78:79], v[46:47]
	v_cvt_pk_bf16_f32 v235, v78, v79
	global_store_dwordx4 v1, v[232:235], s[8:9] offset:0
	v_pk_fma_f32 v[80:81], v[16:17], v[80:81], v[48:49]
	v_cvt_pk_bf16_f32 v236, v80, v81
	v_pk_fma_f32 v[82:83], v[18:19], v[82:83], v[50:51]
	v_cvt_pk_bf16_f32 v237, v82, v83
	v_pk_fma_f32 v[84:85], v[20:21], v[84:85], v[52:53]
	v_cvt_pk_bf16_f32 v238, v84, v85
	v_pk_fma_f32 v[86:87], v[22:23], v[86:87], v[54:55]
	v_cvt_pk_bf16_f32 v239, v86, v87
	global_store_dwordx4 v1, v[236:239], s[8:9] offset:1024
	v_pk_fma_f32 v[88:89], v[24:25], v[88:89], v[56:57]
	v_cvt_pk_bf16_f32 v232, v88, v89
	v_pk_fma_f32 v[90:91], v[26:27], v[90:91], v[58:59]
	v_cvt_pk_bf16_f32 v233, v90, v91
	v_pk_fma_f32 v[92:93], v[28:29], v[92:93], v[60:61]
	v_cvt_pk_bf16_f32 v234, v92, v93
	v_pk_fma_f32 v[94:95], v[30:31], v[94:95], v[62:63]
	v_cvt_pk_bf16_f32 v235, v94, v95
	global_store_dwordx4 v1, v[232:235], s[8:9] offset:2048
	v_pk_fma_f32 v[96:97], v[32:33], v[96:97], v[64:65]
	v_cvt_pk_bf16_f32 v236, v96, v97
	v_pk_fma_f32 v[98:99], v[34:35], v[98:99], v[66:67]
	v_cvt_pk_bf16_f32 v237, v98, v99
	v_pk_fma_f32 v[100:101], v[36:37], v[100:101], v[68:69]
	v_cvt_pk_bf16_f32 v238, v100, v101
	v_pk_fma_f32 v[102:103], v[38:39], v[102:103], v[70:71]
	v_cvt_pk_bf16_f32 v239, v102, v103
	global_store_dwordx4 v1, v[236:239], s[8:9] offset:3072
	s_waitcnt vmcnt(28)
	v_cvt_f32_f16_e32 v72, v184
	v_cvt_f32_f16_sdwa v73, v184 dst_sel:DWORD dst_unused:UNUSED_PAD src0_sel:WORD_1
	v_cvt_f32_f16_e32 v74, v185
	v_cvt_f32_f16_sdwa v75, v185 dst_sel:DWORD dst_unused:UNUSED_PAD src0_sel:WORD_1
	v_cvt_f32_f16_e32 v76, v186
	v_cvt_f32_f16_sdwa v77, v186 dst_sel:DWORD dst_unused:UNUSED_PAD src0_sel:WORD_1
	v_cvt_f32_f16_e32 v78, v187
	v_cvt_f32_f16_sdwa v79, v187 dst_sel:DWORD dst_unused:UNUSED_PAD src0_sel:WORD_1
	v_cvt_f32_f16_e32 v80, v188
	v_cvt_f32_f16_sdwa v81, v188 dst_sel:DWORD dst_unused:UNUSED_PAD src0_sel:WORD_1
	v_cvt_f32_f16_e32 v82, v189
	v_cvt_f32_f16_sdwa v83, v189 dst_sel:DWORD dst_unused:UNUSED_PAD src0_sel:WORD_1
	v_cvt_f32_f16_e32 v84, v190
	v_cvt_f32_f16_sdwa v85, v190 dst_sel:DWORD dst_unused:UNUSED_PAD src0_sel:WORD_1
	v_cvt_f32_f16_e32 v86, v191
	v_cvt_f32_f16_sdwa v87, v191 dst_sel:DWORD dst_unused:UNUSED_PAD src0_sel:WORD_1
	v_cvt_f32_f16_e32 v88, v192
	v_cvt_f32_f16_sdwa v89, v192 dst_sel:DWORD dst_unused:UNUSED_PAD src0_sel:WORD_1
	v_cvt_f32_f16_e32 v90, v193
	v_cvt_f32_f16_sdwa v91, v193 dst_sel:DWORD dst_unused:UNUSED_PAD src0_sel:WORD_1
	v_cvt_f32_f16_e32 v92, v194
	v_cvt_f32_f16_sdwa v93, v194 dst_sel:DWORD dst_unused:UNUSED_PAD src0_sel:WORD_1
	v_cvt_f32_f16_e32 v94, v195
	v_cvt_f32_f16_sdwa v95, v195 dst_sel:DWORD dst_unused:UNUSED_PAD src0_sel:WORD_1
	v_cvt_f32_f16_e32 v96, v196
	v_cvt_f32_f16_sdwa v97, v196 dst_sel:DWORD dst_unused:UNUSED_PAD src0_sel:WORD_1
	v_cvt_f32_f16_e32 v98, v197
	v_cvt_f32_f16_sdwa v99, v197 dst_sel:DWORD dst_unused:UNUSED_PAD src0_sel:WORD_1
	v_cvt_f32_f16_e32 v100, v198
	v_cvt_f32_f16_sdwa v101, v198 dst_sel:DWORD dst_unused:UNUSED_PAD src0_sel:WORD_1
	v_cvt_f32_f16_e32 v102, v199
	v_cvt_f32_f16_sdwa v103, v199 dst_sel:DWORD dst_unused:UNUSED_PAD src0_sel:WORD_1
	v_pk_mul_f32 v[232:233], v[72:73], v[72:73]
	v_pk_mul_f32 v[234:235], v[74:75], v[74:75]
	v_pk_mul_f32 v[236:237], v[76:77], v[76:77]
	v_pk_mul_f32 v[238:239], v[78:79], v[78:79]
	v_pk_fma_f32 v[232:233], v[80:81], v[80:81], v[232:233]
	v_pk_fma_f32 v[234:235], v[82:83], v[82:83], v[234:235]
	v_pk_fma_f32 v[236:237], v[84:85], v[84:85], v[236:237]
	v_pk_fma_f32 v[238:239], v[86:87], v[86:87], v[238:239]
	v_pk_fma_f32 v[232:233], v[88:89], v[88:89], v[232:233]
	v_pk_fma_f32 v[234:235], v[90:91], v[90:91], v[234:235]
	v_pk_fma_f32 v[236:237], v[92:93], v[92:93], v[236:237]
	v_pk_fma_f32 v[238:239], v[94:95], v[94:95], v[238:239]
	v_pk_fma_f32 v[232:233], v[96:97], v[96:97], v[232:233]
	v_pk_fma_f32 v[234:235], v[98:99], v[98:99], v[234:235]
	v_pk_fma_f32 v[236:237], v[100:101], v[100:101], v[236:237]
	v_pk_fma_f32 v[238:239], v[102:103], v[102:103], v[238:239]
	v_pk_add_f32 v[232:233], v[232:233], v[234:235]
	v_pk_add_f32 v[236:237], v[236:237], v[238:239]
	v_pk_add_f32 v[232:233], v[232:233], v[236:237]
	v_add_f32_e32 v240, v232, v233
	s_nop 1
	v_add_f32_dpp v240, v240, v240 quad_perm:[1,0,3,2] row_mask:0xf bank_mask:0xf
	s_nop 1
	v_add_f32_dpp v240, v240, v240 quad_perm:[2,3,0,1] row_mask:0xf bank_mask:0xf
	s_nop 1
	v_add_f32_dpp v240, v240, v240 row_half_mirror row_mask:0xf bank_mask:0xf
	s_nop 1
	v_add_f32_dpp v240, v240, v240 row_mirror row_mask:0xf bank_mask:0xf
	s_nop 1
	v_readlane_b32 s0, v240, 0
	v_readlane_b32 s1, v240, 16
	v_readlane_b32 s4, v240, 32
	v_readlane_b32 s5, v240, 48
	v_mov_b32_e32 v249, 0x358637bd
	s_nop 1
	v_mov_b32_e32 v240, s0
	v_add_f32_e32 v240, s1, v240
	v_add_f32_e32 v240, s4, v240
	v_add_f32_e32 v240, s5, v240
	v_fmamk_f32 v240, v240, 0x3a000000, v249
	s_mov_b32 s0, 0xf800000
	v_mul_f32_e32 v241, 0x4f800000, v240
	v_cmp_gt_f32_e32 vcc, s0, v240
	s_nop 1
	v_cndmask_b32_e32 v240, v240, v241, vcc
	v_sqrt_f32_e32 v241, v240
	s_nop 0
	v_add_u32_e32 v242, -1, v241
	v_fma_f32 v243, -v242, v241, v240
	v_cmp_ge_f32_e64 s[0:1], 0, v243
	v_add_u32_e32 v243, 1, v241
	s_nop 0
	v_cndmask_b32_e64 v242, v241, v242, s[0:1]
	v_fma_f32 v241, -v243, v241, v240
	v_cmp_lt_f32_e64 s[0:1], 0, v241
	s_nop 1
	v_cndmask_b32_e64 v241, v242, v243, s[0:1]
	v_mul_f32_e32 v242, 0x37800000, v241
	v_cndmask_b32_e32 v241, v241, v242, vcc
	v_cmp_class_f32_e32 vcc, v240, v248
	s_nop 1
	v_cndmask_b32_e32 v240, v241, v240, vcc
	v_div_scale_f32 v241, s[0:1], v240, v240, 1.0
	v_rcp_f32_e32 v242, v241
	s_nop 0
	v_fma_f32 v243, -v241, v242, 1.0
	v_fmac_f32_e32 v242, v243, v242
	v_div_scale_f32 v243, vcc, 1.0, v240, 1.0
	v_mul_f32_e32 v244, v243, v242
	v_fma_f32 v247, -v241, v244, v243
	v_fmac_f32_e32 v244, v247, v242
	v_fma_f32 v241, -v241, v244, v243
	s_nop 1
	v_div_fmas_f32 v241, v241, v242, v244
	v_div_fixup_f32 v246, v241, v240, 1.0
	v_pk_mul_f32 v[72:73], v[72:73], v[246:247] op_sel_hi:[1,0]
	v_pk_mul_f32 v[74:75], v[74:75], v[246:247] op_sel_hi:[1,0]
	v_pk_mul_f32 v[76:77], v[76:77], v[246:247] op_sel_hi:[1,0]
	v_pk_mul_f32 v[78:79], v[78:79], v[246:247] op_sel_hi:[1,0]
	v_pk_mul_f32 v[80:81], v[80:81], v[246:247] op_sel_hi:[1,0]
	v_pk_mul_f32 v[82:83], v[82:83], v[246:247] op_sel_hi:[1,0]
	v_pk_mul_f32 v[84:85], v[84:85], v[246:247] op_sel_hi:[1,0]
	v_pk_mul_f32 v[86:87], v[86:87], v[246:247] op_sel_hi:[1,0]
	v_pk_mul_f32 v[88:89], v[88:89], v[246:247] op_sel_hi:[1,0]
	v_pk_mul_f32 v[90:91], v[90:91], v[246:247] op_sel_hi:[1,0]
	v_pk_mul_f32 v[92:93], v[92:93], v[246:247] op_sel_hi:[1,0]
	v_pk_mul_f32 v[94:95], v[94:95], v[246:247] op_sel_hi:[1,0]
	v_pk_mul_f32 v[96:97], v[96:97], v[246:247] op_sel_hi:[1,0]
	v_pk_mul_f32 v[98:99], v[98:99], v[246:247] op_sel_hi:[1,0]
	v_pk_mul_f32 v[100:101], v[100:101], v[246:247] op_sel_hi:[1,0]
	v_pk_mul_f32 v[102:103], v[102:103], v[246:247] op_sel_hi:[1,0]
	s_add_u32 s8, s10, 0xa0000
	s_addc_u32 s9, s11, 0
	v_pk_fma_f32 v[72:73], v[8:9], v[72:73], v[40:41]
	v_cvt_pk_bf16_f32 v232, v72, v73
	v_pk_fma_f32 v[74:75], v[10:11], v[74:75], v[42:43]
	v_cvt_pk_bf16_f32 v233, v74, v75
	v_pk_fma_f32 v[76:77], v[12:13], v[76:77], v[44:45]
	v_cvt_pk_bf16_f32 v234, v76, v77
	v_pk_fma_f32 v[78:79], v[14:15], v[78:79], v[46:47]
	v_cvt_pk_bf16_f32 v235, v78, v79
	global_store_dwordx4 v1, v[232:235], s[8:9] offset:0
	v_pk_fma_f32 v[80:81], v[16:17], v[80:81], v[48:49]
	v_cvt_pk_bf16_f32 v236, v80, v81
	v_pk_fma_f32 v[82:83], v[18:19], v[82:83], v[50:51]
	v_cvt_pk_bf16_f32 v237, v82, v83
	v_pk_fma_f32 v[84:85], v[20:21], v[84:85], v[52:53]
	v_cvt_pk_bf16_f32 v238, v84, v85
	v_pk_fma_f32 v[86:87], v[22:23], v[86:87], v[54:55]
	v_cvt_pk_bf16_f32 v239, v86, v87
	global_store_dwordx4 v1, v[236:239], s[8:9] offset:1024
	v_pk_fma_f32 v[88:89], v[24:25], v[88:89], v[56:57]
	v_cvt_pk_bf16_f32 v232, v88, v89
	v_pk_fma_f32 v[90:91], v[26:27], v[90:91], v[58:59]
	v_cvt_pk_bf16_f32 v233, v90, v91
	v_pk_fma_f32 v[92:93], v[28:29], v[92:93], v[60:61]
	v_cvt_pk_bf16_f32 v234, v92, v93
	v_pk_fma_f32 v[94:95], v[30:31], v[94:95], v[62:63]
	v_cvt_pk_bf16_f32 v235, v94, v95
	global_store_dwordx4 v1, v[232:235], s[8:9] offset:2048
	v_pk_fma_f32 v[96:97], v[32:33], v[96:97], v[64:65]
	v_cvt_pk_bf16_f32 v236, v96, v97
	v_pk_fma_f32 v[98:99], v[34:35], v[98:99], v[66:67]
	v_cvt_pk_bf16_f32 v237, v98, v99
	v_pk_fma_f32 v[100:101], v[36:37], v[100:101], v[68:69]
	v_cvt_pk_bf16_f32 v238, v100, v101
	v_pk_fma_f32 v[102:103], v[38:39], v[102:103], v[70:71]
	v_cvt_pk_bf16_f32 v239, v102, v103
	global_store_dwordx4 v1, v[236:239], s[8:9] offset:3072
	s_waitcnt vmcnt(28)
	v_cvt_f32_f16_e32 v72, v200
	v_cvt_f32_f16_sdwa v73, v200 dst_sel:DWORD dst_unused:UNUSED_PAD src0_sel:WORD_1
	v_cvt_f32_f16_e32 v74, v201
	v_cvt_f32_f16_sdwa v75, v201 dst_sel:DWORD dst_unused:UNUSED_PAD src0_sel:WORD_1
	v_cvt_f32_f16_e32 v76, v202
	v_cvt_f32_f16_sdwa v77, v202 dst_sel:DWORD dst_unused:UNUSED_PAD src0_sel:WORD_1
	v_cvt_f32_f16_e32 v78, v203
	v_cvt_f32_f16_sdwa v79, v203 dst_sel:DWORD dst_unused:UNUSED_PAD src0_sel:WORD_1
	v_cvt_f32_f16_e32 v80, v204
	v_cvt_f32_f16_sdwa v81, v204 dst_sel:DWORD dst_unused:UNUSED_PAD src0_sel:WORD_1
	v_cvt_f32_f16_e32 v82, v205
	v_cvt_f32_f16_sdwa v83, v205 dst_sel:DWORD dst_unused:UNUSED_PAD src0_sel:WORD_1
	v_cvt_f32_f16_e32 v84, v206
	v_cvt_f32_f16_sdwa v85, v206 dst_sel:DWORD dst_unused:UNUSED_PAD src0_sel:WORD_1
	v_cvt_f32_f16_e32 v86, v207
	v_cvt_f32_f16_sdwa v87, v207 dst_sel:DWORD dst_unused:UNUSED_PAD src0_sel:WORD_1
	v_cvt_f32_f16_e32 v88, v208
	v_cvt_f32_f16_sdwa v89, v208 dst_sel:DWORD dst_unused:UNUSED_PAD src0_sel:WORD_1
	v_cvt_f32_f16_e32 v90, v209
	v_cvt_f32_f16_sdwa v91, v209 dst_sel:DWORD dst_unused:UNUSED_PAD src0_sel:WORD_1
	v_cvt_f32_f16_e32 v92, v210
	v_cvt_f32_f16_sdwa v93, v210 dst_sel:DWORD dst_unused:UNUSED_PAD src0_sel:WORD_1
	v_cvt_f32_f16_e32 v94, v211
	v_cvt_f32_f16_sdwa v95, v211 dst_sel:DWORD dst_unused:UNUSED_PAD src0_sel:WORD_1
	v_cvt_f32_f16_e32 v96, v212
	v_cvt_f32_f16_sdwa v97, v212 dst_sel:DWORD dst_unused:UNUSED_PAD src0_sel:WORD_1
	v_cvt_f32_f16_e32 v98, v213
	v_cvt_f32_f16_sdwa v99, v213 dst_sel:DWORD dst_unused:UNUSED_PAD src0_sel:WORD_1
	v_cvt_f32_f16_e32 v100, v214
	v_cvt_f32_f16_sdwa v101, v214 dst_sel:DWORD dst_unused:UNUSED_PAD src0_sel:WORD_1
	v_cvt_f32_f16_e32 v102, v215
	v_cvt_f32_f16_sdwa v103, v215 dst_sel:DWORD dst_unused:UNUSED_PAD src0_sel:WORD_1
	v_pk_mul_f32 v[232:233], v[72:73], v[72:73]
	v_pk_mul_f32 v[234:235], v[74:75], v[74:75]
	v_pk_mul_f32 v[236:237], v[76:77], v[76:77]
	v_pk_mul_f32 v[238:239], v[78:79], v[78:79]
	v_pk_fma_f32 v[232:233], v[80:81], v[80:81], v[232:233]
	v_pk_fma_f32 v[234:235], v[82:83], v[82:83], v[234:235]
	v_pk_fma_f32 v[236:237], v[84:85], v[84:85], v[236:237]
	v_pk_fma_f32 v[238:239], v[86:87], v[86:87], v[238:239]
	v_pk_fma_f32 v[232:233], v[88:89], v[88:89], v[232:233]
	v_pk_fma_f32 v[234:235], v[90:91], v[90:91], v[234:235]
	v_pk_fma_f32 v[236:237], v[92:93], v[92:93], v[236:237]
	v_pk_fma_f32 v[238:239], v[94:95], v[94:95], v[238:239]
	v_pk_fma_f32 v[232:233], v[96:97], v[96:97], v[232:233]
	v_pk_fma_f32 v[234:235], v[98:99], v[98:99], v[234:235]
	v_pk_fma_f32 v[236:237], v[100:101], v[100:101], v[236:237]
	v_pk_fma_f32 v[238:239], v[102:103], v[102:103], v[238:239]
	v_pk_add_f32 v[232:233], v[232:233], v[234:235]
	v_pk_add_f32 v[236:237], v[236:237], v[238:239]
	v_pk_add_f32 v[232:233], v[232:233], v[236:237]
	v_add_f32_e32 v240, v232, v233
	s_nop 1
	v_add_f32_dpp v240, v240, v240 quad_perm:[1,0,3,2] row_mask:0xf bank_mask:0xf
	s_nop 1
	v_add_f32_dpp v240, v240, v240 quad_perm:[2,3,0,1] row_mask:0xf bank_mask:0xf
	s_nop 1
	v_add_f32_dpp v240, v240, v240 row_half_mirror row_mask:0xf bank_mask:0xf
	s_nop 1
	v_add_f32_dpp v240, v240, v240 row_mirror row_mask:0xf bank_mask:0xf
	s_nop 1
	v_readlane_b32 s0, v240, 0
	v_readlane_b32 s1, v240, 16
	v_readlane_b32 s4, v240, 32
	v_readlane_b32 s5, v240, 48
	v_mov_b32_e32 v249, 0x358637bd
	s_nop 1
	v_mov_b32_e32 v240, s0
	v_add_f32_e32 v240, s1, v240
	v_add_f32_e32 v240, s4, v240
	v_add_f32_e32 v240, s5, v240
	v_fmamk_f32 v240, v240, 0x3a000000, v249
	s_mov_b32 s0, 0xf800000
	v_mul_f32_e32 v241, 0x4f800000, v240
	v_cmp_gt_f32_e32 vcc, s0, v240
	s_nop 1
	v_cndmask_b32_e32 v240, v240, v241, vcc
	v_sqrt_f32_e32 v241, v240
	s_nop 0
	v_add_u32_e32 v242, -1, v241
	v_fma_f32 v243, -v242, v241, v240
	v_cmp_ge_f32_e64 s[0:1], 0, v243
	v_add_u32_e32 v243, 1, v241
	s_nop 0
	v_cndmask_b32_e64 v242, v241, v242, s[0:1]
	v_fma_f32 v241, -v243, v241, v240
	v_cmp_lt_f32_e64 s[0:1], 0, v241
	s_nop 1
	v_cndmask_b32_e64 v241, v242, v243, s[0:1]
	v_mul_f32_e32 v242, 0x37800000, v241
	v_cndmask_b32_e32 v241, v241, v242, vcc
	v_cmp_class_f32_e32 vcc, v240, v248
	s_nop 1
	v_cndmask_b32_e32 v240, v241, v240, vcc
	v_div_scale_f32 v241, s[0:1], v240, v240, 1.0
	v_rcp_f32_e32 v242, v241
	s_nop 0
	v_fma_f32 v243, -v241, v242, 1.0
	v_fmac_f32_e32 v242, v243, v242
	v_div_scale_f32 v243, vcc, 1.0, v240, 1.0
	v_mul_f32_e32 v244, v243, v242
	v_fma_f32 v247, -v241, v244, v243
	v_fmac_f32_e32 v244, v247, v242
	v_fma_f32 v241, -v241, v244, v243
	s_nop 1
	v_div_fmas_f32 v241, v241, v242, v244
	v_div_fixup_f32 v246, v241, v240, 1.0
	v_pk_mul_f32 v[72:73], v[72:73], v[246:247] op_sel_hi:[1,0]
	v_pk_mul_f32 v[74:75], v[74:75], v[246:247] op_sel_hi:[1,0]
	v_pk_mul_f32 v[76:77], v[76:77], v[246:247] op_sel_hi:[1,0]
	v_pk_mul_f32 v[78:79], v[78:79], v[246:247] op_sel_hi:[1,0]
	v_pk_mul_f32 v[80:81], v[80:81], v[246:247] op_sel_hi:[1,0]
	v_pk_mul_f32 v[82:83], v[82:83], v[246:247] op_sel_hi:[1,0]
	v_pk_mul_f32 v[84:85], v[84:85], v[246:247] op_sel_hi:[1,0]
	v_pk_mul_f32 v[86:87], v[86:87], v[246:247] op_sel_hi:[1,0]
	v_pk_mul_f32 v[88:89], v[88:89], v[246:247] op_sel_hi:[1,0]
	v_pk_mul_f32 v[90:91], v[90:91], v[246:247] op_sel_hi:[1,0]
	v_pk_mul_f32 v[92:93], v[92:93], v[246:247] op_sel_hi:[1,0]
	v_pk_mul_f32 v[94:95], v[94:95], v[246:247] op_sel_hi:[1,0]
	v_pk_mul_f32 v[96:97], v[96:97], v[246:247] op_sel_hi:[1,0]
	v_pk_mul_f32 v[98:99], v[98:99], v[246:247] op_sel_hi:[1,0]
	v_pk_mul_f32 v[100:101], v[100:101], v[246:247] op_sel_hi:[1,0]
	v_pk_mul_f32 v[102:103], v[102:103], v[246:247] op_sel_hi:[1,0]
	s_add_u32 s8, s10, 0xc0000
	s_addc_u32 s9, s11, 0
	v_pk_fma_f32 v[72:73], v[8:9], v[72:73], v[40:41]
	v_cvt_pk_bf16_f32 v232, v72, v73
	v_pk_fma_f32 v[74:75], v[10:11], v[74:75], v[42:43]
	v_cvt_pk_bf16_f32 v233, v74, v75
	v_pk_fma_f32 v[76:77], v[12:13], v[76:77], v[44:45]
	v_cvt_pk_bf16_f32 v234, v76, v77
	v_pk_fma_f32 v[78:79], v[14:15], v[78:79], v[46:47]
	v_cvt_pk_bf16_f32 v235, v78, v79
	global_store_dwordx4 v1, v[232:235], s[8:9] offset:0
	v_pk_fma_f32 v[80:81], v[16:17], v[80:81], v[48:49]
	v_cvt_pk_bf16_f32 v236, v80, v81
	v_pk_fma_f32 v[82:83], v[18:19], v[82:83], v[50:51]
	v_cvt_pk_bf16_f32 v237, v82, v83
	v_pk_fma_f32 v[84:85], v[20:21], v[84:85], v[52:53]
	v_cvt_pk_bf16_f32 v238, v84, v85
	v_pk_fma_f32 v[86:87], v[22:23], v[86:87], v[54:55]
	v_cvt_pk_bf16_f32 v239, v86, v87
	global_store_dwordx4 v1, v[236:239], s[8:9] offset:1024
	v_pk_fma_f32 v[88:89], v[24:25], v[88:89], v[56:57]
	v_cvt_pk_bf16_f32 v232, v88, v89
	v_pk_fma_f32 v[90:91], v[26:27], v[90:91], v[58:59]
	v_cvt_pk_bf16_f32 v233, v90, v91
	v_pk_fma_f32 v[92:93], v[28:29], v[92:93], v[60:61]
	v_cvt_pk_bf16_f32 v234, v92, v93
	v_pk_fma_f32 v[94:95], v[30:31], v[94:95], v[62:63]
	v_cvt_pk_bf16_f32 v235, v94, v95
	global_store_dwordx4 v1, v[232:235], s[8:9] offset:2048
	v_pk_fma_f32 v[96:97], v[32:33], v[96:97], v[64:65]
	v_cvt_pk_bf16_f32 v236, v96, v97
	v_pk_fma_f32 v[98:99], v[34:35], v[98:99], v[66:67]
	v_cvt_pk_bf16_f32 v237, v98, v99
	v_pk_fma_f32 v[100:101], v[36:37], v[100:101], v[68:69]
	v_cvt_pk_bf16_f32 v238, v100, v101
	v_pk_fma_f32 v[102:103], v[38:39], v[102:103], v[70:71]
	v_cvt_pk_bf16_f32 v239, v102, v103
	global_store_dwordx4 v1, v[236:239], s[8:9] offset:3072
	s_waitcnt vmcnt(28)
	v_cvt_f32_f16_e32 v72, v216
	v_cvt_f32_f16_sdwa v73, v216 dst_sel:DWORD dst_unused:UNUSED_PAD src0_sel:WORD_1
	v_cvt_f32_f16_e32 v74, v217
	v_cvt_f32_f16_sdwa v75, v217 dst_sel:DWORD dst_unused:UNUSED_PAD src0_sel:WORD_1
	v_cvt_f32_f16_e32 v76, v218
	v_cvt_f32_f16_sdwa v77, v218 dst_sel:DWORD dst_unused:UNUSED_PAD src0_sel:WORD_1
	v_cvt_f32_f16_e32 v78, v219
	v_cvt_f32_f16_sdwa v79, v219 dst_sel:DWORD dst_unused:UNUSED_PAD src0_sel:WORD_1
	v_cvt_f32_f16_e32 v80, v220
	v_cvt_f32_f16_sdwa v81, v220 dst_sel:DWORD dst_unused:UNUSED_PAD src0_sel:WORD_1
	v_cvt_f32_f16_e32 v82, v221
	v_cvt_f32_f16_sdwa v83, v221 dst_sel:DWORD dst_unused:UNUSED_PAD src0_sel:WORD_1
	v_cvt_f32_f16_e32 v84, v222
	v_cvt_f32_f16_sdwa v85, v222 dst_sel:DWORD dst_unused:UNUSED_PAD src0_sel:WORD_1
	v_cvt_f32_f16_e32 v86, v223
	v_cvt_f32_f16_sdwa v87, v223 dst_sel:DWORD dst_unused:UNUSED_PAD src0_sel:WORD_1
	v_cvt_f32_f16_e32 v88, v224
	v_cvt_f32_f16_sdwa v89, v224 dst_sel:DWORD dst_unused:UNUSED_PAD src0_sel:WORD_1
	v_cvt_f32_f16_e32 v90, v225
	v_cvt_f32_f16_sdwa v91, v225 dst_sel:DWORD dst_unused:UNUSED_PAD src0_sel:WORD_1
	v_cvt_f32_f16_e32 v92, v226
	v_cvt_f32_f16_sdwa v93, v226 dst_sel:DWORD dst_unused:UNUSED_PAD src0_sel:WORD_1
	v_cvt_f32_f16_e32 v94, v227
	v_cvt_f32_f16_sdwa v95, v227 dst_sel:DWORD dst_unused:UNUSED_PAD src0_sel:WORD_1
	v_cvt_f32_f16_e32 v96, v228
	v_cvt_f32_f16_sdwa v97, v228 dst_sel:DWORD dst_unused:UNUSED_PAD src0_sel:WORD_1
	v_cvt_f32_f16_e32 v98, v229
	v_cvt_f32_f16_sdwa v99, v229 dst_sel:DWORD dst_unused:UNUSED_PAD src0_sel:WORD_1
	v_cvt_f32_f16_e32 v100, v230
	v_cvt_f32_f16_sdwa v101, v230 dst_sel:DWORD dst_unused:UNUSED_PAD src0_sel:WORD_1
	v_cvt_f32_f16_e32 v102, v231
	v_cvt_f32_f16_sdwa v103, v231 dst_sel:DWORD dst_unused:UNUSED_PAD src0_sel:WORD_1
	v_pk_mul_f32 v[232:233], v[72:73], v[72:73]
	v_pk_mul_f32 v[234:235], v[74:75], v[74:75]
	v_pk_mul_f32 v[236:237], v[76:77], v[76:77]
	v_pk_mul_f32 v[238:239], v[78:79], v[78:79]
	v_pk_fma_f32 v[232:233], v[80:81], v[80:81], v[232:233]
	v_pk_fma_f32 v[234:235], v[82:83], v[82:83], v[234:235]
	v_pk_fma_f32 v[236:237], v[84:85], v[84:85], v[236:237]
	v_pk_fma_f32 v[238:239], v[86:87], v[86:87], v[238:239]
	v_pk_fma_f32 v[232:233], v[88:89], v[88:89], v[232:233]
	v_pk_fma_f32 v[234:235], v[90:91], v[90:91], v[234:235]
	v_pk_fma_f32 v[236:237], v[92:93], v[92:93], v[236:237]
	v_pk_fma_f32 v[238:239], v[94:95], v[94:95], v[238:239]
	v_pk_fma_f32 v[232:233], v[96:97], v[96:97], v[232:233]
	v_pk_fma_f32 v[234:235], v[98:99], v[98:99], v[234:235]
	v_pk_fma_f32 v[236:237], v[100:101], v[100:101], v[236:237]
	v_pk_fma_f32 v[238:239], v[102:103], v[102:103], v[238:239]
	v_pk_add_f32 v[232:233], v[232:233], v[234:235]
	v_pk_add_f32 v[236:237], v[236:237], v[238:239]
	v_pk_add_f32 v[232:233], v[232:233], v[236:237]
	v_add_f32_e32 v240, v232, v233
	s_nop 1
	v_add_f32_dpp v240, v240, v240 quad_perm:[1,0,3,2] row_mask:0xf bank_mask:0xf
	s_nop 1
	v_add_f32_dpp v240, v240, v240 quad_perm:[2,3,0,1] row_mask:0xf bank_mask:0xf
	s_nop 1
	v_add_f32_dpp v240, v240, v240 row_half_mirror row_mask:0xf bank_mask:0xf
	s_nop 1
	v_add_f32_dpp v240, v240, v240 row_mirror row_mask:0xf bank_mask:0xf
	s_nop 1
	v_readlane_b32 s0, v240, 0
	v_readlane_b32 s1, v240, 16
	v_readlane_b32 s4, v240, 32
	v_readlane_b32 s5, v240, 48
	v_mov_b32_e32 v249, 0x358637bd
	s_nop 1
	v_mov_b32_e32 v240, s0
	v_add_f32_e32 v240, s1, v240
	v_add_f32_e32 v240, s4, v240
	v_add_f32_e32 v240, s5, v240
	v_fmamk_f32 v240, v240, 0x3a000000, v249
	s_mov_b32 s0, 0xf800000
	v_mul_f32_e32 v241, 0x4f800000, v240
	v_cmp_gt_f32_e32 vcc, s0, v240
	s_nop 1
	v_cndmask_b32_e32 v240, v240, v241, vcc
	v_sqrt_f32_e32 v241, v240
	s_nop 0
	v_add_u32_e32 v242, -1, v241
	v_fma_f32 v243, -v242, v241, v240
	v_cmp_ge_f32_e64 s[0:1], 0, v243
	v_add_u32_e32 v243, 1, v241
	s_nop 0
	v_cndmask_b32_e64 v242, v241, v242, s[0:1]
	v_fma_f32 v241, -v243, v241, v240
	v_cmp_lt_f32_e64 s[0:1], 0, v241
	s_nop 1
	v_cndmask_b32_e64 v241, v242, v243, s[0:1]
	v_mul_f32_e32 v242, 0x37800000, v241
	v_cndmask_b32_e32 v241, v241, v242, vcc
	v_cmp_class_f32_e32 vcc, v240, v248
	s_nop 1
	v_cndmask_b32_e32 v240, v241, v240, vcc
	v_div_scale_f32 v241, s[0:1], v240, v240, 1.0
	v_rcp_f32_e32 v242, v241
	s_nop 0
	v_fma_f32 v243, -v241, v242, 1.0
	v_fmac_f32_e32 v242, v243, v242
	v_div_scale_f32 v243, vcc, 1.0, v240, 1.0
	v_mul_f32_e32 v244, v243, v242
	v_fma_f32 v247, -v241, v244, v243
	v_fmac_f32_e32 v244, v247, v242
	v_fma_f32 v241, -v241, v244, v243
	s_nop 1
	v_div_fmas_f32 v241, v241, v242, v244
	v_div_fixup_f32 v246, v241, v240, 1.0
	v_pk_mul_f32 v[72:73], v[72:73], v[246:247] op_sel_hi:[1,0]
	v_pk_mul_f32 v[74:75], v[74:75], v[246:247] op_sel_hi:[1,0]
	v_pk_mul_f32 v[76:77], v[76:77], v[246:247] op_sel_hi:[1,0]
	v_pk_mul_f32 v[78:79], v[78:79], v[246:247] op_sel_hi:[1,0]
	v_pk_mul_f32 v[80:81], v[80:81], v[246:247] op_sel_hi:[1,0]
	v_pk_mul_f32 v[82:83], v[82:83], v[246:247] op_sel_hi:[1,0]
	v_pk_mul_f32 v[84:85], v[84:85], v[246:247] op_sel_hi:[1,0]
	v_pk_mul_f32 v[86:87], v[86:87], v[246:247] op_sel_hi:[1,0]
	v_pk_mul_f32 v[88:89], v[88:89], v[246:247] op_sel_hi:[1,0]
	v_pk_mul_f32 v[90:91], v[90:91], v[246:247] op_sel_hi:[1,0]
	v_pk_mul_f32 v[92:93], v[92:93], v[246:247] op_sel_hi:[1,0]
	v_pk_mul_f32 v[94:95], v[94:95], v[246:247] op_sel_hi:[1,0]
	v_pk_mul_f32 v[96:97], v[96:97], v[246:247] op_sel_hi:[1,0]
	v_pk_mul_f32 v[98:99], v[98:99], v[246:247] op_sel_hi:[1,0]
	v_pk_mul_f32 v[100:101], v[100:101], v[246:247] op_sel_hi:[1,0]
	v_pk_mul_f32 v[102:103], v[102:103], v[246:247] op_sel_hi:[1,0]
	s_add_u32 s8, s10, 0xe0000
	s_addc_u32 s9, s11, 0
	v_pk_fma_f32 v[72:73], v[8:9], v[72:73], v[40:41]
	v_cvt_pk_bf16_f32 v232, v72, v73
	v_pk_fma_f32 v[74:75], v[10:11], v[74:75], v[42:43]
	v_cvt_pk_bf16_f32 v233, v74, v75
	v_pk_fma_f32 v[76:77], v[12:13], v[76:77], v[44:45]
	v_cvt_pk_bf16_f32 v234, v76, v77
	v_pk_fma_f32 v[78:79], v[14:15], v[78:79], v[46:47]
	v_cvt_pk_bf16_f32 v235, v78, v79
	global_store_dwordx4 v1, v[232:235], s[8:9] offset:0
	v_pk_fma_f32 v[80:81], v[16:17], v[80:81], v[48:49]
	v_cvt_pk_bf16_f32 v236, v80, v81
	v_pk_fma_f32 v[82:83], v[18:19], v[82:83], v[50:51]
	v_cvt_pk_bf16_f32 v237, v82, v83
	v_pk_fma_f32 v[84:85], v[20:21], v[84:85], v[52:53]
	v_cvt_pk_bf16_f32 v238, v84, v85
	v_pk_fma_f32 v[86:87], v[22:23], v[86:87], v[54:55]
	v_cvt_pk_bf16_f32 v239, v86, v87
	global_store_dwordx4 v1, v[236:239], s[8:9] offset:1024
	v_pk_fma_f32 v[88:89], v[24:25], v[88:89], v[56:57]
	v_cvt_pk_bf16_f32 v232, v88, v89
	v_pk_fma_f32 v[90:91], v[26:27], v[90:91], v[58:59]
	v_cvt_pk_bf16_f32 v233, v90, v91
	v_pk_fma_f32 v[92:93], v[28:29], v[92:93], v[60:61]
	v_cvt_pk_bf16_f32 v234, v92, v93
	v_pk_fma_f32 v[94:95], v[30:31], v[94:95], v[62:63]
	v_cvt_pk_bf16_f32 v235, v94, v95
	global_store_dwordx4 v1, v[232:235], s[8:9] offset:2048
	v_pk_fma_f32 v[96:97], v[32:33], v[96:97], v[64:65]
	v_cvt_pk_bf16_f32 v236, v96, v97
	v_pk_fma_f32 v[98:99], v[34:35], v[98:99], v[66:67]
	v_cvt_pk_bf16_f32 v237, v98, v99
	v_pk_fma_f32 v[100:101], v[36:37], v[100:101], v[68:69]
	v_cvt_pk_bf16_f32 v238, v100, v101
	v_pk_fma_f32 v[102:103], v[38:39], v[102:103], v[70:71]
	v_cvt_pk_bf16_f32 v239, v102, v103
	global_store_dwordx4 v1, v[236:239], s[8:9] offset:3072
	s_branch .LBB0_1143

.LBB0_1435:
	v_readlane_b32 s4, v250, 12
	s_cmp_lt_i32 s4, 13
	s_cselect_b64 s[0:1], -1, 0
	s_and_b64 s[2:3], s[0:1], s[2:3]
	s_andn2_b64 vcc, exec, s[2:3]
	v_readlane_b32 s5, v250, 13
	v_readlane_b32 s6, v250, 14
	v_readlane_b32 s7, v250, 15
	s_cbranch_vccnz .LBB0_1447
	v_mov_b32_e32 v1, 0x2416c
	ds_read_b32 v2, v1
	ds_read_b32 v1, v1 offset:4
	s_waitcnt lgkmcnt(0)
	v_readfirstlane_b32 s4, v2
	v_readfirstlane_b32 s5, v1
	s_cmp_lt_i32 s4, 1
	s_cbranch_scc1 .Lnorm_fb_2
	v_and_b32_e32 v1, 63, v0
	v_lshlrev_b32_e32 v2, 5, v1
	v_add_u32_e32 v3, 0x1000, v2
	v_lshlrev_b32_e32 v1, 4, v1
	v_readfirstlane_b32 s0, v0
	s_lshr_b32 s1, s0, 6
	s_add_i32 s4, s4, -1
	s_lshl_b32 s18, s4, 8
	s_lshl_b32 s19, s5, 3
	s_add_i32 s18, s18, s19
	s_add_i32 s18, s18, s1
	s_lshr_b32 s19, s4, 4
	s_lshl_b32 s20, s18, 12
	s_lshl_b32 s21, s18, 13
	s_add_u32 s6, s88, 0x45c00000
	s_addc_u32 s7, s89, 0
	s_add_u32 s6, s6, s20
	s_addc_u32 s7, s7, 0
	s_add_u32 s10, s88, 0x13e00000
	s_addc_u32 s11, s89, 0
	s_add_u32 s10, s10, s20
	s_addc_u32 s11, s11, 0
	s_add_u32 s12, s88, 0x17e00000
	s_addc_u32 s13, s89, 0
	s_add_u32 s12, s12, s20
	s_addc_u32 s13, s13, 0
	s_add_u32 s16, s44, 0x6000
	s_addc_u32 s17, s45, 0
	s_mul_i32 s22, s19, 0x12000
	s_add_u32 s24, s88, 0x148000
	s_addc_u32 s25, s89, 0
	s_add_u32 s24, s24, s22
	s_addc_u32 s25, s25, 0
	s_mul_i32 s22, s19, 0x12000
	s_add_u32 s26, s88, 0x14a000
	s_addc_u32 s27, s89, 0
	s_add_u32 s26, s26, s22
	s_addc_u32 s27, s27, 0
	global_load_dwordx4 v[136:139], v2, s[16:17] offset:0
	global_load_dwordx4 v[140:143], v2, s[16:17] offset:16
	global_load_dwordx4 v[144:147], v2, s[16:17] offset:2048
	global_load_dwordx4 v[148:151], v2, s[16:17] offset:2064
	global_load_dwordx4 v[152:155], v3, s[16:17] offset:0
	global_load_dwordx4 v[156:159], v3, s[16:17] offset:16
	global_load_dwordx4 v[160:163], v3, s[16:17] offset:2048
	global_load_dwordx4 v[164:167], v3, s[16:17] offset:2064
	global_load_dwordx4 v[8:11], v2, s[26:27] offset:0
	global_load_dwordx4 v[12:15], v2, s[26:27] offset:16
	global_load_dwordx4 v[16:19], v2, s[26:27] offset:2048
	global_load_dwordx4 v[20:23], v2, s[26:27] offset:2064
	global_load_dwordx4 v[24:27], v3, s[26:27] offset:0
	global_load_dwordx4 v[28:31], v3, s[26:27] offset:16
	global_load_dwordx4 v[32:35], v3, s[26:27] offset:2048
	global_load_dwordx4 v[36:39], v3, s[26:27] offset:2064
	global_load_dwordx4 v[40:43], v2, s[24:25] offset:0
	global_load_dwordx4 v[44:47], v2, s[24:25] offset:16
	global_load_dwordx4 v[48:51], v2, s[24:25] offset:2048
	global_load_dwordx4 v[52:55], v2, s[24:25] offset:2064
	global_load_dwordx4 v[56:59], v3, s[24:25] offset:0
	global_load_dwordx4 v[60:63], v3, s[24:25] offset:16
	global_load_dwordx4 v[64:67], v3, s[24:25] offset:2048
	global_load_dwordx4 v[68:71], v3, s[24:25] offset:2064
	s_waitcnt vmcnt(0)
	v_pk_add_f32 v[8:9], v[8:9], 1.0 op_sel_hi:[1,0]
	v_pk_add_f32 v[10:11], v[10:11], 1.0 op_sel_hi:[1,0]
	v_pk_add_f32 v[12:13], v[12:13], 1.0 op_sel_hi:[1,0]
	v_pk_add_f32 v[14:15], v[14:15], 1.0 op_sel_hi:[1,0]
	v_pk_add_f32 v[16:17], v[16:17], 1.0 op_sel_hi:[1,0]
	v_pk_add_f32 v[18:19], v[18:19], 1.0 op_sel_hi:[1,0]
	v_pk_add_f32 v[20:21], v[20:21], 1.0 op_sel_hi:[1,0]
	v_pk_add_f32 v[22:23], v[22:23], 1.0 op_sel_hi:[1,0]
	v_pk_add_f32 v[24:25], v[24:25], 1.0 op_sel_hi:[1,0]
	v_pk_add_f32 v[26:27], v[26:27], 1.0 op_sel_hi:[1,0]
	v_pk_add_f32 v[28:29], v[28:29], 1.0 op_sel_hi:[1,0]
	v_pk_add_f32 v[30:31], v[30:31], 1.0 op_sel_hi:[1,0]
	v_pk_add_f32 v[32:33], v[32:33], 1.0 op_sel_hi:[1,0]
	v_pk_add_f32 v[34:35], v[34:35], 1.0 op_sel_hi:[1,0]
	v_pk_add_f32 v[36:37], v[36:37], 1.0 op_sel_hi:[1,0]
	v_pk_add_f32 v[38:39], v[38:39], 1.0 op_sel_hi:[1,0]
	v_pk_mul_f32 v[8:9], v[136:137], v[8:9]
	v_pk_mul_f32 v[10:11], v[138:139], v[10:11]
	v_pk_mul_f32 v[12:13], v[140:141], v[12:13]
	v_pk_mul_f32 v[14:15], v[142:143], v[14:15]
	v_pk_mul_f32 v[16:17], v[144:145], v[16:17]
	v_pk_mul_f32 v[18:19], v[146:147], v[18:19]
	v_pk_mul_f32 v[20:21], v[148:149], v[20:21]
	v_pk_mul_f32 v[22:23], v[150:151], v[22:23]
	v_pk_mul_f32 v[24:25], v[152:153], v[24:25]
	v_pk_mul_f32 v[26:27], v[154:155], v[26:27]
	v_pk_mul_f32 v[28:29], v[156:157], v[28:29]
	v_pk_mul_f32 v[30:31], v[158:159], v[30:31]
	v_pk_mul_f32 v[32:33], v[160:161], v[32:33]
	v_pk_mul_f32 v[34:35], v[162:163], v[34:35]
	v_pk_mul_f32 v[36:37], v[164:165], v[36:37]
	v_pk_mul_f32 v[38:39], v[166:167], v[38:39]
	s_add_u32 s16, s62, 0x0
	s_addc_u32 s17, s63, 0
	s_mul_i32 s22, s19, 0x4000
	s_add_u32 s24, s88, 0x190000
	s_addc_u32 s25, s89, 0
	s_add_u32 s24, s24, s22
	s_addc_u32 s25, s25, 0
	s_mul_i32 s22, s19, 0x4000
	s_add_u32 s26, s88, 0x192000
	s_addc_u32 s27, s89, 0
	s_add_u32 s26, s26, s22
	s_addc_u32 s27, s27, 0
	global_load_dwordx4 v[136:139], v2, s[16:17] offset:0
	global_load_dwordx4 v[140:143], v2, s[16:17] offset:16
	global_load_dwordx4 v[144:147], v2, s[16:17] offset:2048
	global_load_dwordx4 v[148:151], v2, s[16:17] offset:2064
	global_load_dwordx4 v[152:155], v3, s[16:17] offset:0
	global_load_dwordx4 v[156:159], v3, s[16:17] offset:16
	global_load_dwordx4 v[160:163], v3, s[16:17] offset:2048
	global_load_dwordx4 v[164:167], v3, s[16:17] offset:2064
	global_load_dwordx4 v[72:75], v2, s[26:27] offset:0
	global_load_dwordx4 v[76:79], v2, s[26:27] offset:16
	global_load_dwordx4 v[80:83], v2, s[26:27] offset:2048
	global_load_dwordx4 v[84:87], v2, s[26:27] offset:2064
	global_load_dwordx4 v[88:91], v3, s[26:27] offset:0
	global_load_dwordx4 v[92:95], v3, s[26:27] offset:16
	global_load_dwordx4 v[96:99], v3, s[26:27] offset:2048
	global_load_dwordx4 v[100:103], v3, s[26:27] offset:2064
	global_load_dwordx4 v[104:107], v2, s[24:25] offset:0
	global_load_dwordx4 v[108:111], v2, s[24:25] offset:16
	global_load_dwordx4 v[112:115], v2, s[24:25] offset:2048
	global_load_dwordx4 v[116:119], v2, s[24:25] offset:2064
	global_load_dwordx4 v[120:123], v3, s[24:25] offset:0
	global_load_dwordx4 v[124:127], v3, s[24:25] offset:16
	global_load_dwordx4 v[128:131], v3, s[24:25] offset:2048
	global_load_dwordx4 v[132:135], v3, s[24:25] offset:2064
	s_add_u32 s8, s6, 0x0
	s_addc_u32 s9, s7, 0
	global_load_dwordx4 v[168:171], v1, s[8:9] offset:0 nt
	global_load_dwordx4 v[172:175], v1, s[8:9] offset:1024 nt
	global_load_dwordx4 v[176:179], v1, s[8:9] offset:2048 nt
	global_load_dwordx4 v[180:183], v1, s[8:9] offset:3072 nt
	s_add_u32 s8, s6, 0x20000
	s_addc_u32 s9, s7, 0
	global_load_dwordx4 v[184:187], v1, s[8:9] offset:0 nt
	global_load_dwordx4 v[188:191], v1, s[8:9] offset:1024 nt
	global_load_dwordx4 v[192:195], v1, s[8:9] offset:2048 nt
	global_load_dwordx4 v[196:199], v1, s[8:9] offset:3072 nt
	s_add_u32 s8, s6, 0x40000
	s_addc_u32 s9, s7, 0
	global_load_dwordx4 v[200:203], v1, s[8:9] offset:0 nt
	global_load_dwordx4 v[204:207], v1, s[8:9] offset:1024 nt
	global_load_dwordx4 v[208:211], v1, s[8:9] offset:2048 nt
	global_load_dwordx4 v[212:215], v1, s[8:9] offset:3072 nt
	s_add_u32 s8, s6, 0x60000
	s_addc_u32 s9, s7, 0
	global_load_dwordx4 v[216:219], v1, s[8:9] offset:0 nt
	global_load_dwordx4 v[220:223], v1, s[8:9] offset:1024 nt
	global_load_dwordx4 v[224:227], v1, s[8:9] offset:2048 nt
	global_load_dwordx4 v[228:231], v1, s[8:9] offset:3072 nt
	s_waitcnt vmcnt(16)
	v_pk_add_f32 v[72:73], v[72:73], 1.0 op_sel_hi:[1,0]
	v_pk_add_f32 v[74:75], v[74:75], 1.0 op_sel_hi:[1,0]
	v_pk_add_f32 v[76:77], v[76:77], 1.0 op_sel_hi:[1,0]
	v_pk_add_f32 v[78:79], v[78:79], 1.0 op_sel_hi:[1,0]
	v_pk_add_f32 v[80:81], v[80:81], 1.0 op_sel_hi:[1,0]
	v_pk_add_f32 v[82:83], v[82:83], 1.0 op_sel_hi:[1,0]
	v_pk_add_f32 v[84:85], v[84:85], 1.0 op_sel_hi:[1,0]
	v_pk_add_f32 v[86:87], v[86:87], 1.0 op_sel_hi:[1,0]
	v_pk_add_f32 v[88:89], v[88:89], 1.0 op_sel_hi:[1,0]
	v_pk_add_f32 v[90:91], v[90:91], 1.0 op_sel_hi:[1,0]
	v_pk_add_f32 v[92:93], v[92:93], 1.0 op_sel_hi:[1,0]
	v_pk_add_f32 v[94:95], v[94:95], 1.0 op_sel_hi:[1,0]
	v_pk_add_f32 v[96:97], v[96:97], 1.0 op_sel_hi:[1,0]
	v_pk_add_f32 v[98:99], v[98:99], 1.0 op_sel_hi:[1,0]
	v_pk_add_f32 v[100:101], v[100:101], 1.0 op_sel_hi:[1,0]
	v_pk_add_f32 v[102:103], v[102:103], 1.0 op_sel_hi:[1,0]
	v_pk_mul_f32 v[72:73], v[136:137], v[72:73]
	v_pk_mul_f32 v[74:75], v[138:139], v[74:75]
	v_pk_mul_f32 v[76:77], v[140:141], v[76:77]
	v_pk_mul_f32 v[78:79], v[142:143], v[78:79]
	v_pk_mul_f32 v[80:81], v[144:145], v[80:81]
	v_pk_mul_f32 v[82:83], v[146:147], v[82:83]
	v_pk_mul_f32 v[84:85], v[148:149], v[84:85]
	v_pk_mul_f32 v[86:87], v[150:151], v[86:87]
	v_pk_mul_f32 v[88:89], v[152:153], v[88:89]
	v_pk_mul_f32 v[90:91], v[154:155], v[90:91]
	v_pk_mul_f32 v[92:93], v[156:157], v[92:93]
	v_pk_mul_f32 v[94:95], v[158:159], v[94:95]
	v_pk_mul_f32 v[96:97], v[160:161], v[96:97]
	v_pk_mul_f32 v[98:99], v[162:163], v[98:99]
	v_pk_mul_f32 v[100:101], v[164:165], v[100:101]
	v_pk_mul_f32 v[102:103], v[166:167], v[102:103]
	v_mov_b32_e32 v248, 0x260
	s_waitcnt vmcnt(12)
	v_cvt_f32_f16_e32 v136, v168
	v_cvt_f32_f16_sdwa v137, v168 dst_sel:DWORD dst_unused:UNUSED_PAD src0_sel:WORD_1
	v_cvt_f32_f16_e32 v138, v169
	v_cvt_f32_f16_sdwa v139, v169 dst_sel:DWORD dst_unused:UNUSED_PAD src0_sel:WORD_1
	v_cvt_f32_f16_e32 v140, v170
	v_cvt_f32_f16_sdwa v141, v170 dst_sel:DWORD dst_unused:UNUSED_PAD src0_sel:WORD_1
	v_cvt_f32_f16_e32 v142, v171
	v_cvt_f32_f16_sdwa v143, v171 dst_sel:DWORD dst_unused:UNUSED_PAD src0_sel:WORD_1
	v_cvt_f32_f16_e32 v144, v172
	v_cvt_f32_f16_sdwa v145, v172 dst_sel:DWORD dst_unused:UNUSED_PAD src0_sel:WORD_1
	v_cvt_f32_f16_e32 v146, v173
	v_cvt_f32_f16_sdwa v147, v173 dst_sel:DWORD dst_unused:UNUSED_PAD src0_sel:WORD_1
	v_cvt_f32_f16_e32 v148, v174
	v_cvt_f32_f16_sdwa v149, v174 dst_sel:DWORD dst_unused:UNUSED_PAD src0_sel:WORD_1
	v_cvt_f32_f16_e32 v150, v175
	v_cvt_f32_f16_sdwa v151, v175 dst_sel:DWORD dst_unused:UNUSED_PAD src0_sel:WORD_1
	v_cvt_f32_f16_e32 v152, v176
	v_cvt_f32_f16_sdwa v153, v176 dst_sel:DWORD dst_unused:UNUSED_PAD src0_sel:WORD_1
	v_cvt_f32_f16_e32 v154, v177
	v_cvt_f32_f16_sdwa v155, v177 dst_sel:DWORD dst_unused:UNUSED_PAD src0_sel:WORD_1
	v_cvt_f32_f16_e32 v156, v178
	v_cvt_f32_f16_sdwa v157, v178 dst_sel:DWORD dst_unused:UNUSED_PAD src0_sel:WORD_1
	v_cvt_f32_f16_e32 v158, v179
	v_cvt_f32_f16_sdwa v159, v179 dst_sel:DWORD dst_unused:UNUSED_PAD src0_sel:WORD_1
	v_cvt_f32_f16_e32 v160, v180
	v_cvt_f32_f16_sdwa v161, v180 dst_sel:DWORD dst_unused:UNUSED_PAD src0_sel:WORD_1
	v_cvt_f32_f16_e32 v162, v181
	v_cvt_f32_f16_sdwa v163, v181 dst_sel:DWORD dst_unused:UNUSED_PAD src0_sel:WORD_1
	v_cvt_f32_f16_e32 v164, v182
	v_cvt_f32_f16_sdwa v165, v182 dst_sel:DWORD dst_unused:UNUSED_PAD src0_sel:WORD_1
	v_cvt_f32_f16_e32 v166, v183
	v_cvt_f32_f16_sdwa v167, v183 dst_sel:DWORD dst_unused:UNUSED_PAD src0_sel:WORD_1
	s_add_u32 s8, s6, 0x80000
	s_addc_u32 s9, s7, 0
	global_load_dwordx4 v[168:171], v1, s[8:9] offset:0 nt
	global_load_dwordx4 v[172:175], v1, s[8:9] offset:1024 nt
	global_load_dwordx4 v[176:179], v1, s[8:9] offset:2048 nt
	global_load_dwordx4 v[180:183], v1, s[8:9] offset:3072 nt
	v_pk_mul_f32 v[232:233], v[136:137], v[136:137]
	v_pk_mul_f32 v[234:235], v[138:139], v[138:139]
	v_pk_mul_f32 v[236:237], v[140:141], v[140:141]
	v_pk_mul_f32 v[238:239], v[142:143], v[142:143]
	v_pk_fma_f32 v[232:233], v[144:145], v[144:145], v[232:233]
	v_pk_fma_f32 v[234:235], v[146:147], v[146:147], v[234:235]
	v_pk_fma_f32 v[236:237], v[148:149], v[148:149], v[236:237]
	v_pk_fma_f32 v[238:239], v[150:151], v[150:151], v[238:239]
	v_pk_fma_f32 v[232:233], v[152:153], v[152:153], v[232:233]
	v_pk_fma_f32 v[234:235], v[154:155], v[154:155], v[234:235]
	v_pk_fma_f32 v[236:237], v[156:157], v[156:157], v[236:237]
	v_pk_fma_f32 v[238:239], v[158:159], v[158:159], v[238:239]
	v_pk_fma_f32 v[232:233], v[160:161], v[160:161], v[232:233]
	v_pk_fma_f32 v[234:235], v[162:163], v[162:163], v[234:235]
	v_pk_fma_f32 v[236:237], v[164:165], v[164:165], v[236:237]
	v_pk_fma_f32 v[238:239], v[166:167], v[166:167], v[238:239]
	v_pk_add_f32 v[232:233], v[232:233], v[234:235]
	v_pk_add_f32 v[236:237], v[236:237], v[238:239]
	v_pk_add_f32 v[232:233], v[232:233], v[236:237]
	v_add_f32_e32 v240, v232, v233
	s_nop 1
	v_add_f32_dpp v240, v240, v240 quad_perm:[1,0,3,2] row_mask:0xf bank_mask:0xf
	s_nop 1
	v_add_f32_dpp v240, v240, v240 quad_perm:[2,3,0,1] row_mask:0xf bank_mask:0xf
	s_nop 1
	v_add_f32_dpp v240, v240, v240 row_half_mirror row_mask:0xf bank_mask:0xf
	s_nop 1
	v_add_f32_dpp v240, v240, v240 row_mirror row_mask:0xf bank_mask:0xf
	s_nop 1
	v_readlane_b32 s0, v240, 0
	v_readlane_b32 s1, v240, 16
	v_readlane_b32 s4, v240, 32
	v_readlane_b32 s5, v240, 48
	v_mov_b32_e32 v249, 0x358637bd
	s_nop 1
	v_mov_b32_e32 v240, s0
	v_add_f32_e32 v240, s1, v240
	v_add_f32_e32 v240, s4, v240
	v_add_f32_e32 v240, s5, v240
	v_fmamk_f32 v240, v240, 0x3a000000, v249
	s_mov_b32 s0, 0xf800000
	v_mul_f32_e32 v241, 0x4f800000, v240
	v_cmp_gt_f32_e32 vcc, s0, v240
	s_nop 1
	v_cndmask_b32_e32 v240, v240, v241, vcc
	v_sqrt_f32_e32 v241, v240
	s_nop 0
	v_add_u32_e32 v242, -1, v241
	v_fma_f32 v243, -v242, v241, v240
	v_cmp_ge_f32_e64 s[0:1], 0, v243
	v_add_u32_e32 v243, 1, v241
	s_nop 0
	v_cndmask_b32_e64 v242, v241, v242, s[0:1]
	v_fma_f32 v241, -v243, v241, v240
	v_cmp_lt_f32_e64 s[0:1], 0, v241
	s_nop 1
	v_cndmask_b32_e64 v241, v242, v243, s[0:1]
	v_mul_f32_e32 v242, 0x37800000, v241
	v_cndmask_b32_e32 v241, v241, v242, vcc
	v_cmp_class_f32_e32 vcc, v240, v248
	s_nop 1
	v_cndmask_b32_e32 v240, v241, v240, vcc
	v_div_scale_f32 v241, s[0:1], v240, v240, 1.0
	v_rcp_f32_e32 v242, v241
	s_nop 0
	v_fma_f32 v243, -v241, v242, 1.0
	v_fmac_f32_e32 v242, v243, v242
	v_div_scale_f32 v243, vcc, 1.0, v240, 1.0
	v_mul_f32_e32 v244, v243, v242
	v_fma_f32 v247, -v241, v244, v243
	v_fmac_f32_e32 v244, v247, v242
	v_fma_f32 v241, -v241, v244, v243
	s_nop 1
	v_div_fmas_f32 v241, v241, v242, v244
	v_div_fixup_f32 v246, v241, v240, 1.0
	v_pk_mul_f32 v[136:137], v[136:137], v[246:247] op_sel_hi:[1,0]
	v_pk_mul_f32 v[138:139], v[138:139], v[246:247] op_sel_hi:[1,0]
	v_pk_mul_f32 v[140:141], v[140:141], v[246:247] op_sel_hi:[1,0]
	v_pk_mul_f32 v[142:143], v[142:143], v[246:247] op_sel_hi:[1,0]
	v_pk_mul_f32 v[144:145], v[144:145], v[246:247] op_sel_hi:[1,0]
	v_pk_mul_f32 v[146:147], v[146:147], v[246:247] op_sel_hi:[1,0]
	v_pk_mul_f32 v[148:149], v[148:149], v[246:247] op_sel_hi:[1,0]
	v_pk_mul_f32 v[150:151], v[150:151], v[246:247] op_sel_hi:[1,0]
	v_pk_mul_f32 v[152:153], v[152:153], v[246:247] op_sel_hi:[1,0]
	v_pk_mul_f32 v[154:155], v[154:155], v[246:247] op_sel_hi:[1,0]
	v_pk_mul_f32 v[156:157], v[156:157], v[246:247] op_sel_hi:[1,0]
	v_pk_mul_f32 v[158:159], v[158:159], v[246:247] op_sel_hi:[1,0]
	v_pk_mul_f32 v[160:161], v[160:161], v[246:247] op_sel_hi:[1,0]
	v_pk_mul_f32 v[162:163], v[162:163], v[246:247] op_sel_hi:[1,0]
	v_pk_mul_f32 v[164:165], v[164:165], v[246:247] op_sel_hi:[1,0]
	v_pk_mul_f32 v[166:167], v[166:167], v[246:247] op_sel_hi:[1,0]
	s_add_u32 s8, s10, 0x0
	s_addc_u32 s9, s11, 0
	v_pk_fma_f32 v[4:5], v[8:9], v[136:137], v[40:41]
	v_cvt_pk_bf16_f32 v232, v4, v5
	v_pk_fma_f32 v[4:5], v[10:11], v[138:139], v[42:43]
	v_cvt_pk_bf16_f32 v233, v4, v5
	v_pk_fma_f32 v[4:5], v[12:13], v[140:141], v[44:45]
	v_cvt_pk_bf16_f32 v234, v4, v5
	v_pk_fma_f32 v[4:5], v[14:15], v[142:143], v[46:47]
	v_cvt_pk_bf16_f32 v235, v4, v5
	global_store_dwordx4 v1, v[232:235], s[8:9] offset:0
	v_pk_fma_f32 v[4:5], v[16:17], v[144:145], v[48:49]
	v_cvt_pk_bf16_f32 v236, v4, v5
	v_pk_fma_f32 v[4:5], v[18:19], v[146:147], v[50:51]
	v_cvt_pk_bf16_f32 v237, v4, v5
	v_pk_fma_f32 v[4:5], v[20:21], v[148:149], v[52:53]
	v_cvt_pk_bf16_f32 v238, v4, v5
	v_pk_fma_f32 v[4:5], v[22:23], v[150:151], v[54:55]
	v_cvt_pk_bf16_f32 v239, v4, v5
	global_store_dwordx4 v1, v[236:239], s[8:9] offset:1024
	v_pk_fma_f32 v[4:5], v[24:25], v[152:153], v[56:57]
	v_cvt_pk_bf16_f32 v232, v4, v5
	v_pk_fma_f32 v[4:5], v[26:27], v[154:155], v[58:59]
	v_cvt_pk_bf16_f32 v233, v4, v5
	v_pk_fma_f32 v[4:5], v[28:29], v[156:157], v[60:61]
	v_cvt_pk_bf16_f32 v234, v4, v5
	v_pk_fma_f32 v[4:5], v[30:31], v[158:159], v[62:63]
	v_cvt_pk_bf16_f32 v235, v4, v5
	global_store_dwordx4 v1, v[232:235], s[8:9] offset:2048
	v_pk_fma_f32 v[4:5], v[32:33], v[160:161], v[64:65]
	v_cvt_pk_bf16_f32 v236, v4, v5
	v_pk_fma_f32 v[4:5], v[34:35], v[162:163], v[66:67]
	v_cvt_pk_bf16_f32 v237, v4, v5
	v_pk_fma_f32 v[4:5], v[36:37], v[164:165], v[68:69]
	v_cvt_pk_bf16_f32 v238, v4, v5
	v_pk_fma_f32 v[4:5], v[38:39], v[166:167], v[70:71]
	v_cvt_pk_bf16_f32 v239, v4, v5
	global_store_dwordx4 v1, v[236:239], s[8:9] offset:3072
	s_add_u32 s8, s12, 0x0
	s_addc_u32 s9, s13, 0
	v_pk_fma_f32 v[136:137], v[72:73], v[136:137], v[104:105]
	v_cvt_pk_bf16_f32 v232, v136, v137
	v_pk_fma_f32 v[138:139], v[74:75], v[138:139], v[106:107]
	v_cvt_pk_bf16_f32 v233, v138, v139
	v_pk_fma_f32 v[140:141], v[76:77], v[140:141], v[108:109]
	v_cvt_pk_bf16_f32 v234, v140, v141
	v_pk_fma_f32 v[142:143], v[78:79], v[142:143], v[110:111]
	v_cvt_pk_bf16_f32 v235, v142, v143
	global_store_dwordx4 v1, v[232:235], s[8:9] offset:0
	v_pk_fma_f32 v[144:145], v[80:81], v[144:145], v[112:113]
	v_cvt_pk_bf16_f32 v236, v144, v145
	v_pk_fma_f32 v[146:147], v[82:83], v[146:147], v[114:115]
	v_cvt_pk_bf16_f32 v237, v146, v147
	v_pk_fma_f32 v[148:149], v[84:85], v[148:149], v[116:117]
	v_cvt_pk_bf16_f32 v238, v148, v149
	v_pk_fma_f32 v[150:151], v[86:87], v[150:151], v[118:119]
	v_cvt_pk_bf16_f32 v239, v150, v151
	global_store_dwordx4 v1, v[236:239], s[8:9] offset:1024
	v_pk_fma_f32 v[152:153], v[88:89], v[152:153], v[120:121]
	v_cvt_pk_bf16_f32 v232, v152, v153
	v_pk_fma_f32 v[154:155], v[90:91], v[154:155], v[122:123]
	v_cvt_pk_bf16_f32 v233, v154, v155
	v_pk_fma_f32 v[156:157], v[92:93], v[156:157], v[124:125]
	v_cvt_pk_bf16_f32 v234, v156, v157
	v_pk_fma_f32 v[158:159], v[94:95], v[158:159], v[126:127]
	v_cvt_pk_bf16_f32 v235, v158, v159
	global_store_dwordx4 v1, v[232:235], s[8:9] offset:2048
	v_pk_fma_f32 v[160:161], v[96:97], v[160:161], v[128:129]
	v_cvt_pk_bf16_f32 v236, v160, v161
	v_pk_fma_f32 v[162:163], v[98:99], v[162:163], v[130:131]
	v_cvt_pk_bf16_f32 v237, v162, v163
	v_pk_fma_f32 v[164:165], v[100:101], v[164:165], v[132:133]
	v_cvt_pk_bf16_f32 v238, v164, v165
	v_pk_fma_f32 v[166:167], v[102:103], v[166:167], v[134:135]
	v_cvt_pk_bf16_f32 v239, v166, v167
	global_store_dwordx4 v1, v[236:239], s[8:9] offset:3072
	s_waitcnt vmcnt(20)
	v_cvt_f32_f16_e32 v136, v184
	v_cvt_f32_f16_sdwa v137, v184 dst_sel:DWORD dst_unused:UNUSED_PAD src0_sel:WORD_1
	v_cvt_f32_f16_e32 v138, v185
	v_cvt_f32_f16_sdwa v139, v185 dst_sel:DWORD dst_unused:UNUSED_PAD src0_sel:WORD_1
	v_cvt_f32_f16_e32 v140, v186
	v_cvt_f32_f16_sdwa v141, v186 dst_sel:DWORD dst_unused:UNUSED_PAD src0_sel:WORD_1
	v_cvt_f32_f16_e32 v142, v187
	v_cvt_f32_f16_sdwa v143, v187 dst_sel:DWORD dst_unused:UNUSED_PAD src0_sel:WORD_1
	v_cvt_f32_f16_e32 v144, v188
	v_cvt_f32_f16_sdwa v145, v188 dst_sel:DWORD dst_unused:UNUSED_PAD src0_sel:WORD_1
	v_cvt_f32_f16_e32 v146, v189
	v_cvt_f32_f16_sdwa v147, v189 dst_sel:DWORD dst_unused:UNUSED_PAD src0_sel:WORD_1
	v_cvt_f32_f16_e32 v148, v190
	v_cvt_f32_f16_sdwa v149, v190 dst_sel:DWORD dst_unused:UNUSED_PAD src0_sel:WORD_1
	v_cvt_f32_f16_e32 v150, v191
	v_cvt_f32_f16_sdwa v151, v191 dst_sel:DWORD dst_unused:UNUSED_PAD src0_sel:WORD_1
	v_cvt_f32_f16_e32 v152, v192
	v_cvt_f32_f16_sdwa v153, v192 dst_sel:DWORD dst_unused:UNUSED_PAD src0_sel:WORD_1
	v_cvt_f32_f16_e32 v154, v193
	v_cvt_f32_f16_sdwa v155, v193 dst_sel:DWORD dst_unused:UNUSED_PAD src0_sel:WORD_1
	v_cvt_f32_f16_e32 v156, v194
	v_cvt_f32_f16_sdwa v157, v194 dst_sel:DWORD dst_unused:UNUSED_PAD src0_sel:WORD_1
	v_cvt_f32_f16_e32 v158, v195
	v_cvt_f32_f16_sdwa v159, v195 dst_sel:DWORD dst_unused:UNUSED_PAD src0_sel:WORD_1
	v_cvt_f32_f16_e32 v160, v196
	v_cvt_f32_f16_sdwa v161, v196 dst_sel:DWORD dst_unused:UNUSED_PAD src0_sel:WORD_1
	v_cvt_f32_f16_e32 v162, v197
	v_cvt_f32_f16_sdwa v163, v197 dst_sel:DWORD dst_unused:UNUSED_PAD src0_sel:WORD_1
	v_cvt_f32_f16_e32 v164, v198
	v_cvt_f32_f16_sdwa v165, v198 dst_sel:DWORD dst_unused:UNUSED_PAD src0_sel:WORD_1
	v_cvt_f32_f16_e32 v166, v199
	v_cvt_f32_f16_sdwa v167, v199 dst_sel:DWORD dst_unused:UNUSED_PAD src0_sel:WORD_1
	s_add_u32 s8, s6, 0xa0000
	s_addc_u32 s9, s7, 0
	global_load_dwordx4 v[184:187], v1, s[8:9] offset:0 nt
	global_load_dwordx4 v[188:191], v1, s[8:9] offset:1024 nt
	global_load_dwordx4 v[192:195], v1, s[8:9] offset:2048 nt
	global_load_dwordx4 v[196:199], v1, s[8:9] offset:3072 nt
	v_pk_mul_f32 v[232:233], v[136:137], v[136:137]
	v_pk_mul_f32 v[234:235], v[138:139], v[138:139]
	v_pk_mul_f32 v[236:237], v[140:141], v[140:141]
	v_pk_mul_f32 v[238:239], v[142:143], v[142:143]
	v_pk_fma_f32 v[232:233], v[144:145], v[144:145], v[232:233]
	v_pk_fma_f32 v[234:235], v[146:147], v[146:147], v[234:235]
	v_pk_fma_f32 v[236:237], v[148:149], v[148:149], v[236:237]
	v_pk_fma_f32 v[238:239], v[150:151], v[150:151], v[238:239]
	v_pk_fma_f32 v[232:233], v[152:153], v[152:153], v[232:233]
	v_pk_fma_f32 v[234:235], v[154:155], v[154:155], v[234:235]
	v_pk_fma_f32 v[236:237], v[156:157], v[156:157], v[236:237]
	v_pk_fma_f32 v[238:239], v[158:159], v[158:159], v[238:239]
	v_pk_fma_f32 v[232:233], v[160:161], v[160:161], v[232:233]
	v_pk_fma_f32 v[234:235], v[162:163], v[162:163], v[234:235]
	v_pk_fma_f32 v[236:237], v[164:165], v[164:165], v[236:237]
	v_pk_fma_f32 v[238:239], v[166:167], v[166:167], v[238:239]
	v_pk_add_f32 v[232:233], v[232:233], v[234:235]
	v_pk_add_f32 v[236:237], v[236:237], v[238:239]
	v_pk_add_f32 v[232:233], v[232:233], v[236:237]
	v_add_f32_e32 v240, v232, v233
	s_nop 1
	v_add_f32_dpp v240, v240, v240 quad_perm:[1,0,3,2] row_mask:0xf bank_mask:0xf
	s_nop 1
	v_add_f32_dpp v240, v240, v240 quad_perm:[2,3,0,1] row_mask:0xf bank_mask:0xf
	s_nop 1
	v_add_f32_dpp v240, v240, v240 row_half_mirror row_mask:0xf bank_mask:0xf
	s_nop 1
	v_add_f32_dpp v240, v240, v240 row_mirror row_mask:0xf bank_mask:0xf
	s_nop 1
	v_readlane_b32 s0, v240, 0
	v_readlane_b32 s1, v240, 16
	v_readlane_b32 s4, v240, 32
	v_readlane_b32 s5, v240, 48
	v_mov_b32_e32 v249, 0x358637bd
	s_nop 1
	v_mov_b32_e32 v240, s0
	v_add_f32_e32 v240, s1, v240
	v_add_f32_e32 v240, s4, v240
	v_add_f32_e32 v240, s5, v240
	v_fmamk_f32 v240, v240, 0x3a000000, v249
	s_mov_b32 s0, 0xf800000
	v_mul_f32_e32 v241, 0x4f800000, v240
	v_cmp_gt_f32_e32 vcc, s0, v240
	s_nop 1
	v_cndmask_b32_e32 v240, v240, v241, vcc
	v_sqrt_f32_e32 v241, v240
	s_nop 0
	v_add_u32_e32 v242, -1, v241
	v_fma_f32 v243, -v242, v241, v240
	v_cmp_ge_f32_e64 s[0:1], 0, v243
	v_add_u32_e32 v243, 1, v241
	s_nop 0
	v_cndmask_b32_e64 v242, v241, v242, s[0:1]
	v_fma_f32 v241, -v243, v241, v240
	v_cmp_lt_f32_e64 s[0:1], 0, v241
	s_nop 1
	v_cndmask_b32_e64 v241, v242, v243, s[0:1]
	v_mul_f32_e32 v242, 0x37800000, v241
	v_cndmask_b32_e32 v241, v241, v242, vcc
	v_cmp_class_f32_e32 vcc, v240, v248
	s_nop 1
	v_cndmask_b32_e32 v240, v241, v240, vcc
	v_div_scale_f32 v241, s[0:1], v240, v240, 1.0
	v_rcp_f32_e32 v242, v241
	s_nop 0
	v_fma_f32 v243, -v241, v242, 1.0
	v_fmac_f32_e32 v242, v243, v242
	v_div_scale_f32 v243, vcc, 1.0, v240, 1.0
	v_mul_f32_e32 v244, v243, v242
	v_fma_f32 v247, -v241, v244, v243
	v_fmac_f32_e32 v244, v247, v242
	v_fma_f32 v241, -v241, v244, v243
	s_nop 1
	v_div_fmas_f32 v241, v241, v242, v244
	v_div_fixup_f32 v246, v241, v240, 1.0
	v_pk_mul_f32 v[136:137], v[136:137], v[246:247] op_sel_hi:[1,0]
	v_pk_mul_f32 v[138:139], v[138:139], v[246:247] op_sel_hi:[1,0]
	v_pk_mul_f32 v[140:141], v[140:141], v[246:247] op_sel_hi:[1,0]
	v_pk_mul_f32 v[142:143], v[142:143], v[246:247] op_sel_hi:[1,0]
	v_pk_mul_f32 v[144:145], v[144:145], v[246:247] op_sel_hi:[1,0]
	v_pk_mul_f32 v[146:147], v[146:147], v[246:247] op_sel_hi:[1,0]
	v_pk_mul_f32 v[148:149], v[148:149], v[246:247] op_sel_hi:[1,0]
	v_pk_mul_f32 v[150:151], v[150:151], v[246:247] op_sel_hi:[1,0]
	v_pk_mul_f32 v[152:153], v[152:153], v[246:247] op_sel_hi:[1,0]
	v_pk_mul_f32 v[154:155], v[154:155], v[246:247] op_sel_hi:[1,0]
	v_pk_mul_f32 v[156:157], v[156:157], v[246:247] op_sel_hi:[1,0]
	v_pk_mul_f32 v[158:159], v[158:159], v[246:247] op_sel_hi:[1,0]
	v_pk_mul_f32 v[160:161], v[160:161], v[246:247] op_sel_hi:[1,0]
	v_pk_mul_f32 v[162:163], v[162:163], v[246:247] op_sel_hi:[1,0]
	v_pk_mul_f32 v[164:165], v[164:165], v[246:247] op_sel_hi:[1,0]
	v_pk_mul_f32 v[166:167], v[166:167], v[246:247] op_sel_hi:[1,0]
	s_add_u32 s8, s10, 0x20000
	s_addc_u32 s9, s11, 0
	v_pk_fma_f32 v[4:5], v[8:9], v[136:137], v[40:41]
	v_cvt_pk_bf16_f32 v232, v4, v5
	v_pk_fma_f32 v[4:5], v[10:11], v[138:139], v[42:43]
	v_cvt_pk_bf16_f32 v233, v4, v5
	v_pk_fma_f32 v[4:5], v[12:13], v[140:141], v[44:45]
	v_cvt_pk_bf16_f32 v234, v4, v5
	v_pk_fma_f32 v[4:5], v[14:15], v[142:143], v[46:47]
	v_cvt_pk_bf16_f32 v235, v4, v5
	global_store_dwordx4 v1, v[232:235], s[8:9] offset:0
	v_pk_fma_f32 v[4:5], v[16:17], v[144:145], v[48:49]
	v_cvt_pk_bf16_f32 v236, v4, v5
	v_pk_fma_f32 v[4:5], v[18:19], v[146:147], v[50:51]
	v_cvt_pk_bf16_f32 v237, v4, v5
	v_pk_fma_f32 v[4:5], v[20:21], v[148:149], v[52:53]
	v_cvt_pk_bf16_f32 v238, v4, v5
	v_pk_fma_f32 v[4:5], v[22:23], v[150:151], v[54:55]
	v_cvt_pk_bf16_f32 v239, v4, v5
	global_store_dwordx4 v1, v[236:239], s[8:9] offset:1024
	v_pk_fma_f32 v[4:5], v[24:25], v[152:153], v[56:57]
	v_cvt_pk_bf16_f32 v232, v4, v5
	v_pk_fma_f32 v[4:5], v[26:27], v[154:155], v[58:59]
	v_cvt_pk_bf16_f32 v233, v4, v5
	v_pk_fma_f32 v[4:5], v[28:29], v[156:157], v[60:61]
	v_cvt_pk_bf16_f32 v234, v4, v5
	v_pk_fma_f32 v[4:5], v[30:31], v[158:159], v[62:63]
	v_cvt_pk_bf16_f32 v235, v4, v5
	global_store_dwordx4 v1, v[232:235], s[8:9] offset:2048
	v_pk_fma_f32 v[4:5], v[32:33], v[160:161], v[64:65]
	v_cvt_pk_bf16_f32 v236, v4, v5
	v_pk_fma_f32 v[4:5], v[34:35], v[162:163], v[66:67]
	v_cvt_pk_bf16_f32 v237, v4, v5
	v_pk_fma_f32 v[4:5], v[36:37], v[164:165], v[68:69]
	v_cvt_pk_bf16_f32 v238, v4, v5
	v_pk_fma_f32 v[4:5], v[38:39], v[166:167], v[70:71]
	v_cvt_pk_bf16_f32 v239, v4, v5
	global_store_dwordx4 v1, v[236:239], s[8:9] offset:3072
	s_add_u32 s8, s12, 0x20000
	s_addc_u32 s9, s13, 0
	v_pk_fma_f32 v[136:137], v[72:73], v[136:137], v[104:105]
	v_cvt_pk_bf16_f32 v232, v136, v137
	v_pk_fma_f32 v[138:139], v[74:75], v[138:139], v[106:107]
	v_cvt_pk_bf16_f32 v233, v138, v139
	v_pk_fma_f32 v[140:141], v[76:77], v[140:141], v[108:109]
	v_cvt_pk_bf16_f32 v234, v140, v141
	v_pk_fma_f32 v[142:143], v[78:79], v[142:143], v[110:111]
	v_cvt_pk_bf16_f32 v235, v142, v143
	global_store_dwordx4 v1, v[232:235], s[8:9] offset:0
	v_pk_fma_f32 v[144:145], v[80:81], v[144:145], v[112:113]
	v_cvt_pk_bf16_f32 v236, v144, v145
	v_pk_fma_f32 v[146:147], v[82:83], v[146:147], v[114:115]
	v_cvt_pk_bf16_f32 v237, v146, v147
	v_pk_fma_f32 v[148:149], v[84:85], v[148:149], v[116:117]
	v_cvt_pk_bf16_f32 v238, v148, v149
	v_pk_fma_f32 v[150:151], v[86:87], v[150:151], v[118:119]
	v_cvt_pk_bf16_f32 v239, v150, v151
	global_store_dwordx4 v1, v[236:239], s[8:9] offset:1024
	v_pk_fma_f32 v[152:153], v[88:89], v[152:153], v[120:121]
	v_cvt_pk_bf16_f32 v232, v152, v153
	v_pk_fma_f32 v[154:155], v[90:91], v[154:155], v[122:123]
	v_cvt_pk_bf16_f32 v233, v154, v155
	v_pk_fma_f32 v[156:157], v[92:93], v[156:157], v[124:125]
	v_cvt_pk_bf16_f32 v234, v156, v157
	v_pk_fma_f32 v[158:159], v[94:95], v[158:159], v[126:127]
	v_cvt_pk_bf16_f32 v235, v158, v159
	global_store_dwordx4 v1, v[232:235], s[8:9] offset:2048
	v_pk_fma_f32 v[160:161], v[96:97], v[160:161], v[128:129]
	v_cvt_pk_bf16_f32 v236, v160, v161
	v_pk_fma_f32 v[162:163], v[98:99], v[162:163], v[130:131]
	v_cvt_pk_bf16_f32 v237, v162, v163
	v_pk_fma_f32 v[164:165], v[100:101], v[164:165], v[132:133]
	v_cvt_pk_bf16_f32 v238, v164, v165
	v_pk_fma_f32 v[166:167], v[102:103], v[166:167], v[134:135]
	v_cvt_pk_bf16_f32 v239, v166, v167
	global_store_dwordx4 v1, v[236:239], s[8:9] offset:3072
	s_waitcnt vmcnt(28)
	v_cvt_f32_f16_e32 v136, v200
	v_cvt_f32_f16_sdwa v137, v200 dst_sel:DWORD dst_unused:UNUSED_PAD src0_sel:WORD_1
	v_cvt_f32_f16_e32 v138, v201
	v_cvt_f32_f16_sdwa v139, v201 dst_sel:DWORD dst_unused:UNUSED_PAD src0_sel:WORD_1
	v_cvt_f32_f16_e32 v140, v202
	v_cvt_f32_f16_sdwa v141, v202 dst_sel:DWORD dst_unused:UNUSED_PAD src0_sel:WORD_1
	v_cvt_f32_f16_e32 v142, v203
	v_cvt_f32_f16_sdwa v143, v203 dst_sel:DWORD dst_unused:UNUSED_PAD src0_sel:WORD_1
	v_cvt_f32_f16_e32 v144, v204
	v_cvt_f32_f16_sdwa v145, v204 dst_sel:DWORD dst_unused:UNUSED_PAD src0_sel:WORD_1
	v_cvt_f32_f16_e32 v146, v205
	v_cvt_f32_f16_sdwa v147, v205 dst_sel:DWORD dst_unused:UNUSED_PAD src0_sel:WORD_1
	v_cvt_f32_f16_e32 v148, v206
	v_cvt_f32_f16_sdwa v149, v206 dst_sel:DWORD dst_unused:UNUSED_PAD src0_sel:WORD_1
	v_cvt_f32_f16_e32 v150, v207
	v_cvt_f32_f16_sdwa v151, v207 dst_sel:DWORD dst_unused:UNUSED_PAD src0_sel:WORD_1
	v_cvt_f32_f16_e32 v152, v208
	v_cvt_f32_f16_sdwa v153, v208 dst_sel:DWORD dst_unused:UNUSED_PAD src0_sel:WORD_1
	v_cvt_f32_f16_e32 v154, v209
	v_cvt_f32_f16_sdwa v155, v209 dst_sel:DWORD dst_unused:UNUSED_PAD src0_sel:WORD_1
	v_cvt_f32_f16_e32 v156, v210
	v_cvt_f32_f16_sdwa v157, v210 dst_sel:DWORD dst_unused:UNUSED_PAD src0_sel:WORD_1
	v_cvt_f32_f16_e32 v158, v211
	v_cvt_f32_f16_sdwa v159, v211 dst_sel:DWORD dst_unused:UNUSED_PAD src0_sel:WORD_1
	v_cvt_f32_f16_e32 v160, v212
	v_cvt_f32_f16_sdwa v161, v212 dst_sel:DWORD dst_unused:UNUSED_PAD src0_sel:WORD_1
	v_cvt_f32_f16_e32 v162, v213
	v_cvt_f32_f16_sdwa v163, v213 dst_sel:DWORD dst_unused:UNUSED_PAD src0_sel:WORD_1
	v_cvt_f32_f16_e32 v164, v214
	v_cvt_f32_f16_sdwa v165, v214 dst_sel:DWORD dst_unused:UNUSED_PAD src0_sel:WORD_1
	v_cvt_f32_f16_e32 v166, v215
	v_cvt_f32_f16_sdwa v167, v215 dst_sel:DWORD dst_unused:UNUSED_PAD src0_sel:WORD_1
	s_add_u32 s8, s6, 0xc0000
	s_addc_u32 s9, s7, 0
	global_load_dwordx4 v[200:203], v1, s[8:9] offset:0 nt
	global_load_dwordx4 v[204:207], v1, s[8:9] offset:1024 nt
	global_load_dwordx4 v[208:211], v1, s[8:9] offset:2048 nt
	global_load_dwordx4 v[212:215], v1, s[8:9] offset:3072 nt
	v_pk_mul_f32 v[232:233], v[136:137], v[136:137]
	v_pk_mul_f32 v[234:235], v[138:139], v[138:139]
	v_pk_mul_f32 v[236:237], v[140:141], v[140:141]
	v_pk_mul_f32 v[238:239], v[142:143], v[142:143]
	v_pk_fma_f32 v[232:233], v[144:145], v[144:145], v[232:233]
	v_pk_fma_f32 v[234:235], v[146:147], v[146:147], v[234:235]
	v_pk_fma_f32 v[236:237], v[148:149], v[148:149], v[236:237]
	v_pk_fma_f32 v[238:239], v[150:151], v[150:151], v[238:239]
	v_pk_fma_f32 v[232:233], v[152:153], v[152:153], v[232:233]
	v_pk_fma_f32 v[234:235], v[154:155], v[154:155], v[234:235]
	v_pk_fma_f32 v[236:237], v[156:157], v[156:157], v[236:237]
	v_pk_fma_f32 v[238:239], v[158:159], v[158:159], v[238:239]
	v_pk_fma_f32 v[232:233], v[160:161], v[160:161], v[232:233]
	v_pk_fma_f32 v[234:235], v[162:163], v[162:163], v[234:235]
	v_pk_fma_f32 v[236:237], v[164:165], v[164:165], v[236:237]
	v_pk_fma_f32 v[238:239], v[166:167], v[166:167], v[238:239]
	v_pk_add_f32 v[232:233], v[232:233], v[234:235]
	v_pk_add_f32 v[236:237], v[236:237], v[238:239]
	v_pk_add_f32 v[232:233], v[232:233], v[236:237]
	v_add_f32_e32 v240, v232, v233
	s_nop 1
	v_add_f32_dpp v240, v240, v240 quad_perm:[1,0,3,2] row_mask:0xf bank_mask:0xf
	s_nop 1
	v_add_f32_dpp v240, v240, v240 quad_perm:[2,3,0,1] row_mask:0xf bank_mask:0xf
	s_nop 1
	v_add_f32_dpp v240, v240, v240 row_half_mirror row_mask:0xf bank_mask:0xf
	s_nop 1
	v_add_f32_dpp v240, v240, v240 row_mirror row_mask:0xf bank_mask:0xf
	s_nop 1
	v_readlane_b32 s0, v240, 0
	v_readlane_b32 s1, v240, 16
	v_readlane_b32 s4, v240, 32
	v_readlane_b32 s5, v240, 48
	v_mov_b32_e32 v249, 0x358637bd
	s_nop 1
	v_mov_b32_e32 v240, s0
	v_add_f32_e32 v240, s1, v240
	v_add_f32_e32 v240, s4, v240
	v_add_f32_e32 v240, s5, v240
	v_fmamk_f32 v240, v240, 0x3a000000, v249
	s_mov_b32 s0, 0xf800000
	v_mul_f32_e32 v241, 0x4f800000, v240
	v_cmp_gt_f32_e32 vcc, s0, v240
	s_nop 1
	v_cndmask_b32_e32 v240, v240, v241, vcc
	v_sqrt_f32_e32 v241, v240
	s_nop 0
	v_add_u32_e32 v242, -1, v241
	v_fma_f32 v243, -v242, v241, v240
	v_cmp_ge_f32_e64 s[0:1], 0, v243
	v_add_u32_e32 v243, 1, v241
	s_nop 0
	v_cndmask_b32_e64 v242, v241, v242, s[0:1]
	v_fma_f32 v241, -v243, v241, v240
	v_cmp_lt_f32_e64 s[0:1], 0, v241
	s_nop 1
	v_cndmask_b32_e64 v241, v242, v243, s[0:1]
	v_mul_f32_e32 v242, 0x37800000, v241
	v_cndmask_b32_e32 v241, v241, v242, vcc
	v_cmp_class_f32_e32 vcc, v240, v248
	s_nop 1
	v_cndmask_b32_e32 v240, v241, v240, vcc
	v_div_scale_f32 v241, s[0:1], v240, v240, 1.0
	v_rcp_f32_e32 v242, v241
	s_nop 0
	v_fma_f32 v243, -v241, v242, 1.0
	v_fmac_f32_e32 v242, v243, v242
	v_div_scale_f32 v243, vcc, 1.0, v240, 1.0
	v_mul_f32_e32 v244, v243, v242
	v_fma_f32 v247, -v241, v244, v243
	v_fmac_f32_e32 v244, v247, v242
	v_fma_f32 v241, -v241, v244, v243
	s_nop 1
	v_div_fmas_f32 v241, v241, v242, v244
	v_div_fixup_f32 v246, v241, v240, 1.0
	v_pk_mul_f32 v[136:137], v[136:137], v[246:247] op_sel_hi:[1,0]
	v_pk_mul_f32 v[138:139], v[138:139], v[246:247] op_sel_hi:[1,0]
	v_pk_mul_f32 v[140:141], v[140:141], v[246:247] op_sel_hi:[1,0]
	v_pk_mul_f32 v[142:143], v[142:143], v[246:247] op_sel_hi:[1,0]
	v_pk_mul_f32 v[144:145], v[144:145], v[246:247] op_sel_hi:[1,0]
	v_pk_mul_f32 v[146:147], v[146:147], v[246:247] op_sel_hi:[1,0]
	v_pk_mul_f32 v[148:149], v[148:149], v[246:247] op_sel_hi:[1,0]
	v_pk_mul_f32 v[150:151], v[150:151], v[246:247] op_sel_hi:[1,0]
	v_pk_mul_f32 v[152:153], v[152:153], v[246:247] op_sel_hi:[1,0]
	v_pk_mul_f32 v[154:155], v[154:155], v[246:247] op_sel_hi:[1,0]
	v_pk_mul_f32 v[156:157], v[156:157], v[246:247] op_sel_hi:[1,0]
	v_pk_mul_f32 v[158:159], v[158:159], v[246:247] op_sel_hi:[1,0]
	v_pk_mul_f32 v[160:161], v[160:161], v[246:247] op_sel_hi:[1,0]
	v_pk_mul_f32 v[162:163], v[162:163], v[246:247] op_sel_hi:[1,0]
	v_pk_mul_f32 v[164:165], v[164:165], v[246:247] op_sel_hi:[1,0]
	v_pk_mul_f32 v[166:167], v[166:167], v[246:247] op_sel_hi:[1,0]
	s_add_u32 s8, s10, 0x40000
	s_addc_u32 s9, s11, 0
	v_pk_fma_f32 v[4:5], v[8:9], v[136:137], v[40:41]
	v_cvt_pk_bf16_f32 v232, v4, v5
	v_pk_fma_f32 v[4:5], v[10:11], v[138:139], v[42:43]
	v_cvt_pk_bf16_f32 v233, v4, v5
	v_pk_fma_f32 v[4:5], v[12:13], v[140:141], v[44:45]
	v_cvt_pk_bf16_f32 v234, v4, v5
	v_pk_fma_f32 v[4:5], v[14:15], v[142:143], v[46:47]
	v_cvt_pk_bf16_f32 v235, v4, v5
	global_store_dwordx4 v1, v[232:235], s[8:9] offset:0
	v_pk_fma_f32 v[4:5], v[16:17], v[144:145], v[48:49]
	v_cvt_pk_bf16_f32 v236, v4, v5
	v_pk_fma_f32 v[4:5], v[18:19], v[146:147], v[50:51]
	v_cvt_pk_bf16_f32 v237, v4, v5
	v_pk_fma_f32 v[4:5], v[20:21], v[148:149], v[52:53]
	v_cvt_pk_bf16_f32 v238, v4, v5
	v_pk_fma_f32 v[4:5], v[22:23], v[150:151], v[54:55]
	v_cvt_pk_bf16_f32 v239, v4, v5
	global_store_dwordx4 v1, v[236:239], s[8:9] offset:1024
	v_pk_fma_f32 v[4:5], v[24:25], v[152:153], v[56:57]
	v_cvt_pk_bf16_f32 v232, v4, v5
	v_pk_fma_f32 v[4:5], v[26:27], v[154:155], v[58:59]
	v_cvt_pk_bf16_f32 v233, v4, v5
	v_pk_fma_f32 v[4:5], v[28:29], v[156:157], v[60:61]
	v_cvt_pk_bf16_f32 v234, v4, v5
	v_pk_fma_f32 v[4:5], v[30:31], v[158:159], v[62:63]
	v_cvt_pk_bf16_f32 v235, v4, v5
	global_store_dwordx4 v1, v[232:235], s[8:9] offset:2048
	v_pk_fma_f32 v[4:5], v[32:33], v[160:161], v[64:65]
	v_cvt_pk_bf16_f32 v236, v4, v5
	v_pk_fma_f32 v[4:5], v[34:35], v[162:163], v[66:67]
	v_cvt_pk_bf16_f32 v237, v4, v5
	v_pk_fma_f32 v[4:5], v[36:37], v[164:165], v[68:69]
	v_cvt_pk_bf16_f32 v238, v4, v5
	v_pk_fma_f32 v[4:5], v[38:39], v[166:167], v[70:71]
	v_cvt_pk_bf16_f32 v239, v4, v5
	global_store_dwordx4 v1, v[236:239], s[8:9] offset:3072
	s_add_u32 s8, s12, 0x40000
	s_addc_u32 s9, s13, 0
	v_pk_fma_f32 v[136:137], v[72:73], v[136:137], v[104:105]
	v_cvt_pk_bf16_f32 v232, v136, v137
	v_pk_fma_f32 v[138:139], v[74:75], v[138:139], v[106:107]
	v_cvt_pk_bf16_f32 v233, v138, v139
	v_pk_fma_f32 v[140:141], v[76:77], v[140:141], v[108:109]
	v_cvt_pk_bf16_f32 v234, v140, v141
	v_pk_fma_f32 v[142:143], v[78:79], v[142:143], v[110:111]
	v_cvt_pk_bf16_f32 v235, v142, v143
	global_store_dwordx4 v1, v[232:235], s[8:9] offset:0
	v_pk_fma_f32 v[144:145], v[80:81], v[144:145], v[112:113]
	v_cvt_pk_bf16_f32 v236, v144, v145
	v_pk_fma_f32 v[146:147], v[82:83], v[146:147], v[114:115]
	v_cvt_pk_bf16_f32 v237, v146, v147
	v_pk_fma_f32 v[148:149], v[84:85], v[148:149], v[116:117]
	v_cvt_pk_bf16_f32 v238, v148, v149
	v_pk_fma_f32 v[150:151], v[86:87], v[150:151], v[118:119]
	v_cvt_pk_bf16_f32 v239, v150, v151
	global_store_dwordx4 v1, v[236:239], s[8:9] offset:1024
	v_pk_fma_f32 v[152:153], v[88:89], v[152:153], v[120:121]
	v_cvt_pk_bf16_f32 v232, v152, v153
	v_pk_fma_f32 v[154:155], v[90:91], v[154:155], v[122:123]
	v_cvt_pk_bf16_f32 v233, v154, v155
	v_pk_fma_f32 v[156:157], v[92:93], v[156:157], v[124:125]
	v_cvt_pk_bf16_f32 v234, v156, v157
	v_pk_fma_f32 v[158:159], v[94:95], v[158:159], v[126:127]
	v_cvt_pk_bf16_f32 v235, v158, v159
	global_store_dwordx4 v1, v[232:235], s[8:9] offset:2048
	v_pk_fma_f32 v[160:161], v[96:97], v[160:161], v[128:129]
	v_cvt_pk_bf16_f32 v236, v160, v161
	v_pk_fma_f32 v[162:163], v[98:99], v[162:163], v[130:131]
	v_cvt_pk_bf16_f32 v237, v162, v163
	v_pk_fma_f32 v[164:165], v[100:101], v[164:165], v[132:133]
	v_cvt_pk_bf16_f32 v238, v164, v165
	v_pk_fma_f32 v[166:167], v[102:103], v[166:167], v[134:135]
	v_cvt_pk_bf16_f32 v239, v166, v167
	global_store_dwordx4 v1, v[236:239], s[8:9] offset:3072
	s_waitcnt vmcnt(36)
	v_cvt_f32_f16_e32 v136, v216
	v_cvt_f32_f16_sdwa v137, v216 dst_sel:DWORD dst_unused:UNUSED_PAD src0_sel:WORD_1
	v_cvt_f32_f16_e32 v138, v217
	v_cvt_f32_f16_sdwa v139, v217 dst_sel:DWORD dst_unused:UNUSED_PAD src0_sel:WORD_1
	v_cvt_f32_f16_e32 v140, v218
	v_cvt_f32_f16_sdwa v141, v218 dst_sel:DWORD dst_unused:UNUSED_PAD src0_sel:WORD_1
	v_cvt_f32_f16_e32 v142, v219
	v_cvt_f32_f16_sdwa v143, v219 dst_sel:DWORD dst_unused:UNUSED_PAD src0_sel:WORD_1
	v_cvt_f32_f16_e32 v144, v220
	v_cvt_f32_f16_sdwa v145, v220 dst_sel:DWORD dst_unused:UNUSED_PAD src0_sel:WORD_1
	v_cvt_f32_f16_e32 v146, v221
	v_cvt_f32_f16_sdwa v147, v221 dst_sel:DWORD dst_unused:UNUSED_PAD src0_sel:WORD_1
	v_cvt_f32_f16_e32 v148, v222
	v_cvt_f32_f16_sdwa v149, v222 dst_sel:DWORD dst_unused:UNUSED_PAD src0_sel:WORD_1
	v_cvt_f32_f16_e32 v150, v223
	v_cvt_f32_f16_sdwa v151, v223 dst_sel:DWORD dst_unused:UNUSED_PAD src0_sel:WORD_1
	v_cvt_f32_f16_e32 v152, v224
	v_cvt_f32_f16_sdwa v153, v224 dst_sel:DWORD dst_unused:UNUSED_PAD src0_sel:WORD_1
	v_cvt_f32_f16_e32 v154, v225
	v_cvt_f32_f16_sdwa v155, v225 dst_sel:DWORD dst_unused:UNUSED_PAD src0_sel:WORD_1
	v_cvt_f32_f16_e32 v156, v226
	v_cvt_f32_f16_sdwa v157, v226 dst_sel:DWORD dst_unused:UNUSED_PAD src0_sel:WORD_1
	v_cvt_f32_f16_e32 v158, v227
	v_cvt_f32_f16_sdwa v159, v227 dst_sel:DWORD dst_unused:UNUSED_PAD src0_sel:WORD_1
	v_cvt_f32_f16_e32 v160, v228
	v_cvt_f32_f16_sdwa v161, v228 dst_sel:DWORD dst_unused:UNUSED_PAD src0_sel:WORD_1
	v_cvt_f32_f16_e32 v162, v229
	v_cvt_f32_f16_sdwa v163, v229 dst_sel:DWORD dst_unused:UNUSED_PAD src0_sel:WORD_1
	v_cvt_f32_f16_e32 v164, v230
	v_cvt_f32_f16_sdwa v165, v230 dst_sel:DWORD dst_unused:UNUSED_PAD src0_sel:WORD_1
	v_cvt_f32_f16_e32 v166, v231
	v_cvt_f32_f16_sdwa v167, v231 dst_sel:DWORD dst_unused:UNUSED_PAD src0_sel:WORD_1
	s_add_u32 s8, s6, 0xe0000
	s_addc_u32 s9, s7, 0
	global_load_dwordx4 v[216:219], v1, s[8:9] offset:0 nt
	global_load_dwordx4 v[220:223], v1, s[8:9] offset:1024 nt
	global_load_dwordx4 v[224:227], v1, s[8:9] offset:2048 nt
	global_load_dwordx4 v[228:231], v1, s[8:9] offset:3072 nt
	v_pk_mul_f32 v[232:233], v[136:137], v[136:137]
	v_pk_mul_f32 v[234:235], v[138:139], v[138:139]
	v_pk_mul_f32 v[236:237], v[140:141], v[140:141]
	v_pk_mul_f32 v[238:239], v[142:143], v[142:143]
	v_pk_fma_f32 v[232:233], v[144:145], v[144:145], v[232:233]
	v_pk_fma_f32 v[234:235], v[146:147], v[146:147], v[234:235]
	v_pk_fma_f32 v[236:237], v[148:149], v[148:149], v[236:237]
	v_pk_fma_f32 v[238:239], v[150:151], v[150:151], v[238:239]
	v_pk_fma_f32 v[232:233], v[152:153], v[152:153], v[232:233]
	v_pk_fma_f32 v[234:235], v[154:155], v[154:155], v[234:235]
	v_pk_fma_f32 v[236:237], v[156:157], v[156:157], v[236:237]
	v_pk_fma_f32 v[238:239], v[158:159], v[158:159], v[238:239]
	v_pk_fma_f32 v[232:233], v[160:161], v[160:161], v[232:233]
	v_pk_fma_f32 v[234:235], v[162:163], v[162:163], v[234:235]
	v_pk_fma_f32 v[236:237], v[164:165], v[164:165], v[236:237]
	v_pk_fma_f32 v[238:239], v[166:167], v[166:167], v[238:239]
	v_pk_add_f32 v[232:233], v[232:233], v[234:235]
	v_pk_add_f32 v[236:237], v[236:237], v[238:239]
	v_pk_add_f32 v[232:233], v[232:233], v[236:237]
	v_add_f32_e32 v240, v232, v233
	s_nop 1
	v_add_f32_dpp v240, v240, v240 quad_perm:[1,0,3,2] row_mask:0xf bank_mask:0xf
	s_nop 1
	v_add_f32_dpp v240, v240, v240 quad_perm:[2,3,0,1] row_mask:0xf bank_mask:0xf
	s_nop 1
	v_add_f32_dpp v240, v240, v240 row_half_mirror row_mask:0xf bank_mask:0xf
	s_nop 1
	v_add_f32_dpp v240, v240, v240 row_mirror row_mask:0xf bank_mask:0xf
	s_nop 1
	v_readlane_b32 s0, v240, 0
	v_readlane_b32 s1, v240, 16
	v_readlane_b32 s4, v240, 32
	v_readlane_b32 s5, v240, 48
	v_mov_b32_e32 v249, 0x358637bd
	s_nop 1
	v_mov_b32_e32 v240, s0
	v_add_f32_e32 v240, s1, v240
	v_add_f32_e32 v240, s4, v240
	v_add_f32_e32 v240, s5, v240
	v_fmamk_f32 v240, v240, 0x3a000000, v249
	s_mov_b32 s0, 0xf800000
	v_mul_f32_e32 v241, 0x4f800000, v240
	v_cmp_gt_f32_e32 vcc, s0, v240
	s_nop 1
	v_cndmask_b32_e32 v240, v240, v241, vcc
	v_sqrt_f32_e32 v241, v240
	s_nop 0
	v_add_u32_e32 v242, -1, v241
	v_fma_f32 v243, -v242, v241, v240
	v_cmp_ge_f32_e64 s[0:1], 0, v243
	v_add_u32_e32 v243, 1, v241
	s_nop 0
	v_cndmask_b32_e64 v242, v241, v242, s[0:1]
	v_fma_f32 v241, -v243, v241, v240
	v_cmp_lt_f32_e64 s[0:1], 0, v241
	s_nop 1
	v_cndmask_b32_e64 v241, v242, v243, s[0:1]
	v_mul_f32_e32 v242, 0x37800000, v241
	v_cndmask_b32_e32 v241, v241, v242, vcc
	v_cmp_class_f32_e32 vcc, v240, v248
	s_nop 1
	v_cndmask_b32_e32 v240, v241, v240, vcc
	v_div_scale_f32 v241, s[0:1], v240, v240, 1.0
	v_rcp_f32_e32 v242, v241
	s_nop 0
	v_fma_f32 v243, -v241, v242, 1.0
	v_fmac_f32_e32 v242, v243, v242
	v_div_scale_f32 v243, vcc, 1.0, v240, 1.0
	v_mul_f32_e32 v244, v243, v242
	v_fma_f32 v247, -v241, v244, v243
	v_fmac_f32_e32 v244, v247, v242
	v_fma_f32 v241, -v241, v244, v243
	s_nop 1
	v_div_fmas_f32 v241, v241, v242, v244
	v_div_fixup_f32 v246, v241, v240, 1.0
	v_pk_mul_f32 v[136:137], v[136:137], v[246:247] op_sel_hi:[1,0]
	v_pk_mul_f32 v[138:139], v[138:139], v[246:247] op_sel_hi:[1,0]
	v_pk_mul_f32 v[140:141], v[140:141], v[246:247] op_sel_hi:[1,0]
	v_pk_mul_f32 v[142:143], v[142:143], v[246:247] op_sel_hi:[1,0]
	v_pk_mul_f32 v[144:145], v[144:145], v[246:247] op_sel_hi:[1,0]
	v_pk_mul_f32 v[146:147], v[146:147], v[246:247] op_sel_hi:[1,0]
	v_pk_mul_f32 v[148:149], v[148:149], v[246:247] op_sel_hi:[1,0]
	v_pk_mul_f32 v[150:151], v[150:151], v[246:247] op_sel_hi:[1,0]
	v_pk_mul_f32 v[152:153], v[152:153], v[246:247] op_sel_hi:[1,0]
	v_pk_mul_f32 v[154:155], v[154:155], v[246:247] op_sel_hi:[1,0]
	v_pk_mul_f32 v[156:157], v[156:157], v[246:247] op_sel_hi:[1,0]
	v_pk_mul_f32 v[158:159], v[158:159], v[246:247] op_sel_hi:[1,0]
	v_pk_mul_f32 v[160:161], v[160:161], v[246:247] op_sel_hi:[1,0]
	v_pk_mul_f32 v[162:163], v[162:163], v[246:247] op_sel_hi:[1,0]
	v_pk_mul_f32 v[164:165], v[164:165], v[246:247] op_sel_hi:[1,0]
	v_pk_mul_f32 v[166:167], v[166:167], v[246:247] op_sel_hi:[1,0]
	s_add_u32 s8, s10, 0x60000
	s_addc_u32 s9, s11, 0
	v_pk_fma_f32 v[4:5], v[8:9], v[136:137], v[40:41]
	v_cvt_pk_bf16_f32 v232, v4, v5
	v_pk_fma_f32 v[4:5], v[10:11], v[138:139], v[42:43]
	v_cvt_pk_bf16_f32 v233, v4, v5
	v_pk_fma_f32 v[4:5], v[12:13], v[140:141], v[44:45]
	v_cvt_pk_bf16_f32 v234, v4, v5
	v_pk_fma_f32 v[4:5], v[14:15], v[142:143], v[46:47]
	v_cvt_pk_bf16_f32 v235, v4, v5
	global_store_dwordx4 v1, v[232:235], s[8:9] offset:0
	v_pk_fma_f32 v[4:5], v[16:17], v[144:145], v[48:49]
	v_cvt_pk_bf16_f32 v236, v4, v5
	v_pk_fma_f32 v[4:5], v[18:19], v[146:147], v[50:51]
	v_cvt_pk_bf16_f32 v237, v4, v5
	v_pk_fma_f32 v[4:5], v[20:21], v[148:149], v[52:53]
	v_cvt_pk_bf16_f32 v238, v4, v5
	v_pk_fma_f32 v[4:5], v[22:23], v[150:151], v[54:55]
	v_cvt_pk_bf16_f32 v239, v4, v5
	global_store_dwordx4 v1, v[236:239], s[8:9] offset:1024
	v_pk_fma_f32 v[4:5], v[24:25], v[152:153], v[56:57]
	v_cvt_pk_bf16_f32 v232, v4, v5
	v_pk_fma_f32 v[4:5], v[26:27], v[154:155], v[58:59]
	v_cvt_pk_bf16_f32 v233, v4, v5
	v_pk_fma_f32 v[4:5], v[28:29], v[156:157], v[60:61]
	v_cvt_pk_bf16_f32 v234, v4, v5
	v_pk_fma_f32 v[4:5], v[30:31], v[158:159], v[62:63]
	v_cvt_pk_bf16_f32 v235, v4, v5
	global_store_dwordx4 v1, v[232:235], s[8:9] offset:2048
	v_pk_fma_f32 v[4:5], v[32:33], v[160:161], v[64:65]
	v_cvt_pk_bf16_f32 v236, v4, v5
	v_pk_fma_f32 v[4:5], v[34:35], v[162:163], v[66:67]
	v_cvt_pk_bf16_f32 v237, v4, v5
	v_pk_fma_f32 v[4:5], v[36:37], v[164:165], v[68:69]
	v_cvt_pk_bf16_f32 v238, v4, v5
	v_pk_fma_f32 v[4:5], v[38:39], v[166:167], v[70:71]
	v_cvt_pk_bf16_f32 v239, v4, v5
	global_store_dwordx4 v1, v[236:239], s[8:9] offset:3072
	s_add_u32 s8, s12, 0x60000
	s_addc_u32 s9, s13, 0
	v_pk_fma_f32 v[136:137], v[72:73], v[136:137], v[104:105]
	v_cvt_pk_bf16_f32 v232, v136, v137
	v_pk_fma_f32 v[138:139], v[74:75], v[138:139], v[106:107]
	v_cvt_pk_bf16_f32 v233, v138, v139
	v_pk_fma_f32 v[140:141], v[76:77], v[140:141], v[108:109]
	v_cvt_pk_bf16_f32 v234, v140, v141
	v_pk_fma_f32 v[142:143], v[78:79], v[142:143], v[110:111]
	v_cvt_pk_bf16_f32 v235, v142, v143
	global_store_dwordx4 v1, v[232:235], s[8:9] offset:0
	v_pk_fma_f32 v[144:145], v[80:81], v[144:145], v[112:113]
	v_cvt_pk_bf16_f32 v236, v144, v145
	v_pk_fma_f32 v[146:147], v[82:83], v[146:147], v[114:115]
	v_cvt_pk_bf16_f32 v237, v146, v147
	v_pk_fma_f32 v[148:149], v[84:85], v[148:149], v[116:117]
	v_cvt_pk_bf16_f32 v238, v148, v149
	v_pk_fma_f32 v[150:151], v[86:87], v[150:151], v[118:119]
	v_cvt_pk_bf16_f32 v239, v150, v151
	global_store_dwordx4 v1, v[236:239], s[8:9] offset:1024
	v_pk_fma_f32 v[152:153], v[88:89], v[152:153], v[120:121]
	v_cvt_pk_bf16_f32 v232, v152, v153
	v_pk_fma_f32 v[154:155], v[90:91], v[154:155], v[122:123]
	v_cvt_pk_bf16_f32 v233, v154, v155
	v_pk_fma_f32 v[156:157], v[92:93], v[156:157], v[124:125]
	v_cvt_pk_bf16_f32 v234, v156, v157
	v_pk_fma_f32 v[158:159], v[94:95], v[158:159], v[126:127]
	v_cvt_pk_bf16_f32 v235, v158, v159
	global_store_dwordx4 v1, v[232:235], s[8:9] offset:2048
	v_pk_fma_f32 v[160:161], v[96:97], v[160:161], v[128:129]
	v_cvt_pk_bf16_f32 v236, v160, v161
	v_pk_fma_f32 v[162:163], v[98:99], v[162:163], v[130:131]
	v_cvt_pk_bf16_f32 v237, v162, v163
	v_pk_fma_f32 v[164:165], v[100:101], v[164:165], v[132:133]
	v_cvt_pk_bf16_f32 v238, v164, v165
	v_pk_fma_f32 v[166:167], v[102:103], v[166:167], v[134:135]
	v_cvt_pk_bf16_f32 v239, v166, v167
	global_store_dwordx4 v1, v[236:239], s[8:9] offset:3072
	s_waitcnt vmcnt(44)
	v_cvt_f32_f16_e32 v136, v168
	v_cvt_f32_f16_sdwa v137, v168 dst_sel:DWORD dst_unused:UNUSED_PAD src0_sel:WORD_1
	v_cvt_f32_f16_e32 v138, v169
	v_cvt_f32_f16_sdwa v139, v169 dst_sel:DWORD dst_unused:UNUSED_PAD src0_sel:WORD_1
	v_cvt_f32_f16_e32 v140, v170
	v_cvt_f32_f16_sdwa v141, v170 dst_sel:DWORD dst_unused:UNUSED_PAD src0_sel:WORD_1
	v_cvt_f32_f16_e32 v142, v171
	v_cvt_f32_f16_sdwa v143, v171 dst_sel:DWORD dst_unused:UNUSED_PAD src0_sel:WORD_1
	v_cvt_f32_f16_e32 v144, v172
	v_cvt_f32_f16_sdwa v145, v172 dst_sel:DWORD dst_unused:UNUSED_PAD src0_sel:WORD_1
	v_cvt_f32_f16_e32 v146, v173
	v_cvt_f32_f16_sdwa v147, v173 dst_sel:DWORD dst_unused:UNUSED_PAD src0_sel:WORD_1
	v_cvt_f32_f16_e32 v148, v174
	v_cvt_f32_f16_sdwa v149, v174 dst_sel:DWORD dst_unused:UNUSED_PAD src0_sel:WORD_1
	v_cvt_f32_f16_e32 v150, v175
	v_cvt_f32_f16_sdwa v151, v175 dst_sel:DWORD dst_unused:UNUSED_PAD src0_sel:WORD_1
	v_cvt_f32_f16_e32 v152, v176
	v_cvt_f32_f16_sdwa v153, v176 dst_sel:DWORD dst_unused:UNUSED_PAD src0_sel:WORD_1
	v_cvt_f32_f16_e32 v154, v177
	v_cvt_f32_f16_sdwa v155, v177 dst_sel:DWORD dst_unused:UNUSED_PAD src0_sel:WORD_1
	v_cvt_f32_f16_e32 v156, v178
	v_cvt_f32_f16_sdwa v157, v178 dst_sel:DWORD dst_unused:UNUSED_PAD src0_sel:WORD_1
	v_cvt_f32_f16_e32 v158, v179
	v_cvt_f32_f16_sdwa v159, v179 dst_sel:DWORD dst_unused:UNUSED_PAD src0_sel:WORD_1
	v_cvt_f32_f16_e32 v160, v180
	v_cvt_f32_f16_sdwa v161, v180 dst_sel:DWORD dst_unused:UNUSED_PAD src0_sel:WORD_1
	v_cvt_f32_f16_e32 v162, v181
	v_cvt_f32_f16_sdwa v163, v181 dst_sel:DWORD dst_unused:UNUSED_PAD src0_sel:WORD_1
	v_cvt_f32_f16_e32 v164, v182
	v_cvt_f32_f16_sdwa v165, v182 dst_sel:DWORD dst_unused:UNUSED_PAD src0_sel:WORD_1
	v_cvt_f32_f16_e32 v166, v183
	v_cvt_f32_f16_sdwa v167, v183 dst_sel:DWORD dst_unused:UNUSED_PAD src0_sel:WORD_1
	v_pk_mul_f32 v[232:233], v[136:137], v[136:137]
	v_pk_mul_f32 v[234:235], v[138:139], v[138:139]
	v_pk_mul_f32 v[236:237], v[140:141], v[140:141]
	v_pk_mul_f32 v[238:239], v[142:143], v[142:143]
	v_pk_fma_f32 v[232:233], v[144:145], v[144:145], v[232:233]
	v_pk_fma_f32 v[234:235], v[146:147], v[146:147], v[234:235]
	v_pk_fma_f32 v[236:237], v[148:149], v[148:149], v[236:237]
	v_pk_fma_f32 v[238:239], v[150:151], v[150:151], v[238:239]
	v_pk_fma_f32 v[232:233], v[152:153], v[152:153], v[232:233]
	v_pk_fma_f32 v[234:235], v[154:155], v[154:155], v[234:235]
	v_pk_fma_f32 v[236:237], v[156:157], v[156:157], v[236:237]
	v_pk_fma_f32 v[238:239], v[158:159], v[158:159], v[238:239]
	v_pk_fma_f32 v[232:233], v[160:161], v[160:161], v[232:233]
	v_pk_fma_f32 v[234:235], v[162:163], v[162:163], v[234:235]
	v_pk_fma_f32 v[236:237], v[164:165], v[164:165], v[236:237]
	v_pk_fma_f32 v[238:239], v[166:167], v[166:167], v[238:239]
	v_pk_add_f32 v[232:233], v[232:233], v[234:235]
	v_pk_add_f32 v[236:237], v[236:237], v[238:239]
	v_pk_add_f32 v[232:233], v[232:233], v[236:237]
	v_add_f32_e32 v240, v232, v233
	s_nop 1
	v_add_f32_dpp v240, v240, v240 quad_perm:[1,0,3,2] row_mask:0xf bank_mask:0xf
	s_nop 1
	v_add_f32_dpp v240, v240, v240 quad_perm:[2,3,0,1] row_mask:0xf bank_mask:0xf
	s_nop 1
	v_add_f32_dpp v240, v240, v240 row_half_mirror row_mask:0xf bank_mask:0xf
	s_nop 1
	v_add_f32_dpp v240, v240, v240 row_mirror row_mask:0xf bank_mask:0xf
	s_nop 1
	v_readlane_b32 s0, v240, 0
	v_readlane_b32 s1, v240, 16
	v_readlane_b32 s4, v240, 32
	v_readlane_b32 s5, v240, 48
	v_mov_b32_e32 v249, 0x358637bd
	s_nop 1
	v_mov_b32_e32 v240, s0
	v_add_f32_e32 v240, s1, v240
	v_add_f32_e32 v240, s4, v240
	v_add_f32_e32 v240, s5, v240
	v_fmamk_f32 v240, v240, 0x3a000000, v249
	s_mov_b32 s0, 0xf800000
	v_mul_f32_e32 v241, 0x4f800000, v240
	v_cmp_gt_f32_e32 vcc, s0, v240
	s_nop 1
	v_cndmask_b32_e32 v240, v240, v241, vcc
	v_sqrt_f32_e32 v241, v240
	s_nop 0
	v_add_u32_e32 v242, -1, v241
	v_fma_f32 v243, -v242, v241, v240
	v_cmp_ge_f32_e64 s[0:1], 0, v243
	v_add_u32_e32 v243, 1, v241
	s_nop 0
	v_cndmask_b32_e64 v242, v241, v242, s[0:1]
	v_fma_f32 v241, -v243, v241, v240
	v_cmp_lt_f32_e64 s[0:1], 0, v241
	s_nop 1
	v_cndmask_b32_e64 v241, v242, v243, s[0:1]
	v_mul_f32_e32 v242, 0x37800000, v241
	v_cndmask_b32_e32 v241, v241, v242, vcc
	v_cmp_class_f32_e32 vcc, v240, v248
	s_nop 1
	v_cndmask_b32_e32 v240, v241, v240, vcc
	v_div_scale_f32 v241, s[0:1], v240, v240, 1.0
	v_rcp_f32_e32 v242, v241
	s_nop 0
	v_fma_f32 v243, -v241, v242, 1.0
	v_fmac_f32_e32 v242, v243, v242
	v_div_scale_f32 v243, vcc, 1.0, v240, 1.0
	v_mul_f32_e32 v244, v243, v242
	v_fma_f32 v247, -v241, v244, v243
	v_fmac_f32_e32 v244, v247, v242
	v_fma_f32 v241, -v241, v244, v243
	s_nop 1
	v_div_fmas_f32 v241, v241, v242, v244
	v_div_fixup_f32 v246, v241, v240, 1.0
	v_pk_mul_f32 v[136:137], v[136:137], v[246:247] op_sel_hi:[1,0]
	v_pk_mul_f32 v[138:139], v[138:139], v[246:247] op_sel_hi:[1,0]
	v_pk_mul_f32 v[140:141], v[140:141], v[246:247] op_sel_hi:[1,0]
	v_pk_mul_f32 v[142:143], v[142:143], v[246:247] op_sel_hi:[1,0]
	v_pk_mul_f32 v[144:145], v[144:145], v[246:247] op_sel_hi:[1,0]
	v_pk_mul_f32 v[146:147], v[146:147], v[246:247] op_sel_hi:[1,0]
	v_pk_mul_f32 v[148:149], v[148:149], v[246:247] op_sel_hi:[1,0]
	v_pk_mul_f32 v[150:151], v[150:151], v[246:247] op_sel_hi:[1,0]
	v_pk_mul_f32 v[152:153], v[152:153], v[246:247] op_sel_hi:[1,0]
	v_pk_mul_f32 v[154:155], v[154:155], v[246:247] op_sel_hi:[1,0]
	v_pk_mul_f32 v[156:157], v[156:157], v[246:247] op_sel_hi:[1,0]
	v_pk_mul_f32 v[158:159], v[158:159], v[246:247] op_sel_hi:[1,0]
	v_pk_mul_f32 v[160:161], v[160:161], v[246:247] op_sel_hi:[1,0]
	v_pk_mul_f32 v[162:163], v[162:163], v[246:247] op_sel_hi:[1,0]
	v_pk_mul_f32 v[164:165], v[164:165], v[246:247] op_sel_hi:[1,0]
	v_pk_mul_f32 v[166:167], v[166:167], v[246:247] op_sel_hi:[1,0]
	s_add_u32 s8, s10, 0x80000
	s_addc_u32 s9, s11, 0
	v_pk_fma_f32 v[4:5], v[8:9], v[136:137], v[40:41]
	v_cvt_pk_bf16_f32 v232, v4, v5
	v_pk_fma_f32 v[4:5], v[10:11], v[138:139], v[42:43]
	v_cvt_pk_bf16_f32 v233, v4, v5
	v_pk_fma_f32 v[4:5], v[12:13], v[140:141], v[44:45]
	v_cvt_pk_bf16_f32 v234, v4, v5
	v_pk_fma_f32 v[4:5], v[14:15], v[142:143], v[46:47]
	v_cvt_pk_bf16_f32 v235, v4, v5
	global_store_dwordx4 v1, v[232:235], s[8:9] offset:0
	v_pk_fma_f32 v[4:5], v[16:17], v[144:145], v[48:49]
	v_cvt_pk_bf16_f32 v236, v4, v5
	v_pk_fma_f32 v[4:5], v[18:19], v[146:147], v[50:51]
	v_cvt_pk_bf16_f32 v237, v4, v5
	v_pk_fma_f32 v[4:5], v[20:21], v[148:149], v[52:53]
	v_cvt_pk_bf16_f32 v238, v4, v5
	v_pk_fma_f32 v[4:5], v[22:23], v[150:151], v[54:55]
	v_cvt_pk_bf16_f32 v239, v4, v5
	global_store_dwordx4 v1, v[236:239], s[8:9] offset:1024
	v_pk_fma_f32 v[4:5], v[24:25], v[152:153], v[56:57]
	v_cvt_pk_bf16_f32 v232, v4, v5
	v_pk_fma_f32 v[4:5], v[26:27], v[154:155], v[58:59]
	v_cvt_pk_bf16_f32 v233, v4, v5
	v_pk_fma_f32 v[4:5], v[28:29], v[156:157], v[60:61]
	v_cvt_pk_bf16_f32 v234, v4, v5
	v_pk_fma_f32 v[4:5], v[30:31], v[158:159], v[62:63]
	v_cvt_pk_bf16_f32 v235, v4, v5
	global_store_dwordx4 v1, v[232:235], s[8:9] offset:2048
	v_pk_fma_f32 v[4:5], v[32:33], v[160:161], v[64:65]
	v_cvt_pk_bf16_f32 v236, v4, v5
	v_pk_fma_f32 v[4:5], v[34:35], v[162:163], v[66:67]
	v_cvt_pk_bf16_f32 v237, v4, v5
	v_pk_fma_f32 v[4:5], v[36:37], v[164:165], v[68:69]
	v_cvt_pk_bf16_f32 v238, v4, v5
	v_pk_fma_f32 v[4:5], v[38:39], v[166:167], v[70:71]
	v_cvt_pk_bf16_f32 v239, v4, v5
	global_store_dwordx4 v1, v[236:239], s[8:9] offset:3072
	s_add_u32 s8, s12, 0x80000
	s_addc_u32 s9, s13, 0
	v_pk_fma_f32 v[136:137], v[72:73], v[136:137], v[104:105]
	v_cvt_pk_bf16_f32 v232, v136, v137
	v_pk_fma_f32 v[138:139], v[74:75], v[138:139], v[106:107]
	v_cvt_pk_bf16_f32 v233, v138, v139
	v_pk_fma_f32 v[140:141], v[76:77], v[140:141], v[108:109]
	v_cvt_pk_bf16_f32 v234, v140, v141
	v_pk_fma_f32 v[142:143], v[78:79], v[142:143], v[110:111]
	v_cvt_pk_bf16_f32 v235, v142, v143
	global_store_dwordx4 v1, v[232:235], s[8:9] offset:0
	v_pk_fma_f32 v[144:145], v[80:81], v[144:145], v[112:113]
	v_cvt_pk_bf16_f32 v236, v144, v145
	v_pk_fma_f32 v[146:147], v[82:83], v[146:147], v[114:115]
	v_cvt_pk_bf16_f32 v237, v146, v147
	v_pk_fma_f32 v[148:149], v[84:85], v[148:149], v[116:117]
	v_cvt_pk_bf16_f32 v238, v148, v149
	v_pk_fma_f32 v[150:151], v[86:87], v[150:151], v[118:119]
	v_cvt_pk_bf16_f32 v239, v150, v151
	global_store_dwordx4 v1, v[236:239], s[8:9] offset:1024
	v_pk_fma_f32 v[152:153], v[88:89], v[152:153], v[120:121]
	v_cvt_pk_bf16_f32 v232, v152, v153
	v_pk_fma_f32 v[154:155], v[90:91], v[154:155], v[122:123]
	v_cvt_pk_bf16_f32 v233, v154, v155
	v_pk_fma_f32 v[156:157], v[92:93], v[156:157], v[124:125]
	v_cvt_pk_bf16_f32 v234, v156, v157
	v_pk_fma_f32 v[158:159], v[94:95], v[158:159], v[126:127]
	v_cvt_pk_bf16_f32 v235, v158, v159
	global_store_dwordx4 v1, v[232:235], s[8:9] offset:2048
	v_pk_fma_f32 v[160:161], v[96:97], v[160:161], v[128:129]
	v_cvt_pk_bf16_f32 v236, v160, v161
	v_pk_fma_f32 v[162:163], v[98:99], v[162:163], v[130:131]
	v_cvt_pk_bf16_f32 v237, v162, v163
	v_pk_fma_f32 v[164:165], v[100:101], v[164:165], v[132:133]
	v_cvt_pk_bf16_f32 v238, v164, v165
	v_pk_fma_f32 v[166:167], v[102:103], v[166:167], v[134:135]
	v_cvt_pk_bf16_f32 v239, v166, v167
	global_store_dwordx4 v1, v[236:239], s[8:9] offset:3072
	s_waitcnt vmcnt(40)
	v_cvt_f32_f16_e32 v136, v184
	v_cvt_f32_f16_sdwa v137, v184 dst_sel:DWORD dst_unused:UNUSED_PAD src0_sel:WORD_1
	v_cvt_f32_f16_e32 v138, v185
	v_cvt_f32_f16_sdwa v139, v185 dst_sel:DWORD dst_unused:UNUSED_PAD src0_sel:WORD_1
	v_cvt_f32_f16_e32 v140, v186
	v_cvt_f32_f16_sdwa v141, v186 dst_sel:DWORD dst_unused:UNUSED_PAD src0_sel:WORD_1
	v_cvt_f32_f16_e32 v142, v187
	v_cvt_f32_f16_sdwa v143, v187 dst_sel:DWORD dst_unused:UNUSED_PAD src0_sel:WORD_1
	v_cvt_f32_f16_e32 v144, v188
	v_cvt_f32_f16_sdwa v145, v188 dst_sel:DWORD dst_unused:UNUSED_PAD src0_sel:WORD_1
	v_cvt_f32_f16_e32 v146, v189
	v_cvt_f32_f16_sdwa v147, v189 dst_sel:DWORD dst_unused:UNUSED_PAD src0_sel:WORD_1
	v_cvt_f32_f16_e32 v148, v190
	v_cvt_f32_f16_sdwa v149, v190 dst_sel:DWORD dst_unused:UNUSED_PAD src0_sel:WORD_1
	v_cvt_f32_f16_e32 v150, v191
	v_cvt_f32_f16_sdwa v151, v191 dst_sel:DWORD dst_unused:UNUSED_PAD src0_sel:WORD_1
	v_cvt_f32_f16_e32 v152, v192
	v_cvt_f32_f16_sdwa v153, v192 dst_sel:DWORD dst_unused:UNUSED_PAD src0_sel:WORD_1
	v_cvt_f32_f16_e32 v154, v193
	v_cvt_f32_f16_sdwa v155, v193 dst_sel:DWORD dst_unused:UNUSED_PAD src0_sel:WORD_1
	v_cvt_f32_f16_e32 v156, v194
	v_cvt_f32_f16_sdwa v157, v194 dst_sel:DWORD dst_unused:UNUSED_PAD src0_sel:WORD_1
	v_cvt_f32_f16_e32 v158, v195
	v_cvt_f32_f16_sdwa v159, v195 dst_sel:DWORD dst_unused:UNUSED_PAD src0_sel:WORD_1
	v_cvt_f32_f16_e32 v160, v196
	v_cvt_f32_f16_sdwa v161, v196 dst_sel:DWORD dst_unused:UNUSED_PAD src0_sel:WORD_1
	v_cvt_f32_f16_e32 v162, v197
	v_cvt_f32_f16_sdwa v163, v197 dst_sel:DWORD dst_unused:UNUSED_PAD src0_sel:WORD_1
	v_cvt_f32_f16_e32 v164, v198
	v_cvt_f32_f16_sdwa v165, v198 dst_sel:DWORD dst_unused:UNUSED_PAD src0_sel:WORD_1
	v_cvt_f32_f16_e32 v166, v199
	v_cvt_f32_f16_sdwa v167, v199 dst_sel:DWORD dst_unused:UNUSED_PAD src0_sel:WORD_1
	v_pk_mul_f32 v[232:233], v[136:137], v[136:137]
	v_pk_mul_f32 v[234:235], v[138:139], v[138:139]
	v_pk_mul_f32 v[236:237], v[140:141], v[140:141]
	v_pk_mul_f32 v[238:239], v[142:143], v[142:143]
	v_pk_fma_f32 v[232:233], v[144:145], v[144:145], v[232:233]
	v_pk_fma_f32 v[234:235], v[146:147], v[146:147], v[234:235]
	v_pk_fma_f32 v[236:237], v[148:149], v[148:149], v[236:237]
	v_pk_fma_f32 v[238:239], v[150:151], v[150:151], v[238:239]
	v_pk_fma_f32 v[232:233], v[152:153], v[152:153], v[232:233]
	v_pk_fma_f32 v[234:235], v[154:155], v[154:155], v[234:235]
	v_pk_fma_f32 v[236:237], v[156:157], v[156:157], v[236:237]
	v_pk_fma_f32 v[238:239], v[158:159], v[158:159], v[238:239]
	v_pk_fma_f32 v[232:233], v[160:161], v[160:161], v[232:233]
	v_pk_fma_f32 v[234:235], v[162:163], v[162:163], v[234:235]
	v_pk_fma_f32 v[236:237], v[164:165], v[164:165], v[236:237]
	v_pk_fma_f32 v[238:239], v[166:167], v[166:167], v[238:239]
	v_pk_add_f32 v[232:233], v[232:233], v[234:235]
	v_pk_add_f32 v[236:237], v[236:237], v[238:239]
	v_pk_add_f32 v[232:233], v[232:233], v[236:237]
	v_add_f32_e32 v240, v232, v233
	s_nop 1
	v_add_f32_dpp v240, v240, v240 quad_perm:[1,0,3,2] row_mask:0xf bank_mask:0xf
	s_nop 1
	v_add_f32_dpp v240, v240, v240 quad_perm:[2,3,0,1] row_mask:0xf bank_mask:0xf
	s_nop 1
	v_add_f32_dpp v240, v240, v240 row_half_mirror row_mask:0xf bank_mask:0xf
	s_nop 1
	v_add_f32_dpp v240, v240, v240 row_mirror row_mask:0xf bank_mask:0xf
	s_nop 1
	v_readlane_b32 s0, v240, 0
	v_readlane_b32 s1, v240, 16
	v_readlane_b32 s4, v240, 32
	v_readlane_b32 s5, v240, 48
	v_mov_b32_e32 v249, 0x358637bd
	s_nop 1
	v_mov_b32_e32 v240, s0
	v_add_f32_e32 v240, s1, v240
	v_add_f32_e32 v240, s4, v240
	v_add_f32_e32 v240, s5, v240
	v_fmamk_f32 v240, v240, 0x3a000000, v249
	s_mov_b32 s0, 0xf800000
	v_mul_f32_e32 v241, 0x4f800000, v240
	v_cmp_gt_f32_e32 vcc, s0, v240
	s_nop 1
	v_cndmask_b32_e32 v240, v240, v241, vcc
	v_sqrt_f32_e32 v241, v240
	s_nop 0
	v_add_u32_e32 v242, -1, v241
	v_fma_f32 v243, -v242, v241, v240
	v_cmp_ge_f32_e64 s[0:1], 0, v243
	v_add_u32_e32 v243, 1, v241
	s_nop 0
	v_cndmask_b32_e64 v242, v241, v242, s[0:1]
	v_fma_f32 v241, -v243, v241, v240
	v_cmp_lt_f32_e64 s[0:1], 0, v241
	s_nop 1
	v_cndmask_b32_e64 v241, v242, v243, s[0:1]
	v_mul_f32_e32 v242, 0x37800000, v241
	v_cndmask_b32_e32 v241, v241, v242, vcc
	v_cmp_class_f32_e32 vcc, v240, v248
	s_nop 1
	v_cndmask_b32_e32 v240, v241, v240, vcc
	v_div_scale_f32 v241, s[0:1], v240, v240, 1.0
	v_rcp_f32_e32 v242, v241
	s_nop 0
	v_fma_f32 v243, -v241, v242, 1.0
	v_fmac_f32_e32 v242, v243, v242
	v_div_scale_f32 v243, vcc, 1.0, v240, 1.0
	v_mul_f32_e32 v244, v243, v242
	v_fma_f32 v247, -v241, v244, v243
	v_fmac_f32_e32 v244, v247, v242
	v_fma_f32 v241, -v241, v244, v243
	s_nop 1
	v_div_fmas_f32 v241, v241, v242, v244
	v_div_fixup_f32 v246, v241, v240, 1.0
	v_pk_mul_f32 v[136:137], v[136:137], v[246:247] op_sel_hi:[1,0]
	v_pk_mul_f32 v[138:139], v[138:139], v[246:247] op_sel_hi:[1,0]
	v_pk_mul_f32 v[140:141], v[140:141], v[246:247] op_sel_hi:[1,0]
	v_pk_mul_f32 v[142:143], v[142:143], v[246:247] op_sel_hi:[1,0]
	v_pk_mul_f32 v[144:145], v[144:145], v[246:247] op_sel_hi:[1,0]
	v_pk_mul_f32 v[146:147], v[146:147], v[246:247] op_sel_hi:[1,0]
	v_pk_mul_f32 v[148:149], v[148:149], v[246:247] op_sel_hi:[1,0]
	v_pk_mul_f32 v[150:151], v[150:151], v[246:247] op_sel_hi:[1,0]
	v_pk_mul_f32 v[152:153], v[152:153], v[246:247] op_sel_hi:[1,0]
	v_pk_mul_f32 v[154:155], v[154:155], v[246:247] op_sel_hi:[1,0]
	v_pk_mul_f32 v[156:157], v[156:157], v[246:247] op_sel_hi:[1,0]
	v_pk_mul_f32 v[158:159], v[158:159], v[246:247] op_sel_hi:[1,0]
	v_pk_mul_f32 v[160:161], v[160:161], v[246:247] op_sel_hi:[1,0]
	v_pk_mul_f32 v[162:163], v[162:163], v[246:247] op_sel_hi:[1,0]
	v_pk_mul_f32 v[164:165], v[164:165], v[246:247] op_sel_hi:[1,0]
	v_pk_mul_f32 v[166:167], v[166:167], v[246:247] op_sel_hi:[1,0]
	s_add_u32 s8, s10, 0xa0000
	s_addc_u32 s9, s11, 0
	v_pk_fma_f32 v[4:5], v[8:9], v[136:137], v[40:41]
	v_cvt_pk_bf16_f32 v232, v4, v5
	v_pk_fma_f32 v[4:5], v[10:11], v[138:139], v[42:43]
	v_cvt_pk_bf16_f32 v233, v4, v5
	v_pk_fma_f32 v[4:5], v[12:13], v[140:141], v[44:45]
	v_cvt_pk_bf16_f32 v234, v4, v5
	v_pk_fma_f32 v[4:5], v[14:15], v[142:143], v[46:47]
	v_cvt_pk_bf16_f32 v235, v4, v5
	global_store_dwordx4 v1, v[232:235], s[8:9] offset:0
	v_pk_fma_f32 v[4:5], v[16:17], v[144:145], v[48:49]
	v_cvt_pk_bf16_f32 v236, v4, v5
	v_pk_fma_f32 v[4:5], v[18:19], v[146:147], v[50:51]
	v_cvt_pk_bf16_f32 v237, v4, v5
	v_pk_fma_f32 v[4:5], v[20:21], v[148:149], v[52:53]
	v_cvt_pk_bf16_f32 v238, v4, v5
	v_pk_fma_f32 v[4:5], v[22:23], v[150:151], v[54:55]
	v_cvt_pk_bf16_f32 v239, v4, v5
	global_store_dwordx4 v1, v[236:239], s[8:9] offset:1024
	v_pk_fma_f32 v[4:5], v[24:25], v[152:153], v[56:57]
	v_cvt_pk_bf16_f32 v232, v4, v5
	v_pk_fma_f32 v[4:5], v[26:27], v[154:155], v[58:59]
	v_cvt_pk_bf16_f32 v233, v4, v5
	v_pk_fma_f32 v[4:5], v[28:29], v[156:157], v[60:61]
	v_cvt_pk_bf16_f32 v234, v4, v5
	v_pk_fma_f32 v[4:5], v[30:31], v[158:159], v[62:63]
	v_cvt_pk_bf16_f32 v235, v4, v5
	global_store_dwordx4 v1, v[232:235], s[8:9] offset:2048
	v_pk_fma_f32 v[4:5], v[32:33], v[160:161], v[64:65]
	v_cvt_pk_bf16_f32 v236, v4, v5
	v_pk_fma_f32 v[4:5], v[34:35], v[162:163], v[66:67]
	v_cvt_pk_bf16_f32 v237, v4, v5
	v_pk_fma_f32 v[4:5], v[36:37], v[164:165], v[68:69]
	v_cvt_pk_bf16_f32 v238, v4, v5
	v_pk_fma_f32 v[4:5], v[38:39], v[166:167], v[70:71]
	v_cvt_pk_bf16_f32 v239, v4, v5
	global_store_dwordx4 v1, v[236:239], s[8:9] offset:3072
	s_add_u32 s8, s12, 0xa0000
	s_addc_u32 s9, s13, 0
	v_pk_fma_f32 v[136:137], v[72:73], v[136:137], v[104:105]
	v_cvt_pk_bf16_f32 v232, v136, v137
	v_pk_fma_f32 v[138:139], v[74:75], v[138:139], v[106:107]
	v_cvt_pk_bf16_f32 v233, v138, v139
	v_pk_fma_f32 v[140:141], v[76:77], v[140:141], v[108:109]
	v_cvt_pk_bf16_f32 v234, v140, v141
	v_pk_fma_f32 v[142:143], v[78:79], v[142:143], v[110:111]
	v_cvt_pk_bf16_f32 v235, v142, v143
	global_store_dwordx4 v1, v[232:235], s[8:9] offset:0
	v_pk_fma_f32 v[144:145], v[80:81], v[144:145], v[112:113]
	v_cvt_pk_bf16_f32 v236, v144, v145
	v_pk_fma_f32 v[146:147], v[82:83], v[146:147], v[114:115]
	v_cvt_pk_bf16_f32 v237, v146, v147
	v_pk_fma_f32 v[148:149], v[84:85], v[148:149], v[116:117]
	v_cvt_pk_bf16_f32 v238, v148, v149
	v_pk_fma_f32 v[150:151], v[86:87], v[150:151], v[118:119]
	v_cvt_pk_bf16_f32 v239, v150, v151
	global_store_dwordx4 v1, v[236:239], s[8:9] offset:1024
	v_pk_fma_f32 v[152:153], v[88:89], v[152:153], v[120:121]
	v_cvt_pk_bf16_f32 v232, v152, v153
	v_pk_fma_f32 v[154:155], v[90:91], v[154:155], v[122:123]
	v_cvt_pk_bf16_f32 v233, v154, v155
	v_pk_fma_f32 v[156:157], v[92:93], v[156:157], v[124:125]
	v_cvt_pk_bf16_f32 v234, v156, v157
	v_pk_fma_f32 v[158:159], v[94:95], v[158:159], v[126:127]
	v_cvt_pk_bf16_f32 v235, v158, v159
	global_store_dwordx4 v1, v[232:235], s[8:9] offset:2048
	v_pk_fma_f32 v[160:161], v[96:97], v[160:161], v[128:129]
	v_cvt_pk_bf16_f32 v236, v160, v161
	v_pk_fma_f32 v[162:163], v[98:99], v[162:163], v[130:131]
	v_cvt_pk_bf16_f32 v237, v162, v163
	v_pk_fma_f32 v[164:165], v[100:101], v[164:165], v[132:133]
	v_cvt_pk_bf16_f32 v238, v164, v165
	v_pk_fma_f32 v[166:167], v[102:103], v[166:167], v[134:135]
	v_cvt_pk_bf16_f32 v239, v166, v167
	global_store_dwordx4 v1, v[236:239], s[8:9] offset:3072
	s_waitcnt vmcnt(36)
	v_cvt_f32_f16_e32 v136, v200
	v_cvt_f32_f16_sdwa v137, v200 dst_sel:DWORD dst_unused:UNUSED_PAD src0_sel:WORD_1
	v_cvt_f32_f16_e32 v138, v201
	v_cvt_f32_f16_sdwa v139, v201 dst_sel:DWORD dst_unused:UNUSED_PAD src0_sel:WORD_1
	v_cvt_f32_f16_e32 v140, v202
	v_cvt_f32_f16_sdwa v141, v202 dst_sel:DWORD dst_unused:UNUSED_PAD src0_sel:WORD_1
	v_cvt_f32_f16_e32 v142, v203
	v_cvt_f32_f16_sdwa v143, v203 dst_sel:DWORD dst_unused:UNUSED_PAD src0_sel:WORD_1
	v_cvt_f32_f16_e32 v144, v204
	v_cvt_f32_f16_sdwa v145, v204 dst_sel:DWORD dst_unused:UNUSED_PAD src0_sel:WORD_1
	v_cvt_f32_f16_e32 v146, v205
	v_cvt_f32_f16_sdwa v147, v205 dst_sel:DWORD dst_unused:UNUSED_PAD src0_sel:WORD_1
	v_cvt_f32_f16_e32 v148, v206
	v_cvt_f32_f16_sdwa v149, v206 dst_sel:DWORD dst_unused:UNUSED_PAD src0_sel:WORD_1
	v_cvt_f32_f16_e32 v150, v207
	v_cvt_f32_f16_sdwa v151, v207 dst_sel:DWORD dst_unused:UNUSED_PAD src0_sel:WORD_1
	v_cvt_f32_f16_e32 v152, v208
	v_cvt_f32_f16_sdwa v153, v208 dst_sel:DWORD dst_unused:UNUSED_PAD src0_sel:WORD_1
	v_cvt_f32_f16_e32 v154, v209
	v_cvt_f32_f16_sdwa v155, v209 dst_sel:DWORD dst_unused:UNUSED_PAD src0_sel:WORD_1
	v_cvt_f32_f16_e32 v156, v210
	v_cvt_f32_f16_sdwa v157, v210 dst_sel:DWORD dst_unused:UNUSED_PAD src0_sel:WORD_1
	v_cvt_f32_f16_e32 v158, v211
	v_cvt_f32_f16_sdwa v159, v211 dst_sel:DWORD dst_unused:UNUSED_PAD src0_sel:WORD_1
	v_cvt_f32_f16_e32 v160, v212
	v_cvt_f32_f16_sdwa v161, v212 dst_sel:DWORD dst_unused:UNUSED_PAD src0_sel:WORD_1
	v_cvt_f32_f16_e32 v162, v213
	v_cvt_f32_f16_sdwa v163, v213 dst_sel:DWORD dst_unused:UNUSED_PAD src0_sel:WORD_1
	v_cvt_f32_f16_e32 v164, v214
	v_cvt_f32_f16_sdwa v165, v214 dst_sel:DWORD dst_unused:UNUSED_PAD src0_sel:WORD_1
	v_cvt_f32_f16_e32 v166, v215
	v_cvt_f32_f16_sdwa v167, v215 dst_sel:DWORD dst_unused:UNUSED_PAD src0_sel:WORD_1
	v_pk_mul_f32 v[232:233], v[136:137], v[136:137]
	v_pk_mul_f32 v[234:235], v[138:139], v[138:139]
	v_pk_mul_f32 v[236:237], v[140:141], v[140:141]
	v_pk_mul_f32 v[238:239], v[142:143], v[142:143]
	v_pk_fma_f32 v[232:233], v[144:145], v[144:145], v[232:233]
	v_pk_fma_f32 v[234:235], v[146:147], v[146:147], v[234:235]
	v_pk_fma_f32 v[236:237], v[148:149], v[148:149], v[236:237]
	v_pk_fma_f32 v[238:239], v[150:151], v[150:151], v[238:239]
	v_pk_fma_f32 v[232:233], v[152:153], v[152:153], v[232:233]
	v_pk_fma_f32 v[234:235], v[154:155], v[154:155], v[234:235]
	v_pk_fma_f32 v[236:237], v[156:157], v[156:157], v[236:237]
	v_pk_fma_f32 v[238:239], v[158:159], v[158:159], v[238:239]
	v_pk_fma_f32 v[232:233], v[160:161], v[160:161], v[232:233]
	v_pk_fma_f32 v[234:235], v[162:163], v[162:163], v[234:235]
	v_pk_fma_f32 v[236:237], v[164:165], v[164:165], v[236:237]
	v_pk_fma_f32 v[238:239], v[166:167], v[166:167], v[238:239]
	v_pk_add_f32 v[232:233], v[232:233], v[234:235]
	v_pk_add_f32 v[236:237], v[236:237], v[238:239]
	v_pk_add_f32 v[232:233], v[232:233], v[236:237]
	v_add_f32_e32 v240, v232, v233
	s_nop 1
	v_add_f32_dpp v240, v240, v240 quad_perm:[1,0,3,2] row_mask:0xf bank_mask:0xf
	s_nop 1
	v_add_f32_dpp v240, v240, v240 quad_perm:[2,3,0,1] row_mask:0xf bank_mask:0xf
	s_nop 1
	v_add_f32_dpp v240, v240, v240 row_half_mirror row_mask:0xf bank_mask:0xf
	s_nop 1
	v_add_f32_dpp v240, v240, v240 row_mirror row_mask:0xf bank_mask:0xf
	s_nop 1
	v_readlane_b32 s0, v240, 0
	v_readlane_b32 s1, v240, 16
	v_readlane_b32 s4, v240, 32
	v_readlane_b32 s5, v240, 48
	v_mov_b32_e32 v249, 0x358637bd
	s_nop 1
	v_mov_b32_e32 v240, s0
	v_add_f32_e32 v240, s1, v240
	v_add_f32_e32 v240, s4, v240
	v_add_f32_e32 v240, s5, v240
	v_fmamk_f32 v240, v240, 0x3a000000, v249
	s_mov_b32 s0, 0xf800000
	v_mul_f32_e32 v241, 0x4f800000, v240
	v_cmp_gt_f32_e32 vcc, s0, v240
	s_nop 1
	v_cndmask_b32_e32 v240, v240, v241, vcc
	v_sqrt_f32_e32 v241, v240
	s_nop 0
	v_add_u32_e32 v242, -1, v241
	v_fma_f32 v243, -v242, v241, v240
	v_cmp_ge_f32_e64 s[0:1], 0, v243
	v_add_u32_e32 v243, 1, v241
	s_nop 0
	v_cndmask_b32_e64 v242, v241, v242, s[0:1]
	v_fma_f32 v241, -v243, v241, v240
	v_cmp_lt_f32_e64 s[0:1], 0, v241
	s_nop 1
	v_cndmask_b32_e64 v241, v242, v243, s[0:1]
	v_mul_f32_e32 v242, 0x37800000, v241
	v_cndmask_b32_e32 v241, v241, v242, vcc
	v_cmp_class_f32_e32 vcc, v240, v248
	s_nop 1
	v_cndmask_b32_e32 v240, v241, v240, vcc
	v_div_scale_f32 v241, s[0:1], v240, v240, 1.0
	v_rcp_f32_e32 v242, v241
	s_nop 0
	v_fma_f32 v243, -v241, v242, 1.0
	v_fmac_f32_e32 v242, v243, v242
	v_div_scale_f32 v243, vcc, 1.0, v240, 1.0
	v_mul_f32_e32 v244, v243, v242
	v_fma_f32 v247, -v241, v244, v243
	v_fmac_f32_e32 v244, v247, v242
	v_fma_f32 v241, -v241, v244, v243
	s_nop 1
	v_div_fmas_f32 v241, v241, v242, v244
	v_div_fixup_f32 v246, v241, v240, 1.0
	v_pk_mul_f32 v[136:137], v[136:137], v[246:247] op_sel_hi:[1,0]
	v_pk_mul_f32 v[138:139], v[138:139], v[246:247] op_sel_hi:[1,0]
	v_pk_mul_f32 v[140:141], v[140:141], v[246:247] op_sel_hi:[1,0]
	v_pk_mul_f32 v[142:143], v[142:143], v[246:247] op_sel_hi:[1,0]
	v_pk_mul_f32 v[144:145], v[144:145], v[246:247] op_sel_hi:[1,0]
	v_pk_mul_f32 v[146:147], v[146:147], v[246:247] op_sel_hi:[1,0]
	v_pk_mul_f32 v[148:149], v[148:149], v[246:247] op_sel_hi:[1,0]
	v_pk_mul_f32 v[150:151], v[150:151], v[246:247] op_sel_hi:[1,0]
	v_pk_mul_f32 v[152:153], v[152:153], v[246:247] op_sel_hi:[1,0]
	v_pk_mul_f32 v[154:155], v[154:155], v[246:247] op_sel_hi:[1,0]
	v_pk_mul_f32 v[156:157], v[156:157], v[246:247] op_sel_hi:[1,0]
	v_pk_mul_f32 v[158:159], v[158:159], v[246:247] op_sel_hi:[1,0]
	v_pk_mul_f32 v[160:161], v[160:161], v[246:247] op_sel_hi:[1,0]
	v_pk_mul_f32 v[162:163], v[162:163], v[246:247] op_sel_hi:[1,0]
	v_pk_mul_f32 v[164:165], v[164:165], v[246:247] op_sel_hi:[1,0]
	v_pk_mul_f32 v[166:167], v[166:167], v[246:247] op_sel_hi:[1,0]
	s_add_u32 s8, s10, 0xc0000
	s_addc_u32 s9, s11, 0
	v_pk_fma_f32 v[4:5], v[8:9], v[136:137], v[40:41]
	v_cvt_pk_bf16_f32 v232, v4, v5
	v_pk_fma_f32 v[4:5], v[10:11], v[138:139], v[42:43]
	v_cvt_pk_bf16_f32 v233, v4, v5
	v_pk_fma_f32 v[4:5], v[12:13], v[140:141], v[44:45]
	v_cvt_pk_bf16_f32 v234, v4, v5
	v_pk_fma_f32 v[4:5], v[14:15], v[142:143], v[46:47]
	v_cvt_pk_bf16_f32 v235, v4, v5
	global_store_dwordx4 v1, v[232:235], s[8:9] offset:0
	v_pk_fma_f32 v[4:5], v[16:17], v[144:145], v[48:49]
	v_cvt_pk_bf16_f32 v236, v4, v5
	v_pk_fma_f32 v[4:5], v[18:19], v[146:147], v[50:51]
	v_cvt_pk_bf16_f32 v237, v4, v5
	v_pk_fma_f32 v[4:5], v[20:21], v[148:149], v[52:53]
	v_cvt_pk_bf16_f32 v238, v4, v5
	v_pk_fma_f32 v[4:5], v[22:23], v[150:151], v[54:55]
	v_cvt_pk_bf16_f32 v239, v4, v5
	global_store_dwordx4 v1, v[236:239], s[8:9] offset:1024
	v_pk_fma_f32 v[4:5], v[24:25], v[152:153], v[56:57]
	v_cvt_pk_bf16_f32 v232, v4, v5
	v_pk_fma_f32 v[4:5], v[26:27], v[154:155], v[58:59]
	v_cvt_pk_bf16_f32 v233, v4, v5
	v_pk_fma_f32 v[4:5], v[28:29], v[156:157], v[60:61]
	v_cvt_pk_bf16_f32 v234, v4, v5
	v_pk_fma_f32 v[4:5], v[30:31], v[158:159], v[62:63]
	v_cvt_pk_bf16_f32 v235, v4, v5
	global_store_dwordx4 v1, v[232:235], s[8:9] offset:2048
	v_pk_fma_f32 v[4:5], v[32:33], v[160:161], v[64:65]
	v_cvt_pk_bf16_f32 v236, v4, v5
	v_pk_fma_f32 v[4:5], v[34:35], v[162:163], v[66:67]
	v_cvt_pk_bf16_f32 v237, v4, v5
	v_pk_fma_f32 v[4:5], v[36:37], v[164:165], v[68:69]
	v_cvt_pk_bf16_f32 v238, v4, v5
	v_pk_fma_f32 v[4:5], v[38:39], v[166:167], v[70:71]
	v_cvt_pk_bf16_f32 v239, v4, v5
	global_store_dwordx4 v1, v[236:239], s[8:9] offset:3072
	s_add_u32 s8, s12, 0xc0000
	s_addc_u32 s9, s13, 0
	v_pk_fma_f32 v[136:137], v[72:73], v[136:137], v[104:105]
	v_cvt_pk_bf16_f32 v232, v136, v137
	v_pk_fma_f32 v[138:139], v[74:75], v[138:139], v[106:107]
	v_cvt_pk_bf16_f32 v233, v138, v139
	v_pk_fma_f32 v[140:141], v[76:77], v[140:141], v[108:109]
	v_cvt_pk_bf16_f32 v234, v140, v141
	v_pk_fma_f32 v[142:143], v[78:79], v[142:143], v[110:111]
	v_cvt_pk_bf16_f32 v235, v142, v143
	global_store_dwordx4 v1, v[232:235], s[8:9] offset:0
	v_pk_fma_f32 v[144:145], v[80:81], v[144:145], v[112:113]
	v_cvt_pk_bf16_f32 v236, v144, v145
	v_pk_fma_f32 v[146:147], v[82:83], v[146:147], v[114:115]
	v_cvt_pk_bf16_f32 v237, v146, v147
	v_pk_fma_f32 v[148:149], v[84:85], v[148:149], v[116:117]
	v_cvt_pk_bf16_f32 v238, v148, v149
	v_pk_fma_f32 v[150:151], v[86:87], v[150:151], v[118:119]
	v_cvt_pk_bf16_f32 v239, v150, v151
	global_store_dwordx4 v1, v[236:239], s[8:9] offset:1024
	v_pk_fma_f32 v[152:153], v[88:89], v[152:153], v[120:121]
	v_cvt_pk_bf16_f32 v232, v152, v153
	v_pk_fma_f32 v[154:155], v[90:91], v[154:155], v[122:123]
	v_cvt_pk_bf16_f32 v233, v154, v155
	v_pk_fma_f32 v[156:157], v[92:93], v[156:157], v[124:125]
	v_cvt_pk_bf16_f32 v234, v156, v157
	v_pk_fma_f32 v[158:159], v[94:95], v[158:159], v[126:127]
	v_cvt_pk_bf16_f32 v235, v158, v159
	global_store_dwordx4 v1, v[232:235], s[8:9] offset:2048
	v_pk_fma_f32 v[160:161], v[96:97], v[160:161], v[128:129]
	v_cvt_pk_bf16_f32 v236, v160, v161
	v_pk_fma_f32 v[162:163], v[98:99], v[162:163], v[130:131]
	v_cvt_pk_bf16_f32 v237, v162, v163
	v_pk_fma_f32 v[164:165], v[100:101], v[164:165], v[132:133]
	v_cvt_pk_bf16_f32 v238, v164, v165
	v_pk_fma_f32 v[166:167], v[102:103], v[166:167], v[134:135]
	v_cvt_pk_bf16_f32 v239, v166, v167
	global_store_dwordx4 v1, v[236:239], s[8:9] offset:3072
	s_waitcnt vmcnt(32)
	v_cvt_f32_f16_e32 v136, v216
	v_cvt_f32_f16_sdwa v137, v216 dst_sel:DWORD dst_unused:UNUSED_PAD src0_sel:WORD_1
	v_cvt_f32_f16_e32 v138, v217
	v_cvt_f32_f16_sdwa v139, v217 dst_sel:DWORD dst_unused:UNUSED_PAD src0_sel:WORD_1
	v_cvt_f32_f16_e32 v140, v218
	v_cvt_f32_f16_sdwa v141, v218 dst_sel:DWORD dst_unused:UNUSED_PAD src0_sel:WORD_1
	v_cvt_f32_f16_e32 v142, v219
	v_cvt_f32_f16_sdwa v143, v219 dst_sel:DWORD dst_unused:UNUSED_PAD src0_sel:WORD_1
	v_cvt_f32_f16_e32 v144, v220
	v_cvt_f32_f16_sdwa v145, v220 dst_sel:DWORD dst_unused:UNUSED_PAD src0_sel:WORD_1
	v_cvt_f32_f16_e32 v146, v221
	v_cvt_f32_f16_sdwa v147, v221 dst_sel:DWORD dst_unused:UNUSED_PAD src0_sel:WORD_1
	v_cvt_f32_f16_e32 v148, v222
	v_cvt_f32_f16_sdwa v149, v222 dst_sel:DWORD dst_unused:UNUSED_PAD src0_sel:WORD_1
	v_cvt_f32_f16_e32 v150, v223
	v_cvt_f32_f16_sdwa v151, v223 dst_sel:DWORD dst_unused:UNUSED_PAD src0_sel:WORD_1
	v_cvt_f32_f16_e32 v152, v224
	v_cvt_f32_f16_sdwa v153, v224 dst_sel:DWORD dst_unused:UNUSED_PAD src0_sel:WORD_1
	v_cvt_f32_f16_e32 v154, v225
	v_cvt_f32_f16_sdwa v155, v225 dst_sel:DWORD dst_unused:UNUSED_PAD src0_sel:WORD_1
	v_cvt_f32_f16_e32 v156, v226
	v_cvt_f32_f16_sdwa v157, v226 dst_sel:DWORD dst_unused:UNUSED_PAD src0_sel:WORD_1
	v_cvt_f32_f16_e32 v158, v227
	v_cvt_f32_f16_sdwa v159, v227 dst_sel:DWORD dst_unused:UNUSED_PAD src0_sel:WORD_1
	v_cvt_f32_f16_e32 v160, v228
	v_cvt_f32_f16_sdwa v161, v228 dst_sel:DWORD dst_unused:UNUSED_PAD src0_sel:WORD_1
	v_cvt_f32_f16_e32 v162, v229
	v_cvt_f32_f16_sdwa v163, v229 dst_sel:DWORD dst_unused:UNUSED_PAD src0_sel:WORD_1
	v_cvt_f32_f16_e32 v164, v230
	v_cvt_f32_f16_sdwa v165, v230 dst_sel:DWORD dst_unused:UNUSED_PAD src0_sel:WORD_1
	v_cvt_f32_f16_e32 v166, v231
	v_cvt_f32_f16_sdwa v167, v231 dst_sel:DWORD dst_unused:UNUSED_PAD src0_sel:WORD_1
	v_pk_mul_f32 v[232:233], v[136:137], v[136:137]
	v_pk_mul_f32 v[234:235], v[138:139], v[138:139]
	v_pk_mul_f32 v[236:237], v[140:141], v[140:141]
	v_pk_mul_f32 v[238:239], v[142:143], v[142:143]
	v_pk_fma_f32 v[232:233], v[144:145], v[144:145], v[232:233]
	v_pk_fma_f32 v[234:235], v[146:147], v[146:147], v[234:235]
	v_pk_fma_f32 v[236:237], v[148:149], v[148:149], v[236:237]
	v_pk_fma_f32 v[238:239], v[150:151], v[150:151], v[238:239]
	v_pk_fma_f32 v[232:233], v[152:153], v[152:153], v[232:233]
	v_pk_fma_f32 v[234:235], v[154:155], v[154:155], v[234:235]
	v_pk_fma_f32 v[236:237], v[156:157], v[156:157], v[236:237]
	v_pk_fma_f32 v[238:239], v[158:159], v[158:159], v[238:239]
	v_pk_fma_f32 v[232:233], v[160:161], v[160:161], v[232:233]
	v_pk_fma_f32 v[234:235], v[162:163], v[162:163], v[234:235]
	v_pk_fma_f32 v[236:237], v[164:165], v[164:165], v[236:237]
	v_pk_fma_f32 v[238:239], v[166:167], v[166:167], v[238:239]
	v_pk_add_f32 v[232:233], v[232:233], v[234:235]
	v_pk_add_f32 v[236:237], v[236:237], v[238:239]
	v_pk_add_f32 v[232:233], v[232:233], v[236:237]
	v_add_f32_e32 v240, v232, v233
	s_nop 1
	v_add_f32_dpp v240, v240, v240 quad_perm:[1,0,3,2] row_mask:0xf bank_mask:0xf
	s_nop 1
	v_add_f32_dpp v240, v240, v240 quad_perm:[2,3,0,1] row_mask:0xf bank_mask:0xf
	s_nop 1
	v_add_f32_dpp v240, v240, v240 row_half_mirror row_mask:0xf bank_mask:0xf
	s_nop 1
	v_add_f32_dpp v240, v240, v240 row_mirror row_mask:0xf bank_mask:0xf
	s_nop 1
	v_readlane_b32 s0, v240, 0
	v_readlane_b32 s1, v240, 16
	v_readlane_b32 s4, v240, 32
	v_readlane_b32 s5, v240, 48
	v_mov_b32_e32 v249, 0x358637bd
	s_nop 1
	v_mov_b32_e32 v240, s0
	v_add_f32_e32 v240, s1, v240
	v_add_f32_e32 v240, s4, v240
	v_add_f32_e32 v240, s5, v240
	v_fmamk_f32 v240, v240, 0x3a000000, v249
	s_mov_b32 s0, 0xf800000
	v_mul_f32_e32 v241, 0x4f800000, v240
	v_cmp_gt_f32_e32 vcc, s0, v240
	s_nop 1
	v_cndmask_b32_e32 v240, v240, v241, vcc
	v_sqrt_f32_e32 v241, v240
	s_nop 0
	v_add_u32_e32 v242, -1, v241
	v_fma_f32 v243, -v242, v241, v240
	v_cmp_ge_f32_e64 s[0:1], 0, v243
	v_add_u32_e32 v243, 1, v241
	s_nop 0
	v_cndmask_b32_e64 v242, v241, v242, s[0:1]
	v_fma_f32 v241, -v243, v241, v240
	v_cmp_lt_f32_e64 s[0:1], 0, v241
	s_nop 1
	v_cndmask_b32_e64 v241, v242, v243, s[0:1]
	v_mul_f32_e32 v242, 0x37800000, v241
	v_cndmask_b32_e32 v241, v241, v242, vcc
	v_cmp_class_f32_e32 vcc, v240, v248
	s_nop 1
	v_cndmask_b32_e32 v240, v241, v240, vcc
	v_div_scale_f32 v241, s[0:1], v240, v240, 1.0
	v_rcp_f32_e32 v242, v241
	s_nop 0
	v_fma_f32 v243, -v241, v242, 1.0
	v_fmac_f32_e32 v242, v243, v242
	v_div_scale_f32 v243, vcc, 1.0, v240, 1.0
	v_mul_f32_e32 v244, v243, v242
	v_fma_f32 v247, -v241, v244, v243
	v_fmac_f32_e32 v244, v247, v242
	v_fma_f32 v241, -v241, v244, v243
	s_nop 1
	v_div_fmas_f32 v241, v241, v242, v244
	v_div_fixup_f32 v246, v241, v240, 1.0
	v_pk_mul_f32 v[136:137], v[136:137], v[246:247] op_sel_hi:[1,0]
	v_pk_mul_f32 v[138:139], v[138:139], v[246:247] op_sel_hi:[1,0]
	v_pk_mul_f32 v[140:141], v[140:141], v[246:247] op_sel_hi:[1,0]
	v_pk_mul_f32 v[142:143], v[142:143], v[246:247] op_sel_hi:[1,0]
	v_pk_mul_f32 v[144:145], v[144:145], v[246:247] op_sel_hi:[1,0]
	v_pk_mul_f32 v[146:147], v[146:147], v[246:247] op_sel_hi:[1,0]
	v_pk_mul_f32 v[148:149], v[148:149], v[246:247] op_sel_hi:[1,0]
	v_pk_mul_f32 v[150:151], v[150:151], v[246:247] op_sel_hi:[1,0]
	v_pk_mul_f32 v[152:153], v[152:153], v[246:247] op_sel_hi:[1,0]
	v_pk_mul_f32 v[154:155], v[154:155], v[246:247] op_sel_hi:[1,0]
	v_pk_mul_f32 v[156:157], v[156:157], v[246:247] op_sel_hi:[1,0]
	v_pk_mul_f32 v[158:159], v[158:159], v[246:247] op_sel_hi:[1,0]
	v_pk_mul_f32 v[160:161], v[160:161], v[246:247] op_sel_hi:[1,0]
	v_pk_mul_f32 v[162:163], v[162:163], v[246:247] op_sel_hi:[1,0]
	v_pk_mul_f32 v[164:165], v[164:165], v[246:247] op_sel_hi:[1,0]
	v_pk_mul_f32 v[166:167], v[166:167], v[246:247] op_sel_hi:[1,0]
	s_add_u32 s8, s10, 0xe0000
	s_addc_u32 s9, s11, 0
	v_pk_fma_f32 v[4:5], v[8:9], v[136:137], v[40:41]
	v_cvt_pk_bf16_f32 v232, v4, v5
	v_pk_fma_f32 v[4:5], v[10:11], v[138:139], v[42:43]
	v_cvt_pk_bf16_f32 v233, v4, v5
	v_pk_fma_f32 v[4:5], v[12:13], v[140:141], v[44:45]
	v_cvt_pk_bf16_f32 v234, v4, v5
	v_pk_fma_f32 v[4:5], v[14:15], v[142:143], v[46:47]
	v_cvt_pk_bf16_f32 v235, v4, v5
	global_store_dwordx4 v1, v[232:235], s[8:9] offset:0
	v_pk_fma_f32 v[4:5], v[16:17], v[144:145], v[48:49]
	v_cvt_pk_bf16_f32 v236, v4, v5
	v_pk_fma_f32 v[4:5], v[18:19], v[146:147], v[50:51]
	v_cvt_pk_bf16_f32 v237, v4, v5
	v_pk_fma_f32 v[4:5], v[20:21], v[148:149], v[52:53]
	v_cvt_pk_bf16_f32 v238, v4, v5
	v_pk_fma_f32 v[4:5], v[22:23], v[150:151], v[54:55]
	v_cvt_pk_bf16_f32 v239, v4, v5
	global_store_dwordx4 v1, v[236:239], s[8:9] offset:1024
	v_pk_fma_f32 v[4:5], v[24:25], v[152:153], v[56:57]
	v_cvt_pk_bf16_f32 v232, v4, v5
	v_pk_fma_f32 v[4:5], v[26:27], v[154:155], v[58:59]
	v_cvt_pk_bf16_f32 v233, v4, v5
	v_pk_fma_f32 v[4:5], v[28:29], v[156:157], v[60:61]
	v_cvt_pk_bf16_f32 v234, v4, v5
	v_pk_fma_f32 v[4:5], v[30:31], v[158:159], v[62:63]
	v_cvt_pk_bf16_f32 v235, v4, v5
	global_store_dwordx4 v1, v[232:235], s[8:9] offset:2048
	v_pk_fma_f32 v[4:5], v[32:33], v[160:161], v[64:65]
	v_cvt_pk_bf16_f32 v236, v4, v5
	v_pk_fma_f32 v[4:5], v[34:35], v[162:163], v[66:67]
	v_cvt_pk_bf16_f32 v237, v4, v5
	v_pk_fma_f32 v[4:5], v[36:37], v[164:165], v[68:69]
	v_cvt_pk_bf16_f32 v238, v4, v5
	v_pk_fma_f32 v[4:5], v[38:39], v[166:167], v[70:71]
	v_cvt_pk_bf16_f32 v239, v4, v5
	global_store_dwordx4 v1, v[236:239], s[8:9] offset:3072
	s_add_u32 s8, s12, 0xe0000
	s_addc_u32 s9, s13, 0
	v_pk_fma_f32 v[136:137], v[72:73], v[136:137], v[104:105]
	v_cvt_pk_bf16_f32 v232, v136, v137
	v_pk_fma_f32 v[138:139], v[74:75], v[138:139], v[106:107]
	v_cvt_pk_bf16_f32 v233, v138, v139
	v_pk_fma_f32 v[140:141], v[76:77], v[140:141], v[108:109]
	v_cvt_pk_bf16_f32 v234, v140, v141
	v_pk_fma_f32 v[142:143], v[78:79], v[142:143], v[110:111]
	v_cvt_pk_bf16_f32 v235, v142, v143
	global_store_dwordx4 v1, v[232:235], s[8:9] offset:0
	v_pk_fma_f32 v[144:145], v[80:81], v[144:145], v[112:113]
	v_cvt_pk_bf16_f32 v236, v144, v145
	v_pk_fma_f32 v[146:147], v[82:83], v[146:147], v[114:115]
	v_cvt_pk_bf16_f32 v237, v146, v147
	v_pk_fma_f32 v[148:149], v[84:85], v[148:149], v[116:117]
	v_cvt_pk_bf16_f32 v238, v148, v149
	v_pk_fma_f32 v[150:151], v[86:87], v[150:151], v[118:119]
	v_cvt_pk_bf16_f32 v239, v150, v151
	global_store_dwordx4 v1, v[236:239], s[8:9] offset:1024
	v_pk_fma_f32 v[152:153], v[88:89], v[152:153], v[120:121]
	v_cvt_pk_bf16_f32 v232, v152, v153
	v_pk_fma_f32 v[154:155], v[90:91], v[154:155], v[122:123]
	v_cvt_pk_bf16_f32 v233, v154, v155
	v_pk_fma_f32 v[156:157], v[92:93], v[156:157], v[124:125]
	v_cvt_pk_bf16_f32 v234, v156, v157
	v_pk_fma_f32 v[158:159], v[94:95], v[158:159], v[126:127]
	v_cvt_pk_bf16_f32 v235, v158, v159
	global_store_dwordx4 v1, v[232:235], s[8:9] offset:2048
	v_pk_fma_f32 v[160:161], v[96:97], v[160:161], v[128:129]
	v_cvt_pk_bf16_f32 v236, v160, v161
	v_pk_fma_f32 v[162:163], v[98:99], v[162:163], v[130:131]
	v_cvt_pk_bf16_f32 v237, v162, v163
	v_pk_fma_f32 v[164:165], v[100:101], v[164:165], v[132:133]
	v_cvt_pk_bf16_f32 v238, v164, v165
	v_pk_fma_f32 v[166:167], v[102:103], v[166:167], v[134:135]
	v_cvt_pk_bf16_f32 v239, v166, v167
	global_store_dwordx4 v1, v[236:239], s[8:9] offset:3072
	s_branch .LBB0_1447

.LBB0_2030:
	v_readlane_b32 s4, v250, 12
	s_cmp_lt_i32 s4, 17
	s_cselect_b64 s[0:1], -1, 0
	s_and_b64 s[2:3], s[0:1], s[2:3]
	s_andn2_b64 vcc, exec, s[2:3]
	v_readlane_b32 s5, v250, 13
	v_readlane_b32 s6, v250, 14
	v_readlane_b32 s7, v250, 15
	s_cbranch_vccnz .LBB0_2042
	v_mov_b32_e32 v1, 0x2416c
	ds_read_b32 v2, v1
	ds_read_b32 v1, v1 offset:4
	s_waitcnt lgkmcnt(0)
	v_readfirstlane_b32 s4, v2
	v_readfirstlane_b32 s5, v1
	s_cmp_lt_i32 s4, 1
	s_cbranch_scc1 .Lnorm_fb_3
	v_and_b32_e32 v1, 63, v0
	v_lshlrev_b32_e32 v2, 5, v1
	v_add_u32_e32 v3, 0x1000, v2
	v_lshlrev_b32_e32 v1, 4, v1
	v_readfirstlane_b32 s0, v0
	s_lshr_b32 s1, s0, 6
	s_add_i32 s4, s4, -1
	s_lshl_b32 s18, s4, 8
	s_lshl_b32 s19, s5, 3
	s_add_i32 s18, s18, s19
	s_add_i32 s18, s18, s1
	s_lshr_b32 s19, s4, 4
	s_lshl_b32 s20, s18, 12
	s_lshl_b32 s21, s18, 13
	s_add_u32 s6, s88, 0x45c00000
	s_addc_u32 s7, s89, 0
	s_add_u32 s6, s6, s20
	s_addc_u32 s7, s7, 0
	s_add_u32 s10, s88, 0x13e00000
	s_addc_u32 s11, s89, 0
	s_add_u32 s10, s10, s20
	s_addc_u32 s11, s11, 0
	s_add_u32 s16, s44, 0x8000
	s_addc_u32 s17, s45, 0
	s_mul_i32 s22, s19, 0x12000
	s_add_u32 s24, s88, 0x14e000
	s_addc_u32 s25, s89, 0
	s_add_u32 s24, s24, s22
	s_addc_u32 s25, s25, 0
	s_mul_i32 s22, s19, 0x12000
	s_add_u32 s26, s88, 0x150000
	s_addc_u32 s27, s89, 0
	s_add_u32 s26, s26, s22
	s_addc_u32 s27, s27, 0
	global_load_dwordx4 v[72:75], v2, s[16:17] offset:0
	global_load_dwordx4 v[76:79], v2, s[16:17] offset:16
	global_load_dwordx4 v[80:83], v2, s[16:17] offset:2048
	global_load_dwordx4 v[84:87], v2, s[16:17] offset:2064
	global_load_dwordx4 v[88:91], v3, s[16:17] offset:0
	global_load_dwordx4 v[92:95], v3, s[16:17] offset:16
	global_load_dwordx4 v[96:99], v3, s[16:17] offset:2048
	global_load_dwordx4 v[100:103], v3, s[16:17] offset:2064
	global_load_dwordx4 v[8:11], v2, s[26:27] offset:0
	global_load_dwordx4 v[12:15], v2, s[26:27] offset:16
	global_load_dwordx4 v[16:19], v2, s[26:27] offset:2048
	global_load_dwordx4 v[20:23], v2, s[26:27] offset:2064
	global_load_dwordx4 v[24:27], v3, s[26:27] offset:0
	global_load_dwordx4 v[28:31], v3, s[26:27] offset:16
	global_load_dwordx4 v[32:35], v3, s[26:27] offset:2048
	global_load_dwordx4 v[36:39], v3, s[26:27] offset:2064
	global_load_dwordx4 v[40:43], v2, s[24:25] offset:0
	global_load_dwordx4 v[44:47], v2, s[24:25] offset:16
	global_load_dwordx4 v[48:51], v2, s[24:25] offset:2048
	global_load_dwordx4 v[52:55], v2, s[24:25] offset:2064
	global_load_dwordx4 v[56:59], v3, s[24:25] offset:0
	global_load_dwordx4 v[60:63], v3, s[24:25] offset:16
	global_load_dwordx4 v[64:67], v3, s[24:25] offset:2048
	global_load_dwordx4 v[68:71], v3, s[24:25] offset:2064
	s_add_u32 s8, s6, 0x0
	s_addc_u32 s9, s7, 0
	global_load_dwordx4 v[104:107], v1, s[8:9] offset:0 nt
	global_load_dwordx4 v[108:111], v1, s[8:9] offset:1024 nt
	global_load_dwordx4 v[112:115], v1, s[8:9] offset:2048 nt
	global_load_dwordx4 v[116:119], v1, s[8:9] offset:3072 nt
	s_add_u32 s8, s6, 0x20000
	s_addc_u32 s9, s7, 0
	global_load_dwordx4 v[120:123], v1, s[8:9] offset:0 nt
	global_load_dwordx4 v[124:127], v1, s[8:9] offset:1024 nt
	global_load_dwordx4 v[128:131], v1, s[8:9] offset:2048 nt
	global_load_dwordx4 v[132:135], v1, s[8:9] offset:3072 nt
	s_add_u32 s8, s6, 0x40000
	s_addc_u32 s9, s7, 0
	global_load_dwordx4 v[136:139], v1, s[8:9] offset:0 nt
	global_load_dwordx4 v[140:143], v1, s[8:9] offset:1024 nt
	global_load_dwordx4 v[144:147], v1, s[8:9] offset:2048 nt
	global_load_dwordx4 v[148:151], v1, s[8:9] offset:3072 nt
	s_add_u32 s8, s6, 0x60000
	s_addc_u32 s9, s7, 0
	global_load_dwordx4 v[152:155], v1, s[8:9] offset:0 nt
	global_load_dwordx4 v[156:159], v1, s[8:9] offset:1024 nt
	global_load_dwordx4 v[160:163], v1, s[8:9] offset:2048 nt
	global_load_dwordx4 v[164:167], v1, s[8:9] offset:3072 nt
	s_add_u32 s8, s6, 0x80000
	s_addc_u32 s9, s7, 0
	global_load_dwordx4 v[168:171], v1, s[8:9] offset:0 nt
	global_load_dwordx4 v[172:175], v1, s[8:9] offset:1024 nt
	global_load_dwordx4 v[176:179], v1, s[8:9] offset:2048 nt
	global_load_dwordx4 v[180:183], v1, s[8:9] offset:3072 nt
	s_add_u32 s8, s6, 0xa0000
	s_addc_u32 s9, s7, 0
	global_load_dwordx4 v[184:187], v1, s[8:9] offset:0 nt
	global_load_dwordx4 v[188:191], v1, s[8:9] offset:1024 nt
	global_load_dwordx4 v[192:195], v1, s[8:9] offset:2048 nt
	global_load_dwordx4 v[196:199], v1, s[8:9] offset:3072 nt
	s_add_u32 s8, s6, 0xc0000
	s_addc_u32 s9, s7, 0
	global_load_dwordx4 v[200:203], v1, s[8:9] offset:0 nt
	global_load_dwordx4 v[204:207], v1, s[8:9] offset:1024 nt
	global_load_dwordx4 v[208:211], v1, s[8:9] offset:2048 nt
	global_load_dwordx4 v[212:215], v1, s[8:9] offset:3072 nt
	s_add_u32 s8, s6, 0xe0000
	s_addc_u32 s9, s7, 0
	global_load_dwordx4 v[216:219], v1, s[8:9] offset:0 nt
	global_load_dwordx4 v[220:223], v1, s[8:9] offset:1024 nt
	global_load_dwordx4 v[224:227], v1, s[8:9] offset:2048 nt
	global_load_dwordx4 v[228:231], v1, s[8:9] offset:3072 nt
	s_waitcnt vmcnt(32)
	v_pk_add_f32 v[8:9], v[8:9], 1.0 op_sel_hi:[1,0]
	v_pk_add_f32 v[10:11], v[10:11], 1.0 op_sel_hi:[1,0]
	v_pk_add_f32 v[12:13], v[12:13], 1.0 op_sel_hi:[1,0]
	v_pk_add_f32 v[14:15], v[14:15], 1.0 op_sel_hi:[1,0]
	v_pk_add_f32 v[16:17], v[16:17], 1.0 op_sel_hi:[1,0]
	v_pk_add_f32 v[18:19], v[18:19], 1.0 op_sel_hi:[1,0]
	v_pk_add_f32 v[20:21], v[20:21], 1.0 op_sel_hi:[1,0]
	v_pk_add_f32 v[22:23], v[22:23], 1.0 op_sel_hi:[1,0]
	v_pk_add_f32 v[24:25], v[24:25], 1.0 op_sel_hi:[1,0]
	v_pk_add_f32 v[26:27], v[26:27], 1.0 op_sel_hi:[1,0]
	v_pk_add_f32 v[28:29], v[28:29], 1.0 op_sel_hi:[1,0]
	v_pk_add_f32 v[30:31], v[30:31], 1.0 op_sel_hi:[1,0]
	v_pk_add_f32 v[32:33], v[32:33], 1.0 op_sel_hi:[1,0]
	v_pk_add_f32 v[34:35], v[34:35], 1.0 op_sel_hi:[1,0]
	v_pk_add_f32 v[36:37], v[36:37], 1.0 op_sel_hi:[1,0]
	v_pk_add_f32 v[38:39], v[38:39], 1.0 op_sel_hi:[1,0]
	v_pk_mul_f32 v[8:9], v[72:73], v[8:9]
	v_pk_mul_f32 v[10:11], v[74:75], v[10:11]
	v_pk_mul_f32 v[12:13], v[76:77], v[12:13]
	v_pk_mul_f32 v[14:15], v[78:79], v[14:15]
	v_pk_mul_f32 v[16:17], v[80:81], v[16:17]
	v_pk_mul_f32 v[18:19], v[82:83], v[18:19]
	v_pk_mul_f32 v[20:21], v[84:85], v[20:21]
	v_pk_mul_f32 v[22:23], v[86:87], v[22:23]
	v_pk_mul_f32 v[24:25], v[88:89], v[24:25]
	v_pk_mul_f32 v[26:27], v[90:91], v[26:27]
	v_pk_mul_f32 v[28:29], v[92:93], v[28:29]
	v_pk_mul_f32 v[30:31], v[94:95], v[30:31]
	v_pk_mul_f32 v[32:33], v[96:97], v[32:33]
	v_pk_mul_f32 v[34:35], v[98:99], v[34:35]
	v_pk_mul_f32 v[36:37], v[100:101], v[36:37]
	v_pk_mul_f32 v[38:39], v[102:103], v[38:39]
	v_mov_b32_e32 v248, 0x260
	s_waitcnt vmcnt(28)
	v_cvt_f32_f16_e32 v72, v104
	v_cvt_f32_f16_sdwa v73, v104 dst_sel:DWORD dst_unused:UNUSED_PAD src0_sel:WORD_1
	v_cvt_f32_f16_e32 v74, v105
	v_cvt_f32_f16_sdwa v75, v105 dst_sel:DWORD dst_unused:UNUSED_PAD src0_sel:WORD_1
	v_cvt_f32_f16_e32 v76, v106
	v_cvt_f32_f16_sdwa v77, v106 dst_sel:DWORD dst_unused:UNUSED_PAD src0_sel:WORD_1
	v_cvt_f32_f16_e32 v78, v107
	v_cvt_f32_f16_sdwa v79, v107 dst_sel:DWORD dst_unused:UNUSED_PAD src0_sel:WORD_1
	v_cvt_f32_f16_e32 v80, v108
	v_cvt_f32_f16_sdwa v81, v108 dst_sel:DWORD dst_unused:UNUSED_PAD src0_sel:WORD_1
	v_cvt_f32_f16_e32 v82, v109
	v_cvt_f32_f16_sdwa v83, v109 dst_sel:DWORD dst_unused:UNUSED_PAD src0_sel:WORD_1
	v_cvt_f32_f16_e32 v84, v110
	v_cvt_f32_f16_sdwa v85, v110 dst_sel:DWORD dst_unused:UNUSED_PAD src0_sel:WORD_1
	v_cvt_f32_f16_e32 v86, v111
	v_cvt_f32_f16_sdwa v87, v111 dst_sel:DWORD dst_unused:UNUSED_PAD src0_sel:WORD_1
	v_cvt_f32_f16_e32 v88, v112
	v_cvt_f32_f16_sdwa v89, v112 dst_sel:DWORD dst_unused:UNUSED_PAD src0_sel:WORD_1
	v_cvt_f32_f16_e32 v90, v113
	v_cvt_f32_f16_sdwa v91, v113 dst_sel:DWORD dst_unused:UNUSED_PAD src0_sel:WORD_1
	v_cvt_f32_f16_e32 v92, v114
	v_cvt_f32_f16_sdwa v93, v114 dst_sel:DWORD dst_unused:UNUSED_PAD src0_sel:WORD_1
	v_cvt_f32_f16_e32 v94, v115
	v_cvt_f32_f16_sdwa v95, v115 dst_sel:DWORD dst_unused:UNUSED_PAD src0_sel:WORD_1
	v_cvt_f32_f16_e32 v96, v116
	v_cvt_f32_f16_sdwa v97, v116 dst_sel:DWORD dst_unused:UNUSED_PAD src0_sel:WORD_1
	v_cvt_f32_f16_e32 v98, v117
	v_cvt_f32_f16_sdwa v99, v117 dst_sel:DWORD dst_unused:UNUSED_PAD src0_sel:WORD_1
	v_cvt_f32_f16_e32 v100, v118
	v_cvt_f32_f16_sdwa v101, v118 dst_sel:DWORD dst_unused:UNUSED_PAD src0_sel:WORD_1
	v_cvt_f32_f16_e32 v102, v119
	v_cvt_f32_f16_sdwa v103, v119 dst_sel:DWORD dst_unused:UNUSED_PAD src0_sel:WORD_1
	v_pk_mul_f32 v[232:233], v[72:73], v[72:73]
	v_pk_mul_f32 v[234:235], v[74:75], v[74:75]
	v_pk_mul_f32 v[236:237], v[76:77], v[76:77]
	v_pk_mul_f32 v[238:239], v[78:79], v[78:79]
	v_pk_fma_f32 v[232:233], v[80:81], v[80:81], v[232:233]
	v_pk_fma_f32 v[234:235], v[82:83], v[82:83], v[234:235]
	v_pk_fma_f32 v[236:237], v[84:85], v[84:85], v[236:237]
	v_pk_fma_f32 v[238:239], v[86:87], v[86:87], v[238:239]
	v_pk_fma_f32 v[232:233], v[88:89], v[88:89], v[232:233]
	v_pk_fma_f32 v[234:235], v[90:91], v[90:91], v[234:235]
	v_pk_fma_f32 v[236:237], v[92:93], v[92:93], v[236:237]
	v_pk_fma_f32 v[238:239], v[94:95], v[94:95], v[238:239]
	v_pk_fma_f32 v[232:233], v[96:97], v[96:97], v[232:233]
	v_pk_fma_f32 v[234:235], v[98:99], v[98:99], v[234:235]
	v_pk_fma_f32 v[236:237], v[100:101], v[100:101], v[236:237]
	v_pk_fma_f32 v[238:239], v[102:103], v[102:103], v[238:239]
	v_pk_add_f32 v[232:233], v[232:233], v[234:235]
	v_pk_add_f32 v[236:237], v[236:237], v[238:239]
	v_pk_add_f32 v[232:233], v[232:233], v[236:237]
	v_add_f32_e32 v240, v232, v233
	s_nop 1
	v_add_f32_dpp v240, v240, v240 quad_perm:[1,0,3,2] row_mask:0xf bank_mask:0xf
	s_nop 1
	v_add_f32_dpp v240, v240, v240 quad_perm:[2,3,0,1] row_mask:0xf bank_mask:0xf
	s_nop 1
	v_add_f32_dpp v240, v240, v240 row_half_mirror row_mask:0xf bank_mask:0xf
	s_nop 1
	v_add_f32_dpp v240, v240, v240 row_mirror row_mask:0xf bank_mask:0xf
	s_nop 1
	v_readlane_b32 s0, v240, 0
	v_readlane_b32 s1, v240, 16
	v_readlane_b32 s4, v240, 32
	v_readlane_b32 s5, v240, 48
	v_mov_b32_e32 v249, 0x358637bd
	s_nop 1
	v_mov_b32_e32 v240, s0
	v_add_f32_e32 v240, s1, v240
	v_add_f32_e32 v240, s4, v240
	v_add_f32_e32 v240, s5, v240
	v_fmamk_f32 v240, v240, 0x3a000000, v249
	s_mov_b32 s0, 0xf800000
	v_mul_f32_e32 v241, 0x4f800000, v240
	v_cmp_gt_f32_e32 vcc, s0, v240
	s_nop 1
	v_cndmask_b32_e32 v240, v240, v241, vcc
	v_sqrt_f32_e32 v241, v240
	s_nop 0
	v_add_u32_e32 v242, -1, v241
	v_fma_f32 v243, -v242, v241, v240
	v_cmp_ge_f32_e64 s[0:1], 0, v243
	v_add_u32_e32 v243, 1, v241
	s_nop 0
	v_cndmask_b32_e64 v242, v241, v242, s[0:1]
	v_fma_f32 v241, -v243, v241, v240
	v_cmp_lt_f32_e64 s[0:1], 0, v241
	s_nop 1
	v_cndmask_b32_e64 v241, v242, v243, s[0:1]
	v_mul_f32_e32 v242, 0x37800000, v241
	v_cndmask_b32_e32 v241, v241, v242, vcc
	v_cmp_class_f32_e32 vcc, v240, v248
	s_nop 1
	v_cndmask_b32_e32 v240, v241, v240, vcc
	v_div_scale_f32 v241, s[0:1], v240, v240, 1.0
	v_rcp_f32_e32 v242, v241
	s_nop 0
	v_fma_f32 v243, -v241, v242, 1.0
	v_fmac_f32_e32 v242, v243, v242
	v_div_scale_f32 v243, vcc, 1.0, v240, 1.0
	v_mul_f32_e32 v244, v243, v242
	v_fma_f32 v247, -v241, v244, v243
	v_fmac_f32_e32 v244, v247, v242
	v_fma_f32 v241, -v241, v244, v243
	s_nop 1
	v_div_fmas_f32 v241, v241, v242, v244
	v_div_fixup_f32 v246, v241, v240, 1.0
	v_pk_mul_f32 v[72:73], v[72:73], v[246:247] op_sel_hi:[1,0]
	v_pk_mul_f32 v[74:75], v[74:75], v[246:247] op_sel_hi:[1,0]
	v_pk_mul_f32 v[76:77], v[76:77], v[246:247] op_sel_hi:[1,0]
	v_pk_mul_f32 v[78:79], v[78:79], v[246:247] op_sel_hi:[1,0]
	v_pk_mul_f32 v[80:81], v[80:81], v[246:247] op_sel_hi:[1,0]
	v_pk_mul_f32 v[82:83], v[82:83], v[246:247] op_sel_hi:[1,0]
	v_pk_mul_f32 v[84:85], v[84:85], v[246:247] op_sel_hi:[1,0]
	v_pk_mul_f32 v[86:87], v[86:87], v[246:247] op_sel_hi:[1,0]
	v_pk_mul_f32 v[88:89], v[88:89], v[246:247] op_sel_hi:[1,0]
	v_pk_mul_f32 v[90:91], v[90:91], v[246:247] op_sel_hi:[1,0]
	v_pk_mul_f32 v[92:93], v[92:93], v[246:247] op_sel_hi:[1,0]
	v_pk_mul_f32 v[94:95], v[94:95], v[246:247] op_sel_hi:[1,0]
	v_pk_mul_f32 v[96:97], v[96:97], v[246:247] op_sel_hi:[1,0]
	v_pk_mul_f32 v[98:99], v[98:99], v[246:247] op_sel_hi:[1,0]
	v_pk_mul_f32 v[100:101], v[100:101], v[246:247] op_sel_hi:[1,0]
	v_pk_mul_f32 v[102:103], v[102:103], v[246:247] op_sel_hi:[1,0]
	s_add_u32 s8, s10, 0x0
	s_addc_u32 s9, s11, 0
	v_pk_fma_f32 v[72:73], v[8:9], v[72:73], v[40:41]
	v_cvt_pk_bf16_f32 v232, v72, v73
	v_pk_fma_f32 v[74:75], v[10:11], v[74:75], v[42:43]
	v_cvt_pk_bf16_f32 v233, v74, v75
	v_pk_fma_f32 v[76:77], v[12:13], v[76:77], v[44:45]
	v_cvt_pk_bf16_f32 v234, v76, v77
	v_pk_fma_f32 v[78:79], v[14:15], v[78:79], v[46:47]
	v_cvt_pk_bf16_f32 v235, v78, v79
	global_store_dwordx4 v1, v[232:235], s[8:9] offset:0
	v_pk_fma_f32 v[80:81], v[16:17], v[80:81], v[48:49]
	v_cvt_pk_bf16_f32 v236, v80, v81
	v_pk_fma_f32 v[82:83], v[18:19], v[82:83], v[50:51]
	v_cvt_pk_bf16_f32 v237, v82, v83
	v_pk_fma_f32 v[84:85], v[20:21], v[84:85], v[52:53]
	v_cvt_pk_bf16_f32 v238, v84, v85
	v_pk_fma_f32 v[86:87], v[22:23], v[86:87], v[54:55]
	v_cvt_pk_bf16_f32 v239, v86, v87
	global_store_dwordx4 v1, v[236:239], s[8:9] offset:1024
	v_pk_fma_f32 v[88:89], v[24:25], v[88:89], v[56:57]
	v_cvt_pk_bf16_f32 v232, v88, v89
	v_pk_fma_f32 v[90:91], v[26:27], v[90:91], v[58:59]
	v_cvt_pk_bf16_f32 v233, v90, v91
	v_pk_fma_f32 v[92:93], v[28:29], v[92:93], v[60:61]
	v_cvt_pk_bf16_f32 v234, v92, v93
	v_pk_fma_f32 v[94:95], v[30:31], v[94:95], v[62:63]
	v_cvt_pk_bf16_f32 v235, v94, v95
	global_store_dwordx4 v1, v[232:235], s[8:9] offset:2048
	v_pk_fma_f32 v[96:97], v[32:33], v[96:97], v[64:65]
	v_cvt_pk_bf16_f32 v236, v96, v97
	v_pk_fma_f32 v[98:99], v[34:35], v[98:99], v[66:67]
	v_cvt_pk_bf16_f32 v237, v98, v99
	v_pk_fma_f32 v[100:101], v[36:37], v[100:101], v[68:69]
	v_cvt_pk_bf16_f32 v238, v100, v101
	v_pk_fma_f32 v[102:103], v[38:39], v[102:103], v[70:71]
	v_cvt_pk_bf16_f32 v239, v102, v103
	global_store_dwordx4 v1, v[236:239], s[8:9] offset:3072
	s_waitcnt vmcnt(28)
	v_cvt_f32_f16_e32 v72, v120
	v_cvt_f32_f16_sdwa v73, v120 dst_sel:DWORD dst_unused:UNUSED_PAD src0_sel:WORD_1
	v_cvt_f32_f16_e32 v74, v121
	v_cvt_f32_f16_sdwa v75, v121 dst_sel:DWORD dst_unused:UNUSED_PAD src0_sel:WORD_1
	v_cvt_f32_f16_e32 v76, v122
	v_cvt_f32_f16_sdwa v77, v122 dst_sel:DWORD dst_unused:UNUSED_PAD src0_sel:WORD_1
	v_cvt_f32_f16_e32 v78, v123
	v_cvt_f32_f16_sdwa v79, v123 dst_sel:DWORD dst_unused:UNUSED_PAD src0_sel:WORD_1
	v_cvt_f32_f16_e32 v80, v124
	v_cvt_f32_f16_sdwa v81, v124 dst_sel:DWORD dst_unused:UNUSED_PAD src0_sel:WORD_1
	v_cvt_f32_f16_e32 v82, v125
	v_cvt_f32_f16_sdwa v83, v125 dst_sel:DWORD dst_unused:UNUSED_PAD src0_sel:WORD_1
	v_cvt_f32_f16_e32 v84, v126
	v_cvt_f32_f16_sdwa v85, v126 dst_sel:DWORD dst_unused:UNUSED_PAD src0_sel:WORD_1
	v_cvt_f32_f16_e32 v86, v127
	v_cvt_f32_f16_sdwa v87, v127 dst_sel:DWORD dst_unused:UNUSED_PAD src0_sel:WORD_1
	v_cvt_f32_f16_e32 v88, v128
	v_cvt_f32_f16_sdwa v89, v128 dst_sel:DWORD dst_unused:UNUSED_PAD src0_sel:WORD_1
	v_cvt_f32_f16_e32 v90, v129
	v_cvt_f32_f16_sdwa v91, v129 dst_sel:DWORD dst_unused:UNUSED_PAD src0_sel:WORD_1
	v_cvt_f32_f16_e32 v92, v130
	v_cvt_f32_f16_sdwa v93, v130 dst_sel:DWORD dst_unused:UNUSED_PAD src0_sel:WORD_1
	v_cvt_f32_f16_e32 v94, v131
	v_cvt_f32_f16_sdwa v95, v131 dst_sel:DWORD dst_unused:UNUSED_PAD src0_sel:WORD_1
	v_cvt_f32_f16_e32 v96, v132
	v_cvt_f32_f16_sdwa v97, v132 dst_sel:DWORD dst_unused:UNUSED_PAD src0_sel:WORD_1
	v_cvt_f32_f16_e32 v98, v133
	v_cvt_f32_f16_sdwa v99, v133 dst_sel:DWORD dst_unused:UNUSED_PAD src0_sel:WORD_1
	v_cvt_f32_f16_e32 v100, v134
	v_cvt_f32_f16_sdwa v101, v134 dst_sel:DWORD dst_unused:UNUSED_PAD src0_sel:WORD_1
	v_cvt_f32_f16_e32 v102, v135
	v_cvt_f32_f16_sdwa v103, v135 dst_sel:DWORD dst_unused:UNUSED_PAD src0_sel:WORD_1
	v_pk_mul_f32 v[232:233], v[72:73], v[72:73]
	v_pk_mul_f32 v[234:235], v[74:75], v[74:75]
	v_pk_mul_f32 v[236:237], v[76:77], v[76:77]
	v_pk_mul_f32 v[238:239], v[78:79], v[78:79]
	v_pk_fma_f32 v[232:233], v[80:81], v[80:81], v[232:233]
	v_pk_fma_f32 v[234:235], v[82:83], v[82:83], v[234:235]
	v_pk_fma_f32 v[236:237], v[84:85], v[84:85], v[236:237]
	v_pk_fma_f32 v[238:239], v[86:87], v[86:87], v[238:239]
	v_pk_fma_f32 v[232:233], v[88:89], v[88:89], v[232:233]
	v_pk_fma_f32 v[234:235], v[90:91], v[90:91], v[234:235]
	v_pk_fma_f32 v[236:237], v[92:93], v[92:93], v[236:237]
	v_pk_fma_f32 v[238:239], v[94:95], v[94:95], v[238:239]
	v_pk_fma_f32 v[232:233], v[96:97], v[96:97], v[232:233]
	v_pk_fma_f32 v[234:235], v[98:99], v[98:99], v[234:235]
	v_pk_fma_f32 v[236:237], v[100:101], v[100:101], v[236:237]
	v_pk_fma_f32 v[238:239], v[102:103], v[102:103], v[238:239]
	v_pk_add_f32 v[232:233], v[232:233], v[234:235]
	v_pk_add_f32 v[236:237], v[236:237], v[238:239]
	v_pk_add_f32 v[232:233], v[232:233], v[236:237]
	v_add_f32_e32 v240, v232, v233
	s_nop 1
	v_add_f32_dpp v240, v240, v240 quad_perm:[1,0,3,2] row_mask:0xf bank_mask:0xf
	s_nop 1
	v_add_f32_dpp v240, v240, v240 quad_perm:[2,3,0,1] row_mask:0xf bank_mask:0xf
	s_nop 1
	v_add_f32_dpp v240, v240, v240 row_half_mirror row_mask:0xf bank_mask:0xf
	s_nop 1
	v_add_f32_dpp v240, v240, v240 row_mirror row_mask:0xf bank_mask:0xf
	s_nop 1
	v_readlane_b32 s0, v240, 0
	v_readlane_b32 s1, v240, 16
	v_readlane_b32 s4, v240, 32
	v_readlane_b32 s5, v240, 48
	v_mov_b32_e32 v249, 0x358637bd
	s_nop 1
	v_mov_b32_e32 v240, s0
	v_add_f32_e32 v240, s1, v240
	v_add_f32_e32 v240, s4, v240
	v_add_f32_e32 v240, s5, v240
	v_fmamk_f32 v240, v240, 0x3a000000, v249
	s_mov_b32 s0, 0xf800000
	v_mul_f32_e32 v241, 0x4f800000, v240
	v_cmp_gt_f32_e32 vcc, s0, v240
	s_nop 1
	v_cndmask_b32_e32 v240, v240, v241, vcc
	v_sqrt_f32_e32 v241, v240
	s_nop 0
	v_add_u32_e32 v242, -1, v241
	v_fma_f32 v243, -v242, v241, v240
	v_cmp_ge_f32_e64 s[0:1], 0, v243
	v_add_u32_e32 v243, 1, v241
	s_nop 0
	v_cndmask_b32_e64 v242, v241, v242, s[0:1]
	v_fma_f32 v241, -v243, v241, v240
	v_cmp_lt_f32_e64 s[0:1], 0, v241
	s_nop 1
	v_cndmask_b32_e64 v241, v242, v243, s[0:1]
	v_mul_f32_e32 v242, 0x37800000, v241
	v_cndmask_b32_e32 v241, v241, v242, vcc
	v_cmp_class_f32_e32 vcc, v240, v248
	s_nop 1
	v_cndmask_b32_e32 v240, v241, v240, vcc
	v_div_scale_f32 v241, s[0:1], v240, v240, 1.0
	v_rcp_f32_e32 v242, v241
	s_nop 0
	v_fma_f32 v243, -v241, v242, 1.0
	v_fmac_f32_e32 v242, v243, v242
	v_div_scale_f32 v243, vcc, 1.0, v240, 1.0
	v_mul_f32_e32 v244, v243, v242
	v_fma_f32 v247, -v241, v244, v243
	v_fmac_f32_e32 v244, v247, v242
	v_fma_f32 v241, -v241, v244, v243
	s_nop 1
	v_div_fmas_f32 v241, v241, v242, v244
	v_div_fixup_f32 v246, v241, v240, 1.0
	v_pk_mul_f32 v[72:73], v[72:73], v[246:247] op_sel_hi:[1,0]
	v_pk_mul_f32 v[74:75], v[74:75], v[246:247] op_sel_hi:[1,0]
	v_pk_mul_f32 v[76:77], v[76:77], v[246:247] op_sel_hi:[1,0]
	v_pk_mul_f32 v[78:79], v[78:79], v[246:247] op_sel_hi:[1,0]
	v_pk_mul_f32 v[80:81], v[80:81], v[246:247] op_sel_hi:[1,0]
	v_pk_mul_f32 v[82:83], v[82:83], v[246:247] op_sel_hi:[1,0]
	v_pk_mul_f32 v[84:85], v[84:85], v[246:247] op_sel_hi:[1,0]
	v_pk_mul_f32 v[86:87], v[86:87], v[246:247] op_sel_hi:[1,0]
	v_pk_mul_f32 v[88:89], v[88:89], v[246:247] op_sel_hi:[1,0]
	v_pk_mul_f32 v[90:91], v[90:91], v[246:247] op_sel_hi:[1,0]
	v_pk_mul_f32 v[92:93], v[92:93], v[246:247] op_sel_hi:[1,0]
	v_pk_mul_f32 v[94:95], v[94:95], v[246:247] op_sel_hi:[1,0]
	v_pk_mul_f32 v[96:97], v[96:97], v[246:247] op_sel_hi:[1,0]
	v_pk_mul_f32 v[98:99], v[98:99], v[246:247] op_sel_hi:[1,0]
	v_pk_mul_f32 v[100:101], v[100:101], v[246:247] op_sel_hi:[1,0]
	v_pk_mul_f32 v[102:103], v[102:103], v[246:247] op_sel_hi:[1,0]
	s_add_u32 s8, s10, 0x20000
	s_addc_u32 s9, s11, 0
	v_pk_fma_f32 v[72:73], v[8:9], v[72:73], v[40:41]
	v_cvt_pk_bf16_f32 v232, v72, v73
	v_pk_fma_f32 v[74:75], v[10:11], v[74:75], v[42:43]
	v_cvt_pk_bf16_f32 v233, v74, v75
	v_pk_fma_f32 v[76:77], v[12:13], v[76:77], v[44:45]
	v_cvt_pk_bf16_f32 v234, v76, v77
	v_pk_fma_f32 v[78:79], v[14:15], v[78:79], v[46:47]
	v_cvt_pk_bf16_f32 v235, v78, v79
	global_store_dwordx4 v1, v[232:235], s[8:9] offset:0
	v_pk_fma_f32 v[80:81], v[16:17], v[80:81], v[48:49]
	v_cvt_pk_bf16_f32 v236, v80, v81
	v_pk_fma_f32 v[82:83], v[18:19], v[82:83], v[50:51]
	v_cvt_pk_bf16_f32 v237, v82, v83
	v_pk_fma_f32 v[84:85], v[20:21], v[84:85], v[52:53]
	v_cvt_pk_bf16_f32 v238, v84, v85
	v_pk_fma_f32 v[86:87], v[22:23], v[86:87], v[54:55]
	v_cvt_pk_bf16_f32 v239, v86, v87
	global_store_dwordx4 v1, v[236:239], s[8:9] offset:1024
	v_pk_fma_f32 v[88:89], v[24:25], v[88:89], v[56:57]
	v_cvt_pk_bf16_f32 v232, v88, v89
	v_pk_fma_f32 v[90:91], v[26:27], v[90:91], v[58:59]
	v_cvt_pk_bf16_f32 v233, v90, v91
	v_pk_fma_f32 v[92:93], v[28:29], v[92:93], v[60:61]
	v_cvt_pk_bf16_f32 v234, v92, v93
	v_pk_fma_f32 v[94:95], v[30:31], v[94:95], v[62:63]
	v_cvt_pk_bf16_f32 v235, v94, v95
	global_store_dwordx4 v1, v[232:235], s[8:9] offset:2048
	v_pk_fma_f32 v[96:97], v[32:33], v[96:97], v[64:65]
	v_cvt_pk_bf16_f32 v236, v96, v97
	v_pk_fma_f32 v[98:99], v[34:35], v[98:99], v[66:67]
	v_cvt_pk_bf16_f32 v237, v98, v99
	v_pk_fma_f32 v[100:101], v[36:37], v[100:101], v[68:69]
	v_cvt_pk_bf16_f32 v238, v100, v101
	v_pk_fma_f32 v[102:103], v[38:39], v[102:103], v[70:71]
	v_cvt_pk_bf16_f32 v239, v102, v103
	global_store_dwordx4 v1, v[236:239], s[8:9] offset:3072
	s_waitcnt vmcnt(28)
	v_cvt_f32_f16_e32 v72, v136
	v_cvt_f32_f16_sdwa v73, v136 dst_sel:DWORD dst_unused:UNUSED_PAD src0_sel:WORD_1
	v_cvt_f32_f16_e32 v74, v137
	v_cvt_f32_f16_sdwa v75, v137 dst_sel:DWORD dst_unused:UNUSED_PAD src0_sel:WORD_1
	v_cvt_f32_f16_e32 v76, v138
	v_cvt_f32_f16_sdwa v77, v138 dst_sel:DWORD dst_unused:UNUSED_PAD src0_sel:WORD_1
	v_cvt_f32_f16_e32 v78, v139
	v_cvt_f32_f16_sdwa v79, v139 dst_sel:DWORD dst_unused:UNUSED_PAD src0_sel:WORD_1
	v_cvt_f32_f16_e32 v80, v140
	v_cvt_f32_f16_sdwa v81, v140 dst_sel:DWORD dst_unused:UNUSED_PAD src0_sel:WORD_1
	v_cvt_f32_f16_e32 v82, v141
	v_cvt_f32_f16_sdwa v83, v141 dst_sel:DWORD dst_unused:UNUSED_PAD src0_sel:WORD_1
	v_cvt_f32_f16_e32 v84, v142
	v_cvt_f32_f16_sdwa v85, v142 dst_sel:DWORD dst_unused:UNUSED_PAD src0_sel:WORD_1
	v_cvt_f32_f16_e32 v86, v143
	v_cvt_f32_f16_sdwa v87, v143 dst_sel:DWORD dst_unused:UNUSED_PAD src0_sel:WORD_1
	v_cvt_f32_f16_e32 v88, v144
	v_cvt_f32_f16_sdwa v89, v144 dst_sel:DWORD dst_unused:UNUSED_PAD src0_sel:WORD_1
	v_cvt_f32_f16_e32 v90, v145
	v_cvt_f32_f16_sdwa v91, v145 dst_sel:DWORD dst_unused:UNUSED_PAD src0_sel:WORD_1
	v_cvt_f32_f16_e32 v92, v146
	v_cvt_f32_f16_sdwa v93, v146 dst_sel:DWORD dst_unused:UNUSED_PAD src0_sel:WORD_1
	v_cvt_f32_f16_e32 v94, v147
	v_cvt_f32_f16_sdwa v95, v147 dst_sel:DWORD dst_unused:UNUSED_PAD src0_sel:WORD_1
	v_cvt_f32_f16_e32 v96, v148
	v_cvt_f32_f16_sdwa v97, v148 dst_sel:DWORD dst_unused:UNUSED_PAD src0_sel:WORD_1
	v_cvt_f32_f16_e32 v98, v149
	v_cvt_f32_f16_sdwa v99, v149 dst_sel:DWORD dst_unused:UNUSED_PAD src0_sel:WORD_1
	v_cvt_f32_f16_e32 v100, v150
	v_cvt_f32_f16_sdwa v101, v150 dst_sel:DWORD dst_unused:UNUSED_PAD src0_sel:WORD_1
	v_cvt_f32_f16_e32 v102, v151
	v_cvt_f32_f16_sdwa v103, v151 dst_sel:DWORD dst_unused:UNUSED_PAD src0_sel:WORD_1
	v_pk_mul_f32 v[232:233], v[72:73], v[72:73]
	v_pk_mul_f32 v[234:235], v[74:75], v[74:75]
	v_pk_mul_f32 v[236:237], v[76:77], v[76:77]
	v_pk_mul_f32 v[238:239], v[78:79], v[78:79]
	v_pk_fma_f32 v[232:233], v[80:81], v[80:81], v[232:233]
	v_pk_fma_f32 v[234:235], v[82:83], v[82:83], v[234:235]
	v_pk_fma_f32 v[236:237], v[84:85], v[84:85], v[236:237]
	v_pk_fma_f32 v[238:239], v[86:87], v[86:87], v[238:239]
	v_pk_fma_f32 v[232:233], v[88:89], v[88:89], v[232:233]
	v_pk_fma_f32 v[234:235], v[90:91], v[90:91], v[234:235]
	v_pk_fma_f32 v[236:237], v[92:93], v[92:93], v[236:237]
	v_pk_fma_f32 v[238:239], v[94:95], v[94:95], v[238:239]
	v_pk_fma_f32 v[232:233], v[96:97], v[96:97], v[232:233]
	v_pk_fma_f32 v[234:235], v[98:99], v[98:99], v[234:235]
	v_pk_fma_f32 v[236:237], v[100:101], v[100:101], v[236:237]
	v_pk_fma_f32 v[238:239], v[102:103], v[102:103], v[238:239]
	v_pk_add_f32 v[232:233], v[232:233], v[234:235]
	v_pk_add_f32 v[236:237], v[236:237], v[238:239]
	v_pk_add_f32 v[232:233], v[232:233], v[236:237]
	v_add_f32_e32 v240, v232, v233
	s_nop 1
	v_add_f32_dpp v240, v240, v240 quad_perm:[1,0,3,2] row_mask:0xf bank_mask:0xf
	s_nop 1
	v_add_f32_dpp v240, v240, v240 quad_perm:[2,3,0,1] row_mask:0xf bank_mask:0xf
	s_nop 1
	v_add_f32_dpp v240, v240, v240 row_half_mirror row_mask:0xf bank_mask:0xf
	s_nop 1
	v_add_f32_dpp v240, v240, v240 row_mirror row_mask:0xf bank_mask:0xf
	s_nop 1
	v_readlane_b32 s0, v240, 0
	v_readlane_b32 s1, v240, 16
	v_readlane_b32 s4, v240, 32
	v_readlane_b32 s5, v240, 48
	v_mov_b32_e32 v249, 0x358637bd
	s_nop 1
	v_mov_b32_e32 v240, s0
	v_add_f32_e32 v240, s1, v240
	v_add_f32_e32 v240, s4, v240
	v_add_f32_e32 v240, s5, v240
	v_fmamk_f32 v240, v240, 0x3a000000, v249
	s_mov_b32 s0, 0xf800000
	v_mul_f32_e32 v241, 0x4f800000, v240
	v_cmp_gt_f32_e32 vcc, s0, v240
	s_nop 1
	v_cndmask_b32_e32 v240, v240, v241, vcc
	v_sqrt_f32_e32 v241, v240
	s_nop 0
	v_add_u32_e32 v242, -1, v241
	v_fma_f32 v243, -v242, v241, v240
	v_cmp_ge_f32_e64 s[0:1], 0, v243
	v_add_u32_e32 v243, 1, v241
	s_nop 0
	v_cndmask_b32_e64 v242, v241, v242, s[0:1]
	v_fma_f32 v241, -v243, v241, v240
	v_cmp_lt_f32_e64 s[0:1], 0, v241
	s_nop 1
	v_cndmask_b32_e64 v241, v242, v243, s[0:1]
	v_mul_f32_e32 v242, 0x37800000, v241
	v_cndmask_b32_e32 v241, v241, v242, vcc
	v_cmp_class_f32_e32 vcc, v240, v248
	s_nop 1
	v_cndmask_b32_e32 v240, v241, v240, vcc
	v_div_scale_f32 v241, s[0:1], v240, v240, 1.0
	v_rcp_f32_e32 v242, v241
	s_nop 0
	v_fma_f32 v243, -v241, v242, 1.0
	v_fmac_f32_e32 v242, v243, v242
	v_div_scale_f32 v243, vcc, 1.0, v240, 1.0
	v_mul_f32_e32 v244, v243, v242
	v_fma_f32 v247, -v241, v244, v243
	v_fmac_f32_e32 v244, v247, v242
	v_fma_f32 v241, -v241, v244, v243
	s_nop 1
	v_div_fmas_f32 v241, v241, v242, v244
	v_div_fixup_f32 v246, v241, v240, 1.0
	v_pk_mul_f32 v[72:73], v[72:73], v[246:247] op_sel_hi:[1,0]
	v_pk_mul_f32 v[74:75], v[74:75], v[246:247] op_sel_hi:[1,0]
	v_pk_mul_f32 v[76:77], v[76:77], v[246:247] op_sel_hi:[1,0]
	v_pk_mul_f32 v[78:79], v[78:79], v[246:247] op_sel_hi:[1,0]
	v_pk_mul_f32 v[80:81], v[80:81], v[246:247] op_sel_hi:[1,0]
	v_pk_mul_f32 v[82:83], v[82:83], v[246:247] op_sel_hi:[1,0]
	v_pk_mul_f32 v[84:85], v[84:85], v[246:247] op_sel_hi:[1,0]
	v_pk_mul_f32 v[86:87], v[86:87], v[246:247] op_sel_hi:[1,0]
	v_pk_mul_f32 v[88:89], v[88:89], v[246:247] op_sel_hi:[1,0]
	v_pk_mul_f32 v[90:91], v[90:91], v[246:247] op_sel_hi:[1,0]
	v_pk_mul_f32 v[92:93], v[92:93], v[246:247] op_sel_hi:[1,0]
	v_pk_mul_f32 v[94:95], v[94:95], v[246:247] op_sel_hi:[1,0]
	v_pk_mul_f32 v[96:97], v[96:97], v[246:247] op_sel_hi:[1,0]
	v_pk_mul_f32 v[98:99], v[98:99], v[246:247] op_sel_hi:[1,0]
	v_pk_mul_f32 v[100:101], v[100:101], v[246:247] op_sel_hi:[1,0]
	v_pk_mul_f32 v[102:103], v[102:103], v[246:247] op_sel_hi:[1,0]
	s_add_u32 s8, s10, 0x40000
	s_addc_u32 s9, s11, 0
	v_pk_fma_f32 v[72:73], v[8:9], v[72:73], v[40:41]
	v_cvt_pk_bf16_f32 v232, v72, v73
	v_pk_fma_f32 v[74:75], v[10:11], v[74:75], v[42:43]
	v_cvt_pk_bf16_f32 v233, v74, v75
	v_pk_fma_f32 v[76:77], v[12:13], v[76:77], v[44:45]
	v_cvt_pk_bf16_f32 v234, v76, v77
	v_pk_fma_f32 v[78:79], v[14:15], v[78:79], v[46:47]
	v_cvt_pk_bf16_f32 v235, v78, v79
	global_store_dwordx4 v1, v[232:235], s[8:9] offset:0
	v_pk_fma_f32 v[80:81], v[16:17], v[80:81], v[48:49]
	v_cvt_pk_bf16_f32 v236, v80, v81
	v_pk_fma_f32 v[82:83], v[18:19], v[82:83], v[50:51]
	v_cvt_pk_bf16_f32 v237, v82, v83
	v_pk_fma_f32 v[84:85], v[20:21], v[84:85], v[52:53]
	v_cvt_pk_bf16_f32 v238, v84, v85
	v_pk_fma_f32 v[86:87], v[22:23], v[86:87], v[54:55]
	v_cvt_pk_bf16_f32 v239, v86, v87
	global_store_dwordx4 v1, v[236:239], s[8:9] offset:1024
	v_pk_fma_f32 v[88:89], v[24:25], v[88:89], v[56:57]
	v_cvt_pk_bf16_f32 v232, v88, v89
	v_pk_fma_f32 v[90:91], v[26:27], v[90:91], v[58:59]
	v_cvt_pk_bf16_f32 v233, v90, v91
	v_pk_fma_f32 v[92:93], v[28:29], v[92:93], v[60:61]
	v_cvt_pk_bf16_f32 v234, v92, v93
	v_pk_fma_f32 v[94:95], v[30:31], v[94:95], v[62:63]
	v_cvt_pk_bf16_f32 v235, v94, v95
	global_store_dwordx4 v1, v[232:235], s[8:9] offset:2048
	v_pk_fma_f32 v[96:97], v[32:33], v[96:97], v[64:65]
	v_cvt_pk_bf16_f32 v236, v96, v97
	v_pk_fma_f32 v[98:99], v[34:35], v[98:99], v[66:67]
	v_cvt_pk_bf16_f32 v237, v98, v99
	v_pk_fma_f32 v[100:101], v[36:37], v[100:101], v[68:69]
	v_cvt_pk_bf16_f32 v238, v100, v101
	v_pk_fma_f32 v[102:103], v[38:39], v[102:103], v[70:71]
	v_cvt_pk_bf16_f32 v239, v102, v103
	global_store_dwordx4 v1, v[236:239], s[8:9] offset:3072
	s_waitcnt vmcnt(28)
	v_cvt_f32_f16_e32 v72, v152
	v_cvt_f32_f16_sdwa v73, v152 dst_sel:DWORD dst_unused:UNUSED_PAD src0_sel:WORD_1
	v_cvt_f32_f16_e32 v74, v153
	v_cvt_f32_f16_sdwa v75, v153 dst_sel:DWORD dst_unused:UNUSED_PAD src0_sel:WORD_1
	v_cvt_f32_f16_e32 v76, v154
	v_cvt_f32_f16_sdwa v77, v154 dst_sel:DWORD dst_unused:UNUSED_PAD src0_sel:WORD_1
	v_cvt_f32_f16_e32 v78, v155
	v_cvt_f32_f16_sdwa v79, v155 dst_sel:DWORD dst_unused:UNUSED_PAD src0_sel:WORD_1
	v_cvt_f32_f16_e32 v80, v156
	v_cvt_f32_f16_sdwa v81, v156 dst_sel:DWORD dst_unused:UNUSED_PAD src0_sel:WORD_1
	v_cvt_f32_f16_e32 v82, v157
	v_cvt_f32_f16_sdwa v83, v157 dst_sel:DWORD dst_unused:UNUSED_PAD src0_sel:WORD_1
	v_cvt_f32_f16_e32 v84, v158
	v_cvt_f32_f16_sdwa v85, v158 dst_sel:DWORD dst_unused:UNUSED_PAD src0_sel:WORD_1
	v_cvt_f32_f16_e32 v86, v159
	v_cvt_f32_f16_sdwa v87, v159 dst_sel:DWORD dst_unused:UNUSED_PAD src0_sel:WORD_1
	v_cvt_f32_f16_e32 v88, v160
	v_cvt_f32_f16_sdwa v89, v160 dst_sel:DWORD dst_unused:UNUSED_PAD src0_sel:WORD_1
	v_cvt_f32_f16_e32 v90, v161
	v_cvt_f32_f16_sdwa v91, v161 dst_sel:DWORD dst_unused:UNUSED_PAD src0_sel:WORD_1
	v_cvt_f32_f16_e32 v92, v162
	v_cvt_f32_f16_sdwa v93, v162 dst_sel:DWORD dst_unused:UNUSED_PAD src0_sel:WORD_1
	v_cvt_f32_f16_e32 v94, v163
	v_cvt_f32_f16_sdwa v95, v163 dst_sel:DWORD dst_unused:UNUSED_PAD src0_sel:WORD_1
	v_cvt_f32_f16_e32 v96, v164
	v_cvt_f32_f16_sdwa v97, v164 dst_sel:DWORD dst_unused:UNUSED_PAD src0_sel:WORD_1
	v_cvt_f32_f16_e32 v98, v165
	v_cvt_f32_f16_sdwa v99, v165 dst_sel:DWORD dst_unused:UNUSED_PAD src0_sel:WORD_1
	v_cvt_f32_f16_e32 v100, v166
	v_cvt_f32_f16_sdwa v101, v166 dst_sel:DWORD dst_unused:UNUSED_PAD src0_sel:WORD_1
	v_cvt_f32_f16_e32 v102, v167
	v_cvt_f32_f16_sdwa v103, v167 dst_sel:DWORD dst_unused:UNUSED_PAD src0_sel:WORD_1
	v_pk_mul_f32 v[232:233], v[72:73], v[72:73]
	v_pk_mul_f32 v[234:235], v[74:75], v[74:75]
	v_pk_mul_f32 v[236:237], v[76:77], v[76:77]
	v_pk_mul_f32 v[238:239], v[78:79], v[78:79]
	v_pk_fma_f32 v[232:233], v[80:81], v[80:81], v[232:233]
	v_pk_fma_f32 v[234:235], v[82:83], v[82:83], v[234:235]
	v_pk_fma_f32 v[236:237], v[84:85], v[84:85], v[236:237]
	v_pk_fma_f32 v[238:239], v[86:87], v[86:87], v[238:239]
	v_pk_fma_f32 v[232:233], v[88:89], v[88:89], v[232:233]
	v_pk_fma_f32 v[234:235], v[90:91], v[90:91], v[234:235]
	v_pk_fma_f32 v[236:237], v[92:93], v[92:93], v[236:237]
	v_pk_fma_f32 v[238:239], v[94:95], v[94:95], v[238:239]
	v_pk_fma_f32 v[232:233], v[96:97], v[96:97], v[232:233]
	v_pk_fma_f32 v[234:235], v[98:99], v[98:99], v[234:235]
	v_pk_fma_f32 v[236:237], v[100:101], v[100:101], v[236:237]
	v_pk_fma_f32 v[238:239], v[102:103], v[102:103], v[238:239]
	v_pk_add_f32 v[232:233], v[232:233], v[234:235]
	v_pk_add_f32 v[236:237], v[236:237], v[238:239]
	v_pk_add_f32 v[232:233], v[232:233], v[236:237]
	v_add_f32_e32 v240, v232, v233
	s_nop 1
	v_add_f32_dpp v240, v240, v240 quad_perm:[1,0,3,2] row_mask:0xf bank_mask:0xf
	s_nop 1
	v_add_f32_dpp v240, v240, v240 quad_perm:[2,3,0,1] row_mask:0xf bank_mask:0xf
	s_nop 1
	v_add_f32_dpp v240, v240, v240 row_half_mirror row_mask:0xf bank_mask:0xf
	s_nop 1
	v_add_f32_dpp v240, v240, v240 row_mirror row_mask:0xf bank_mask:0xf
	s_nop 1
	v_readlane_b32 s0, v240, 0
	v_readlane_b32 s1, v240, 16
	v_readlane_b32 s4, v240, 32
	v_readlane_b32 s5, v240, 48
	v_mov_b32_e32 v249, 0x358637bd
	s_nop 1
	v_mov_b32_e32 v240, s0
	v_add_f32_e32 v240, s1, v240
	v_add_f32_e32 v240, s4, v240
	v_add_f32_e32 v240, s5, v240
	v_fmamk_f32 v240, v240, 0x3a000000, v249
	s_mov_b32 s0, 0xf800000
	v_mul_f32_e32 v241, 0x4f800000, v240
	v_cmp_gt_f32_e32 vcc, s0, v240
	s_nop 1
	v_cndmask_b32_e32 v240, v240, v241, vcc
	v_sqrt_f32_e32 v241, v240
	s_nop 0
	v_add_u32_e32 v242, -1, v241
	v_fma_f32 v243, -v242, v241, v240
	v_cmp_ge_f32_e64 s[0:1], 0, v243
	v_add_u32_e32 v243, 1, v241
	s_nop 0
	v_cndmask_b32_e64 v242, v241, v242, s[0:1]
	v_fma_f32 v241, -v243, v241, v240
	v_cmp_lt_f32_e64 s[0:1], 0, v241
	s_nop 1
	v_cndmask_b32_e64 v241, v242, v243, s[0:1]
	v_mul_f32_e32 v242, 0x37800000, v241
	v_cndmask_b32_e32 v241, v241, v242, vcc
	v_cmp_class_f32_e32 vcc, v240, v248
	s_nop 1
	v_cndmask_b32_e32 v240, v241, v240, vcc
	v_div_scale_f32 v241, s[0:1], v240, v240, 1.0
	v_rcp_f32_e32 v242, v241
	s_nop 0
	v_fma_f32 v243, -v241, v242, 1.0
	v_fmac_f32_e32 v242, v243, v242
	v_div_scale_f32 v243, vcc, 1.0, v240, 1.0
	v_mul_f32_e32 v244, v243, v242
	v_fma_f32 v247, -v241, v244, v243
	v_fmac_f32_e32 v244, v247, v242
	v_fma_f32 v241, -v241, v244, v243
	s_nop 1
	v_div_fmas_f32 v241, v241, v242, v244
	v_div_fixup_f32 v246, v241, v240, 1.0
	v_pk_mul_f32 v[72:73], v[72:73], v[246:247] op_sel_hi:[1,0]
	v_pk_mul_f32 v[74:75], v[74:75], v[246:247] op_sel_hi:[1,0]
	v_pk_mul_f32 v[76:77], v[76:77], v[246:247] op_sel_hi:[1,0]
	v_pk_mul_f32 v[78:79], v[78:79], v[246:247] op_sel_hi:[1,0]
	v_pk_mul_f32 v[80:81], v[80:81], v[246:247] op_sel_hi:[1,0]
	v_pk_mul_f32 v[82:83], v[82:83], v[246:247] op_sel_hi:[1,0]
	v_pk_mul_f32 v[84:85], v[84:85], v[246:247] op_sel_hi:[1,0]
	v_pk_mul_f32 v[86:87], v[86:87], v[246:247] op_sel_hi:[1,0]
	v_pk_mul_f32 v[88:89], v[88:89], v[246:247] op_sel_hi:[1,0]
	v_pk_mul_f32 v[90:91], v[90:91], v[246:247] op_sel_hi:[1,0]
	v_pk_mul_f32 v[92:93], v[92:93], v[246:247] op_sel_hi:[1,0]
	v_pk_mul_f32 v[94:95], v[94:95], v[246:247] op_sel_hi:[1,0]
	v_pk_mul_f32 v[96:97], v[96:97], v[246:247] op_sel_hi:[1,0]
	v_pk_mul_f32 v[98:99], v[98:99], v[246:247] op_sel_hi:[1,0]
	v_pk_mul_f32 v[100:101], v[100:101], v[246:247] op_sel_hi:[1,0]
	v_pk_mul_f32 v[102:103], v[102:103], v[246:247] op_sel_hi:[1,0]
	s_add_u32 s8, s10, 0x60000
	s_addc_u32 s9, s11, 0
	v_pk_fma_f32 v[72:73], v[8:9], v[72:73], v[40:41]
	v_cvt_pk_bf16_f32 v232, v72, v73
	v_pk_fma_f32 v[74:75], v[10:11], v[74:75], v[42:43]
	v_cvt_pk_bf16_f32 v233, v74, v75
	v_pk_fma_f32 v[76:77], v[12:13], v[76:77], v[44:45]
	v_cvt_pk_bf16_f32 v234, v76, v77
	v_pk_fma_f32 v[78:79], v[14:15], v[78:79], v[46:47]
	v_cvt_pk_bf16_f32 v235, v78, v79
	global_store_dwordx4 v1, v[232:235], s[8:9] offset:0
	v_pk_fma_f32 v[80:81], v[16:17], v[80:81], v[48:49]
	v_cvt_pk_bf16_f32 v236, v80, v81
	v_pk_fma_f32 v[82:83], v[18:19], v[82:83], v[50:51]
	v_cvt_pk_bf16_f32 v237, v82, v83
	v_pk_fma_f32 v[84:85], v[20:21], v[84:85], v[52:53]
	v_cvt_pk_bf16_f32 v238, v84, v85
	v_pk_fma_f32 v[86:87], v[22:23], v[86:87], v[54:55]
	v_cvt_pk_bf16_f32 v239, v86, v87
	global_store_dwordx4 v1, v[236:239], s[8:9] offset:1024
	v_pk_fma_f32 v[88:89], v[24:25], v[88:89], v[56:57]
	v_cvt_pk_bf16_f32 v232, v88, v89
	v_pk_fma_f32 v[90:91], v[26:27], v[90:91], v[58:59]
	v_cvt_pk_bf16_f32 v233, v90, v91
	v_pk_fma_f32 v[92:93], v[28:29], v[92:93], v[60:61]
	v_cvt_pk_bf16_f32 v234, v92, v93
	v_pk_fma_f32 v[94:95], v[30:31], v[94:95], v[62:63]
	v_cvt_pk_bf16_f32 v235, v94, v95
	global_store_dwordx4 v1, v[232:235], s[8:9] offset:2048
	v_pk_fma_f32 v[96:97], v[32:33], v[96:97], v[64:65]
	v_cvt_pk_bf16_f32 v236, v96, v97
	v_pk_fma_f32 v[98:99], v[34:35], v[98:99], v[66:67]
	v_cvt_pk_bf16_f32 v237, v98, v99
	v_pk_fma_f32 v[100:101], v[36:37], v[100:101], v[68:69]
	v_cvt_pk_bf16_f32 v238, v100, v101
	v_pk_fma_f32 v[102:103], v[38:39], v[102:103], v[70:71]
	v_cvt_pk_bf16_f32 v239, v102, v103
	global_store_dwordx4 v1, v[236:239], s[8:9] offset:3072
	s_waitcnt vmcnt(28)
	v_cvt_f32_f16_e32 v72, v168
	v_cvt_f32_f16_sdwa v73, v168 dst_sel:DWORD dst_unused:UNUSED_PAD src0_sel:WORD_1
	v_cvt_f32_f16_e32 v74, v169
	v_cvt_f32_f16_sdwa v75, v169 dst_sel:DWORD dst_unused:UNUSED_PAD src0_sel:WORD_1
	v_cvt_f32_f16_e32 v76, v170
	v_cvt_f32_f16_sdwa v77, v170 dst_sel:DWORD dst_unused:UNUSED_PAD src0_sel:WORD_1
	v_cvt_f32_f16_e32 v78, v171
	v_cvt_f32_f16_sdwa v79, v171 dst_sel:DWORD dst_unused:UNUSED_PAD src0_sel:WORD_1
	v_cvt_f32_f16_e32 v80, v172
	v_cvt_f32_f16_sdwa v81, v172 dst_sel:DWORD dst_unused:UNUSED_PAD src0_sel:WORD_1
	v_cvt_f32_f16_e32 v82, v173
	v_cvt_f32_f16_sdwa v83, v173 dst_sel:DWORD dst_unused:UNUSED_PAD src0_sel:WORD_1
	v_cvt_f32_f16_e32 v84, v174
	v_cvt_f32_f16_sdwa v85, v174 dst_sel:DWORD dst_unused:UNUSED_PAD src0_sel:WORD_1
	v_cvt_f32_f16_e32 v86, v175
	v_cvt_f32_f16_sdwa v87, v175 dst_sel:DWORD dst_unused:UNUSED_PAD src0_sel:WORD_1
	v_cvt_f32_f16_e32 v88, v176
	v_cvt_f32_f16_sdwa v89, v176 dst_sel:DWORD dst_unused:UNUSED_PAD src0_sel:WORD_1
	v_cvt_f32_f16_e32 v90, v177
	v_cvt_f32_f16_sdwa v91, v177 dst_sel:DWORD dst_unused:UNUSED_PAD src0_sel:WORD_1
	v_cvt_f32_f16_e32 v92, v178
	v_cvt_f32_f16_sdwa v93, v178 dst_sel:DWORD dst_unused:UNUSED_PAD src0_sel:WORD_1
	v_cvt_f32_f16_e32 v94, v179
	v_cvt_f32_f16_sdwa v95, v179 dst_sel:DWORD dst_unused:UNUSED_PAD src0_sel:WORD_1
	v_cvt_f32_f16_e32 v96, v180
	v_cvt_f32_f16_sdwa v97, v180 dst_sel:DWORD dst_unused:UNUSED_PAD src0_sel:WORD_1
	v_cvt_f32_f16_e32 v98, v181
	v_cvt_f32_f16_sdwa v99, v181 dst_sel:DWORD dst_unused:UNUSED_PAD src0_sel:WORD_1
	v_cvt_f32_f16_e32 v100, v182
	v_cvt_f32_f16_sdwa v101, v182 dst_sel:DWORD dst_unused:UNUSED_PAD src0_sel:WORD_1
	v_cvt_f32_f16_e32 v102, v183
	v_cvt_f32_f16_sdwa v103, v183 dst_sel:DWORD dst_unused:UNUSED_PAD src0_sel:WORD_1
	v_pk_mul_f32 v[232:233], v[72:73], v[72:73]
	v_pk_mul_f32 v[234:235], v[74:75], v[74:75]
	v_pk_mul_f32 v[236:237], v[76:77], v[76:77]
	v_pk_mul_f32 v[238:239], v[78:79], v[78:79]
	v_pk_fma_f32 v[232:233], v[80:81], v[80:81], v[232:233]
	v_pk_fma_f32 v[234:235], v[82:83], v[82:83], v[234:235]
	v_pk_fma_f32 v[236:237], v[84:85], v[84:85], v[236:237]
	v_pk_fma_f32 v[238:239], v[86:87], v[86:87], v[238:239]
	v_pk_fma_f32 v[232:233], v[88:89], v[88:89], v[232:233]
	v_pk_fma_f32 v[234:235], v[90:91], v[90:91], v[234:235]
	v_pk_fma_f32 v[236:237], v[92:93], v[92:93], v[236:237]
	v_pk_fma_f32 v[238:239], v[94:95], v[94:95], v[238:239]
	v_pk_fma_f32 v[232:233], v[96:97], v[96:97], v[232:233]
	v_pk_fma_f32 v[234:235], v[98:99], v[98:99], v[234:235]
	v_pk_fma_f32 v[236:237], v[100:101], v[100:101], v[236:237]
	v_pk_fma_f32 v[238:239], v[102:103], v[102:103], v[238:239]
	v_pk_add_f32 v[232:233], v[232:233], v[234:235]
	v_pk_add_f32 v[236:237], v[236:237], v[238:239]
	v_pk_add_f32 v[232:233], v[232:233], v[236:237]
	v_add_f32_e32 v240, v232, v233
	s_nop 1
	v_add_f32_dpp v240, v240, v240 quad_perm:[1,0,3,2] row_mask:0xf bank_mask:0xf
	s_nop 1
	v_add_f32_dpp v240, v240, v240 quad_perm:[2,3,0,1] row_mask:0xf bank_mask:0xf
	s_nop 1
	v_add_f32_dpp v240, v240, v240 row_half_mirror row_mask:0xf bank_mask:0xf
	s_nop 1
	v_add_f32_dpp v240, v240, v240 row_mirror row_mask:0xf bank_mask:0xf
	s_nop 1
	v_readlane_b32 s0, v240, 0
	v_readlane_b32 s1, v240, 16
	v_readlane_b32 s4, v240, 32
	v_readlane_b32 s5, v240, 48
	v_mov_b32_e32 v249, 0x358637bd
	s_nop 1
	v_mov_b32_e32 v240, s0
	v_add_f32_e32 v240, s1, v240
	v_add_f32_e32 v240, s4, v240
	v_add_f32_e32 v240, s5, v240
	v_fmamk_f32 v240, v240, 0x3a000000, v249
	s_mov_b32 s0, 0xf800000
	v_mul_f32_e32 v241, 0x4f800000, v240
	v_cmp_gt_f32_e32 vcc, s0, v240
	s_nop 1
	v_cndmask_b32_e32 v240, v240, v241, vcc
	v_sqrt_f32_e32 v241, v240
	s_nop 0
	v_add_u32_e32 v242, -1, v241
	v_fma_f32 v243, -v242, v241, v240
	v_cmp_ge_f32_e64 s[0:1], 0, v243
	v_add_u32_e32 v243, 1, v241
	s_nop 0
	v_cndmask_b32_e64 v242, v241, v242, s[0:1]
	v_fma_f32 v241, -v243, v241, v240
	v_cmp_lt_f32_e64 s[0:1], 0, v241
	s_nop 1
	v_cndmask_b32_e64 v241, v242, v243, s[0:1]
	v_mul_f32_e32 v242, 0x37800000, v241
	v_cndmask_b32_e32 v241, v241, v242, vcc
	v_cmp_class_f32_e32 vcc, v240, v248
	s_nop 1
	v_cndmask_b32_e32 v240, v241, v240, vcc
	v_div_scale_f32 v241, s[0:1], v240, v240, 1.0
	v_rcp_f32_e32 v242, v241
	s_nop 0
	v_fma_f32 v243, -v241, v242, 1.0
	v_fmac_f32_e32 v242, v243, v242
	v_div_scale_f32 v243, vcc, 1.0, v240, 1.0
	v_mul_f32_e32 v244, v243, v242
	v_fma_f32 v247, -v241, v244, v243
	v_fmac_f32_e32 v244, v247, v242
	v_fma_f32 v241, -v241, v244, v243
	s_nop 1
	v_div_fmas_f32 v241, v241, v242, v244
	v_div_fixup_f32 v246, v241, v240, 1.0
	v_pk_mul_f32 v[72:73], v[72:73], v[246:247] op_sel_hi:[1,0]
	v_pk_mul_f32 v[74:75], v[74:75], v[246:247] op_sel_hi:[1,0]
	v_pk_mul_f32 v[76:77], v[76:77], v[246:247] op_sel_hi:[1,0]
	v_pk_mul_f32 v[78:79], v[78:79], v[246:247] op_sel_hi:[1,0]
	v_pk_mul_f32 v[80:81], v[80:81], v[246:247] op_sel_hi:[1,0]
	v_pk_mul_f32 v[82:83], v[82:83], v[246:247] op_sel_hi:[1,0]
	v_pk_mul_f32 v[84:85], v[84:85], v[246:247] op_sel_hi:[1,0]
	v_pk_mul_f32 v[86:87], v[86:87], v[246:247] op_sel_hi:[1,0]
	v_pk_mul_f32 v[88:89], v[88:89], v[246:247] op_sel_hi:[1,0]
	v_pk_mul_f32 v[90:91], v[90:91], v[246:247] op_sel_hi:[1,0]
	v_pk_mul_f32 v[92:93], v[92:93], v[246:247] op_sel_hi:[1,0]
	v_pk_mul_f32 v[94:95], v[94:95], v[246:247] op_sel_hi:[1,0]
	v_pk_mul_f32 v[96:97], v[96:97], v[246:247] op_sel_hi:[1,0]
	v_pk_mul_f32 v[98:99], v[98:99], v[246:247] op_sel_hi:[1,0]
	v_pk_mul_f32 v[100:101], v[100:101], v[246:247] op_sel_hi:[1,0]
	v_pk_mul_f32 v[102:103], v[102:103], v[246:247] op_sel_hi:[1,0]
	s_add_u32 s8, s10, 0x80000
	s_addc_u32 s9, s11, 0
	v_pk_fma_f32 v[72:73], v[8:9], v[72:73], v[40:41]
	v_cvt_pk_bf16_f32 v232, v72, v73
	v_pk_fma_f32 v[74:75], v[10:11], v[74:75], v[42:43]
	v_cvt_pk_bf16_f32 v233, v74, v75
	v_pk_fma_f32 v[76:77], v[12:13], v[76:77], v[44:45]
	v_cvt_pk_bf16_f32 v234, v76, v77
	v_pk_fma_f32 v[78:79], v[14:15], v[78:79], v[46:47]
	v_cvt_pk_bf16_f32 v235, v78, v79
	global_store_dwordx4 v1, v[232:235], s[8:9] offset:0
	v_pk_fma_f32 v[80:81], v[16:17], v[80:81], v[48:49]
	v_cvt_pk_bf16_f32 v236, v80, v81
	v_pk_fma_f32 v[82:83], v[18:19], v[82:83], v[50:51]
	v_cvt_pk_bf16_f32 v237, v82, v83
	v_pk_fma_f32 v[84:85], v[20:21], v[84:85], v[52:53]
	v_cvt_pk_bf16_f32 v238, v84, v85
	v_pk_fma_f32 v[86:87], v[22:23], v[86:87], v[54:55]
	v_cvt_pk_bf16_f32 v239, v86, v87
	global_store_dwordx4 v1, v[236:239], s[8:9] offset:1024
	v_pk_fma_f32 v[88:89], v[24:25], v[88:89], v[56:57]
	v_cvt_pk_bf16_f32 v232, v88, v89
	v_pk_fma_f32 v[90:91], v[26:27], v[90:91], v[58:59]
	v_cvt_pk_bf16_f32 v233, v90, v91
	v_pk_fma_f32 v[92:93], v[28:29], v[92:93], v[60:61]
	v_cvt_pk_bf16_f32 v234, v92, v93
	v_pk_fma_f32 v[94:95], v[30:31], v[94:95], v[62:63]
	v_cvt_pk_bf16_f32 v235, v94, v95
	global_store_dwordx4 v1, v[232:235], s[8:9] offset:2048
	v_pk_fma_f32 v[96:97], v[32:33], v[96:97], v[64:65]
	v_cvt_pk_bf16_f32 v236, v96, v97
	v_pk_fma_f32 v[98:99], v[34:35], v[98:99], v[66:67]
	v_cvt_pk_bf16_f32 v237, v98, v99
	v_pk_fma_f32 v[100:101], v[36:37], v[100:101], v[68:69]
	v_cvt_pk_bf16_f32 v238, v100, v101
	v_pk_fma_f32 v[102:103], v[38:39], v[102:103], v[70:71]
	v_cvt_pk_bf16_f32 v239, v102, v103
	global_store_dwordx4 v1, v[236:239], s[8:9] offset:3072
	s_waitcnt vmcnt(28)
	v_cvt_f32_f16_e32 v72, v184
	v_cvt_f32_f16_sdwa v73, v184 dst_sel:DWORD dst_unused:UNUSED_PAD src0_sel:WORD_1
	v_cvt_f32_f16_e32 v74, v185
	v_cvt_f32_f16_sdwa v75, v185 dst_sel:DWORD dst_unused:UNUSED_PAD src0_sel:WORD_1
	v_cvt_f32_f16_e32 v76, v186
	v_cvt_f32_f16_sdwa v77, v186 dst_sel:DWORD dst_unused:UNUSED_PAD src0_sel:WORD_1
	v_cvt_f32_f16_e32 v78, v187
	v_cvt_f32_f16_sdwa v79, v187 dst_sel:DWORD dst_unused:UNUSED_PAD src0_sel:WORD_1
	v_cvt_f32_f16_e32 v80, v188
	v_cvt_f32_f16_sdwa v81, v188 dst_sel:DWORD dst_unused:UNUSED_PAD src0_sel:WORD_1
	v_cvt_f32_f16_e32 v82, v189
	v_cvt_f32_f16_sdwa v83, v189 dst_sel:DWORD dst_unused:UNUSED_PAD src0_sel:WORD_1
	v_cvt_f32_f16_e32 v84, v190
	v_cvt_f32_f16_sdwa v85, v190 dst_sel:DWORD dst_unused:UNUSED_PAD src0_sel:WORD_1
	v_cvt_f32_f16_e32 v86, v191
	v_cvt_f32_f16_sdwa v87, v191 dst_sel:DWORD dst_unused:UNUSED_PAD src0_sel:WORD_1
	v_cvt_f32_f16_e32 v88, v192
	v_cvt_f32_f16_sdwa v89, v192 dst_sel:DWORD dst_unused:UNUSED_PAD src0_sel:WORD_1
	v_cvt_f32_f16_e32 v90, v193
	v_cvt_f32_f16_sdwa v91, v193 dst_sel:DWORD dst_unused:UNUSED_PAD src0_sel:WORD_1
	v_cvt_f32_f16_e32 v92, v194
	v_cvt_f32_f16_sdwa v93, v194 dst_sel:DWORD dst_unused:UNUSED_PAD src0_sel:WORD_1
	v_cvt_f32_f16_e32 v94, v195
	v_cvt_f32_f16_sdwa v95, v195 dst_sel:DWORD dst_unused:UNUSED_PAD src0_sel:WORD_1
	v_cvt_f32_f16_e32 v96, v196
	v_cvt_f32_f16_sdwa v97, v196 dst_sel:DWORD dst_unused:UNUSED_PAD src0_sel:WORD_1
	v_cvt_f32_f16_e32 v98, v197
	v_cvt_f32_f16_sdwa v99, v197 dst_sel:DWORD dst_unused:UNUSED_PAD src0_sel:WORD_1
	v_cvt_f32_f16_e32 v100, v198
	v_cvt_f32_f16_sdwa v101, v198 dst_sel:DWORD dst_unused:UNUSED_PAD src0_sel:WORD_1
	v_cvt_f32_f16_e32 v102, v199
	v_cvt_f32_f16_sdwa v103, v199 dst_sel:DWORD dst_unused:UNUSED_PAD src0_sel:WORD_1
	v_pk_mul_f32 v[232:233], v[72:73], v[72:73]
	v_pk_mul_f32 v[234:235], v[74:75], v[74:75]
	v_pk_mul_f32 v[236:237], v[76:77], v[76:77]
	v_pk_mul_f32 v[238:239], v[78:79], v[78:79]
	v_pk_fma_f32 v[232:233], v[80:81], v[80:81], v[232:233]
	v_pk_fma_f32 v[234:235], v[82:83], v[82:83], v[234:235]
	v_pk_fma_f32 v[236:237], v[84:85], v[84:85], v[236:237]
	v_pk_fma_f32 v[238:239], v[86:87], v[86:87], v[238:239]
	v_pk_fma_f32 v[232:233], v[88:89], v[88:89], v[232:233]
	v_pk_fma_f32 v[234:235], v[90:91], v[90:91], v[234:235]
	v_pk_fma_f32 v[236:237], v[92:93], v[92:93], v[236:237]
	v_pk_fma_f32 v[238:239], v[94:95], v[94:95], v[238:239]
	v_pk_fma_f32 v[232:233], v[96:97], v[96:97], v[232:233]
	v_pk_fma_f32 v[234:235], v[98:99], v[98:99], v[234:235]
	v_pk_fma_f32 v[236:237], v[100:101], v[100:101], v[236:237]
	v_pk_fma_f32 v[238:239], v[102:103], v[102:103], v[238:239]
	v_pk_add_f32 v[232:233], v[232:233], v[234:235]
	v_pk_add_f32 v[236:237], v[236:237], v[238:239]
	v_pk_add_f32 v[232:233], v[232:233], v[236:237]
	v_add_f32_e32 v240, v232, v233
	s_nop 1
	v_add_f32_dpp v240, v240, v240 quad_perm:[1,0,3,2] row_mask:0xf bank_mask:0xf
	s_nop 1
	v_add_f32_dpp v240, v240, v240 quad_perm:[2,3,0,1] row_mask:0xf bank_mask:0xf
	s_nop 1
	v_add_f32_dpp v240, v240, v240 row_half_mirror row_mask:0xf bank_mask:0xf
	s_nop 1
	v_add_f32_dpp v240, v240, v240 row_mirror row_mask:0xf bank_mask:0xf
	s_nop 1
	v_readlane_b32 s0, v240, 0
	v_readlane_b32 s1, v240, 16
	v_readlane_b32 s4, v240, 32
	v_readlane_b32 s5, v240, 48
	v_mov_b32_e32 v249, 0x358637bd
	s_nop 1
	v_mov_b32_e32 v240, s0
	v_add_f32_e32 v240, s1, v240
	v_add_f32_e32 v240, s4, v240
	v_add_f32_e32 v240, s5, v240
	v_fmamk_f32 v240, v240, 0x3a000000, v249
	s_mov_b32 s0, 0xf800000
	v_mul_f32_e32 v241, 0x4f800000, v240
	v_cmp_gt_f32_e32 vcc, s0, v240
	s_nop 1
	v_cndmask_b32_e32 v240, v240, v241, vcc
	v_sqrt_f32_e32 v241, v240
	s_nop 0
	v_add_u32_e32 v242, -1, v241
	v_fma_f32 v243, -v242, v241, v240
	v_cmp_ge_f32_e64 s[0:1], 0, v243
	v_add_u32_e32 v243, 1, v241
	s_nop 0
	v_cndmask_b32_e64 v242, v241, v242, s[0:1]
	v_fma_f32 v241, -v243, v241, v240
	v_cmp_lt_f32_e64 s[0:1], 0, v241
	s_nop 1
	v_cndmask_b32_e64 v241, v242, v243, s[0:1]
	v_mul_f32_e32 v242, 0x37800000, v241
	v_cndmask_b32_e32 v241, v241, v242, vcc
	v_cmp_class_f32_e32 vcc, v240, v248
	s_nop 1
	v_cndmask_b32_e32 v240, v241, v240, vcc
	v_div_scale_f32 v241, s[0:1], v240, v240, 1.0
	v_rcp_f32_e32 v242, v241
	s_nop 0
	v_fma_f32 v243, -v241, v242, 1.0
	v_fmac_f32_e32 v242, v243, v242
	v_div_scale_f32 v243, vcc, 1.0, v240, 1.0
	v_mul_f32_e32 v244, v243, v242
	v_fma_f32 v247, -v241, v244, v243
	v_fmac_f32_e32 v244, v247, v242
	v_fma_f32 v241, -v241, v244, v243
	s_nop 1
	v_div_fmas_f32 v241, v241, v242, v244
	v_div_fixup_f32 v246, v241, v240, 1.0
	v_pk_mul_f32 v[72:73], v[72:73], v[246:247] op_sel_hi:[1,0]
	v_pk_mul_f32 v[74:75], v[74:75], v[246:247] op_sel_hi:[1,0]
	v_pk_mul_f32 v[76:77], v[76:77], v[246:247] op_sel_hi:[1,0]
	v_pk_mul_f32 v[78:79], v[78:79], v[246:247] op_sel_hi:[1,0]
	v_pk_mul_f32 v[80:81], v[80:81], v[246:247] op_sel_hi:[1,0]
	v_pk_mul_f32 v[82:83], v[82:83], v[246:247] op_sel_hi:[1,0]
	v_pk_mul_f32 v[84:85], v[84:85], v[246:247] op_sel_hi:[1,0]
	v_pk_mul_f32 v[86:87], v[86:87], v[246:247] op_sel_hi:[1,0]
	v_pk_mul_f32 v[88:89], v[88:89], v[246:247] op_sel_hi:[1,0]
	v_pk_mul_f32 v[90:91], v[90:91], v[246:247] op_sel_hi:[1,0]
	v_pk_mul_f32 v[92:93], v[92:93], v[246:247] op_sel_hi:[1,0]
	v_pk_mul_f32 v[94:95], v[94:95], v[246:247] op_sel_hi:[1,0]
	v_pk_mul_f32 v[96:97], v[96:97], v[246:247] op_sel_hi:[1,0]
	v_pk_mul_f32 v[98:99], v[98:99], v[246:247] op_sel_hi:[1,0]
	v_pk_mul_f32 v[100:101], v[100:101], v[246:247] op_sel_hi:[1,0]
	v_pk_mul_f32 v[102:103], v[102:103], v[246:247] op_sel_hi:[1,0]
	s_add_u32 s8, s10, 0xa0000
	s_addc_u32 s9, s11, 0
	v_pk_fma_f32 v[72:73], v[8:9], v[72:73], v[40:41]
	v_cvt_pk_bf16_f32 v232, v72, v73
	v_pk_fma_f32 v[74:75], v[10:11], v[74:75], v[42:43]
	v_cvt_pk_bf16_f32 v233, v74, v75
	v_pk_fma_f32 v[76:77], v[12:13], v[76:77], v[44:45]
	v_cvt_pk_bf16_f32 v234, v76, v77
	v_pk_fma_f32 v[78:79], v[14:15], v[78:79], v[46:47]
	v_cvt_pk_bf16_f32 v235, v78, v79
	global_store_dwordx4 v1, v[232:235], s[8:9] offset:0
	v_pk_fma_f32 v[80:81], v[16:17], v[80:81], v[48:49]
	v_cvt_pk_bf16_f32 v236, v80, v81
	v_pk_fma_f32 v[82:83], v[18:19], v[82:83], v[50:51]
	v_cvt_pk_bf16_f32 v237, v82, v83
	v_pk_fma_f32 v[84:85], v[20:21], v[84:85], v[52:53]
	v_cvt_pk_bf16_f32 v238, v84, v85
	v_pk_fma_f32 v[86:87], v[22:23], v[86:87], v[54:55]
	v_cvt_pk_bf16_f32 v239, v86, v87
	global_store_dwordx4 v1, v[236:239], s[8:9] offset:1024
	v_pk_fma_f32 v[88:89], v[24:25], v[88:89], v[56:57]
	v_cvt_pk_bf16_f32 v232, v88, v89
	v_pk_fma_f32 v[90:91], v[26:27], v[90:91], v[58:59]
	v_cvt_pk_bf16_f32 v233, v90, v91
	v_pk_fma_f32 v[92:93], v[28:29], v[92:93], v[60:61]
	v_cvt_pk_bf16_f32 v234, v92, v93
	v_pk_fma_f32 v[94:95], v[30:31], v[94:95], v[62:63]
	v_cvt_pk_bf16_f32 v235, v94, v95
	global_store_dwordx4 v1, v[232:235], s[8:9] offset:2048
	v_pk_fma_f32 v[96:97], v[32:33], v[96:97], v[64:65]
	v_cvt_pk_bf16_f32 v236, v96, v97
	v_pk_fma_f32 v[98:99], v[34:35], v[98:99], v[66:67]
	v_cvt_pk_bf16_f32 v237, v98, v99
	v_pk_fma_f32 v[100:101], v[36:37], v[100:101], v[68:69]
	v_cvt_pk_bf16_f32 v238, v100, v101
	v_pk_fma_f32 v[102:103], v[38:39], v[102:103], v[70:71]
	v_cvt_pk_bf16_f32 v239, v102, v103
	global_store_dwordx4 v1, v[236:239], s[8:9] offset:3072
	s_waitcnt vmcnt(28)
	v_cvt_f32_f16_e32 v72, v200
	v_cvt_f32_f16_sdwa v73, v200 dst_sel:DWORD dst_unused:UNUSED_PAD src0_sel:WORD_1
	v_cvt_f32_f16_e32 v74, v201
	v_cvt_f32_f16_sdwa v75, v201 dst_sel:DWORD dst_unused:UNUSED_PAD src0_sel:WORD_1
	v_cvt_f32_f16_e32 v76, v202
	v_cvt_f32_f16_sdwa v77, v202 dst_sel:DWORD dst_unused:UNUSED_PAD src0_sel:WORD_1
	v_cvt_f32_f16_e32 v78, v203
	v_cvt_f32_f16_sdwa v79, v203 dst_sel:DWORD dst_unused:UNUSED_PAD src0_sel:WORD_1
	v_cvt_f32_f16_e32 v80, v204
	v_cvt_f32_f16_sdwa v81, v204 dst_sel:DWORD dst_unused:UNUSED_PAD src0_sel:WORD_1
	v_cvt_f32_f16_e32 v82, v205
	v_cvt_f32_f16_sdwa v83, v205 dst_sel:DWORD dst_unused:UNUSED_PAD src0_sel:WORD_1
	v_cvt_f32_f16_e32 v84, v206
	v_cvt_f32_f16_sdwa v85, v206 dst_sel:DWORD dst_unused:UNUSED_PAD src0_sel:WORD_1
	v_cvt_f32_f16_e32 v86, v207
	v_cvt_f32_f16_sdwa v87, v207 dst_sel:DWORD dst_unused:UNUSED_PAD src0_sel:WORD_1
	v_cvt_f32_f16_e32 v88, v208
	v_cvt_f32_f16_sdwa v89, v208 dst_sel:DWORD dst_unused:UNUSED_PAD src0_sel:WORD_1
	v_cvt_f32_f16_e32 v90, v209
	v_cvt_f32_f16_sdwa v91, v209 dst_sel:DWORD dst_unused:UNUSED_PAD src0_sel:WORD_1
	v_cvt_f32_f16_e32 v92, v210
	v_cvt_f32_f16_sdwa v93, v210 dst_sel:DWORD dst_unused:UNUSED_PAD src0_sel:WORD_1
	v_cvt_f32_f16_e32 v94, v211
	v_cvt_f32_f16_sdwa v95, v211 dst_sel:DWORD dst_unused:UNUSED_PAD src0_sel:WORD_1
	v_cvt_f32_f16_e32 v96, v212
	v_cvt_f32_f16_sdwa v97, v212 dst_sel:DWORD dst_unused:UNUSED_PAD src0_sel:WORD_1
	v_cvt_f32_f16_e32 v98, v213
	v_cvt_f32_f16_sdwa v99, v213 dst_sel:DWORD dst_unused:UNUSED_PAD src0_sel:WORD_1
	v_cvt_f32_f16_e32 v100, v214
	v_cvt_f32_f16_sdwa v101, v214 dst_sel:DWORD dst_unused:UNUSED_PAD src0_sel:WORD_1
	v_cvt_f32_f16_e32 v102, v215
	v_cvt_f32_f16_sdwa v103, v215 dst_sel:DWORD dst_unused:UNUSED_PAD src0_sel:WORD_1
	v_pk_mul_f32 v[232:233], v[72:73], v[72:73]
	v_pk_mul_f32 v[234:235], v[74:75], v[74:75]
	v_pk_mul_f32 v[236:237], v[76:77], v[76:77]
	v_pk_mul_f32 v[238:239], v[78:79], v[78:79]
	v_pk_fma_f32 v[232:233], v[80:81], v[80:81], v[232:233]
	v_pk_fma_f32 v[234:235], v[82:83], v[82:83], v[234:235]
	v_pk_fma_f32 v[236:237], v[84:85], v[84:85], v[236:237]
	v_pk_fma_f32 v[238:239], v[86:87], v[86:87], v[238:239]
	v_pk_fma_f32 v[232:233], v[88:89], v[88:89], v[232:233]
	v_pk_fma_f32 v[234:235], v[90:91], v[90:91], v[234:235]
	v_pk_fma_f32 v[236:237], v[92:93], v[92:93], v[236:237]
	v_pk_fma_f32 v[238:239], v[94:95], v[94:95], v[238:239]
	v_pk_fma_f32 v[232:233], v[96:97], v[96:97], v[232:233]
	v_pk_fma_f32 v[234:235], v[98:99], v[98:99], v[234:235]
	v_pk_fma_f32 v[236:237], v[100:101], v[100:101], v[236:237]
	v_pk_fma_f32 v[238:239], v[102:103], v[102:103], v[238:239]
	v_pk_add_f32 v[232:233], v[232:233], v[234:235]
	v_pk_add_f32 v[236:237], v[236:237], v[238:239]
	v_pk_add_f32 v[232:233], v[232:233], v[236:237]
	v_add_f32_e32 v240, v232, v233
	s_nop 1
	v_add_f32_dpp v240, v240, v240 quad_perm:[1,0,3,2] row_mask:0xf bank_mask:0xf
	s_nop 1
	v_add_f32_dpp v240, v240, v240 quad_perm:[2,3,0,1] row_mask:0xf bank_mask:0xf
	s_nop 1
	v_add_f32_dpp v240, v240, v240 row_half_mirror row_mask:0xf bank_mask:0xf
	s_nop 1
	v_add_f32_dpp v240, v240, v240 row_mirror row_mask:0xf bank_mask:0xf
	s_nop 1
	v_readlane_b32 s0, v240, 0
	v_readlane_b32 s1, v240, 16
	v_readlane_b32 s4, v240, 32
	v_readlane_b32 s5, v240, 48
	v_mov_b32_e32 v249, 0x358637bd
	s_nop 1
	v_mov_b32_e32 v240, s0
	v_add_f32_e32 v240, s1, v240
	v_add_f32_e32 v240, s4, v240
	v_add_f32_e32 v240, s5, v240
	v_fmamk_f32 v240, v240, 0x3a000000, v249
	s_mov_b32 s0, 0xf800000
	v_mul_f32_e32 v241, 0x4f800000, v240
	v_cmp_gt_f32_e32 vcc, s0, v240
	s_nop 1
	v_cndmask_b32_e32 v240, v240, v241, vcc
	v_sqrt_f32_e32 v241, v240
	s_nop 0
	v_add_u32_e32 v242, -1, v241
	v_fma_f32 v243, -v242, v241, v240
	v_cmp_ge_f32_e64 s[0:1], 0, v243
	v_add_u32_e32 v243, 1, v241
	s_nop 0
	v_cndmask_b32_e64 v242, v241, v242, s[0:1]
	v_fma_f32 v241, -v243, v241, v240
	v_cmp_lt_f32_e64 s[0:1], 0, v241
	s_nop 1
	v_cndmask_b32_e64 v241, v242, v243, s[0:1]
	v_mul_f32_e32 v242, 0x37800000, v241
	v_cndmask_b32_e32 v241, v241, v242, vcc
	v_cmp_class_f32_e32 vcc, v240, v248
	s_nop 1
	v_cndmask_b32_e32 v240, v241, v240, vcc
	v_div_scale_f32 v241, s[0:1], v240, v240, 1.0
	v_rcp_f32_e32 v242, v241
	s_nop 0
	v_fma_f32 v243, -v241, v242, 1.0
	v_fmac_f32_e32 v242, v243, v242
	v_div_scale_f32 v243, vcc, 1.0, v240, 1.0
	v_mul_f32_e32 v244, v243, v242
	v_fma_f32 v247, -v241, v244, v243
	v_fmac_f32_e32 v244, v247, v242
	v_fma_f32 v241, -v241, v244, v243
	s_nop 1
	v_div_fmas_f32 v241, v241, v242, v244
	v_div_fixup_f32 v246, v241, v240, 1.0
	v_pk_mul_f32 v[72:73], v[72:73], v[246:247] op_sel_hi:[1,0]
	v_pk_mul_f32 v[74:75], v[74:75], v[246:247] op_sel_hi:[1,0]
	v_pk_mul_f32 v[76:77], v[76:77], v[246:247] op_sel_hi:[1,0]
	v_pk_mul_f32 v[78:79], v[78:79], v[246:247] op_sel_hi:[1,0]
	v_pk_mul_f32 v[80:81], v[80:81], v[246:247] op_sel_hi:[1,0]
	v_pk_mul_f32 v[82:83], v[82:83], v[246:247] op_sel_hi:[1,0]
	v_pk_mul_f32 v[84:85], v[84:85], v[246:247] op_sel_hi:[1,0]
	v_pk_mul_f32 v[86:87], v[86:87], v[246:247] op_sel_hi:[1,0]
	v_pk_mul_f32 v[88:89], v[88:89], v[246:247] op_sel_hi:[1,0]
	v_pk_mul_f32 v[90:91], v[90:91], v[246:247] op_sel_hi:[1,0]
	v_pk_mul_f32 v[92:93], v[92:93], v[246:247] op_sel_hi:[1,0]
	v_pk_mul_f32 v[94:95], v[94:95], v[246:247] op_sel_hi:[1,0]
	v_pk_mul_f32 v[96:97], v[96:97], v[246:247] op_sel_hi:[1,0]
	v_pk_mul_f32 v[98:99], v[98:99], v[246:247] op_sel_hi:[1,0]
	v_pk_mul_f32 v[100:101], v[100:101], v[246:247] op_sel_hi:[1,0]
	v_pk_mul_f32 v[102:103], v[102:103], v[246:247] op_sel_hi:[1,0]
	s_add_u32 s8, s10, 0xc0000
	s_addc_u32 s9, s11, 0
	v_pk_fma_f32 v[72:73], v[8:9], v[72:73], v[40:41]
	v_cvt_pk_bf16_f32 v232, v72, v73
	v_pk_fma_f32 v[74:75], v[10:11], v[74:75], v[42:43]
	v_cvt_pk_bf16_f32 v233, v74, v75
	v_pk_fma_f32 v[76:77], v[12:13], v[76:77], v[44:45]
	v_cvt_pk_bf16_f32 v234, v76, v77
	v_pk_fma_f32 v[78:79], v[14:15], v[78:79], v[46:47]
	v_cvt_pk_bf16_f32 v235, v78, v79
	global_store_dwordx4 v1, v[232:235], s[8:9] offset:0
	v_pk_fma_f32 v[80:81], v[16:17], v[80:81], v[48:49]
	v_cvt_pk_bf16_f32 v236, v80, v81
	v_pk_fma_f32 v[82:83], v[18:19], v[82:83], v[50:51]
	v_cvt_pk_bf16_f32 v237, v82, v83
	v_pk_fma_f32 v[84:85], v[20:21], v[84:85], v[52:53]
	v_cvt_pk_bf16_f32 v238, v84, v85
	v_pk_fma_f32 v[86:87], v[22:23], v[86:87], v[54:55]
	v_cvt_pk_bf16_f32 v239, v86, v87
	global_store_dwordx4 v1, v[236:239], s[8:9] offset:1024
	v_pk_fma_f32 v[88:89], v[24:25], v[88:89], v[56:57]
	v_cvt_pk_bf16_f32 v232, v88, v89
	v_pk_fma_f32 v[90:91], v[26:27], v[90:91], v[58:59]
	v_cvt_pk_bf16_f32 v233, v90, v91
	v_pk_fma_f32 v[92:93], v[28:29], v[92:93], v[60:61]
	v_cvt_pk_bf16_f32 v234, v92, v93
	v_pk_fma_f32 v[94:95], v[30:31], v[94:95], v[62:63]
	v_cvt_pk_bf16_f32 v235, v94, v95
	global_store_dwordx4 v1, v[232:235], s[8:9] offset:2048
	v_pk_fma_f32 v[96:97], v[32:33], v[96:97], v[64:65]
	v_cvt_pk_bf16_f32 v236, v96, v97
	v_pk_fma_f32 v[98:99], v[34:35], v[98:99], v[66:67]
	v_cvt_pk_bf16_f32 v237, v98, v99
	v_pk_fma_f32 v[100:101], v[36:37], v[100:101], v[68:69]
	v_cvt_pk_bf16_f32 v238, v100, v101
	v_pk_fma_f32 v[102:103], v[38:39], v[102:103], v[70:71]
	v_cvt_pk_bf16_f32 v239, v102, v103
	global_store_dwordx4 v1, v[236:239], s[8:9] offset:3072
	s_waitcnt vmcnt(28)
	v_cvt_f32_f16_e32 v72, v216
	v_cvt_f32_f16_sdwa v73, v216 dst_sel:DWORD dst_unused:UNUSED_PAD src0_sel:WORD_1
	v_cvt_f32_f16_e32 v74, v217
	v_cvt_f32_f16_sdwa v75, v217 dst_sel:DWORD dst_unused:UNUSED_PAD src0_sel:WORD_1
	v_cvt_f32_f16_e32 v76, v218
	v_cvt_f32_f16_sdwa v77, v218 dst_sel:DWORD dst_unused:UNUSED_PAD src0_sel:WORD_1
	v_cvt_f32_f16_e32 v78, v219
	v_cvt_f32_f16_sdwa v79, v219 dst_sel:DWORD dst_unused:UNUSED_PAD src0_sel:WORD_1
	v_cvt_f32_f16_e32 v80, v220
	v_cvt_f32_f16_sdwa v81, v220 dst_sel:DWORD dst_unused:UNUSED_PAD src0_sel:WORD_1
	v_cvt_f32_f16_e32 v82, v221
	v_cvt_f32_f16_sdwa v83, v221 dst_sel:DWORD dst_unused:UNUSED_PAD src0_sel:WORD_1
	v_cvt_f32_f16_e32 v84, v222
	v_cvt_f32_f16_sdwa v85, v222 dst_sel:DWORD dst_unused:UNUSED_PAD src0_sel:WORD_1
	v_cvt_f32_f16_e32 v86, v223
	v_cvt_f32_f16_sdwa v87, v223 dst_sel:DWORD dst_unused:UNUSED_PAD src0_sel:WORD_1
	v_cvt_f32_f16_e32 v88, v224
	v_cvt_f32_f16_sdwa v89, v224 dst_sel:DWORD dst_unused:UNUSED_PAD src0_sel:WORD_1
	v_cvt_f32_f16_e32 v90, v225
	v_cvt_f32_f16_sdwa v91, v225 dst_sel:DWORD dst_unused:UNUSED_PAD src0_sel:WORD_1
	v_cvt_f32_f16_e32 v92, v226
	v_cvt_f32_f16_sdwa v93, v226 dst_sel:DWORD dst_unused:UNUSED_PAD src0_sel:WORD_1
	v_cvt_f32_f16_e32 v94, v227
	v_cvt_f32_f16_sdwa v95, v227 dst_sel:DWORD dst_unused:UNUSED_PAD src0_sel:WORD_1
	v_cvt_f32_f16_e32 v96, v228
	v_cvt_f32_f16_sdwa v97, v228 dst_sel:DWORD dst_unused:UNUSED_PAD src0_sel:WORD_1
	v_cvt_f32_f16_e32 v98, v229
	v_cvt_f32_f16_sdwa v99, v229 dst_sel:DWORD dst_unused:UNUSED_PAD src0_sel:WORD_1
	v_cvt_f32_f16_e32 v100, v230
	v_cvt_f32_f16_sdwa v101, v230 dst_sel:DWORD dst_unused:UNUSED_PAD src0_sel:WORD_1
	v_cvt_f32_f16_e32 v102, v231
	v_cvt_f32_f16_sdwa v103, v231 dst_sel:DWORD dst_unused:UNUSED_PAD src0_sel:WORD_1
	v_pk_mul_f32 v[232:233], v[72:73], v[72:73]
	v_pk_mul_f32 v[234:235], v[74:75], v[74:75]
	v_pk_mul_f32 v[236:237], v[76:77], v[76:77]
	v_pk_mul_f32 v[238:239], v[78:79], v[78:79]
	v_pk_fma_f32 v[232:233], v[80:81], v[80:81], v[232:233]
	v_pk_fma_f32 v[234:235], v[82:83], v[82:83], v[234:235]
	v_pk_fma_f32 v[236:237], v[84:85], v[84:85], v[236:237]
	v_pk_fma_f32 v[238:239], v[86:87], v[86:87], v[238:239]
	v_pk_fma_f32 v[232:233], v[88:89], v[88:89], v[232:233]
	v_pk_fma_f32 v[234:235], v[90:91], v[90:91], v[234:235]
	v_pk_fma_f32 v[236:237], v[92:93], v[92:93], v[236:237]
	v_pk_fma_f32 v[238:239], v[94:95], v[94:95], v[238:239]
	v_pk_fma_f32 v[232:233], v[96:97], v[96:97], v[232:233]
	v_pk_fma_f32 v[234:235], v[98:99], v[98:99], v[234:235]
	v_pk_fma_f32 v[236:237], v[100:101], v[100:101], v[236:237]
	v_pk_fma_f32 v[238:239], v[102:103], v[102:103], v[238:239]
	v_pk_add_f32 v[232:233], v[232:233], v[234:235]
	v_pk_add_f32 v[236:237], v[236:237], v[238:239]
	v_pk_add_f32 v[232:233], v[232:233], v[236:237]
	v_add_f32_e32 v240, v232, v233
	s_nop 1
	v_add_f32_dpp v240, v240, v240 quad_perm:[1,0,3,2] row_mask:0xf bank_mask:0xf
	s_nop 1
	v_add_f32_dpp v240, v240, v240 quad_perm:[2,3,0,1] row_mask:0xf bank_mask:0xf
	s_nop 1
	v_add_f32_dpp v240, v240, v240 row_half_mirror row_mask:0xf bank_mask:0xf
	s_nop 1
	v_add_f32_dpp v240, v240, v240 row_mirror row_mask:0xf bank_mask:0xf
	s_nop 1
	v_readlane_b32 s0, v240, 0
	v_readlane_b32 s1, v240, 16
	v_readlane_b32 s4, v240, 32
	v_readlane_b32 s5, v240, 48
	v_mov_b32_e32 v249, 0x358637bd
	s_nop 1
	v_mov_b32_e32 v240, s0
	v_add_f32_e32 v240, s1, v240
	v_add_f32_e32 v240, s4, v240
	v_add_f32_e32 v240, s5, v240
	v_fmamk_f32 v240, v240, 0x3a000000, v249
	s_mov_b32 s0, 0xf800000
	v_mul_f32_e32 v241, 0x4f800000, v240
	v_cmp_gt_f32_e32 vcc, s0, v240
	s_nop 1
	v_cndmask_b32_e32 v240, v240, v241, vcc
	v_sqrt_f32_e32 v241, v240
	s_nop 0
	v_add_u32_e32 v242, -1, v241
	v_fma_f32 v243, -v242, v241, v240
	v_cmp_ge_f32_e64 s[0:1], 0, v243
	v_add_u32_e32 v243, 1, v241
	s_nop 0
	v_cndmask_b32_e64 v242, v241, v242, s[0:1]
	v_fma_f32 v241, -v243, v241, v240
	v_cmp_lt_f32_e64 s[0:1], 0, v241
	s_nop 1
	v_cndmask_b32_e64 v241, v242, v243, s[0:1]
	v_mul_f32_e32 v242, 0x37800000, v241
	v_cndmask_b32_e32 v241, v241, v242, vcc
	v_cmp_class_f32_e32 vcc, v240, v248
	s_nop 1
	v_cndmask_b32_e32 v240, v241, v240, vcc
	v_div_scale_f32 v241, s[0:1], v240, v240, 1.0
	v_rcp_f32_e32 v242, v241
	s_nop 0
	v_fma_f32 v243, -v241, v242, 1.0
	v_fmac_f32_e32 v242, v243, v242
	v_div_scale_f32 v243, vcc, 1.0, v240, 1.0
	v_mul_f32_e32 v244, v243, v242
	v_fma_f32 v247, -v241, v244, v243
	v_fmac_f32_e32 v244, v247, v242
	v_fma_f32 v241, -v241, v244, v243
	s_nop 1
	v_div_fmas_f32 v241, v241, v242, v244
	v_div_fixup_f32 v246, v241, v240, 1.0
	v_pk_mul_f32 v[72:73], v[72:73], v[246:247] op_sel_hi:[1,0]
	v_pk_mul_f32 v[74:75], v[74:75], v[246:247] op_sel_hi:[1,0]
	v_pk_mul_f32 v[76:77], v[76:77], v[246:247] op_sel_hi:[1,0]
	v_pk_mul_f32 v[78:79], v[78:79], v[246:247] op_sel_hi:[1,0]
	v_pk_mul_f32 v[80:81], v[80:81], v[246:247] op_sel_hi:[1,0]
	v_pk_mul_f32 v[82:83], v[82:83], v[246:247] op_sel_hi:[1,0]
	v_pk_mul_f32 v[84:85], v[84:85], v[246:247] op_sel_hi:[1,0]
	v_pk_mul_f32 v[86:87], v[86:87], v[246:247] op_sel_hi:[1,0]
	v_pk_mul_f32 v[88:89], v[88:89], v[246:247] op_sel_hi:[1,0]
	v_pk_mul_f32 v[90:91], v[90:91], v[246:247] op_sel_hi:[1,0]
	v_pk_mul_f32 v[92:93], v[92:93], v[246:247] op_sel_hi:[1,0]
	v_pk_mul_f32 v[94:95], v[94:95], v[246:247] op_sel_hi:[1,0]
	v_pk_mul_f32 v[96:97], v[96:97], v[246:247] op_sel_hi:[1,0]
	v_pk_mul_f32 v[98:99], v[98:99], v[246:247] op_sel_hi:[1,0]
	v_pk_mul_f32 v[100:101], v[100:101], v[246:247] op_sel_hi:[1,0]
	v_pk_mul_f32 v[102:103], v[102:103], v[246:247] op_sel_hi:[1,0]
	s_add_u32 s8, s10, 0xe0000
	s_addc_u32 s9, s11, 0
	v_pk_fma_f32 v[72:73], v[8:9], v[72:73], v[40:41]
	v_cvt_pk_bf16_f32 v232, v72, v73
	v_pk_fma_f32 v[74:75], v[10:11], v[74:75], v[42:43]
	v_cvt_pk_bf16_f32 v233, v74, v75
	v_pk_fma_f32 v[76:77], v[12:13], v[76:77], v[44:45]
	v_cvt_pk_bf16_f32 v234, v76, v77
	v_pk_fma_f32 v[78:79], v[14:15], v[78:79], v[46:47]
	v_cvt_pk_bf16_f32 v235, v78, v79
	global_store_dwordx4 v1, v[232:235], s[8:9] offset:0
	v_pk_fma_f32 v[80:81], v[16:17], v[80:81], v[48:49]
	v_cvt_pk_bf16_f32 v236, v80, v81
	v_pk_fma_f32 v[82:83], v[18:19], v[82:83], v[50:51]
	v_cvt_pk_bf16_f32 v237, v82, v83
	v_pk_fma_f32 v[84:85], v[20:21], v[84:85], v[52:53]
	v_cvt_pk_bf16_f32 v238, v84, v85
	v_pk_fma_f32 v[86:87], v[22:23], v[86:87], v[54:55]
	v_cvt_pk_bf16_f32 v239, v86, v87
	global_store_dwordx4 v1, v[236:239], s[8:9] offset:1024
	v_pk_fma_f32 v[88:89], v[24:25], v[88:89], v[56:57]
	v_cvt_pk_bf16_f32 v232, v88, v89
	v_pk_fma_f32 v[90:91], v[26:27], v[90:91], v[58:59]
	v_cvt_pk_bf16_f32 v233, v90, v91
	v_pk_fma_f32 v[92:93], v[28:29], v[92:93], v[60:61]
	v_cvt_pk_bf16_f32 v234, v92, v93
	v_pk_fma_f32 v[94:95], v[30:31], v[94:95], v[62:63]
	v_cvt_pk_bf16_f32 v235, v94, v95
	global_store_dwordx4 v1, v[232:235], s[8:9] offset:2048
	v_pk_fma_f32 v[96:97], v[32:33], v[96:97], v[64:65]
	v_cvt_pk_bf16_f32 v236, v96, v97
	v_pk_fma_f32 v[98:99], v[34:35], v[98:99], v[66:67]
	v_cvt_pk_bf16_f32 v237, v98, v99
	v_pk_fma_f32 v[100:101], v[36:37], v[100:101], v[68:69]
	v_cvt_pk_bf16_f32 v238, v100, v101
	v_pk_fma_f32 v[102:103], v[38:39], v[102:103], v[70:71]
	v_cvt_pk_bf16_f32 v239, v102, v103
	global_store_dwordx4 v1, v[236:239], s[8:9] offset:3072
	s_branch .LBB0_2042

.LBB0_2488:
	v_readlane_b32 s4, v250, 12
	s_cmp_lt_i32 s4, 21
	s_cselect_b64 s[0:1], -1, 0
	s_and_b64 s[2:3], s[0:1], s[2:3]
	s_andn2_b64 vcc, exec, s[2:3]
	v_readlane_b32 s5, v250, 13
	v_readlane_b32 s6, v250, 14
	v_readlane_b32 s7, v250, 15
	s_cbranch_vccnz .LBB0_2500
	v_mov_b32_e32 v1, 0x2416c
	ds_read_b32 v2, v1
	ds_read_b32 v1, v1 offset:4
	s_waitcnt lgkmcnt(0)
	v_readfirstlane_b32 s4, v2
	v_readfirstlane_b32 s5, v1
	s_cmp_lt_i32 s4, 1
	s_cbranch_scc1 .Lnorm_fb_4
	v_and_b32_e32 v1, 63, v0
	v_lshlrev_b32_e32 v2, 5, v1
	v_add_u32_e32 v3, 0x1000, v2
	v_lshlrev_b32_e32 v1, 4, v1
	v_readfirstlane_b32 s0, v0
	s_lshr_b32 s1, s0, 6
	s_add_i32 s4, s4, -1
	s_lshl_b32 s18, s4, 8
	s_lshl_b32 s19, s5, 3
	s_add_i32 s18, s18, s19
	s_add_i32 s18, s18, s1
	s_lshr_b32 s19, s4, 4
	s_lshl_b32 s20, s18, 12
	s_lshl_b32 s21, s18, 13
	s_add_u32 s6, s88, 0x45c00000
	s_addc_u32 s7, s89, 0
	s_add_u32 s6, s6, s20
	s_addc_u32 s7, s7, 0
	s_add_u32 s10, s88, 0x13e00000
	s_addc_u32 s11, s89, 0
	s_add_u32 s10, s10, s20
	s_addc_u32 s11, s11, 0
	s_add_u32 s16, s44, 0xa000
	s_addc_u32 s17, s45, 0
	s_mul_i32 s22, s19, 0x12000
	s_add_u32 s24, s88, 0x154000
	s_addc_u32 s25, s89, 0
	s_add_u32 s24, s24, s22
	s_addc_u32 s25, s25, 0
	s_mul_i32 s22, s19, 0x12000
	s_add_u32 s26, s88, 0x156000
	s_addc_u32 s27, s89, 0
	s_add_u32 s26, s26, s22
	s_addc_u32 s27, s27, 0
	global_load_dwordx4 v[72:75], v2, s[16:17] offset:0
	global_load_dwordx4 v[76:79], v2, s[16:17] offset:16
	global_load_dwordx4 v[80:83], v2, s[16:17] offset:2048
	global_load_dwordx4 v[84:87], v2, s[16:17] offset:2064
	global_load_dwordx4 v[88:91], v3, s[16:17] offset:0
	global_load_dwordx4 v[92:95], v3, s[16:17] offset:16
	global_load_dwordx4 v[96:99], v3, s[16:17] offset:2048
	global_load_dwordx4 v[100:103], v3, s[16:17] offset:2064
	global_load_dwordx4 v[8:11], v2, s[26:27] offset:0
	global_load_dwordx4 v[12:15], v2, s[26:27] offset:16
	global_load_dwordx4 v[16:19], v2, s[26:27] offset:2048
	global_load_dwordx4 v[20:23], v2, s[26:27] offset:2064
	global_load_dwordx4 v[24:27], v3, s[26:27] offset:0
	global_load_dwordx4 v[28:31], v3, s[26:27] offset:16
	global_load_dwordx4 v[32:35], v3, s[26:27] offset:2048
	global_load_dwordx4 v[36:39], v3, s[26:27] offset:2064
	global_load_dwordx4 v[40:43], v2, s[24:25] offset:0
	global_load_dwordx4 v[44:47], v2, s[24:25] offset:16
	global_load_dwordx4 v[48:51], v2, s[24:25] offset:2048
	global_load_dwordx4 v[52:55], v2, s[24:25] offset:2064
	global_load_dwordx4 v[56:59], v3, s[24:25] offset:0
	global_load_dwordx4 v[60:63], v3, s[24:25] offset:16
	global_load_dwordx4 v[64:67], v3, s[24:25] offset:2048
	global_load_dwordx4 v[68:71], v3, s[24:25] offset:2064
	s_add_u32 s8, s6, 0x0
	s_addc_u32 s9, s7, 0
	global_load_dwordx4 v[104:107], v1, s[8:9] offset:0 nt
	global_load_dwordx4 v[108:111], v1, s[8:9] offset:1024 nt
	global_load_dwordx4 v[112:115], v1, s[8:9] offset:2048 nt
	global_load_dwordx4 v[116:119], v1, s[8:9] offset:3072 nt
	s_add_u32 s8, s6, 0x20000
	s_addc_u32 s9, s7, 0
	global_load_dwordx4 v[120:123], v1, s[8:9] offset:0 nt
	global_load_dwordx4 v[124:127], v1, s[8:9] offset:1024 nt
	global_load_dwordx4 v[128:131], v1, s[8:9] offset:2048 nt
	global_load_dwordx4 v[132:135], v1, s[8:9] offset:3072 nt
	s_add_u32 s8, s6, 0x40000
	s_addc_u32 s9, s7, 0
	global_load_dwordx4 v[136:139], v1, s[8:9] offset:0 nt
	global_load_dwordx4 v[140:143], v1, s[8:9] offset:1024 nt
	global_load_dwordx4 v[144:147], v1, s[8:9] offset:2048 nt
	global_load_dwordx4 v[148:151], v1, s[8:9] offset:3072 nt
	s_add_u32 s8, s6, 0x60000
	s_addc_u32 s9, s7, 0
	global_load_dwordx4 v[152:155], v1, s[8:9] offset:0 nt
	global_load_dwordx4 v[156:159], v1, s[8:9] offset:1024 nt
	global_load_dwordx4 v[160:163], v1, s[8:9] offset:2048 nt
	global_load_dwordx4 v[164:167], v1, s[8:9] offset:3072 nt
	s_add_u32 s8, s6, 0x80000
	s_addc_u32 s9, s7, 0
	global_load_dwordx4 v[168:171], v1, s[8:9] offset:0 nt
	global_load_dwordx4 v[172:175], v1, s[8:9] offset:1024 nt
	global_load_dwordx4 v[176:179], v1, s[8:9] offset:2048 nt
	global_load_dwordx4 v[180:183], v1, s[8:9] offset:3072 nt
	s_add_u32 s8, s6, 0xa0000
	s_addc_u32 s9, s7, 0
	global_load_dwordx4 v[184:187], v1, s[8:9] offset:0 nt
	global_load_dwordx4 v[188:191], v1, s[8:9] offset:1024 nt
	global_load_dwordx4 v[192:195], v1, s[8:9] offset:2048 nt
	global_load_dwordx4 v[196:199], v1, s[8:9] offset:3072 nt
	s_add_u32 s8, s6, 0xc0000
	s_addc_u32 s9, s7, 0
	global_load_dwordx4 v[200:203], v1, s[8:9] offset:0 nt
	global_load_dwordx4 v[204:207], v1, s[8:9] offset:1024 nt
	global_load_dwordx4 v[208:211], v1, s[8:9] offset:2048 nt
	global_load_dwordx4 v[212:215], v1, s[8:9] offset:3072 nt
	s_add_u32 s8, s6, 0xe0000
	s_addc_u32 s9, s7, 0
	global_load_dwordx4 v[216:219], v1, s[8:9] offset:0 nt
	global_load_dwordx4 v[220:223], v1, s[8:9] offset:1024 nt
	global_load_dwordx4 v[224:227], v1, s[8:9] offset:2048 nt
	global_load_dwordx4 v[228:231], v1, s[8:9] offset:3072 nt
	s_waitcnt vmcnt(32)
	v_pk_add_f32 v[8:9], v[8:9], 1.0 op_sel_hi:[1,0]
	v_pk_add_f32 v[10:11], v[10:11], 1.0 op_sel_hi:[1,0]
	v_pk_add_f32 v[12:13], v[12:13], 1.0 op_sel_hi:[1,0]
	v_pk_add_f32 v[14:15], v[14:15], 1.0 op_sel_hi:[1,0]
	v_pk_add_f32 v[16:17], v[16:17], 1.0 op_sel_hi:[1,0]
	v_pk_add_f32 v[18:19], v[18:19], 1.0 op_sel_hi:[1,0]
	v_pk_add_f32 v[20:21], v[20:21], 1.0 op_sel_hi:[1,0]
	v_pk_add_f32 v[22:23], v[22:23], 1.0 op_sel_hi:[1,0]
	v_pk_add_f32 v[24:25], v[24:25], 1.0 op_sel_hi:[1,0]
	v_pk_add_f32 v[26:27], v[26:27], 1.0 op_sel_hi:[1,0]
	v_pk_add_f32 v[28:29], v[28:29], 1.0 op_sel_hi:[1,0]
	v_pk_add_f32 v[30:31], v[30:31], 1.0 op_sel_hi:[1,0]
	v_pk_add_f32 v[32:33], v[32:33], 1.0 op_sel_hi:[1,0]
	v_pk_add_f32 v[34:35], v[34:35], 1.0 op_sel_hi:[1,0]
	v_pk_add_f32 v[36:37], v[36:37], 1.0 op_sel_hi:[1,0]
	v_pk_add_f32 v[38:39], v[38:39], 1.0 op_sel_hi:[1,0]
	v_pk_mul_f32 v[8:9], v[72:73], v[8:9]
	v_pk_mul_f32 v[10:11], v[74:75], v[10:11]
	v_pk_mul_f32 v[12:13], v[76:77], v[12:13]
	v_pk_mul_f32 v[14:15], v[78:79], v[14:15]
	v_pk_mul_f32 v[16:17], v[80:81], v[16:17]
	v_pk_mul_f32 v[18:19], v[82:83], v[18:19]
	v_pk_mul_f32 v[20:21], v[84:85], v[20:21]
	v_pk_mul_f32 v[22:23], v[86:87], v[22:23]
	v_pk_mul_f32 v[24:25], v[88:89], v[24:25]
	v_pk_mul_f32 v[26:27], v[90:91], v[26:27]
	v_pk_mul_f32 v[28:29], v[92:93], v[28:29]
	v_pk_mul_f32 v[30:31], v[94:95], v[30:31]
	v_pk_mul_f32 v[32:33], v[96:97], v[32:33]
	v_pk_mul_f32 v[34:35], v[98:99], v[34:35]
	v_pk_mul_f32 v[36:37], v[100:101], v[36:37]
	v_pk_mul_f32 v[38:39], v[102:103], v[38:39]
	v_mov_b32_e32 v248, 0x260
	s_waitcnt vmcnt(28)
	v_cvt_f32_f16_e32 v72, v104
	v_cvt_f32_f16_sdwa v73, v104 dst_sel:DWORD dst_unused:UNUSED_PAD src0_sel:WORD_1
	v_cvt_f32_f16_e32 v74, v105
	v_cvt_f32_f16_sdwa v75, v105 dst_sel:DWORD dst_unused:UNUSED_PAD src0_sel:WORD_1
	v_cvt_f32_f16_e32 v76, v106
	v_cvt_f32_f16_sdwa v77, v106 dst_sel:DWORD dst_unused:UNUSED_PAD src0_sel:WORD_1
	v_cvt_f32_f16_e32 v78, v107
	v_cvt_f32_f16_sdwa v79, v107 dst_sel:DWORD dst_unused:UNUSED_PAD src0_sel:WORD_1
	v_cvt_f32_f16_e32 v80, v108
	v_cvt_f32_f16_sdwa v81, v108 dst_sel:DWORD dst_unused:UNUSED_PAD src0_sel:WORD_1
	v_cvt_f32_f16_e32 v82, v109
	v_cvt_f32_f16_sdwa v83, v109 dst_sel:DWORD dst_unused:UNUSED_PAD src0_sel:WORD_1
	v_cvt_f32_f16_e32 v84, v110
	v_cvt_f32_f16_sdwa v85, v110 dst_sel:DWORD dst_unused:UNUSED_PAD src0_sel:WORD_1
	v_cvt_f32_f16_e32 v86, v111
	v_cvt_f32_f16_sdwa v87, v111 dst_sel:DWORD dst_unused:UNUSED_PAD src0_sel:WORD_1
	v_cvt_f32_f16_e32 v88, v112
	v_cvt_f32_f16_sdwa v89, v112 dst_sel:DWORD dst_unused:UNUSED_PAD src0_sel:WORD_1
	v_cvt_f32_f16_e32 v90, v113
	v_cvt_f32_f16_sdwa v91, v113 dst_sel:DWORD dst_unused:UNUSED_PAD src0_sel:WORD_1
	v_cvt_f32_f16_e32 v92, v114
	v_cvt_f32_f16_sdwa v93, v114 dst_sel:DWORD dst_unused:UNUSED_PAD src0_sel:WORD_1
	v_cvt_f32_f16_e32 v94, v115
	v_cvt_f32_f16_sdwa v95, v115 dst_sel:DWORD dst_unused:UNUSED_PAD src0_sel:WORD_1
	v_cvt_f32_f16_e32 v96, v116
	v_cvt_f32_f16_sdwa v97, v116 dst_sel:DWORD dst_unused:UNUSED_PAD src0_sel:WORD_1
	v_cvt_f32_f16_e32 v98, v117
	v_cvt_f32_f16_sdwa v99, v117 dst_sel:DWORD dst_unused:UNUSED_PAD src0_sel:WORD_1
	v_cvt_f32_f16_e32 v100, v118
	v_cvt_f32_f16_sdwa v101, v118 dst_sel:DWORD dst_unused:UNUSED_PAD src0_sel:WORD_1
	v_cvt_f32_f16_e32 v102, v119
	v_cvt_f32_f16_sdwa v103, v119 dst_sel:DWORD dst_unused:UNUSED_PAD src0_sel:WORD_1
	v_pk_mul_f32 v[232:233], v[72:73], v[72:73]
	v_pk_mul_f32 v[234:235], v[74:75], v[74:75]
	v_pk_mul_f32 v[236:237], v[76:77], v[76:77]
	v_pk_mul_f32 v[238:239], v[78:79], v[78:79]
	v_pk_fma_f32 v[232:233], v[80:81], v[80:81], v[232:233]
	v_pk_fma_f32 v[234:235], v[82:83], v[82:83], v[234:235]
	v_pk_fma_f32 v[236:237], v[84:85], v[84:85], v[236:237]
	v_pk_fma_f32 v[238:239], v[86:87], v[86:87], v[238:239]
	v_pk_fma_f32 v[232:233], v[88:89], v[88:89], v[232:233]
	v_pk_fma_f32 v[234:235], v[90:91], v[90:91], v[234:235]
	v_pk_fma_f32 v[236:237], v[92:93], v[92:93], v[236:237]
	v_pk_fma_f32 v[238:239], v[94:95], v[94:95], v[238:239]
	v_pk_fma_f32 v[232:233], v[96:97], v[96:97], v[232:233]
	v_pk_fma_f32 v[234:235], v[98:99], v[98:99], v[234:235]
	v_pk_fma_f32 v[236:237], v[100:101], v[100:101], v[236:237]
	v_pk_fma_f32 v[238:239], v[102:103], v[102:103], v[238:239]
	v_pk_add_f32 v[232:233], v[232:233], v[234:235]
	v_pk_add_f32 v[236:237], v[236:237], v[238:239]
	v_pk_add_f32 v[232:233], v[232:233], v[236:237]
	v_add_f32_e32 v240, v232, v233
	s_nop 1
	v_add_f32_dpp v240, v240, v240 quad_perm:[1,0,3,2] row_mask:0xf bank_mask:0xf
	s_nop 1
	v_add_f32_dpp v240, v240, v240 quad_perm:[2,3,0,1] row_mask:0xf bank_mask:0xf
	s_nop 1
	v_add_f32_dpp v240, v240, v240 row_half_mirror row_mask:0xf bank_mask:0xf
	s_nop 1
	v_add_f32_dpp v240, v240, v240 row_mirror row_mask:0xf bank_mask:0xf
	s_nop 1
	v_readlane_b32 s0, v240, 0
	v_readlane_b32 s1, v240, 16
	v_readlane_b32 s4, v240, 32
	v_readlane_b32 s5, v240, 48
	v_mov_b32_e32 v249, 0x358637bd
	s_nop 1
	v_mov_b32_e32 v240, s0
	v_add_f32_e32 v240, s1, v240
	v_add_f32_e32 v240, s4, v240
	v_add_f32_e32 v240, s5, v240
	v_fmamk_f32 v240, v240, 0x3a000000, v249
	s_mov_b32 s0, 0xf800000
	v_mul_f32_e32 v241, 0x4f800000, v240
	v_cmp_gt_f32_e32 vcc, s0, v240
	s_nop 1
	v_cndmask_b32_e32 v240, v240, v241, vcc
	v_sqrt_f32_e32 v241, v240
	s_nop 0
	v_add_u32_e32 v242, -1, v241
	v_fma_f32 v243, -v242, v241, v240
	v_cmp_ge_f32_e64 s[0:1], 0, v243
	v_add_u32_e32 v243, 1, v241
	s_nop 0
	v_cndmask_b32_e64 v242, v241, v242, s[0:1]
	v_fma_f32 v241, -v243, v241, v240
	v_cmp_lt_f32_e64 s[0:1], 0, v241
	s_nop 1
	v_cndmask_b32_e64 v241, v242, v243, s[0:1]
	v_mul_f32_e32 v242, 0x37800000, v241
	v_cndmask_b32_e32 v241, v241, v242, vcc
	v_cmp_class_f32_e32 vcc, v240, v248
	s_nop 1
	v_cndmask_b32_e32 v240, v241, v240, vcc
	v_div_scale_f32 v241, s[0:1], v240, v240, 1.0
	v_rcp_f32_e32 v242, v241
	s_nop 0
	v_fma_f32 v243, -v241, v242, 1.0
	v_fmac_f32_e32 v242, v243, v242
	v_div_scale_f32 v243, vcc, 1.0, v240, 1.0
	v_mul_f32_e32 v244, v243, v242
	v_fma_f32 v247, -v241, v244, v243
	v_fmac_f32_e32 v244, v247, v242
	v_fma_f32 v241, -v241, v244, v243
	s_nop 1
	v_div_fmas_f32 v241, v241, v242, v244
	v_div_fixup_f32 v246, v241, v240, 1.0
	v_pk_mul_f32 v[72:73], v[72:73], v[246:247] op_sel_hi:[1,0]
	v_pk_mul_f32 v[74:75], v[74:75], v[246:247] op_sel_hi:[1,0]
	v_pk_mul_f32 v[76:77], v[76:77], v[246:247] op_sel_hi:[1,0]
	v_pk_mul_f32 v[78:79], v[78:79], v[246:247] op_sel_hi:[1,0]
	v_pk_mul_f32 v[80:81], v[80:81], v[246:247] op_sel_hi:[1,0]
	v_pk_mul_f32 v[82:83], v[82:83], v[246:247] op_sel_hi:[1,0]
	v_pk_mul_f32 v[84:85], v[84:85], v[246:247] op_sel_hi:[1,0]
	v_pk_mul_f32 v[86:87], v[86:87], v[246:247] op_sel_hi:[1,0]
	v_pk_mul_f32 v[88:89], v[88:89], v[246:247] op_sel_hi:[1,0]
	v_pk_mul_f32 v[90:91], v[90:91], v[246:247] op_sel_hi:[1,0]
	v_pk_mul_f32 v[92:93], v[92:93], v[246:247] op_sel_hi:[1,0]
	v_pk_mul_f32 v[94:95], v[94:95], v[246:247] op_sel_hi:[1,0]
	v_pk_mul_f32 v[96:97], v[96:97], v[246:247] op_sel_hi:[1,0]
	v_pk_mul_f32 v[98:99], v[98:99], v[246:247] op_sel_hi:[1,0]
	v_pk_mul_f32 v[100:101], v[100:101], v[246:247] op_sel_hi:[1,0]
	v_pk_mul_f32 v[102:103], v[102:103], v[246:247] op_sel_hi:[1,0]
	s_add_u32 s8, s10, 0x0
	s_addc_u32 s9, s11, 0
	v_pk_fma_f32 v[72:73], v[8:9], v[72:73], v[40:41]
	v_cvt_pk_bf16_f32 v232, v72, v73
	v_pk_fma_f32 v[74:75], v[10:11], v[74:75], v[42:43]
	v_cvt_pk_bf16_f32 v233, v74, v75
	v_pk_fma_f32 v[76:77], v[12:13], v[76:77], v[44:45]
	v_cvt_pk_bf16_f32 v234, v76, v77
	v_pk_fma_f32 v[78:79], v[14:15], v[78:79], v[46:47]
	v_cvt_pk_bf16_f32 v235, v78, v79
	global_store_dwordx4 v1, v[232:235], s[8:9] offset:0
	v_pk_fma_f32 v[80:81], v[16:17], v[80:81], v[48:49]
	v_cvt_pk_bf16_f32 v236, v80, v81
	v_pk_fma_f32 v[82:83], v[18:19], v[82:83], v[50:51]
	v_cvt_pk_bf16_f32 v237, v82, v83
	v_pk_fma_f32 v[84:85], v[20:21], v[84:85], v[52:53]
	v_cvt_pk_bf16_f32 v238, v84, v85
	v_pk_fma_f32 v[86:87], v[22:23], v[86:87], v[54:55]
	v_cvt_pk_bf16_f32 v239, v86, v87
	global_store_dwordx4 v1, v[236:239], s[8:9] offset:1024
	v_pk_fma_f32 v[88:89], v[24:25], v[88:89], v[56:57]
	v_cvt_pk_bf16_f32 v232, v88, v89
	v_pk_fma_f32 v[90:91], v[26:27], v[90:91], v[58:59]
	v_cvt_pk_bf16_f32 v233, v90, v91
	v_pk_fma_f32 v[92:93], v[28:29], v[92:93], v[60:61]
	v_cvt_pk_bf16_f32 v234, v92, v93
	v_pk_fma_f32 v[94:95], v[30:31], v[94:95], v[62:63]
	v_cvt_pk_bf16_f32 v235, v94, v95
	global_store_dwordx4 v1, v[232:235], s[8:9] offset:2048
	v_pk_fma_f32 v[96:97], v[32:33], v[96:97], v[64:65]
	v_cvt_pk_bf16_f32 v236, v96, v97
	v_pk_fma_f32 v[98:99], v[34:35], v[98:99], v[66:67]
	v_cvt_pk_bf16_f32 v237, v98, v99
	v_pk_fma_f32 v[100:101], v[36:37], v[100:101], v[68:69]
	v_cvt_pk_bf16_f32 v238, v100, v101
	v_pk_fma_f32 v[102:103], v[38:39], v[102:103], v[70:71]
	v_cvt_pk_bf16_f32 v239, v102, v103
	global_store_dwordx4 v1, v[236:239], s[8:9] offset:3072
	s_waitcnt vmcnt(28)
	v_cvt_f32_f16_e32 v72, v120
	v_cvt_f32_f16_sdwa v73, v120 dst_sel:DWORD dst_unused:UNUSED_PAD src0_sel:WORD_1
	v_cvt_f32_f16_e32 v74, v121
	v_cvt_f32_f16_sdwa v75, v121 dst_sel:DWORD dst_unused:UNUSED_PAD src0_sel:WORD_1
	v_cvt_f32_f16_e32 v76, v122
	v_cvt_f32_f16_sdwa v77, v122 dst_sel:DWORD dst_unused:UNUSED_PAD src0_sel:WORD_1
	v_cvt_f32_f16_e32 v78, v123
	v_cvt_f32_f16_sdwa v79, v123 dst_sel:DWORD dst_unused:UNUSED_PAD src0_sel:WORD_1
	v_cvt_f32_f16_e32 v80, v124
	v_cvt_f32_f16_sdwa v81, v124 dst_sel:DWORD dst_unused:UNUSED_PAD src0_sel:WORD_1
	v_cvt_f32_f16_e32 v82, v125
	v_cvt_f32_f16_sdwa v83, v125 dst_sel:DWORD dst_unused:UNUSED_PAD src0_sel:WORD_1
	v_cvt_f32_f16_e32 v84, v126
	v_cvt_f32_f16_sdwa v85, v126 dst_sel:DWORD dst_unused:UNUSED_PAD src0_sel:WORD_1
	v_cvt_f32_f16_e32 v86, v127
	v_cvt_f32_f16_sdwa v87, v127 dst_sel:DWORD dst_unused:UNUSED_PAD src0_sel:WORD_1
	v_cvt_f32_f16_e32 v88, v128
	v_cvt_f32_f16_sdwa v89, v128 dst_sel:DWORD dst_unused:UNUSED_PAD src0_sel:WORD_1
	v_cvt_f32_f16_e32 v90, v129
	v_cvt_f32_f16_sdwa v91, v129 dst_sel:DWORD dst_unused:UNUSED_PAD src0_sel:WORD_1
	v_cvt_f32_f16_e32 v92, v130
	v_cvt_f32_f16_sdwa v93, v130 dst_sel:DWORD dst_unused:UNUSED_PAD src0_sel:WORD_1
	v_cvt_f32_f16_e32 v94, v131
	v_cvt_f32_f16_sdwa v95, v131 dst_sel:DWORD dst_unused:UNUSED_PAD src0_sel:WORD_1
	v_cvt_f32_f16_e32 v96, v132
	v_cvt_f32_f16_sdwa v97, v132 dst_sel:DWORD dst_unused:UNUSED_PAD src0_sel:WORD_1
	v_cvt_f32_f16_e32 v98, v133
	v_cvt_f32_f16_sdwa v99, v133 dst_sel:DWORD dst_unused:UNUSED_PAD src0_sel:WORD_1
	v_cvt_f32_f16_e32 v100, v134
	v_cvt_f32_f16_sdwa v101, v134 dst_sel:DWORD dst_unused:UNUSED_PAD src0_sel:WORD_1
	v_cvt_f32_f16_e32 v102, v135
	v_cvt_f32_f16_sdwa v103, v135 dst_sel:DWORD dst_unused:UNUSED_PAD src0_sel:WORD_1
	v_pk_mul_f32 v[232:233], v[72:73], v[72:73]
	v_pk_mul_f32 v[234:235], v[74:75], v[74:75]
	v_pk_mul_f32 v[236:237], v[76:77], v[76:77]
	v_pk_mul_f32 v[238:239], v[78:79], v[78:79]
	v_pk_fma_f32 v[232:233], v[80:81], v[80:81], v[232:233]
	v_pk_fma_f32 v[234:235], v[82:83], v[82:83], v[234:235]
	v_pk_fma_f32 v[236:237], v[84:85], v[84:85], v[236:237]
	v_pk_fma_f32 v[238:239], v[86:87], v[86:87], v[238:239]
	v_pk_fma_f32 v[232:233], v[88:89], v[88:89], v[232:233]
	v_pk_fma_f32 v[234:235], v[90:91], v[90:91], v[234:235]
	v_pk_fma_f32 v[236:237], v[92:93], v[92:93], v[236:237]
	v_pk_fma_f32 v[238:239], v[94:95], v[94:95], v[238:239]
	v_pk_fma_f32 v[232:233], v[96:97], v[96:97], v[232:233]
	v_pk_fma_f32 v[234:235], v[98:99], v[98:99], v[234:235]
	v_pk_fma_f32 v[236:237], v[100:101], v[100:101], v[236:237]
	v_pk_fma_f32 v[238:239], v[102:103], v[102:103], v[238:239]
	v_pk_add_f32 v[232:233], v[232:233], v[234:235]
	v_pk_add_f32 v[236:237], v[236:237], v[238:239]
	v_pk_add_f32 v[232:233], v[232:233], v[236:237]
	v_add_f32_e32 v240, v232, v233
	s_nop 1
	v_add_f32_dpp v240, v240, v240 quad_perm:[1,0,3,2] row_mask:0xf bank_mask:0xf
	s_nop 1
	v_add_f32_dpp v240, v240, v240 quad_perm:[2,3,0,1] row_mask:0xf bank_mask:0xf
	s_nop 1
	v_add_f32_dpp v240, v240, v240 row_half_mirror row_mask:0xf bank_mask:0xf
	s_nop 1
	v_add_f32_dpp v240, v240, v240 row_mirror row_mask:0xf bank_mask:0xf
	s_nop 1
	v_readlane_b32 s0, v240, 0
	v_readlane_b32 s1, v240, 16
	v_readlane_b32 s4, v240, 32
	v_readlane_b32 s5, v240, 48
	v_mov_b32_e32 v249, 0x358637bd
	s_nop 1
	v_mov_b32_e32 v240, s0
	v_add_f32_e32 v240, s1, v240
	v_add_f32_e32 v240, s4, v240
	v_add_f32_e32 v240, s5, v240
	v_fmamk_f32 v240, v240, 0x3a000000, v249
	s_mov_b32 s0, 0xf800000
	v_mul_f32_e32 v241, 0x4f800000, v240
	v_cmp_gt_f32_e32 vcc, s0, v240
	s_nop 1
	v_cndmask_b32_e32 v240, v240, v241, vcc
	v_sqrt_f32_e32 v241, v240
	s_nop 0
	v_add_u32_e32 v242, -1, v241
	v_fma_f32 v243, -v242, v241, v240
	v_cmp_ge_f32_e64 s[0:1], 0, v243
	v_add_u32_e32 v243, 1, v241
	s_nop 0
	v_cndmask_b32_e64 v242, v241, v242, s[0:1]
	v_fma_f32 v241, -v243, v241, v240
	v_cmp_lt_f32_e64 s[0:1], 0, v241
	s_nop 1
	v_cndmask_b32_e64 v241, v242, v243, s[0:1]
	v_mul_f32_e32 v242, 0x37800000, v241
	v_cndmask_b32_e32 v241, v241, v242, vcc
	v_cmp_class_f32_e32 vcc, v240, v248
	s_nop 1
	v_cndmask_b32_e32 v240, v241, v240, vcc
	v_div_scale_f32 v241, s[0:1], v240, v240, 1.0
	v_rcp_f32_e32 v242, v241
	s_nop 0
	v_fma_f32 v243, -v241, v242, 1.0
	v_fmac_f32_e32 v242, v243, v242
	v_div_scale_f32 v243, vcc, 1.0, v240, 1.0
	v_mul_f32_e32 v244, v243, v242
	v_fma_f32 v247, -v241, v244, v243
	v_fmac_f32_e32 v244, v247, v242
	v_fma_f32 v241, -v241, v244, v243
	s_nop 1
	v_div_fmas_f32 v241, v241, v242, v244
	v_div_fixup_f32 v246, v241, v240, 1.0
	v_pk_mul_f32 v[72:73], v[72:73], v[246:247] op_sel_hi:[1,0]
	v_pk_mul_f32 v[74:75], v[74:75], v[246:247] op_sel_hi:[1,0]
	v_pk_mul_f32 v[76:77], v[76:77], v[246:247] op_sel_hi:[1,0]
	v_pk_mul_f32 v[78:79], v[78:79], v[246:247] op_sel_hi:[1,0]
	v_pk_mul_f32 v[80:81], v[80:81], v[246:247] op_sel_hi:[1,0]
	v_pk_mul_f32 v[82:83], v[82:83], v[246:247] op_sel_hi:[1,0]
	v_pk_mul_f32 v[84:85], v[84:85], v[246:247] op_sel_hi:[1,0]
	v_pk_mul_f32 v[86:87], v[86:87], v[246:247] op_sel_hi:[1,0]
	v_pk_mul_f32 v[88:89], v[88:89], v[246:247] op_sel_hi:[1,0]
	v_pk_mul_f32 v[90:91], v[90:91], v[246:247] op_sel_hi:[1,0]
	v_pk_mul_f32 v[92:93], v[92:93], v[246:247] op_sel_hi:[1,0]
	v_pk_mul_f32 v[94:95], v[94:95], v[246:247] op_sel_hi:[1,0]
	v_pk_mul_f32 v[96:97], v[96:97], v[246:247] op_sel_hi:[1,0]
	v_pk_mul_f32 v[98:99], v[98:99], v[246:247] op_sel_hi:[1,0]
	v_pk_mul_f32 v[100:101], v[100:101], v[246:247] op_sel_hi:[1,0]
	v_pk_mul_f32 v[102:103], v[102:103], v[246:247] op_sel_hi:[1,0]
	s_add_u32 s8, s10, 0x20000
	s_addc_u32 s9, s11, 0
	v_pk_fma_f32 v[72:73], v[8:9], v[72:73], v[40:41]
	v_cvt_pk_bf16_f32 v232, v72, v73
	v_pk_fma_f32 v[74:75], v[10:11], v[74:75], v[42:43]
	v_cvt_pk_bf16_f32 v233, v74, v75
	v_pk_fma_f32 v[76:77], v[12:13], v[76:77], v[44:45]
	v_cvt_pk_bf16_f32 v234, v76, v77
	v_pk_fma_f32 v[78:79], v[14:15], v[78:79], v[46:47]
	v_cvt_pk_bf16_f32 v235, v78, v79
	global_store_dwordx4 v1, v[232:235], s[8:9] offset:0
	v_pk_fma_f32 v[80:81], v[16:17], v[80:81], v[48:49]
	v_cvt_pk_bf16_f32 v236, v80, v81
	v_pk_fma_f32 v[82:83], v[18:19], v[82:83], v[50:51]
	v_cvt_pk_bf16_f32 v237, v82, v83
	v_pk_fma_f32 v[84:85], v[20:21], v[84:85], v[52:53]
	v_cvt_pk_bf16_f32 v238, v84, v85
	v_pk_fma_f32 v[86:87], v[22:23], v[86:87], v[54:55]
	v_cvt_pk_bf16_f32 v239, v86, v87
	global_store_dwordx4 v1, v[236:239], s[8:9] offset:1024
	v_pk_fma_f32 v[88:89], v[24:25], v[88:89], v[56:57]
	v_cvt_pk_bf16_f32 v232, v88, v89
	v_pk_fma_f32 v[90:91], v[26:27], v[90:91], v[58:59]
	v_cvt_pk_bf16_f32 v233, v90, v91
	v_pk_fma_f32 v[92:93], v[28:29], v[92:93], v[60:61]
	v_cvt_pk_bf16_f32 v234, v92, v93
	v_pk_fma_f32 v[94:95], v[30:31], v[94:95], v[62:63]
	v_cvt_pk_bf16_f32 v235, v94, v95
	global_store_dwordx4 v1, v[232:235], s[8:9] offset:2048
	v_pk_fma_f32 v[96:97], v[32:33], v[96:97], v[64:65]
	v_cvt_pk_bf16_f32 v236, v96, v97
	v_pk_fma_f32 v[98:99], v[34:35], v[98:99], v[66:67]
	v_cvt_pk_bf16_f32 v237, v98, v99
	v_pk_fma_f32 v[100:101], v[36:37], v[100:101], v[68:69]
	v_cvt_pk_bf16_f32 v238, v100, v101
	v_pk_fma_f32 v[102:103], v[38:39], v[102:103], v[70:71]
	v_cvt_pk_bf16_f32 v239, v102, v103
	global_store_dwordx4 v1, v[236:239], s[8:9] offset:3072
	s_waitcnt vmcnt(28)
	v_cvt_f32_f16_e32 v72, v136
	v_cvt_f32_f16_sdwa v73, v136 dst_sel:DWORD dst_unused:UNUSED_PAD src0_sel:WORD_1
	v_cvt_f32_f16_e32 v74, v137
	v_cvt_f32_f16_sdwa v75, v137 dst_sel:DWORD dst_unused:UNUSED_PAD src0_sel:WORD_1
	v_cvt_f32_f16_e32 v76, v138
	v_cvt_f32_f16_sdwa v77, v138 dst_sel:DWORD dst_unused:UNUSED_PAD src0_sel:WORD_1
	v_cvt_f32_f16_e32 v78, v139
	v_cvt_f32_f16_sdwa v79, v139 dst_sel:DWORD dst_unused:UNUSED_PAD src0_sel:WORD_1
	v_cvt_f32_f16_e32 v80, v140
	v_cvt_f32_f16_sdwa v81, v140 dst_sel:DWORD dst_unused:UNUSED_PAD src0_sel:WORD_1
	v_cvt_f32_f16_e32 v82, v141
	v_cvt_f32_f16_sdwa v83, v141 dst_sel:DWORD dst_unused:UNUSED_PAD src0_sel:WORD_1
	v_cvt_f32_f16_e32 v84, v142
	v_cvt_f32_f16_sdwa v85, v142 dst_sel:DWORD dst_unused:UNUSED_PAD src0_sel:WORD_1
	v_cvt_f32_f16_e32 v86, v143
	v_cvt_f32_f16_sdwa v87, v143 dst_sel:DWORD dst_unused:UNUSED_PAD src0_sel:WORD_1
	v_cvt_f32_f16_e32 v88, v144
	v_cvt_f32_f16_sdwa v89, v144 dst_sel:DWORD dst_unused:UNUSED_PAD src0_sel:WORD_1
	v_cvt_f32_f16_e32 v90, v145
	v_cvt_f32_f16_sdwa v91, v145 dst_sel:DWORD dst_unused:UNUSED_PAD src0_sel:WORD_1
	v_cvt_f32_f16_e32 v92, v146
	v_cvt_f32_f16_sdwa v93, v146 dst_sel:DWORD dst_unused:UNUSED_PAD src0_sel:WORD_1
	v_cvt_f32_f16_e32 v94, v147
	v_cvt_f32_f16_sdwa v95, v147 dst_sel:DWORD dst_unused:UNUSED_PAD src0_sel:WORD_1
	v_cvt_f32_f16_e32 v96, v148
	v_cvt_f32_f16_sdwa v97, v148 dst_sel:DWORD dst_unused:UNUSED_PAD src0_sel:WORD_1
	v_cvt_f32_f16_e32 v98, v149
	v_cvt_f32_f16_sdwa v99, v149 dst_sel:DWORD dst_unused:UNUSED_PAD src0_sel:WORD_1
	v_cvt_f32_f16_e32 v100, v150
	v_cvt_f32_f16_sdwa v101, v150 dst_sel:DWORD dst_unused:UNUSED_PAD src0_sel:WORD_1
	v_cvt_f32_f16_e32 v102, v151
	v_cvt_f32_f16_sdwa v103, v151 dst_sel:DWORD dst_unused:UNUSED_PAD src0_sel:WORD_1
	v_pk_mul_f32 v[232:233], v[72:73], v[72:73]
	v_pk_mul_f32 v[234:235], v[74:75], v[74:75]
	v_pk_mul_f32 v[236:237], v[76:77], v[76:77]
	v_pk_mul_f32 v[238:239], v[78:79], v[78:79]
	v_pk_fma_f32 v[232:233], v[80:81], v[80:81], v[232:233]
	v_pk_fma_f32 v[234:235], v[82:83], v[82:83], v[234:235]
	v_pk_fma_f32 v[236:237], v[84:85], v[84:85], v[236:237]
	v_pk_fma_f32 v[238:239], v[86:87], v[86:87], v[238:239]
	v_pk_fma_f32 v[232:233], v[88:89], v[88:89], v[232:233]
	v_pk_fma_f32 v[234:235], v[90:91], v[90:91], v[234:235]
	v_pk_fma_f32 v[236:237], v[92:93], v[92:93], v[236:237]
	v_pk_fma_f32 v[238:239], v[94:95], v[94:95], v[238:239]
	v_pk_fma_f32 v[232:233], v[96:97], v[96:97], v[232:233]
	v_pk_fma_f32 v[234:235], v[98:99], v[98:99], v[234:235]
	v_pk_fma_f32 v[236:237], v[100:101], v[100:101], v[236:237]
	v_pk_fma_f32 v[238:239], v[102:103], v[102:103], v[238:239]
	v_pk_add_f32 v[232:233], v[232:233], v[234:235]
	v_pk_add_f32 v[236:237], v[236:237], v[238:239]
	v_pk_add_f32 v[232:233], v[232:233], v[236:237]
	v_add_f32_e32 v240, v232, v233
	s_nop 1
	v_add_f32_dpp v240, v240, v240 quad_perm:[1,0,3,2] row_mask:0xf bank_mask:0xf
	s_nop 1
	v_add_f32_dpp v240, v240, v240 quad_perm:[2,3,0,1] row_mask:0xf bank_mask:0xf
	s_nop 1
	v_add_f32_dpp v240, v240, v240 row_half_mirror row_mask:0xf bank_mask:0xf
	s_nop 1
	v_add_f32_dpp v240, v240, v240 row_mirror row_mask:0xf bank_mask:0xf
	s_nop 1
	v_readlane_b32 s0, v240, 0
	v_readlane_b32 s1, v240, 16
	v_readlane_b32 s4, v240, 32
	v_readlane_b32 s5, v240, 48
	v_mov_b32_e32 v249, 0x358637bd
	s_nop 1
	v_mov_b32_e32 v240, s0
	v_add_f32_e32 v240, s1, v240
	v_add_f32_e32 v240, s4, v240
	v_add_f32_e32 v240, s5, v240
	v_fmamk_f32 v240, v240, 0x3a000000, v249
	s_mov_b32 s0, 0xf800000
	v_mul_f32_e32 v241, 0x4f800000, v240
	v_cmp_gt_f32_e32 vcc, s0, v240
	s_nop 1
	v_cndmask_b32_e32 v240, v240, v241, vcc
	v_sqrt_f32_e32 v241, v240
	s_nop 0
	v_add_u32_e32 v242, -1, v241
	v_fma_f32 v243, -v242, v241, v240
	v_cmp_ge_f32_e64 s[0:1], 0, v243
	v_add_u32_e32 v243, 1, v241
	s_nop 0
	v_cndmask_b32_e64 v242, v241, v242, s[0:1]
	v_fma_f32 v241, -v243, v241, v240
	v_cmp_lt_f32_e64 s[0:1], 0, v241
	s_nop 1
	v_cndmask_b32_e64 v241, v242, v243, s[0:1]
	v_mul_f32_e32 v242, 0x37800000, v241
	v_cndmask_b32_e32 v241, v241, v242, vcc
	v_cmp_class_f32_e32 vcc, v240, v248
	s_nop 1
	v_cndmask_b32_e32 v240, v241, v240, vcc
	v_div_scale_f32 v241, s[0:1], v240, v240, 1.0
	v_rcp_f32_e32 v242, v241
	s_nop 0
	v_fma_f32 v243, -v241, v242, 1.0
	v_fmac_f32_e32 v242, v243, v242
	v_div_scale_f32 v243, vcc, 1.0, v240, 1.0
	v_mul_f32_e32 v244, v243, v242
	v_fma_f32 v247, -v241, v244, v243
	v_fmac_f32_e32 v244, v247, v242
	v_fma_f32 v241, -v241, v244, v243
	s_nop 1
	v_div_fmas_f32 v241, v241, v242, v244
	v_div_fixup_f32 v246, v241, v240, 1.0
	v_pk_mul_f32 v[72:73], v[72:73], v[246:247] op_sel_hi:[1,0]
	v_pk_mul_f32 v[74:75], v[74:75], v[246:247] op_sel_hi:[1,0]
	v_pk_mul_f32 v[76:77], v[76:77], v[246:247] op_sel_hi:[1,0]
	v_pk_mul_f32 v[78:79], v[78:79], v[246:247] op_sel_hi:[1,0]
	v_pk_mul_f32 v[80:81], v[80:81], v[246:247] op_sel_hi:[1,0]
	v_pk_mul_f32 v[82:83], v[82:83], v[246:247] op_sel_hi:[1,0]
	v_pk_mul_f32 v[84:85], v[84:85], v[246:247] op_sel_hi:[1,0]
	v_pk_mul_f32 v[86:87], v[86:87], v[246:247] op_sel_hi:[1,0]
	v_pk_mul_f32 v[88:89], v[88:89], v[246:247] op_sel_hi:[1,0]
	v_pk_mul_f32 v[90:91], v[90:91], v[246:247] op_sel_hi:[1,0]
	v_pk_mul_f32 v[92:93], v[92:93], v[246:247] op_sel_hi:[1,0]
	v_pk_mul_f32 v[94:95], v[94:95], v[246:247] op_sel_hi:[1,0]
	v_pk_mul_f32 v[96:97], v[96:97], v[246:247] op_sel_hi:[1,0]
	v_pk_mul_f32 v[98:99], v[98:99], v[246:247] op_sel_hi:[1,0]
	v_pk_mul_f32 v[100:101], v[100:101], v[246:247] op_sel_hi:[1,0]
	v_pk_mul_f32 v[102:103], v[102:103], v[246:247] op_sel_hi:[1,0]
	s_add_u32 s8, s10, 0x40000
	s_addc_u32 s9, s11, 0
	v_pk_fma_f32 v[72:73], v[8:9], v[72:73], v[40:41]
	v_cvt_pk_bf16_f32 v232, v72, v73
	v_pk_fma_f32 v[74:75], v[10:11], v[74:75], v[42:43]
	v_cvt_pk_bf16_f32 v233, v74, v75
	v_pk_fma_f32 v[76:77], v[12:13], v[76:77], v[44:45]
	v_cvt_pk_bf16_f32 v234, v76, v77
	v_pk_fma_f32 v[78:79], v[14:15], v[78:79], v[46:47]
	v_cvt_pk_bf16_f32 v235, v78, v79
	global_store_dwordx4 v1, v[232:235], s[8:9] offset:0
	v_pk_fma_f32 v[80:81], v[16:17], v[80:81], v[48:49]
	v_cvt_pk_bf16_f32 v236, v80, v81
	v_pk_fma_f32 v[82:83], v[18:19], v[82:83], v[50:51]
	v_cvt_pk_bf16_f32 v237, v82, v83
	v_pk_fma_f32 v[84:85], v[20:21], v[84:85], v[52:53]
	v_cvt_pk_bf16_f32 v238, v84, v85
	v_pk_fma_f32 v[86:87], v[22:23], v[86:87], v[54:55]
	v_cvt_pk_bf16_f32 v239, v86, v87
	global_store_dwordx4 v1, v[236:239], s[8:9] offset:1024
	v_pk_fma_f32 v[88:89], v[24:25], v[88:89], v[56:57]
	v_cvt_pk_bf16_f32 v232, v88, v89
	v_pk_fma_f32 v[90:91], v[26:27], v[90:91], v[58:59]
	v_cvt_pk_bf16_f32 v233, v90, v91
	v_pk_fma_f32 v[92:93], v[28:29], v[92:93], v[60:61]
	v_cvt_pk_bf16_f32 v234, v92, v93
	v_pk_fma_f32 v[94:95], v[30:31], v[94:95], v[62:63]
	v_cvt_pk_bf16_f32 v235, v94, v95
	global_store_dwordx4 v1, v[232:235], s[8:9] offset:2048
	v_pk_fma_f32 v[96:97], v[32:33], v[96:97], v[64:65]
	v_cvt_pk_bf16_f32 v236, v96, v97
	v_pk_fma_f32 v[98:99], v[34:35], v[98:99], v[66:67]
	v_cvt_pk_bf16_f32 v237, v98, v99
	v_pk_fma_f32 v[100:101], v[36:37], v[100:101], v[68:69]
	v_cvt_pk_bf16_f32 v238, v100, v101
	v_pk_fma_f32 v[102:103], v[38:39], v[102:103], v[70:71]
	v_cvt_pk_bf16_f32 v239, v102, v103
	global_store_dwordx4 v1, v[236:239], s[8:9] offset:3072
	s_waitcnt vmcnt(28)
	v_cvt_f32_f16_e32 v72, v152
	v_cvt_f32_f16_sdwa v73, v152 dst_sel:DWORD dst_unused:UNUSED_PAD src0_sel:WORD_1
	v_cvt_f32_f16_e32 v74, v153
	v_cvt_f32_f16_sdwa v75, v153 dst_sel:DWORD dst_unused:UNUSED_PAD src0_sel:WORD_1
	v_cvt_f32_f16_e32 v76, v154
	v_cvt_f32_f16_sdwa v77, v154 dst_sel:DWORD dst_unused:UNUSED_PAD src0_sel:WORD_1
	v_cvt_f32_f16_e32 v78, v155
	v_cvt_f32_f16_sdwa v79, v155 dst_sel:DWORD dst_unused:UNUSED_PAD src0_sel:WORD_1
	v_cvt_f32_f16_e32 v80, v156
	v_cvt_f32_f16_sdwa v81, v156 dst_sel:DWORD dst_unused:UNUSED_PAD src0_sel:WORD_1
	v_cvt_f32_f16_e32 v82, v157
	v_cvt_f32_f16_sdwa v83, v157 dst_sel:DWORD dst_unused:UNUSED_PAD src0_sel:WORD_1
	v_cvt_f32_f16_e32 v84, v158
	v_cvt_f32_f16_sdwa v85, v158 dst_sel:DWORD dst_unused:UNUSED_PAD src0_sel:WORD_1
	v_cvt_f32_f16_e32 v86, v159
	v_cvt_f32_f16_sdwa v87, v159 dst_sel:DWORD dst_unused:UNUSED_PAD src0_sel:WORD_1
	v_cvt_f32_f16_e32 v88, v160
	v_cvt_f32_f16_sdwa v89, v160 dst_sel:DWORD dst_unused:UNUSED_PAD src0_sel:WORD_1
	v_cvt_f32_f16_e32 v90, v161
	v_cvt_f32_f16_sdwa v91, v161 dst_sel:DWORD dst_unused:UNUSED_PAD src0_sel:WORD_1
	v_cvt_f32_f16_e32 v92, v162
	v_cvt_f32_f16_sdwa v93, v162 dst_sel:DWORD dst_unused:UNUSED_PAD src0_sel:WORD_1
	v_cvt_f32_f16_e32 v94, v163
	v_cvt_f32_f16_sdwa v95, v163 dst_sel:DWORD dst_unused:UNUSED_PAD src0_sel:WORD_1
	v_cvt_f32_f16_e32 v96, v164
	v_cvt_f32_f16_sdwa v97, v164 dst_sel:DWORD dst_unused:UNUSED_PAD src0_sel:WORD_1
	v_cvt_f32_f16_e32 v98, v165
	v_cvt_f32_f16_sdwa v99, v165 dst_sel:DWORD dst_unused:UNUSED_PAD src0_sel:WORD_1
	v_cvt_f32_f16_e32 v100, v166
	v_cvt_f32_f16_sdwa v101, v166 dst_sel:DWORD dst_unused:UNUSED_PAD src0_sel:WORD_1
	v_cvt_f32_f16_e32 v102, v167
	v_cvt_f32_f16_sdwa v103, v167 dst_sel:DWORD dst_unused:UNUSED_PAD src0_sel:WORD_1
	v_pk_mul_f32 v[232:233], v[72:73], v[72:73]
	v_pk_mul_f32 v[234:235], v[74:75], v[74:75]
	v_pk_mul_f32 v[236:237], v[76:77], v[76:77]
	v_pk_mul_f32 v[238:239], v[78:79], v[78:79]
	v_pk_fma_f32 v[232:233], v[80:81], v[80:81], v[232:233]
	v_pk_fma_f32 v[234:235], v[82:83], v[82:83], v[234:235]
	v_pk_fma_f32 v[236:237], v[84:85], v[84:85], v[236:237]
	v_pk_fma_f32 v[238:239], v[86:87], v[86:87], v[238:239]
	v_pk_fma_f32 v[232:233], v[88:89], v[88:89], v[232:233]
	v_pk_fma_f32 v[234:235], v[90:91], v[90:91], v[234:235]
	v_pk_fma_f32 v[236:237], v[92:93], v[92:93], v[236:237]
	v_pk_fma_f32 v[238:239], v[94:95], v[94:95], v[238:239]
	v_pk_fma_f32 v[232:233], v[96:97], v[96:97], v[232:233]
	v_pk_fma_f32 v[234:235], v[98:99], v[98:99], v[234:235]
	v_pk_fma_f32 v[236:237], v[100:101], v[100:101], v[236:237]
	v_pk_fma_f32 v[238:239], v[102:103], v[102:103], v[238:239]
	v_pk_add_f32 v[232:233], v[232:233], v[234:235]
	v_pk_add_f32 v[236:237], v[236:237], v[238:239]
	v_pk_add_f32 v[232:233], v[232:233], v[236:237]
	v_add_f32_e32 v240, v232, v233
	s_nop 1
	v_add_f32_dpp v240, v240, v240 quad_perm:[1,0,3,2] row_mask:0xf bank_mask:0xf
	s_nop 1
	v_add_f32_dpp v240, v240, v240 quad_perm:[2,3,0,1] row_mask:0xf bank_mask:0xf
	s_nop 1
	v_add_f32_dpp v240, v240, v240 row_half_mirror row_mask:0xf bank_mask:0xf
	s_nop 1
	v_add_f32_dpp v240, v240, v240 row_mirror row_mask:0xf bank_mask:0xf
	s_nop 1
	v_readlane_b32 s0, v240, 0
	v_readlane_b32 s1, v240, 16
	v_readlane_b32 s4, v240, 32
	v_readlane_b32 s5, v240, 48
	v_mov_b32_e32 v249, 0x358637bd
	s_nop 1
	v_mov_b32_e32 v240, s0
	v_add_f32_e32 v240, s1, v240
	v_add_f32_e32 v240, s4, v240
	v_add_f32_e32 v240, s5, v240
	v_fmamk_f32 v240, v240, 0x3a000000, v249
	s_mov_b32 s0, 0xf800000
	v_mul_f32_e32 v241, 0x4f800000, v240
	v_cmp_gt_f32_e32 vcc, s0, v240
	s_nop 1
	v_cndmask_b32_e32 v240, v240, v241, vcc
	v_sqrt_f32_e32 v241, v240
	s_nop 0
	v_add_u32_e32 v242, -1, v241
	v_fma_f32 v243, -v242, v241, v240
	v_cmp_ge_f32_e64 s[0:1], 0, v243
	v_add_u32_e32 v243, 1, v241
	s_nop 0
	v_cndmask_b32_e64 v242, v241, v242, s[0:1]
	v_fma_f32 v241, -v243, v241, v240
	v_cmp_lt_f32_e64 s[0:1], 0, v241
	s_nop 1
	v_cndmask_b32_e64 v241, v242, v243, s[0:1]
	v_mul_f32_e32 v242, 0x37800000, v241
	v_cndmask_b32_e32 v241, v241, v242, vcc
	v_cmp_class_f32_e32 vcc, v240, v248
	s_nop 1
	v_cndmask_b32_e32 v240, v241, v240, vcc
	v_div_scale_f32 v241, s[0:1], v240, v240, 1.0
	v_rcp_f32_e32 v242, v241
	s_nop 0
	v_fma_f32 v243, -v241, v242, 1.0
	v_fmac_f32_e32 v242, v243, v242
	v_div_scale_f32 v243, vcc, 1.0, v240, 1.0
	v_mul_f32_e32 v244, v243, v242
	v_fma_f32 v247, -v241, v244, v243
	v_fmac_f32_e32 v244, v247, v242
	v_fma_f32 v241, -v241, v244, v243
	s_nop 1
	v_div_fmas_f32 v241, v241, v242, v244
	v_div_fixup_f32 v246, v241, v240, 1.0
	v_pk_mul_f32 v[72:73], v[72:73], v[246:247] op_sel_hi:[1,0]
	v_pk_mul_f32 v[74:75], v[74:75], v[246:247] op_sel_hi:[1,0]
	v_pk_mul_f32 v[76:77], v[76:77], v[246:247] op_sel_hi:[1,0]
	v_pk_mul_f32 v[78:79], v[78:79], v[246:247] op_sel_hi:[1,0]
	v_pk_mul_f32 v[80:81], v[80:81], v[246:247] op_sel_hi:[1,0]
	v_pk_mul_f32 v[82:83], v[82:83], v[246:247] op_sel_hi:[1,0]
	v_pk_mul_f32 v[84:85], v[84:85], v[246:247] op_sel_hi:[1,0]
	v_pk_mul_f32 v[86:87], v[86:87], v[246:247] op_sel_hi:[1,0]
	v_pk_mul_f32 v[88:89], v[88:89], v[246:247] op_sel_hi:[1,0]
	v_pk_mul_f32 v[90:91], v[90:91], v[246:247] op_sel_hi:[1,0]
	v_pk_mul_f32 v[92:93], v[92:93], v[246:247] op_sel_hi:[1,0]
	v_pk_mul_f32 v[94:95], v[94:95], v[246:247] op_sel_hi:[1,0]
	v_pk_mul_f32 v[96:97], v[96:97], v[246:247] op_sel_hi:[1,0]
	v_pk_mul_f32 v[98:99], v[98:99], v[246:247] op_sel_hi:[1,0]
	v_pk_mul_f32 v[100:101], v[100:101], v[246:247] op_sel_hi:[1,0]
	v_pk_mul_f32 v[102:103], v[102:103], v[246:247] op_sel_hi:[1,0]
	s_add_u32 s8, s10, 0x60000
	s_addc_u32 s9, s11, 0
	v_pk_fma_f32 v[72:73], v[8:9], v[72:73], v[40:41]
	v_cvt_pk_bf16_f32 v232, v72, v73
	v_pk_fma_f32 v[74:75], v[10:11], v[74:75], v[42:43]
	v_cvt_pk_bf16_f32 v233, v74, v75
	v_pk_fma_f32 v[76:77], v[12:13], v[76:77], v[44:45]
	v_cvt_pk_bf16_f32 v234, v76, v77
	v_pk_fma_f32 v[78:79], v[14:15], v[78:79], v[46:47]
	v_cvt_pk_bf16_f32 v235, v78, v79
	global_store_dwordx4 v1, v[232:235], s[8:9] offset:0
	v_pk_fma_f32 v[80:81], v[16:17], v[80:81], v[48:49]
	v_cvt_pk_bf16_f32 v236, v80, v81
	v_pk_fma_f32 v[82:83], v[18:19], v[82:83], v[50:51]
	v_cvt_pk_bf16_f32 v237, v82, v83
	v_pk_fma_f32 v[84:85], v[20:21], v[84:85], v[52:53]
	v_cvt_pk_bf16_f32 v238, v84, v85
	v_pk_fma_f32 v[86:87], v[22:23], v[86:87], v[54:55]
	v_cvt_pk_bf16_f32 v239, v86, v87
	global_store_dwordx4 v1, v[236:239], s[8:9] offset:1024
	v_pk_fma_f32 v[88:89], v[24:25], v[88:89], v[56:57]
	v_cvt_pk_bf16_f32 v232, v88, v89
	v_pk_fma_f32 v[90:91], v[26:27], v[90:91], v[58:59]
	v_cvt_pk_bf16_f32 v233, v90, v91
	v_pk_fma_f32 v[92:93], v[28:29], v[92:93], v[60:61]
	v_cvt_pk_bf16_f32 v234, v92, v93
	v_pk_fma_f32 v[94:95], v[30:31], v[94:95], v[62:63]
	v_cvt_pk_bf16_f32 v235, v94, v95
	global_store_dwordx4 v1, v[232:235], s[8:9] offset:2048
	v_pk_fma_f32 v[96:97], v[32:33], v[96:97], v[64:65]
	v_cvt_pk_bf16_f32 v236, v96, v97
	v_pk_fma_f32 v[98:99], v[34:35], v[98:99], v[66:67]
	v_cvt_pk_bf16_f32 v237, v98, v99
	v_pk_fma_f32 v[100:101], v[36:37], v[100:101], v[68:69]
	v_cvt_pk_bf16_f32 v238, v100, v101
	v_pk_fma_f32 v[102:103], v[38:39], v[102:103], v[70:71]
	v_cvt_pk_bf16_f32 v239, v102, v103
	global_store_dwordx4 v1, v[236:239], s[8:9] offset:3072
	s_waitcnt vmcnt(28)
	v_cvt_f32_f16_e32 v72, v168
	v_cvt_f32_f16_sdwa v73, v168 dst_sel:DWORD dst_unused:UNUSED_PAD src0_sel:WORD_1
	v_cvt_f32_f16_e32 v74, v169
	v_cvt_f32_f16_sdwa v75, v169 dst_sel:DWORD dst_unused:UNUSED_PAD src0_sel:WORD_1
	v_cvt_f32_f16_e32 v76, v170
	v_cvt_f32_f16_sdwa v77, v170 dst_sel:DWORD dst_unused:UNUSED_PAD src0_sel:WORD_1
	v_cvt_f32_f16_e32 v78, v171
	v_cvt_f32_f16_sdwa v79, v171 dst_sel:DWORD dst_unused:UNUSED_PAD src0_sel:WORD_1
	v_cvt_f32_f16_e32 v80, v172
	v_cvt_f32_f16_sdwa v81, v172 dst_sel:DWORD dst_unused:UNUSED_PAD src0_sel:WORD_1
	v_cvt_f32_f16_e32 v82, v173
	v_cvt_f32_f16_sdwa v83, v173 dst_sel:DWORD dst_unused:UNUSED_PAD src0_sel:WORD_1
	v_cvt_f32_f16_e32 v84, v174
	v_cvt_f32_f16_sdwa v85, v174 dst_sel:DWORD dst_unused:UNUSED_PAD src0_sel:WORD_1
	v_cvt_f32_f16_e32 v86, v175
	v_cvt_f32_f16_sdwa v87, v175 dst_sel:DWORD dst_unused:UNUSED_PAD src0_sel:WORD_1
	v_cvt_f32_f16_e32 v88, v176
	v_cvt_f32_f16_sdwa v89, v176 dst_sel:DWORD dst_unused:UNUSED_PAD src0_sel:WORD_1
	v_cvt_f32_f16_e32 v90, v177
	v_cvt_f32_f16_sdwa v91, v177 dst_sel:DWORD dst_unused:UNUSED_PAD src0_sel:WORD_1
	v_cvt_f32_f16_e32 v92, v178
	v_cvt_f32_f16_sdwa v93, v178 dst_sel:DWORD dst_unused:UNUSED_PAD src0_sel:WORD_1
	v_cvt_f32_f16_e32 v94, v179
	v_cvt_f32_f16_sdwa v95, v179 dst_sel:DWORD dst_unused:UNUSED_PAD src0_sel:WORD_1
	v_cvt_f32_f16_e32 v96, v180
	v_cvt_f32_f16_sdwa v97, v180 dst_sel:DWORD dst_unused:UNUSED_PAD src0_sel:WORD_1
	v_cvt_f32_f16_e32 v98, v181
	v_cvt_f32_f16_sdwa v99, v181 dst_sel:DWORD dst_unused:UNUSED_PAD src0_sel:WORD_1
	v_cvt_f32_f16_e32 v100, v182
	v_cvt_f32_f16_sdwa v101, v182 dst_sel:DWORD dst_unused:UNUSED_PAD src0_sel:WORD_1
	v_cvt_f32_f16_e32 v102, v183
	v_cvt_f32_f16_sdwa v103, v183 dst_sel:DWORD dst_unused:UNUSED_PAD src0_sel:WORD_1
	v_pk_mul_f32 v[232:233], v[72:73], v[72:73]
	v_pk_mul_f32 v[234:235], v[74:75], v[74:75]
	v_pk_mul_f32 v[236:237], v[76:77], v[76:77]
	v_pk_mul_f32 v[238:239], v[78:79], v[78:79]
	v_pk_fma_f32 v[232:233], v[80:81], v[80:81], v[232:233]
	v_pk_fma_f32 v[234:235], v[82:83], v[82:83], v[234:235]
	v_pk_fma_f32 v[236:237], v[84:85], v[84:85], v[236:237]
	v_pk_fma_f32 v[238:239], v[86:87], v[86:87], v[238:239]
	v_pk_fma_f32 v[232:233], v[88:89], v[88:89], v[232:233]
	v_pk_fma_f32 v[234:235], v[90:91], v[90:91], v[234:235]
	v_pk_fma_f32 v[236:237], v[92:93], v[92:93], v[236:237]
	v_pk_fma_f32 v[238:239], v[94:95], v[94:95], v[238:239]
	v_pk_fma_f32 v[232:233], v[96:97], v[96:97], v[232:233]
	v_pk_fma_f32 v[234:235], v[98:99], v[98:99], v[234:235]
	v_pk_fma_f32 v[236:237], v[100:101], v[100:101], v[236:237]
	v_pk_fma_f32 v[238:239], v[102:103], v[102:103], v[238:239]
	v_pk_add_f32 v[232:233], v[232:233], v[234:235]
	v_pk_add_f32 v[236:237], v[236:237], v[238:239]
	v_pk_add_f32 v[232:233], v[232:233], v[236:237]
	v_add_f32_e32 v240, v232, v233
	s_nop 1
	v_add_f32_dpp v240, v240, v240 quad_perm:[1,0,3,2] row_mask:0xf bank_mask:0xf
	s_nop 1
	v_add_f32_dpp v240, v240, v240 quad_perm:[2,3,0,1] row_mask:0xf bank_mask:0xf
	s_nop 1
	v_add_f32_dpp v240, v240, v240 row_half_mirror row_mask:0xf bank_mask:0xf
	s_nop 1
	v_add_f32_dpp v240, v240, v240 row_mirror row_mask:0xf bank_mask:0xf
	s_nop 1
	v_readlane_b32 s0, v240, 0
	v_readlane_b32 s1, v240, 16
	v_readlane_b32 s4, v240, 32
	v_readlane_b32 s5, v240, 48
	v_mov_b32_e32 v249, 0x358637bd
	s_nop 1
	v_mov_b32_e32 v240, s0
	v_add_f32_e32 v240, s1, v240
	v_add_f32_e32 v240, s4, v240
	v_add_f32_e32 v240, s5, v240
	v_fmamk_f32 v240, v240, 0x3a000000, v249
	s_mov_b32 s0, 0xf800000
	v_mul_f32_e32 v241, 0x4f800000, v240
	v_cmp_gt_f32_e32 vcc, s0, v240
	s_nop 1
	v_cndmask_b32_e32 v240, v240, v241, vcc
	v_sqrt_f32_e32 v241, v240
	s_nop 0
	v_add_u32_e32 v242, -1, v241
	v_fma_f32 v243, -v242, v241, v240
	v_cmp_ge_f32_e64 s[0:1], 0, v243
	v_add_u32_e32 v243, 1, v241
	s_nop 0
	v_cndmask_b32_e64 v242, v241, v242, s[0:1]
	v_fma_f32 v241, -v243, v241, v240
	v_cmp_lt_f32_e64 s[0:1], 0, v241
	s_nop 1
	v_cndmask_b32_e64 v241, v242, v243, s[0:1]
	v_mul_f32_e32 v242, 0x37800000, v241
	v_cndmask_b32_e32 v241, v241, v242, vcc
	v_cmp_class_f32_e32 vcc, v240, v248
	s_nop 1
	v_cndmask_b32_e32 v240, v241, v240, vcc
	v_div_scale_f32 v241, s[0:1], v240, v240, 1.0
	v_rcp_f32_e32 v242, v241
	s_nop 0
	v_fma_f32 v243, -v241, v242, 1.0
	v_fmac_f32_e32 v242, v243, v242
	v_div_scale_f32 v243, vcc, 1.0, v240, 1.0
	v_mul_f32_e32 v244, v243, v242
	v_fma_f32 v247, -v241, v244, v243
	v_fmac_f32_e32 v244, v247, v242
	v_fma_f32 v241, -v241, v244, v243
	s_nop 1
	v_div_fmas_f32 v241, v241, v242, v244
	v_div_fixup_f32 v246, v241, v240, 1.0
	v_pk_mul_f32 v[72:73], v[72:73], v[246:247] op_sel_hi:[1,0]
	v_pk_mul_f32 v[74:75], v[74:75], v[246:247] op_sel_hi:[1,0]
	v_pk_mul_f32 v[76:77], v[76:77], v[246:247] op_sel_hi:[1,0]
	v_pk_mul_f32 v[78:79], v[78:79], v[246:247] op_sel_hi:[1,0]
	v_pk_mul_f32 v[80:81], v[80:81], v[246:247] op_sel_hi:[1,0]
	v_pk_mul_f32 v[82:83], v[82:83], v[246:247] op_sel_hi:[1,0]
	v_pk_mul_f32 v[84:85], v[84:85], v[246:247] op_sel_hi:[1,0]
	v_pk_mul_f32 v[86:87], v[86:87], v[246:247] op_sel_hi:[1,0]
	v_pk_mul_f32 v[88:89], v[88:89], v[246:247] op_sel_hi:[1,0]
	v_pk_mul_f32 v[90:91], v[90:91], v[246:247] op_sel_hi:[1,0]
	v_pk_mul_f32 v[92:93], v[92:93], v[246:247] op_sel_hi:[1,0]
	v_pk_mul_f32 v[94:95], v[94:95], v[246:247] op_sel_hi:[1,0]
	v_pk_mul_f32 v[96:97], v[96:97], v[246:247] op_sel_hi:[1,0]
	v_pk_mul_f32 v[98:99], v[98:99], v[246:247] op_sel_hi:[1,0]
	v_pk_mul_f32 v[100:101], v[100:101], v[246:247] op_sel_hi:[1,0]
	v_pk_mul_f32 v[102:103], v[102:103], v[246:247] op_sel_hi:[1,0]
	s_add_u32 s8, s10, 0x80000
	s_addc_u32 s9, s11, 0
	v_pk_fma_f32 v[72:73], v[8:9], v[72:73], v[40:41]
	v_cvt_pk_bf16_f32 v232, v72, v73
	v_pk_fma_f32 v[74:75], v[10:11], v[74:75], v[42:43]
	v_cvt_pk_bf16_f32 v233, v74, v75
	v_pk_fma_f32 v[76:77], v[12:13], v[76:77], v[44:45]
	v_cvt_pk_bf16_f32 v234, v76, v77
	v_pk_fma_f32 v[78:79], v[14:15], v[78:79], v[46:47]
	v_cvt_pk_bf16_f32 v235, v78, v79
	global_store_dwordx4 v1, v[232:235], s[8:9] offset:0
	v_pk_fma_f32 v[80:81], v[16:17], v[80:81], v[48:49]
	v_cvt_pk_bf16_f32 v236, v80, v81
	v_pk_fma_f32 v[82:83], v[18:19], v[82:83], v[50:51]
	v_cvt_pk_bf16_f32 v237, v82, v83
	v_pk_fma_f32 v[84:85], v[20:21], v[84:85], v[52:53]
	v_cvt_pk_bf16_f32 v238, v84, v85
	v_pk_fma_f32 v[86:87], v[22:23], v[86:87], v[54:55]
	v_cvt_pk_bf16_f32 v239, v86, v87
	global_store_dwordx4 v1, v[236:239], s[8:9] offset:1024
	v_pk_fma_f32 v[88:89], v[24:25], v[88:89], v[56:57]
	v_cvt_pk_bf16_f32 v232, v88, v89
	v_pk_fma_f32 v[90:91], v[26:27], v[90:91], v[58:59]
	v_cvt_pk_bf16_f32 v233, v90, v91
	v_pk_fma_f32 v[92:93], v[28:29], v[92:93], v[60:61]
	v_cvt_pk_bf16_f32 v234, v92, v93
	v_pk_fma_f32 v[94:95], v[30:31], v[94:95], v[62:63]
	v_cvt_pk_bf16_f32 v235, v94, v95
	global_store_dwordx4 v1, v[232:235], s[8:9] offset:2048
	v_pk_fma_f32 v[96:97], v[32:33], v[96:97], v[64:65]
	v_cvt_pk_bf16_f32 v236, v96, v97
	v_pk_fma_f32 v[98:99], v[34:35], v[98:99], v[66:67]
	v_cvt_pk_bf16_f32 v237, v98, v99
	v_pk_fma_f32 v[100:101], v[36:37], v[100:101], v[68:69]
	v_cvt_pk_bf16_f32 v238, v100, v101
	v_pk_fma_f32 v[102:103], v[38:39], v[102:103], v[70:71]
	v_cvt_pk_bf16_f32 v239, v102, v103
	global_store_dwordx4 v1, v[236:239], s[8:9] offset:3072
	s_waitcnt vmcnt(28)
	v_cvt_f32_f16_e32 v72, v184
	v_cvt_f32_f16_sdwa v73, v184 dst_sel:DWORD dst_unused:UNUSED_PAD src0_sel:WORD_1
	v_cvt_f32_f16_e32 v74, v185
	v_cvt_f32_f16_sdwa v75, v185 dst_sel:DWORD dst_unused:UNUSED_PAD src0_sel:WORD_1
	v_cvt_f32_f16_e32 v76, v186
	v_cvt_f32_f16_sdwa v77, v186 dst_sel:DWORD dst_unused:UNUSED_PAD src0_sel:WORD_1
	v_cvt_f32_f16_e32 v78, v187
	v_cvt_f32_f16_sdwa v79, v187 dst_sel:DWORD dst_unused:UNUSED_PAD src0_sel:WORD_1
	v_cvt_f32_f16_e32 v80, v188
	v_cvt_f32_f16_sdwa v81, v188 dst_sel:DWORD dst_unused:UNUSED_PAD src0_sel:WORD_1
	v_cvt_f32_f16_e32 v82, v189
	v_cvt_f32_f16_sdwa v83, v189 dst_sel:DWORD dst_unused:UNUSED_PAD src0_sel:WORD_1
	v_cvt_f32_f16_e32 v84, v190
	v_cvt_f32_f16_sdwa v85, v190 dst_sel:DWORD dst_unused:UNUSED_PAD src0_sel:WORD_1
	v_cvt_f32_f16_e32 v86, v191
	v_cvt_f32_f16_sdwa v87, v191 dst_sel:DWORD dst_unused:UNUSED_PAD src0_sel:WORD_1
	v_cvt_f32_f16_e32 v88, v192
	v_cvt_f32_f16_sdwa v89, v192 dst_sel:DWORD dst_unused:UNUSED_PAD src0_sel:WORD_1
	v_cvt_f32_f16_e32 v90, v193
	v_cvt_f32_f16_sdwa v91, v193 dst_sel:DWORD dst_unused:UNUSED_PAD src0_sel:WORD_1
	v_cvt_f32_f16_e32 v92, v194
	v_cvt_f32_f16_sdwa v93, v194 dst_sel:DWORD dst_unused:UNUSED_PAD src0_sel:WORD_1
	v_cvt_f32_f16_e32 v94, v195
	v_cvt_f32_f16_sdwa v95, v195 dst_sel:DWORD dst_unused:UNUSED_PAD src0_sel:WORD_1
	v_cvt_f32_f16_e32 v96, v196
	v_cvt_f32_f16_sdwa v97, v196 dst_sel:DWORD dst_unused:UNUSED_PAD src0_sel:WORD_1
	v_cvt_f32_f16_e32 v98, v197
	v_cvt_f32_f16_sdwa v99, v197 dst_sel:DWORD dst_unused:UNUSED_PAD src0_sel:WORD_1
	v_cvt_f32_f16_e32 v100, v198
	v_cvt_f32_f16_sdwa v101, v198 dst_sel:DWORD dst_unused:UNUSED_PAD src0_sel:WORD_1
	v_cvt_f32_f16_e32 v102, v199
	v_cvt_f32_f16_sdwa v103, v199 dst_sel:DWORD dst_unused:UNUSED_PAD src0_sel:WORD_1
	v_pk_mul_f32 v[232:233], v[72:73], v[72:73]
	v_pk_mul_f32 v[234:235], v[74:75], v[74:75]
	v_pk_mul_f32 v[236:237], v[76:77], v[76:77]
	v_pk_mul_f32 v[238:239], v[78:79], v[78:79]
	v_pk_fma_f32 v[232:233], v[80:81], v[80:81], v[232:233]
	v_pk_fma_f32 v[234:235], v[82:83], v[82:83], v[234:235]
	v_pk_fma_f32 v[236:237], v[84:85], v[84:85], v[236:237]
	v_pk_fma_f32 v[238:239], v[86:87], v[86:87], v[238:239]
	v_pk_fma_f32 v[232:233], v[88:89], v[88:89], v[232:233]
	v_pk_fma_f32 v[234:235], v[90:91], v[90:91], v[234:235]
	v_pk_fma_f32 v[236:237], v[92:93], v[92:93], v[236:237]
	v_pk_fma_f32 v[238:239], v[94:95], v[94:95], v[238:239]
	v_pk_fma_f32 v[232:233], v[96:97], v[96:97], v[232:233]
	v_pk_fma_f32 v[234:235], v[98:99], v[98:99], v[234:235]
	v_pk_fma_f32 v[236:237], v[100:101], v[100:101], v[236:237]
	v_pk_fma_f32 v[238:239], v[102:103], v[102:103], v[238:239]
	v_pk_add_f32 v[232:233], v[232:233], v[234:235]
	v_pk_add_f32 v[236:237], v[236:237], v[238:239]
	v_pk_add_f32 v[232:233], v[232:233], v[236:237]
	v_add_f32_e32 v240, v232, v233
	s_nop 1
	v_add_f32_dpp v240, v240, v240 quad_perm:[1,0,3,2] row_mask:0xf bank_mask:0xf
	s_nop 1
	v_add_f32_dpp v240, v240, v240 quad_perm:[2,3,0,1] row_mask:0xf bank_mask:0xf
	s_nop 1
	v_add_f32_dpp v240, v240, v240 row_half_mirror row_mask:0xf bank_mask:0xf
	s_nop 1
	v_add_f32_dpp v240, v240, v240 row_mirror row_mask:0xf bank_mask:0xf
	s_nop 1
	v_readlane_b32 s0, v240, 0
	v_readlane_b32 s1, v240, 16
	v_readlane_b32 s4, v240, 32
	v_readlane_b32 s5, v240, 48
	v_mov_b32_e32 v249, 0x358637bd
	s_nop 1
	v_mov_b32_e32 v240, s0
	v_add_f32_e32 v240, s1, v240
	v_add_f32_e32 v240, s4, v240
	v_add_f32_e32 v240, s5, v240
	v_fmamk_f32 v240, v240, 0x3a000000, v249
	s_mov_b32 s0, 0xf800000
	v_mul_f32_e32 v241, 0x4f800000, v240
	v_cmp_gt_f32_e32 vcc, s0, v240
	s_nop 1
	v_cndmask_b32_e32 v240, v240, v241, vcc
	v_sqrt_f32_e32 v241, v240
	s_nop 0
	v_add_u32_e32 v242, -1, v241
	v_fma_f32 v243, -v242, v241, v240
	v_cmp_ge_f32_e64 s[0:1], 0, v243
	v_add_u32_e32 v243, 1, v241
	s_nop 0
	v_cndmask_b32_e64 v242, v241, v242, s[0:1]
	v_fma_f32 v241, -v243, v241, v240
	v_cmp_lt_f32_e64 s[0:1], 0, v241
	s_nop 1
	v_cndmask_b32_e64 v241, v242, v243, s[0:1]
	v_mul_f32_e32 v242, 0x37800000, v241
	v_cndmask_b32_e32 v241, v241, v242, vcc
	v_cmp_class_f32_e32 vcc, v240, v248
	s_nop 1
	v_cndmask_b32_e32 v240, v241, v240, vcc
	v_div_scale_f32 v241, s[0:1], v240, v240, 1.0
	v_rcp_f32_e32 v242, v241
	s_nop 0
	v_fma_f32 v243, -v241, v242, 1.0
	v_fmac_f32_e32 v242, v243, v242
	v_div_scale_f32 v243, vcc, 1.0, v240, 1.0
	v_mul_f32_e32 v244, v243, v242
	v_fma_f32 v247, -v241, v244, v243
	v_fmac_f32_e32 v244, v247, v242
	v_fma_f32 v241, -v241, v244, v243
	s_nop 1
	v_div_fmas_f32 v241, v241, v242, v244
	v_div_fixup_f32 v246, v241, v240, 1.0
	v_pk_mul_f32 v[72:73], v[72:73], v[246:247] op_sel_hi:[1,0]
	v_pk_mul_f32 v[74:75], v[74:75], v[246:247] op_sel_hi:[1,0]
	v_pk_mul_f32 v[76:77], v[76:77], v[246:247] op_sel_hi:[1,0]
	v_pk_mul_f32 v[78:79], v[78:79], v[246:247] op_sel_hi:[1,0]
	v_pk_mul_f32 v[80:81], v[80:81], v[246:247] op_sel_hi:[1,0]
	v_pk_mul_f32 v[82:83], v[82:83], v[246:247] op_sel_hi:[1,0]
	v_pk_mul_f32 v[84:85], v[84:85], v[246:247] op_sel_hi:[1,0]
	v_pk_mul_f32 v[86:87], v[86:87], v[246:247] op_sel_hi:[1,0]
	v_pk_mul_f32 v[88:89], v[88:89], v[246:247] op_sel_hi:[1,0]
	v_pk_mul_f32 v[90:91], v[90:91], v[246:247] op_sel_hi:[1,0]
	v_pk_mul_f32 v[92:93], v[92:93], v[246:247] op_sel_hi:[1,0]
	v_pk_mul_f32 v[94:95], v[94:95], v[246:247] op_sel_hi:[1,0]
	v_pk_mul_f32 v[96:97], v[96:97], v[246:247] op_sel_hi:[1,0]
	v_pk_mul_f32 v[98:99], v[98:99], v[246:247] op_sel_hi:[1,0]
	v_pk_mul_f32 v[100:101], v[100:101], v[246:247] op_sel_hi:[1,0]
	v_pk_mul_f32 v[102:103], v[102:103], v[246:247] op_sel_hi:[1,0]
	s_add_u32 s8, s10, 0xa0000
	s_addc_u32 s9, s11, 0
	v_pk_fma_f32 v[72:73], v[8:9], v[72:73], v[40:41]
	v_cvt_pk_bf16_f32 v232, v72, v73
	v_pk_fma_f32 v[74:75], v[10:11], v[74:75], v[42:43]
	v_cvt_pk_bf16_f32 v233, v74, v75
	v_pk_fma_f32 v[76:77], v[12:13], v[76:77], v[44:45]
	v_cvt_pk_bf16_f32 v234, v76, v77
	v_pk_fma_f32 v[78:79], v[14:15], v[78:79], v[46:47]
	v_cvt_pk_bf16_f32 v235, v78, v79
	global_store_dwordx4 v1, v[232:235], s[8:9] offset:0
	v_pk_fma_f32 v[80:81], v[16:17], v[80:81], v[48:49]
	v_cvt_pk_bf16_f32 v236, v80, v81
	v_pk_fma_f32 v[82:83], v[18:19], v[82:83], v[50:51]
	v_cvt_pk_bf16_f32 v237, v82, v83
	v_pk_fma_f32 v[84:85], v[20:21], v[84:85], v[52:53]
	v_cvt_pk_bf16_f32 v238, v84, v85
	v_pk_fma_f32 v[86:87], v[22:23], v[86:87], v[54:55]
	v_cvt_pk_bf16_f32 v239, v86, v87
	global_store_dwordx4 v1, v[236:239], s[8:9] offset:1024
	v_pk_fma_f32 v[88:89], v[24:25], v[88:89], v[56:57]
	v_cvt_pk_bf16_f32 v232, v88, v89
	v_pk_fma_f32 v[90:91], v[26:27], v[90:91], v[58:59]
	v_cvt_pk_bf16_f32 v233, v90, v91
	v_pk_fma_f32 v[92:93], v[28:29], v[92:93], v[60:61]
	v_cvt_pk_bf16_f32 v234, v92, v93
	v_pk_fma_f32 v[94:95], v[30:31], v[94:95], v[62:63]
	v_cvt_pk_bf16_f32 v235, v94, v95
	global_store_dwordx4 v1, v[232:235], s[8:9] offset:2048
	v_pk_fma_f32 v[96:97], v[32:33], v[96:97], v[64:65]
	v_cvt_pk_bf16_f32 v236, v96, v97
	v_pk_fma_f32 v[98:99], v[34:35], v[98:99], v[66:67]
	v_cvt_pk_bf16_f32 v237, v98, v99
	v_pk_fma_f32 v[100:101], v[36:37], v[100:101], v[68:69]
	v_cvt_pk_bf16_f32 v238, v100, v101
	v_pk_fma_f32 v[102:103], v[38:39], v[102:103], v[70:71]
	v_cvt_pk_bf16_f32 v239, v102, v103
	global_store_dwordx4 v1, v[236:239], s[8:9] offset:3072
	s_waitcnt vmcnt(28)
	v_cvt_f32_f16_e32 v72, v200
	v_cvt_f32_f16_sdwa v73, v200 dst_sel:DWORD dst_unused:UNUSED_PAD src0_sel:WORD_1
	v_cvt_f32_f16_e32 v74, v201
	v_cvt_f32_f16_sdwa v75, v201 dst_sel:DWORD dst_unused:UNUSED_PAD src0_sel:WORD_1
	v_cvt_f32_f16_e32 v76, v202
	v_cvt_f32_f16_sdwa v77, v202 dst_sel:DWORD dst_unused:UNUSED_PAD src0_sel:WORD_1
	v_cvt_f32_f16_e32 v78, v203
	v_cvt_f32_f16_sdwa v79, v203 dst_sel:DWORD dst_unused:UNUSED_PAD src0_sel:WORD_1
	v_cvt_f32_f16_e32 v80, v204
	v_cvt_f32_f16_sdwa v81, v204 dst_sel:DWORD dst_unused:UNUSED_PAD src0_sel:WORD_1
	v_cvt_f32_f16_e32 v82, v205
	v_cvt_f32_f16_sdwa v83, v205 dst_sel:DWORD dst_unused:UNUSED_PAD src0_sel:WORD_1
	v_cvt_f32_f16_e32 v84, v206
	v_cvt_f32_f16_sdwa v85, v206 dst_sel:DWORD dst_unused:UNUSED_PAD src0_sel:WORD_1
	v_cvt_f32_f16_e32 v86, v207
	v_cvt_f32_f16_sdwa v87, v207 dst_sel:DWORD dst_unused:UNUSED_PAD src0_sel:WORD_1
	v_cvt_f32_f16_e32 v88, v208
	v_cvt_f32_f16_sdwa v89, v208 dst_sel:DWORD dst_unused:UNUSED_PAD src0_sel:WORD_1
	v_cvt_f32_f16_e32 v90, v209
	v_cvt_f32_f16_sdwa v91, v209 dst_sel:DWORD dst_unused:UNUSED_PAD src0_sel:WORD_1
	v_cvt_f32_f16_e32 v92, v210
	v_cvt_f32_f16_sdwa v93, v210 dst_sel:DWORD dst_unused:UNUSED_PAD src0_sel:WORD_1
	v_cvt_f32_f16_e32 v94, v211
	v_cvt_f32_f16_sdwa v95, v211 dst_sel:DWORD dst_unused:UNUSED_PAD src0_sel:WORD_1
	v_cvt_f32_f16_e32 v96, v212
	v_cvt_f32_f16_sdwa v97, v212 dst_sel:DWORD dst_unused:UNUSED_PAD src0_sel:WORD_1
	v_cvt_f32_f16_e32 v98, v213
	v_cvt_f32_f16_sdwa v99, v213 dst_sel:DWORD dst_unused:UNUSED_PAD src0_sel:WORD_1
	v_cvt_f32_f16_e32 v100, v214
	v_cvt_f32_f16_sdwa v101, v214 dst_sel:DWORD dst_unused:UNUSED_PAD src0_sel:WORD_1
	v_cvt_f32_f16_e32 v102, v215
	v_cvt_f32_f16_sdwa v103, v215 dst_sel:DWORD dst_unused:UNUSED_PAD src0_sel:WORD_1
	v_pk_mul_f32 v[232:233], v[72:73], v[72:73]
	v_pk_mul_f32 v[234:235], v[74:75], v[74:75]
	v_pk_mul_f32 v[236:237], v[76:77], v[76:77]
	v_pk_mul_f32 v[238:239], v[78:79], v[78:79]
	v_pk_fma_f32 v[232:233], v[80:81], v[80:81], v[232:233]
	v_pk_fma_f32 v[234:235], v[82:83], v[82:83], v[234:235]
	v_pk_fma_f32 v[236:237], v[84:85], v[84:85], v[236:237]
	v_pk_fma_f32 v[238:239], v[86:87], v[86:87], v[238:239]
	v_pk_fma_f32 v[232:233], v[88:89], v[88:89], v[232:233]
	v_pk_fma_f32 v[234:235], v[90:91], v[90:91], v[234:235]
	v_pk_fma_f32 v[236:237], v[92:93], v[92:93], v[236:237]
	v_pk_fma_f32 v[238:239], v[94:95], v[94:95], v[238:239]
	v_pk_fma_f32 v[232:233], v[96:97], v[96:97], v[232:233]
	v_pk_fma_f32 v[234:235], v[98:99], v[98:99], v[234:235]
	v_pk_fma_f32 v[236:237], v[100:101], v[100:101], v[236:237]
	v_pk_fma_f32 v[238:239], v[102:103], v[102:103], v[238:239]
	v_pk_add_f32 v[232:233], v[232:233], v[234:235]
	v_pk_add_f32 v[236:237], v[236:237], v[238:239]
	v_pk_add_f32 v[232:233], v[232:233], v[236:237]
	v_add_f32_e32 v240, v232, v233
	s_nop 1
	v_add_f32_dpp v240, v240, v240 quad_perm:[1,0,3,2] row_mask:0xf bank_mask:0xf
	s_nop 1
	v_add_f32_dpp v240, v240, v240 quad_perm:[2,3,0,1] row_mask:0xf bank_mask:0xf
	s_nop 1
	v_add_f32_dpp v240, v240, v240 row_half_mirror row_mask:0xf bank_mask:0xf
	s_nop 1
	v_add_f32_dpp v240, v240, v240 row_mirror row_mask:0xf bank_mask:0xf
	s_nop 1
	v_readlane_b32 s0, v240, 0
	v_readlane_b32 s1, v240, 16
	v_readlane_b32 s4, v240, 32
	v_readlane_b32 s5, v240, 48
	v_mov_b32_e32 v249, 0x358637bd
	s_nop 1
	v_mov_b32_e32 v240, s0
	v_add_f32_e32 v240, s1, v240
	v_add_f32_e32 v240, s4, v240
	v_add_f32_e32 v240, s5, v240
	v_fmamk_f32 v240, v240, 0x3a000000, v249
	s_mov_b32 s0, 0xf800000
	v_mul_f32_e32 v241, 0x4f800000, v240
	v_cmp_gt_f32_e32 vcc, s0, v240
	s_nop 1
	v_cndmask_b32_e32 v240, v240, v241, vcc
	v_sqrt_f32_e32 v241, v240
	s_nop 0
	v_add_u32_e32 v242, -1, v241
	v_fma_f32 v243, -v242, v241, v240
	v_cmp_ge_f32_e64 s[0:1], 0, v243
	v_add_u32_e32 v243, 1, v241
	s_nop 0
	v_cndmask_b32_e64 v242, v241, v242, s[0:1]
	v_fma_f32 v241, -v243, v241, v240
	v_cmp_lt_f32_e64 s[0:1], 0, v241
	s_nop 1
	v_cndmask_b32_e64 v241, v242, v243, s[0:1]
	v_mul_f32_e32 v242, 0x37800000, v241
	v_cndmask_b32_e32 v241, v241, v242, vcc
	v_cmp_class_f32_e32 vcc, v240, v248
	s_nop 1
	v_cndmask_b32_e32 v240, v241, v240, vcc
	v_div_scale_f32 v241, s[0:1], v240, v240, 1.0
	v_rcp_f32_e32 v242, v241
	s_nop 0
	v_fma_f32 v243, -v241, v242, 1.0
	v_fmac_f32_e32 v242, v243, v242
	v_div_scale_f32 v243, vcc, 1.0, v240, 1.0
	v_mul_f32_e32 v244, v243, v242
	v_fma_f32 v247, -v241, v244, v243
	v_fmac_f32_e32 v244, v247, v242
	v_fma_f32 v241, -v241, v244, v243
	s_nop 1
	v_div_fmas_f32 v241, v241, v242, v244
	v_div_fixup_f32 v246, v241, v240, 1.0
	v_pk_mul_f32 v[72:73], v[72:73], v[246:247] op_sel_hi:[1,0]
	v_pk_mul_f32 v[74:75], v[74:75], v[246:247] op_sel_hi:[1,0]
	v_pk_mul_f32 v[76:77], v[76:77], v[246:247] op_sel_hi:[1,0]
	v_pk_mul_f32 v[78:79], v[78:79], v[246:247] op_sel_hi:[1,0]
	v_pk_mul_f32 v[80:81], v[80:81], v[246:247] op_sel_hi:[1,0]
	v_pk_mul_f32 v[82:83], v[82:83], v[246:247] op_sel_hi:[1,0]
	v_pk_mul_f32 v[84:85], v[84:85], v[246:247] op_sel_hi:[1,0]
	v_pk_mul_f32 v[86:87], v[86:87], v[246:247] op_sel_hi:[1,0]
	v_pk_mul_f32 v[88:89], v[88:89], v[246:247] op_sel_hi:[1,0]
	v_pk_mul_f32 v[90:91], v[90:91], v[246:247] op_sel_hi:[1,0]
	v_pk_mul_f32 v[92:93], v[92:93], v[246:247] op_sel_hi:[1,0]
	v_pk_mul_f32 v[94:95], v[94:95], v[246:247] op_sel_hi:[1,0]
	v_pk_mul_f32 v[96:97], v[96:97], v[246:247] op_sel_hi:[1,0]
	v_pk_mul_f32 v[98:99], v[98:99], v[246:247] op_sel_hi:[1,0]
	v_pk_mul_f32 v[100:101], v[100:101], v[246:247] op_sel_hi:[1,0]
	v_pk_mul_f32 v[102:103], v[102:103], v[246:247] op_sel_hi:[1,0]
	s_add_u32 s8, s10, 0xc0000
	s_addc_u32 s9, s11, 0
	v_pk_fma_f32 v[72:73], v[8:9], v[72:73], v[40:41]
	v_cvt_pk_bf16_f32 v232, v72, v73
	v_pk_fma_f32 v[74:75], v[10:11], v[74:75], v[42:43]
	v_cvt_pk_bf16_f32 v233, v74, v75
	v_pk_fma_f32 v[76:77], v[12:13], v[76:77], v[44:45]
	v_cvt_pk_bf16_f32 v234, v76, v77
	v_pk_fma_f32 v[78:79], v[14:15], v[78:79], v[46:47]
	v_cvt_pk_bf16_f32 v235, v78, v79
	global_store_dwordx4 v1, v[232:235], s[8:9] offset:0
	v_pk_fma_f32 v[80:81], v[16:17], v[80:81], v[48:49]
	v_cvt_pk_bf16_f32 v236, v80, v81
	v_pk_fma_f32 v[82:83], v[18:19], v[82:83], v[50:51]
	v_cvt_pk_bf16_f32 v237, v82, v83
	v_pk_fma_f32 v[84:85], v[20:21], v[84:85], v[52:53]
	v_cvt_pk_bf16_f32 v238, v84, v85
	v_pk_fma_f32 v[86:87], v[22:23], v[86:87], v[54:55]
	v_cvt_pk_bf16_f32 v239, v86, v87
	global_store_dwordx4 v1, v[236:239], s[8:9] offset:1024
	v_pk_fma_f32 v[88:89], v[24:25], v[88:89], v[56:57]
	v_cvt_pk_bf16_f32 v232, v88, v89
	v_pk_fma_f32 v[90:91], v[26:27], v[90:91], v[58:59]
	v_cvt_pk_bf16_f32 v233, v90, v91
	v_pk_fma_f32 v[92:93], v[28:29], v[92:93], v[60:61]
	v_cvt_pk_bf16_f32 v234, v92, v93
	v_pk_fma_f32 v[94:95], v[30:31], v[94:95], v[62:63]
	v_cvt_pk_bf16_f32 v235, v94, v95
	global_store_dwordx4 v1, v[232:235], s[8:9] offset:2048
	v_pk_fma_f32 v[96:97], v[32:33], v[96:97], v[64:65]
	v_cvt_pk_bf16_f32 v236, v96, v97
	v_pk_fma_f32 v[98:99], v[34:35], v[98:99], v[66:67]
	v_cvt_pk_bf16_f32 v237, v98, v99
	v_pk_fma_f32 v[100:101], v[36:37], v[100:101], v[68:69]
	v_cvt_pk_bf16_f32 v238, v100, v101
	v_pk_fma_f32 v[102:103], v[38:39], v[102:103], v[70:71]
	v_cvt_pk_bf16_f32 v239, v102, v103
	global_store_dwordx4 v1, v[236:239], s[8:9] offset:3072
	s_waitcnt vmcnt(28)
	v_cvt_f32_f16_e32 v72, v216
	v_cvt_f32_f16_sdwa v73, v216 dst_sel:DWORD dst_unused:UNUSED_PAD src0_sel:WORD_1
	v_cvt_f32_f16_e32 v74, v217
	v_cvt_f32_f16_sdwa v75, v217 dst_sel:DWORD dst_unused:UNUSED_PAD src0_sel:WORD_1
	v_cvt_f32_f16_e32 v76, v218
	v_cvt_f32_f16_sdwa v77, v218 dst_sel:DWORD dst_unused:UNUSED_PAD src0_sel:WORD_1
	v_cvt_f32_f16_e32 v78, v219
	v_cvt_f32_f16_sdwa v79, v219 dst_sel:DWORD dst_unused:UNUSED_PAD src0_sel:WORD_1
	v_cvt_f32_f16_e32 v80, v220
	v_cvt_f32_f16_sdwa v81, v220 dst_sel:DWORD dst_unused:UNUSED_PAD src0_sel:WORD_1
	v_cvt_f32_f16_e32 v82, v221
	v_cvt_f32_f16_sdwa v83, v221 dst_sel:DWORD dst_unused:UNUSED_PAD src0_sel:WORD_1
	v_cvt_f32_f16_e32 v84, v222
	v_cvt_f32_f16_sdwa v85, v222 dst_sel:DWORD dst_unused:UNUSED_PAD src0_sel:WORD_1
	v_cvt_f32_f16_e32 v86, v223
	v_cvt_f32_f16_sdwa v87, v223 dst_sel:DWORD dst_unused:UNUSED_PAD src0_sel:WORD_1
	v_cvt_f32_f16_e32 v88, v224
	v_cvt_f32_f16_sdwa v89, v224 dst_sel:DWORD dst_unused:UNUSED_PAD src0_sel:WORD_1
	v_cvt_f32_f16_e32 v90, v225
	v_cvt_f32_f16_sdwa v91, v225 dst_sel:DWORD dst_unused:UNUSED_PAD src0_sel:WORD_1
	v_cvt_f32_f16_e32 v92, v226
	v_cvt_f32_f16_sdwa v93, v226 dst_sel:DWORD dst_unused:UNUSED_PAD src0_sel:WORD_1
	v_cvt_f32_f16_e32 v94, v227
	v_cvt_f32_f16_sdwa v95, v227 dst_sel:DWORD dst_unused:UNUSED_PAD src0_sel:WORD_1
	v_cvt_f32_f16_e32 v96, v228
	v_cvt_f32_f16_sdwa v97, v228 dst_sel:DWORD dst_unused:UNUSED_PAD src0_sel:WORD_1
	v_cvt_f32_f16_e32 v98, v229
	v_cvt_f32_f16_sdwa v99, v229 dst_sel:DWORD dst_unused:UNUSED_PAD src0_sel:WORD_1
	v_cvt_f32_f16_e32 v100, v230
	v_cvt_f32_f16_sdwa v101, v230 dst_sel:DWORD dst_unused:UNUSED_PAD src0_sel:WORD_1
	v_cvt_f32_f16_e32 v102, v231
	v_cvt_f32_f16_sdwa v103, v231 dst_sel:DWORD dst_unused:UNUSED_PAD src0_sel:WORD_1
	v_pk_mul_f32 v[232:233], v[72:73], v[72:73]
	v_pk_mul_f32 v[234:235], v[74:75], v[74:75]
	v_pk_mul_f32 v[236:237], v[76:77], v[76:77]
	v_pk_mul_f32 v[238:239], v[78:79], v[78:79]
	v_pk_fma_f32 v[232:233], v[80:81], v[80:81], v[232:233]
	v_pk_fma_f32 v[234:235], v[82:83], v[82:83], v[234:235]
	v_pk_fma_f32 v[236:237], v[84:85], v[84:85], v[236:237]
	v_pk_fma_f32 v[238:239], v[86:87], v[86:87], v[238:239]
	v_pk_fma_f32 v[232:233], v[88:89], v[88:89], v[232:233]
	v_pk_fma_f32 v[234:235], v[90:91], v[90:91], v[234:235]
	v_pk_fma_f32 v[236:237], v[92:93], v[92:93], v[236:237]
	v_pk_fma_f32 v[238:239], v[94:95], v[94:95], v[238:239]
	v_pk_fma_f32 v[232:233], v[96:97], v[96:97], v[232:233]
	v_pk_fma_f32 v[234:235], v[98:99], v[98:99], v[234:235]
	v_pk_fma_f32 v[236:237], v[100:101], v[100:101], v[236:237]
	v_pk_fma_f32 v[238:239], v[102:103], v[102:103], v[238:239]
	v_pk_add_f32 v[232:233], v[232:233], v[234:235]
	v_pk_add_f32 v[236:237], v[236:237], v[238:239]
	v_pk_add_f32 v[232:233], v[232:233], v[236:237]
	v_add_f32_e32 v240, v232, v233
	s_nop 1
	v_add_f32_dpp v240, v240, v240 quad_perm:[1,0,3,2] row_mask:0xf bank_mask:0xf
	s_nop 1
	v_add_f32_dpp v240, v240, v240 quad_perm:[2,3,0,1] row_mask:0xf bank_mask:0xf
	s_nop 1
	v_add_f32_dpp v240, v240, v240 row_half_mirror row_mask:0xf bank_mask:0xf
	s_nop 1
	v_add_f32_dpp v240, v240, v240 row_mirror row_mask:0xf bank_mask:0xf
	s_nop 1
	v_readlane_b32 s0, v240, 0
	v_readlane_b32 s1, v240, 16
	v_readlane_b32 s4, v240, 32
	v_readlane_b32 s5, v240, 48
	v_mov_b32_e32 v249, 0x358637bd
	s_nop 1
	v_mov_b32_e32 v240, s0
	v_add_f32_e32 v240, s1, v240
	v_add_f32_e32 v240, s4, v240
	v_add_f32_e32 v240, s5, v240
	v_fmamk_f32 v240, v240, 0x3a000000, v249
	s_mov_b32 s0, 0xf800000
	v_mul_f32_e32 v241, 0x4f800000, v240
	v_cmp_gt_f32_e32 vcc, s0, v240
	s_nop 1
	v_cndmask_b32_e32 v240, v240, v241, vcc
	v_sqrt_f32_e32 v241, v240
	s_nop 0
	v_add_u32_e32 v242, -1, v241
	v_fma_f32 v243, -v242, v241, v240
	v_cmp_ge_f32_e64 s[0:1], 0, v243
	v_add_u32_e32 v243, 1, v241
	s_nop 0
	v_cndmask_b32_e64 v242, v241, v242, s[0:1]
	v_fma_f32 v241, -v243, v241, v240
	v_cmp_lt_f32_e64 s[0:1], 0, v241
	s_nop 1
	v_cndmask_b32_e64 v241, v242, v243, s[0:1]
	v_mul_f32_e32 v242, 0x37800000, v241
	v_cndmask_b32_e32 v241, v241, v242, vcc
	v_cmp_class_f32_e32 vcc, v240, v248
	s_nop 1
	v_cndmask_b32_e32 v240, v241, v240, vcc
	v_div_scale_f32 v241, s[0:1], v240, v240, 1.0
	v_rcp_f32_e32 v242, v241
	s_nop 0
	v_fma_f32 v243, -v241, v242, 1.0
	v_fmac_f32_e32 v242, v243, v242
	v_div_scale_f32 v243, vcc, 1.0, v240, 1.0
	v_mul_f32_e32 v244, v243, v242
	v_fma_f32 v247, -v241, v244, v243
	v_fmac_f32_e32 v244, v247, v242
	v_fma_f32 v241, -v241, v244, v243
	s_nop 1
	v_div_fmas_f32 v241, v241, v242, v244
	v_div_fixup_f32 v246, v241, v240, 1.0
	v_pk_mul_f32 v[72:73], v[72:73], v[246:247] op_sel_hi:[1,0]
	v_pk_mul_f32 v[74:75], v[74:75], v[246:247] op_sel_hi:[1,0]
	v_pk_mul_f32 v[76:77], v[76:77], v[246:247] op_sel_hi:[1,0]
	v_pk_mul_f32 v[78:79], v[78:79], v[246:247] op_sel_hi:[1,0]
	v_pk_mul_f32 v[80:81], v[80:81], v[246:247] op_sel_hi:[1,0]
	v_pk_mul_f32 v[82:83], v[82:83], v[246:247] op_sel_hi:[1,0]
	v_pk_mul_f32 v[84:85], v[84:85], v[246:247] op_sel_hi:[1,0]
	v_pk_mul_f32 v[86:87], v[86:87], v[246:247] op_sel_hi:[1,0]
	v_pk_mul_f32 v[88:89], v[88:89], v[246:247] op_sel_hi:[1,0]
	v_pk_mul_f32 v[90:91], v[90:91], v[246:247] op_sel_hi:[1,0]
	v_pk_mul_f32 v[92:93], v[92:93], v[246:247] op_sel_hi:[1,0]
	v_pk_mul_f32 v[94:95], v[94:95], v[246:247] op_sel_hi:[1,0]
	v_pk_mul_f32 v[96:97], v[96:97], v[246:247] op_sel_hi:[1,0]
	v_pk_mul_f32 v[98:99], v[98:99], v[246:247] op_sel_hi:[1,0]
	v_pk_mul_f32 v[100:101], v[100:101], v[246:247] op_sel_hi:[1,0]
	v_pk_mul_f32 v[102:103], v[102:103], v[246:247] op_sel_hi:[1,0]
	s_add_u32 s8, s10, 0xe0000
	s_addc_u32 s9, s11, 0
	v_pk_fma_f32 v[72:73], v[8:9], v[72:73], v[40:41]
	v_cvt_pk_bf16_f32 v232, v72, v73
	v_pk_fma_f32 v[74:75], v[10:11], v[74:75], v[42:43]
	v_cvt_pk_bf16_f32 v233, v74, v75
	v_pk_fma_f32 v[76:77], v[12:13], v[76:77], v[44:45]
	v_cvt_pk_bf16_f32 v234, v76, v77
	v_pk_fma_f32 v[78:79], v[14:15], v[78:79], v[46:47]
	v_cvt_pk_bf16_f32 v235, v78, v79
	global_store_dwordx4 v1, v[232:235], s[8:9] offset:0
	v_pk_fma_f32 v[80:81], v[16:17], v[80:81], v[48:49]
	v_cvt_pk_bf16_f32 v236, v80, v81
	v_pk_fma_f32 v[82:83], v[18:19], v[82:83], v[50:51]
	v_cvt_pk_bf16_f32 v237, v82, v83
	v_pk_fma_f32 v[84:85], v[20:21], v[84:85], v[52:53]
	v_cvt_pk_bf16_f32 v238, v84, v85
	v_pk_fma_f32 v[86:87], v[22:23], v[86:87], v[54:55]
	v_cvt_pk_bf16_f32 v239, v86, v87
	global_store_dwordx4 v1, v[236:239], s[8:9] offset:1024
	v_pk_fma_f32 v[88:89], v[24:25], v[88:89], v[56:57]
	v_cvt_pk_bf16_f32 v232, v88, v89
	v_pk_fma_f32 v[90:91], v[26:27], v[90:91], v[58:59]
	v_cvt_pk_bf16_f32 v233, v90, v91
	v_pk_fma_f32 v[92:93], v[28:29], v[92:93], v[60:61]
	v_cvt_pk_bf16_f32 v234, v92, v93
	v_pk_fma_f32 v[94:95], v[30:31], v[94:95], v[62:63]
	v_cvt_pk_bf16_f32 v235, v94, v95
	global_store_dwordx4 v1, v[232:235], s[8:9] offset:2048
	v_pk_fma_f32 v[96:97], v[32:33], v[96:97], v[64:65]
	v_cvt_pk_bf16_f32 v236, v96, v97
	v_pk_fma_f32 v[98:99], v[34:35], v[98:99], v[66:67]
	v_cvt_pk_bf16_f32 v237, v98, v99
	v_pk_fma_f32 v[100:101], v[36:37], v[100:101], v[68:69]
	v_cvt_pk_bf16_f32 v238, v100, v101
	v_pk_fma_f32 v[102:103], v[38:39], v[102:103], v[70:71]
	v_cvt_pk_bf16_f32 v239, v102, v103
	global_store_dwordx4 v1, v[236:239], s[8:9] offset:3072
	s_branch .LBB0_2500

.LBB0_2870:
	v_readlane_b32 s4, v250, 12
	s_cmp_lt_i32 s4, 24
	s_cselect_b64 s[0:1], -1, 0
	s_and_b64 s[0:1], s[0:1], s[2:3]
	s_andn2_b64 vcc, exec, s[0:1]
	v_readlane_b32 s5, v250, 13
	v_readlane_b32 s6, v250, 14
	v_readlane_b32 s7, v250, 15
	s_cbranch_vccnz .LBB0_2880
	v_mov_b32_e32 v1, 0x2416c
	ds_read_b32 v2, v1
	ds_read_b32 v1, v1 offset:4
	s_waitcnt lgkmcnt(0)
	v_readfirstlane_b32 s4, v2
	v_readfirstlane_b32 s5, v1
	s_cmp_lt_i32 s4, 1
	s_cbranch_scc1 .Lnorm_fb_fin
	v_and_b32_e32 v1, 63, v0
	v_lshlrev_b32_e32 v2, 5, v1
	v_add_u32_e32 v3, 0x1000, v2
	v_lshlrev_b32_e32 v1, 4, v1
	v_readfirstlane_b32 s0, v0
	s_lshr_b32 s1, s0, 6
	s_add_i32 s4, s4, -1
	s_lshl_b32 s18, s4, 8
	s_lshl_b32 s19, s5, 3
	s_add_i32 s18, s18, s19
	s_add_i32 s18, s18, s1
	s_lshr_b32 s19, s4, 4
	s_lshl_b32 s20, s18, 12
	s_lshl_b32 s21, s18, 13
	s_add_u32 s6, s88, 0x45c00000
	s_addc_u32 s7, s89, 0
	s_add_u32 s6, s6, s20
	s_addc_u32 s7, s7, 0
	v_readlane_b32 s10, v250, 2
	v_readlane_b32 s11, v250, 3
	s_nop 4
	s_add_u32 s10, s10, s21
	s_addc_u32 s11, s11, 0
	v_readlane_b32 s16, v250, 0
	v_readlane_b32 s17, v250, 1
	s_nop 4
	global_load_dwordx4 v[8:11], v2, s[16:17] offset:0
	global_load_dwordx4 v[12:15], v2, s[16:17] offset:16
	global_load_dwordx4 v[16:19], v2, s[16:17] offset:2048
	global_load_dwordx4 v[20:23], v2, s[16:17] offset:2064
	global_load_dwordx4 v[24:27], v3, s[16:17] offset:0
	global_load_dwordx4 v[28:31], v3, s[16:17] offset:16
	global_load_dwordx4 v[32:35], v3, s[16:17] offset:2048
	global_load_dwordx4 v[36:39], v3, s[16:17] offset:2064
	s_add_u32 s8, s6, 0x0
	s_addc_u32 s9, s7, 0
	global_load_dwordx4 v[72:75], v1, s[8:9] offset:0 nt
	global_load_dwordx4 v[76:79], v1, s[8:9] offset:1024 nt
	global_load_dwordx4 v[80:83], v1, s[8:9] offset:2048 nt
	global_load_dwordx4 v[84:87], v1, s[8:9] offset:3072 nt
	s_add_u32 s8, s6, 0x20000
	s_addc_u32 s9, s7, 0
	global_load_dwordx4 v[88:91], v1, s[8:9] offset:0 nt
	global_load_dwordx4 v[92:95], v1, s[8:9] offset:1024 nt
	global_load_dwordx4 v[96:99], v1, s[8:9] offset:2048 nt
	global_load_dwordx4 v[100:103], v1, s[8:9] offset:3072 nt
	s_add_u32 s8, s6, 0x40000
	s_addc_u32 s9, s7, 0
	global_load_dwordx4 v[104:107], v1, s[8:9] offset:0 nt
	global_load_dwordx4 v[108:111], v1, s[8:9] offset:1024 nt
	global_load_dwordx4 v[112:115], v1, s[8:9] offset:2048 nt
	global_load_dwordx4 v[116:119], v1, s[8:9] offset:3072 nt
	s_add_u32 s8, s6, 0x60000
	s_addc_u32 s9, s7, 0
	global_load_dwordx4 v[120:123], v1, s[8:9] offset:0 nt
	global_load_dwordx4 v[124:127], v1, s[8:9] offset:1024 nt
	global_load_dwordx4 v[128:131], v1, s[8:9] offset:2048 nt
	global_load_dwordx4 v[132:135], v1, s[8:9] offset:3072 nt
	s_add_u32 s8, s6, 0x80000
	s_addc_u32 s9, s7, 0
	global_load_dwordx4 v[136:139], v1, s[8:9] offset:0 nt
	global_load_dwordx4 v[140:143], v1, s[8:9] offset:1024 nt
	global_load_dwordx4 v[144:147], v1, s[8:9] offset:2048 nt
	global_load_dwordx4 v[148:151], v1, s[8:9] offset:3072 nt
	s_add_u32 s8, s6, 0xa0000
	s_addc_u32 s9, s7, 0
	global_load_dwordx4 v[152:155], v1, s[8:9] offset:0 nt
	global_load_dwordx4 v[156:159], v1, s[8:9] offset:1024 nt
	global_load_dwordx4 v[160:163], v1, s[8:9] offset:2048 nt
	global_load_dwordx4 v[164:167], v1, s[8:9] offset:3072 nt
	s_add_u32 s8, s6, 0xc0000
	s_addc_u32 s9, s7, 0
	global_load_dwordx4 v[168:171], v1, s[8:9] offset:0 nt
	global_load_dwordx4 v[172:175], v1, s[8:9] offset:1024 nt
	global_load_dwordx4 v[176:179], v1, s[8:9] offset:2048 nt
	global_load_dwordx4 v[180:183], v1, s[8:9] offset:3072 nt
	s_add_u32 s8, s6, 0xe0000
	s_addc_u32 s9, s7, 0
	global_load_dwordx4 v[184:187], v1, s[8:9] offset:0 nt
	global_load_dwordx4 v[188:191], v1, s[8:9] offset:1024 nt
	global_load_dwordx4 v[192:195], v1, s[8:9] offset:2048 nt
	global_load_dwordx4 v[196:199], v1, s[8:9] offset:3072 nt
	s_waitcnt vmcnt(32)
	v_mov_b32_e32 v248, 0x260
	s_waitcnt vmcnt(28)
	v_cvt_f32_f16_e32 v40, v72
	v_cvt_f32_f16_sdwa v41, v72 dst_sel:DWORD dst_unused:UNUSED_PAD src0_sel:WORD_1
	v_cvt_f32_f16_e32 v42, v73
	v_cvt_f32_f16_sdwa v43, v73 dst_sel:DWORD dst_unused:UNUSED_PAD src0_sel:WORD_1
	v_cvt_f32_f16_e32 v44, v74
	v_cvt_f32_f16_sdwa v45, v74 dst_sel:DWORD dst_unused:UNUSED_PAD src0_sel:WORD_1
	v_cvt_f32_f16_e32 v46, v75
	v_cvt_f32_f16_sdwa v47, v75 dst_sel:DWORD dst_unused:UNUSED_PAD src0_sel:WORD_1
	v_cvt_f32_f16_e32 v48, v76
	v_cvt_f32_f16_sdwa v49, v76 dst_sel:DWORD dst_unused:UNUSED_PAD src0_sel:WORD_1
	v_cvt_f32_f16_e32 v50, v77
	v_cvt_f32_f16_sdwa v51, v77 dst_sel:DWORD dst_unused:UNUSED_PAD src0_sel:WORD_1
	v_cvt_f32_f16_e32 v52, v78
	v_cvt_f32_f16_sdwa v53, v78 dst_sel:DWORD dst_unused:UNUSED_PAD src0_sel:WORD_1
	v_cvt_f32_f16_e32 v54, v79
	v_cvt_f32_f16_sdwa v55, v79 dst_sel:DWORD dst_unused:UNUSED_PAD src0_sel:WORD_1
	v_cvt_f32_f16_e32 v56, v80
	v_cvt_f32_f16_sdwa v57, v80 dst_sel:DWORD dst_unused:UNUSED_PAD src0_sel:WORD_1
	v_cvt_f32_f16_e32 v58, v81
	v_cvt_f32_f16_sdwa v59, v81 dst_sel:DWORD dst_unused:UNUSED_PAD src0_sel:WORD_1
	v_cvt_f32_f16_e32 v60, v82
	v_cvt_f32_f16_sdwa v61, v82 dst_sel:DWORD dst_unused:UNUSED_PAD src0_sel:WORD_1
	v_cvt_f32_f16_e32 v62, v83
	v_cvt_f32_f16_sdwa v63, v83 dst_sel:DWORD dst_unused:UNUSED_PAD src0_sel:WORD_1
	v_cvt_f32_f16_e32 v64, v84
	v_cvt_f32_f16_sdwa v65, v84 dst_sel:DWORD dst_unused:UNUSED_PAD src0_sel:WORD_1
	v_cvt_f32_f16_e32 v66, v85
	v_cvt_f32_f16_sdwa v67, v85 dst_sel:DWORD dst_unused:UNUSED_PAD src0_sel:WORD_1
	v_cvt_f32_f16_e32 v68, v86
	v_cvt_f32_f16_sdwa v69, v86 dst_sel:DWORD dst_unused:UNUSED_PAD src0_sel:WORD_1
	v_cvt_f32_f16_e32 v70, v87
	v_cvt_f32_f16_sdwa v71, v87 dst_sel:DWORD dst_unused:UNUSED_PAD src0_sel:WORD_1
	v_pk_mul_f32 v[232:233], v[40:41], v[40:41]
	v_pk_mul_f32 v[234:235], v[42:43], v[42:43]
	v_pk_mul_f32 v[236:237], v[44:45], v[44:45]
	v_pk_mul_f32 v[238:239], v[46:47], v[46:47]
	v_pk_fma_f32 v[232:233], v[48:49], v[48:49], v[232:233]
	v_pk_fma_f32 v[234:235], v[50:51], v[50:51], v[234:235]
	v_pk_fma_f32 v[236:237], v[52:53], v[52:53], v[236:237]
	v_pk_fma_f32 v[238:239], v[54:55], v[54:55], v[238:239]
	v_pk_fma_f32 v[232:233], v[56:57], v[56:57], v[232:233]
	v_pk_fma_f32 v[234:235], v[58:59], v[58:59], v[234:235]
	v_pk_fma_f32 v[236:237], v[60:61], v[60:61], v[236:237]
	v_pk_fma_f32 v[238:239], v[62:63], v[62:63], v[238:239]
	v_pk_fma_f32 v[232:233], v[64:65], v[64:65], v[232:233]
	v_pk_fma_f32 v[234:235], v[66:67], v[66:67], v[234:235]
	v_pk_fma_f32 v[236:237], v[68:69], v[68:69], v[236:237]
	v_pk_fma_f32 v[238:239], v[70:71], v[70:71], v[238:239]
	v_pk_add_f32 v[232:233], v[232:233], v[234:235]
	v_pk_add_f32 v[236:237], v[236:237], v[238:239]
	v_pk_add_f32 v[232:233], v[232:233], v[236:237]
	v_add_f32_e32 v240, v232, v233
	s_nop 1
	v_add_f32_dpp v240, v240, v240 quad_perm:[1,0,3,2] row_mask:0xf bank_mask:0xf
	s_nop 1
	v_add_f32_dpp v240, v240, v240 quad_perm:[2,3,0,1] row_mask:0xf bank_mask:0xf
	s_nop 1
	v_add_f32_dpp v240, v240, v240 row_half_mirror row_mask:0xf bank_mask:0xf
	s_nop 1
	v_add_f32_dpp v240, v240, v240 row_mirror row_mask:0xf bank_mask:0xf
	s_nop 1
	v_readlane_b32 s0, v240, 0
	v_readlane_b32 s1, v240, 16
	v_readlane_b32 s4, v240, 32
	v_readlane_b32 s5, v240, 48
	v_mov_b32_e32 v249, 0x358637bd
	s_nop 1
	v_mov_b32_e32 v240, s0
	v_add_f32_e32 v240, s1, v240
	v_add_f32_e32 v240, s4, v240
	v_add_f32_e32 v240, s5, v240
	v_fmamk_f32 v240, v240, 0x3a000000, v249
	s_mov_b32 s0, 0xf800000
	v_mul_f32_e32 v241, 0x4f800000, v240
	v_cmp_gt_f32_e32 vcc, s0, v240
	s_nop 1
	v_cndmask_b32_e32 v240, v240, v241, vcc
	v_sqrt_f32_e32 v241, v240
	s_nop 0
	v_add_u32_e32 v242, -1, v241
	v_fma_f32 v243, -v242, v241, v240
	v_cmp_ge_f32_e64 s[0:1], 0, v243
	v_add_u32_e32 v243, 1, v241
	s_nop 0
	v_cndmask_b32_e64 v242, v241, v242, s[0:1]
	v_fma_f32 v241, -v243, v241, v240
	v_cmp_lt_f32_e64 s[0:1], 0, v241
	s_nop 1
	v_cndmask_b32_e64 v241, v242, v243, s[0:1]
	v_mul_f32_e32 v242, 0x37800000, v241
	v_cndmask_b32_e32 v241, v241, v242, vcc
	v_cmp_class_f32_e32 vcc, v240, v248
	s_nop 1
	v_cndmask_b32_e32 v240, v241, v240, vcc
	v_div_scale_f32 v241, s[0:1], v240, v240, 1.0
	v_rcp_f32_e32 v242, v241
	s_nop 0
	v_fma_f32 v243, -v241, v242, 1.0
	v_fmac_f32_e32 v242, v243, v242
	v_div_scale_f32 v243, vcc, 1.0, v240, 1.0
	v_mul_f32_e32 v244, v243, v242
	v_fma_f32 v247, -v241, v244, v243
	v_fmac_f32_e32 v244, v247, v242
	v_fma_f32 v241, -v241, v244, v243
	s_nop 1
	v_div_fmas_f32 v241, v241, v242, v244
	v_div_fixup_f32 v246, v241, v240, 1.0
	v_pk_mul_f32 v[40:41], v[40:41], v[246:247] op_sel_hi:[1,0]
	v_pk_mul_f32 v[42:43], v[42:43], v[246:247] op_sel_hi:[1,0]
	v_pk_mul_f32 v[44:45], v[44:45], v[246:247] op_sel_hi:[1,0]
	v_pk_mul_f32 v[46:47], v[46:47], v[246:247] op_sel_hi:[1,0]
	v_pk_mul_f32 v[48:49], v[48:49], v[246:247] op_sel_hi:[1,0]
	v_pk_mul_f32 v[50:51], v[50:51], v[246:247] op_sel_hi:[1,0]
	v_pk_mul_f32 v[52:53], v[52:53], v[246:247] op_sel_hi:[1,0]
	v_pk_mul_f32 v[54:55], v[54:55], v[246:247] op_sel_hi:[1,0]
	v_pk_mul_f32 v[56:57], v[56:57], v[246:247] op_sel_hi:[1,0]
	v_pk_mul_f32 v[58:59], v[58:59], v[246:247] op_sel_hi:[1,0]
	v_pk_mul_f32 v[60:61], v[60:61], v[246:247] op_sel_hi:[1,0]
	v_pk_mul_f32 v[62:63], v[62:63], v[246:247] op_sel_hi:[1,0]
	v_pk_mul_f32 v[64:65], v[64:65], v[246:247] op_sel_hi:[1,0]
	v_pk_mul_f32 v[66:67], v[66:67], v[246:247] op_sel_hi:[1,0]
	v_pk_mul_f32 v[68:69], v[68:69], v[246:247] op_sel_hi:[1,0]
	v_pk_mul_f32 v[70:71], v[70:71], v[246:247] op_sel_hi:[1,0]
	s_add_u32 s8, s10, 0x0
	s_addc_u32 s9, s11, 0
	v_pk_mul_f32 v[40:41], v[40:41], v[8:9]
	v_pk_mul_f32 v[42:43], v[42:43], v[10:11]
	global_store_dwordx4 v2, v[40:43], s[8:9] offset:0 nt
	v_pk_mul_f32 v[44:45], v[44:45], v[12:13]
	v_pk_mul_f32 v[46:47], v[46:47], v[14:15]
	global_store_dwordx4 v2, v[44:47], s[8:9] offset:16 nt
	v_pk_mul_f32 v[48:49], v[48:49], v[16:17]
	v_pk_mul_f32 v[50:51], v[50:51], v[18:19]
	global_store_dwordx4 v2, v[48:51], s[8:9] offset:2048 nt
	v_pk_mul_f32 v[52:53], v[52:53], v[20:21]
	v_pk_mul_f32 v[54:55], v[54:55], v[22:23]
	global_store_dwordx4 v2, v[52:55], s[8:9] offset:2064 nt
	v_pk_mul_f32 v[56:57], v[56:57], v[24:25]
	v_pk_mul_f32 v[58:59], v[58:59], v[26:27]
	global_store_dwordx4 v3, v[56:59], s[8:9] offset:0 nt
	v_pk_mul_f32 v[60:61], v[60:61], v[28:29]
	v_pk_mul_f32 v[62:63], v[62:63], v[30:31]
	global_store_dwordx4 v3, v[60:63], s[8:9] offset:16 nt
	v_pk_mul_f32 v[64:65], v[64:65], v[32:33]
	v_pk_mul_f32 v[66:67], v[66:67], v[34:35]
	global_store_dwordx4 v3, v[64:67], s[8:9] offset:2048 nt
	v_pk_mul_f32 v[68:69], v[68:69], v[36:37]
	v_pk_mul_f32 v[70:71], v[70:71], v[38:39]
	global_store_dwordx4 v3, v[68:71], s[8:9] offset:2064 nt
	s_waitcnt vmcnt(32)
	v_cvt_f32_f16_e32 v40, v88
	v_cvt_f32_f16_sdwa v41, v88 dst_sel:DWORD dst_unused:UNUSED_PAD src0_sel:WORD_1
	v_cvt_f32_f16_e32 v42, v89
	v_cvt_f32_f16_sdwa v43, v89 dst_sel:DWORD dst_unused:UNUSED_PAD src0_sel:WORD_1
	v_cvt_f32_f16_e32 v44, v90
	v_cvt_f32_f16_sdwa v45, v90 dst_sel:DWORD dst_unused:UNUSED_PAD src0_sel:WORD_1
	v_cvt_f32_f16_e32 v46, v91
	v_cvt_f32_f16_sdwa v47, v91 dst_sel:DWORD dst_unused:UNUSED_PAD src0_sel:WORD_1
	v_cvt_f32_f16_e32 v48, v92
	v_cvt_f32_f16_sdwa v49, v92 dst_sel:DWORD dst_unused:UNUSED_PAD src0_sel:WORD_1
	v_cvt_f32_f16_e32 v50, v93
	v_cvt_f32_f16_sdwa v51, v93 dst_sel:DWORD dst_unused:UNUSED_PAD src0_sel:WORD_1
	v_cvt_f32_f16_e32 v52, v94
	v_cvt_f32_f16_sdwa v53, v94 dst_sel:DWORD dst_unused:UNUSED_PAD src0_sel:WORD_1
	v_cvt_f32_f16_e32 v54, v95
	v_cvt_f32_f16_sdwa v55, v95 dst_sel:DWORD dst_unused:UNUSED_PAD src0_sel:WORD_1
	v_cvt_f32_f16_e32 v56, v96
	v_cvt_f32_f16_sdwa v57, v96 dst_sel:DWORD dst_unused:UNUSED_PAD src0_sel:WORD_1
	v_cvt_f32_f16_e32 v58, v97
	v_cvt_f32_f16_sdwa v59, v97 dst_sel:DWORD dst_unused:UNUSED_PAD src0_sel:WORD_1
	v_cvt_f32_f16_e32 v60, v98
	v_cvt_f32_f16_sdwa v61, v98 dst_sel:DWORD dst_unused:UNUSED_PAD src0_sel:WORD_1
	v_cvt_f32_f16_e32 v62, v99
	v_cvt_f32_f16_sdwa v63, v99 dst_sel:DWORD dst_unused:UNUSED_PAD src0_sel:WORD_1
	v_cvt_f32_f16_e32 v64, v100
	v_cvt_f32_f16_sdwa v65, v100 dst_sel:DWORD dst_unused:UNUSED_PAD src0_sel:WORD_1
	v_cvt_f32_f16_e32 v66, v101
	v_cvt_f32_f16_sdwa v67, v101 dst_sel:DWORD dst_unused:UNUSED_PAD src0_sel:WORD_1
	v_cvt_f32_f16_e32 v68, v102
	v_cvt_f32_f16_sdwa v69, v102 dst_sel:DWORD dst_unused:UNUSED_PAD src0_sel:WORD_1
	v_cvt_f32_f16_e32 v70, v103
	v_cvt_f32_f16_sdwa v71, v103 dst_sel:DWORD dst_unused:UNUSED_PAD src0_sel:WORD_1
	v_pk_mul_f32 v[232:233], v[40:41], v[40:41]
	v_pk_mul_f32 v[234:235], v[42:43], v[42:43]
	v_pk_mul_f32 v[236:237], v[44:45], v[44:45]
	v_pk_mul_f32 v[238:239], v[46:47], v[46:47]
	v_pk_fma_f32 v[232:233], v[48:49], v[48:49], v[232:233]
	v_pk_fma_f32 v[234:235], v[50:51], v[50:51], v[234:235]
	v_pk_fma_f32 v[236:237], v[52:53], v[52:53], v[236:237]
	v_pk_fma_f32 v[238:239], v[54:55], v[54:55], v[238:239]
	v_pk_fma_f32 v[232:233], v[56:57], v[56:57], v[232:233]
	v_pk_fma_f32 v[234:235], v[58:59], v[58:59], v[234:235]
	v_pk_fma_f32 v[236:237], v[60:61], v[60:61], v[236:237]
	v_pk_fma_f32 v[238:239], v[62:63], v[62:63], v[238:239]
	v_pk_fma_f32 v[232:233], v[64:65], v[64:65], v[232:233]
	v_pk_fma_f32 v[234:235], v[66:67], v[66:67], v[234:235]
	v_pk_fma_f32 v[236:237], v[68:69], v[68:69], v[236:237]
	v_pk_fma_f32 v[238:239], v[70:71], v[70:71], v[238:239]
	v_pk_add_f32 v[232:233], v[232:233], v[234:235]
	v_pk_add_f32 v[236:237], v[236:237], v[238:239]
	v_pk_add_f32 v[232:233], v[232:233], v[236:237]
	v_add_f32_e32 v240, v232, v233
	s_nop 1
	v_add_f32_dpp v240, v240, v240 quad_perm:[1,0,3,2] row_mask:0xf bank_mask:0xf
	s_nop 1
	v_add_f32_dpp v240, v240, v240 quad_perm:[2,3,0,1] row_mask:0xf bank_mask:0xf
	s_nop 1
	v_add_f32_dpp v240, v240, v240 row_half_mirror row_mask:0xf bank_mask:0xf
	s_nop 1
	v_add_f32_dpp v240, v240, v240 row_mirror row_mask:0xf bank_mask:0xf
	s_nop 1
	v_readlane_b32 s0, v240, 0
	v_readlane_b32 s1, v240, 16
	v_readlane_b32 s4, v240, 32
	v_readlane_b32 s5, v240, 48
	v_mov_b32_e32 v249, 0x358637bd
	s_nop 1
	v_mov_b32_e32 v240, s0
	v_add_f32_e32 v240, s1, v240
	v_add_f32_e32 v240, s4, v240
	v_add_f32_e32 v240, s5, v240
	v_fmamk_f32 v240, v240, 0x3a000000, v249
	s_mov_b32 s0, 0xf800000
	v_mul_f32_e32 v241, 0x4f800000, v240
	v_cmp_gt_f32_e32 vcc, s0, v240
	s_nop 1
	v_cndmask_b32_e32 v240, v240, v241, vcc
	v_sqrt_f32_e32 v241, v240
	s_nop 0
	v_add_u32_e32 v242, -1, v241
	v_fma_f32 v243, -v242, v241, v240
	v_cmp_ge_f32_e64 s[0:1], 0, v243
	v_add_u32_e32 v243, 1, v241
	s_nop 0
	v_cndmask_b32_e64 v242, v241, v242, s[0:1]
	v_fma_f32 v241, -v243, v241, v240
	v_cmp_lt_f32_e64 s[0:1], 0, v241
	s_nop 1
	v_cndmask_b32_e64 v241, v242, v243, s[0:1]
	v_mul_f32_e32 v242, 0x37800000, v241
	v_cndmask_b32_e32 v241, v241, v242, vcc
	v_cmp_class_f32_e32 vcc, v240, v248
	s_nop 1
	v_cndmask_b32_e32 v240, v241, v240, vcc
	v_div_scale_f32 v241, s[0:1], v240, v240, 1.0
	v_rcp_f32_e32 v242, v241
	s_nop 0
	v_fma_f32 v243, -v241, v242, 1.0
	v_fmac_f32_e32 v242, v243, v242
	v_div_scale_f32 v243, vcc, 1.0, v240, 1.0
	v_mul_f32_e32 v244, v243, v242
	v_fma_f32 v247, -v241, v244, v243
	v_fmac_f32_e32 v244, v247, v242
	v_fma_f32 v241, -v241, v244, v243
	s_nop 1
	v_div_fmas_f32 v241, v241, v242, v244
	v_div_fixup_f32 v246, v241, v240, 1.0
	v_pk_mul_f32 v[40:41], v[40:41], v[246:247] op_sel_hi:[1,0]
	v_pk_mul_f32 v[42:43], v[42:43], v[246:247] op_sel_hi:[1,0]
	v_pk_mul_f32 v[44:45], v[44:45], v[246:247] op_sel_hi:[1,0]
	v_pk_mul_f32 v[46:47], v[46:47], v[246:247] op_sel_hi:[1,0]
	v_pk_mul_f32 v[48:49], v[48:49], v[246:247] op_sel_hi:[1,0]
	v_pk_mul_f32 v[50:51], v[50:51], v[246:247] op_sel_hi:[1,0]
	v_pk_mul_f32 v[52:53], v[52:53], v[246:247] op_sel_hi:[1,0]
	v_pk_mul_f32 v[54:55], v[54:55], v[246:247] op_sel_hi:[1,0]
	v_pk_mul_f32 v[56:57], v[56:57], v[246:247] op_sel_hi:[1,0]
	v_pk_mul_f32 v[58:59], v[58:59], v[246:247] op_sel_hi:[1,0]
	v_pk_mul_f32 v[60:61], v[60:61], v[246:247] op_sel_hi:[1,0]
	v_pk_mul_f32 v[62:63], v[62:63], v[246:247] op_sel_hi:[1,0]
	v_pk_mul_f32 v[64:65], v[64:65], v[246:247] op_sel_hi:[1,0]
	v_pk_mul_f32 v[66:67], v[66:67], v[246:247] op_sel_hi:[1,0]
	v_pk_mul_f32 v[68:69], v[68:69], v[246:247] op_sel_hi:[1,0]
	v_pk_mul_f32 v[70:71], v[70:71], v[246:247] op_sel_hi:[1,0]
	s_add_u32 s8, s10, 0x40000
	s_addc_u32 s9, s11, 0
	v_pk_mul_f32 v[40:41], v[40:41], v[8:9]
	v_pk_mul_f32 v[42:43], v[42:43], v[10:11]
	global_store_dwordx4 v2, v[40:43], s[8:9] offset:0 nt
	v_pk_mul_f32 v[44:45], v[44:45], v[12:13]
	v_pk_mul_f32 v[46:47], v[46:47], v[14:15]
	global_store_dwordx4 v2, v[44:47], s[8:9] offset:16 nt
	v_pk_mul_f32 v[48:49], v[48:49], v[16:17]
	v_pk_mul_f32 v[50:51], v[50:51], v[18:19]
	global_store_dwordx4 v2, v[48:51], s[8:9] offset:2048 nt
	v_pk_mul_f32 v[52:53], v[52:53], v[20:21]
	v_pk_mul_f32 v[54:55], v[54:55], v[22:23]
	global_store_dwordx4 v2, v[52:55], s[8:9] offset:2064 nt
	v_pk_mul_f32 v[56:57], v[56:57], v[24:25]
	v_pk_mul_f32 v[58:59], v[58:59], v[26:27]
	global_store_dwordx4 v3, v[56:59], s[8:9] offset:0 nt
	v_pk_mul_f32 v[60:61], v[60:61], v[28:29]
	v_pk_mul_f32 v[62:63], v[62:63], v[30:31]
	global_store_dwordx4 v3, v[60:63], s[8:9] offset:16 nt
	v_pk_mul_f32 v[64:65], v[64:65], v[32:33]
	v_pk_mul_f32 v[66:67], v[66:67], v[34:35]
	global_store_dwordx4 v3, v[64:67], s[8:9] offset:2048 nt
	v_pk_mul_f32 v[68:69], v[68:69], v[36:37]
	v_pk_mul_f32 v[70:71], v[70:71], v[38:39]
	global_store_dwordx4 v3, v[68:71], s[8:9] offset:2064 nt
	s_waitcnt vmcnt(36)
	v_cvt_f32_f16_e32 v40, v104
	v_cvt_f32_f16_sdwa v41, v104 dst_sel:DWORD dst_unused:UNUSED_PAD src0_sel:WORD_1
	v_cvt_f32_f16_e32 v42, v105
	v_cvt_f32_f16_sdwa v43, v105 dst_sel:DWORD dst_unused:UNUSED_PAD src0_sel:WORD_1
	v_cvt_f32_f16_e32 v44, v106
	v_cvt_f32_f16_sdwa v45, v106 dst_sel:DWORD dst_unused:UNUSED_PAD src0_sel:WORD_1
	v_cvt_f32_f16_e32 v46, v107
	v_cvt_f32_f16_sdwa v47, v107 dst_sel:DWORD dst_unused:UNUSED_PAD src0_sel:WORD_1
	v_cvt_f32_f16_e32 v48, v108
	v_cvt_f32_f16_sdwa v49, v108 dst_sel:DWORD dst_unused:UNUSED_PAD src0_sel:WORD_1
	v_cvt_f32_f16_e32 v50, v109
	v_cvt_f32_f16_sdwa v51, v109 dst_sel:DWORD dst_unused:UNUSED_PAD src0_sel:WORD_1
	v_cvt_f32_f16_e32 v52, v110
	v_cvt_f32_f16_sdwa v53, v110 dst_sel:DWORD dst_unused:UNUSED_PAD src0_sel:WORD_1
	v_cvt_f32_f16_e32 v54, v111
	v_cvt_f32_f16_sdwa v55, v111 dst_sel:DWORD dst_unused:UNUSED_PAD src0_sel:WORD_1
	v_cvt_f32_f16_e32 v56, v112
	v_cvt_f32_f16_sdwa v57, v112 dst_sel:DWORD dst_unused:UNUSED_PAD src0_sel:WORD_1
	v_cvt_f32_f16_e32 v58, v113
	v_cvt_f32_f16_sdwa v59, v113 dst_sel:DWORD dst_unused:UNUSED_PAD src0_sel:WORD_1
	v_cvt_f32_f16_e32 v60, v114
	v_cvt_f32_f16_sdwa v61, v114 dst_sel:DWORD dst_unused:UNUSED_PAD src0_sel:WORD_1
	v_cvt_f32_f16_e32 v62, v115
	v_cvt_f32_f16_sdwa v63, v115 dst_sel:DWORD dst_unused:UNUSED_PAD src0_sel:WORD_1
	v_cvt_f32_f16_e32 v64, v116
	v_cvt_f32_f16_sdwa v65, v116 dst_sel:DWORD dst_unused:UNUSED_PAD src0_sel:WORD_1
	v_cvt_f32_f16_e32 v66, v117
	v_cvt_f32_f16_sdwa v67, v117 dst_sel:DWORD dst_unused:UNUSED_PAD src0_sel:WORD_1
	v_cvt_f32_f16_e32 v68, v118
	v_cvt_f32_f16_sdwa v69, v118 dst_sel:DWORD dst_unused:UNUSED_PAD src0_sel:WORD_1
	v_cvt_f32_f16_e32 v70, v119
	v_cvt_f32_f16_sdwa v71, v119 dst_sel:DWORD dst_unused:UNUSED_PAD src0_sel:WORD_1
	v_pk_mul_f32 v[232:233], v[40:41], v[40:41]
	v_pk_mul_f32 v[234:235], v[42:43], v[42:43]
	v_pk_mul_f32 v[236:237], v[44:45], v[44:45]
	v_pk_mul_f32 v[238:239], v[46:47], v[46:47]
	v_pk_fma_f32 v[232:233], v[48:49], v[48:49], v[232:233]
	v_pk_fma_f32 v[234:235], v[50:51], v[50:51], v[234:235]
	v_pk_fma_f32 v[236:237], v[52:53], v[52:53], v[236:237]
	v_pk_fma_f32 v[238:239], v[54:55], v[54:55], v[238:239]
	v_pk_fma_f32 v[232:233], v[56:57], v[56:57], v[232:233]
	v_pk_fma_f32 v[234:235], v[58:59], v[58:59], v[234:235]
	v_pk_fma_f32 v[236:237], v[60:61], v[60:61], v[236:237]
	v_pk_fma_f32 v[238:239], v[62:63], v[62:63], v[238:239]
	v_pk_fma_f32 v[232:233], v[64:65], v[64:65], v[232:233]
	v_pk_fma_f32 v[234:235], v[66:67], v[66:67], v[234:235]
	v_pk_fma_f32 v[236:237], v[68:69], v[68:69], v[236:237]
	v_pk_fma_f32 v[238:239], v[70:71], v[70:71], v[238:239]
	v_pk_add_f32 v[232:233], v[232:233], v[234:235]
	v_pk_add_f32 v[236:237], v[236:237], v[238:239]
	v_pk_add_f32 v[232:233], v[232:233], v[236:237]
	v_add_f32_e32 v240, v232, v233
	s_nop 1
	v_add_f32_dpp v240, v240, v240 quad_perm:[1,0,3,2] row_mask:0xf bank_mask:0xf
	s_nop 1
	v_add_f32_dpp v240, v240, v240 quad_perm:[2,3,0,1] row_mask:0xf bank_mask:0xf
	s_nop 1
	v_add_f32_dpp v240, v240, v240 row_half_mirror row_mask:0xf bank_mask:0xf
	s_nop 1
	v_add_f32_dpp v240, v240, v240 row_mirror row_mask:0xf bank_mask:0xf
	s_nop 1
	v_readlane_b32 s0, v240, 0
	v_readlane_b32 s1, v240, 16
	v_readlane_b32 s4, v240, 32
	v_readlane_b32 s5, v240, 48
	v_mov_b32_e32 v249, 0x358637bd
	s_nop 1
	v_mov_b32_e32 v240, s0
	v_add_f32_e32 v240, s1, v240
	v_add_f32_e32 v240, s4, v240
	v_add_f32_e32 v240, s5, v240
	v_fmamk_f32 v240, v240, 0x3a000000, v249
	s_mov_b32 s0, 0xf800000
	v_mul_f32_e32 v241, 0x4f800000, v240
	v_cmp_gt_f32_e32 vcc, s0, v240
	s_nop 1
	v_cndmask_b32_e32 v240, v240, v241, vcc
	v_sqrt_f32_e32 v241, v240
	s_nop 0
	v_add_u32_e32 v242, -1, v241
	v_fma_f32 v243, -v242, v241, v240
	v_cmp_ge_f32_e64 s[0:1], 0, v243
	v_add_u32_e32 v243, 1, v241
	s_nop 0
	v_cndmask_b32_e64 v242, v241, v242, s[0:1]
	v_fma_f32 v241, -v243, v241, v240
	v_cmp_lt_f32_e64 s[0:1], 0, v241
	s_nop 1
	v_cndmask_b32_e64 v241, v242, v243, s[0:1]
	v_mul_f32_e32 v242, 0x37800000, v241
	v_cndmask_b32_e32 v241, v241, v242, vcc
	v_cmp_class_f32_e32 vcc, v240, v248
	s_nop 1
	v_cndmask_b32_e32 v240, v241, v240, vcc
	v_div_scale_f32 v241, s[0:1], v240, v240, 1.0
	v_rcp_f32_e32 v242, v241
	s_nop 0
	v_fma_f32 v243, -v241, v242, 1.0
	v_fmac_f32_e32 v242, v243, v242
	v_div_scale_f32 v243, vcc, 1.0, v240, 1.0
	v_mul_f32_e32 v244, v243, v242
	v_fma_f32 v247, -v241, v244, v243
	v_fmac_f32_e32 v244, v247, v242
	v_fma_f32 v241, -v241, v244, v243
	s_nop 1
	v_div_fmas_f32 v241, v241, v242, v244
	v_div_fixup_f32 v246, v241, v240, 1.0
	v_pk_mul_f32 v[40:41], v[40:41], v[246:247] op_sel_hi:[1,0]
	v_pk_mul_f32 v[42:43], v[42:43], v[246:247] op_sel_hi:[1,0]
	v_pk_mul_f32 v[44:45], v[44:45], v[246:247] op_sel_hi:[1,0]
	v_pk_mul_f32 v[46:47], v[46:47], v[246:247] op_sel_hi:[1,0]
	v_pk_mul_f32 v[48:49], v[48:49], v[246:247] op_sel_hi:[1,0]
	v_pk_mul_f32 v[50:51], v[50:51], v[246:247] op_sel_hi:[1,0]
	v_pk_mul_f32 v[52:53], v[52:53], v[246:247] op_sel_hi:[1,0]
	v_pk_mul_f32 v[54:55], v[54:55], v[246:247] op_sel_hi:[1,0]
	v_pk_mul_f32 v[56:57], v[56:57], v[246:247] op_sel_hi:[1,0]
	v_pk_mul_f32 v[58:59], v[58:59], v[246:247] op_sel_hi:[1,0]
	v_pk_mul_f32 v[60:61], v[60:61], v[246:247] op_sel_hi:[1,0]
	v_pk_mul_f32 v[62:63], v[62:63], v[246:247] op_sel_hi:[1,0]
	v_pk_mul_f32 v[64:65], v[64:65], v[246:247] op_sel_hi:[1,0]
	v_pk_mul_f32 v[66:67], v[66:67], v[246:247] op_sel_hi:[1,0]
	v_pk_mul_f32 v[68:69], v[68:69], v[246:247] op_sel_hi:[1,0]
	v_pk_mul_f32 v[70:71], v[70:71], v[246:247] op_sel_hi:[1,0]
	s_add_u32 s8, s10, 0x80000
	s_addc_u32 s9, s11, 0
	v_pk_mul_f32 v[40:41], v[40:41], v[8:9]
	v_pk_mul_f32 v[42:43], v[42:43], v[10:11]
	global_store_dwordx4 v2, v[40:43], s[8:9] offset:0 nt
	v_pk_mul_f32 v[44:45], v[44:45], v[12:13]
	v_pk_mul_f32 v[46:47], v[46:47], v[14:15]
	global_store_dwordx4 v2, v[44:47], s[8:9] offset:16 nt
	v_pk_mul_f32 v[48:49], v[48:49], v[16:17]
	v_pk_mul_f32 v[50:51], v[50:51], v[18:19]
	global_store_dwordx4 v2, v[48:51], s[8:9] offset:2048 nt
	v_pk_mul_f32 v[52:53], v[52:53], v[20:21]
	v_pk_mul_f32 v[54:55], v[54:55], v[22:23]
	global_store_dwordx4 v2, v[52:55], s[8:9] offset:2064 nt
	v_pk_mul_f32 v[56:57], v[56:57], v[24:25]
	v_pk_mul_f32 v[58:59], v[58:59], v[26:27]
	global_store_dwordx4 v3, v[56:59], s[8:9] offset:0 nt
	v_pk_mul_f32 v[60:61], v[60:61], v[28:29]
	v_pk_mul_f32 v[62:63], v[62:63], v[30:31]
	global_store_dwordx4 v3, v[60:63], s[8:9] offset:16 nt
	v_pk_mul_f32 v[64:65], v[64:65], v[32:33]
	v_pk_mul_f32 v[66:67], v[66:67], v[34:35]
	global_store_dwordx4 v3, v[64:67], s[8:9] offset:2048 nt
	v_pk_mul_f32 v[68:69], v[68:69], v[36:37]
	v_pk_mul_f32 v[70:71], v[70:71], v[38:39]
	global_store_dwordx4 v3, v[68:71], s[8:9] offset:2064 nt
	s_waitcnt vmcnt(40)
	v_cvt_f32_f16_e32 v40, v120
	v_cvt_f32_f16_sdwa v41, v120 dst_sel:DWORD dst_unused:UNUSED_PAD src0_sel:WORD_1
	v_cvt_f32_f16_e32 v42, v121
	v_cvt_f32_f16_sdwa v43, v121 dst_sel:DWORD dst_unused:UNUSED_PAD src0_sel:WORD_1
	v_cvt_f32_f16_e32 v44, v122
	v_cvt_f32_f16_sdwa v45, v122 dst_sel:DWORD dst_unused:UNUSED_PAD src0_sel:WORD_1
	v_cvt_f32_f16_e32 v46, v123
	v_cvt_f32_f16_sdwa v47, v123 dst_sel:DWORD dst_unused:UNUSED_PAD src0_sel:WORD_1
	v_cvt_f32_f16_e32 v48, v124
	v_cvt_f32_f16_sdwa v49, v124 dst_sel:DWORD dst_unused:UNUSED_PAD src0_sel:WORD_1
	v_cvt_f32_f16_e32 v50, v125
	v_cvt_f32_f16_sdwa v51, v125 dst_sel:DWORD dst_unused:UNUSED_PAD src0_sel:WORD_1
	v_cvt_f32_f16_e32 v52, v126
	v_cvt_f32_f16_sdwa v53, v126 dst_sel:DWORD dst_unused:UNUSED_PAD src0_sel:WORD_1
	v_cvt_f32_f16_e32 v54, v127
	v_cvt_f32_f16_sdwa v55, v127 dst_sel:DWORD dst_unused:UNUSED_PAD src0_sel:WORD_1
	v_cvt_f32_f16_e32 v56, v128
	v_cvt_f32_f16_sdwa v57, v128 dst_sel:DWORD dst_unused:UNUSED_PAD src0_sel:WORD_1
	v_cvt_f32_f16_e32 v58, v129
	v_cvt_f32_f16_sdwa v59, v129 dst_sel:DWORD dst_unused:UNUSED_PAD src0_sel:WORD_1
	v_cvt_f32_f16_e32 v60, v130
	v_cvt_f32_f16_sdwa v61, v130 dst_sel:DWORD dst_unused:UNUSED_PAD src0_sel:WORD_1
	v_cvt_f32_f16_e32 v62, v131
	v_cvt_f32_f16_sdwa v63, v131 dst_sel:DWORD dst_unused:UNUSED_PAD src0_sel:WORD_1
	v_cvt_f32_f16_e32 v64, v132
	v_cvt_f32_f16_sdwa v65, v132 dst_sel:DWORD dst_unused:UNUSED_PAD src0_sel:WORD_1
	v_cvt_f32_f16_e32 v66, v133
	v_cvt_f32_f16_sdwa v67, v133 dst_sel:DWORD dst_unused:UNUSED_PAD src0_sel:WORD_1
	v_cvt_f32_f16_e32 v68, v134
	v_cvt_f32_f16_sdwa v69, v134 dst_sel:DWORD dst_unused:UNUSED_PAD src0_sel:WORD_1
	v_cvt_f32_f16_e32 v70, v135
	v_cvt_f32_f16_sdwa v71, v135 dst_sel:DWORD dst_unused:UNUSED_PAD src0_sel:WORD_1
	v_pk_mul_f32 v[232:233], v[40:41], v[40:41]
	v_pk_mul_f32 v[234:235], v[42:43], v[42:43]
	v_pk_mul_f32 v[236:237], v[44:45], v[44:45]
	v_pk_mul_f32 v[238:239], v[46:47], v[46:47]
	v_pk_fma_f32 v[232:233], v[48:49], v[48:49], v[232:233]
	v_pk_fma_f32 v[234:235], v[50:51], v[50:51], v[234:235]
	v_pk_fma_f32 v[236:237], v[52:53], v[52:53], v[236:237]
	v_pk_fma_f32 v[238:239], v[54:55], v[54:55], v[238:239]
	v_pk_fma_f32 v[232:233], v[56:57], v[56:57], v[232:233]
	v_pk_fma_f32 v[234:235], v[58:59], v[58:59], v[234:235]
	v_pk_fma_f32 v[236:237], v[60:61], v[60:61], v[236:237]
	v_pk_fma_f32 v[238:239], v[62:63], v[62:63], v[238:239]
	v_pk_fma_f32 v[232:233], v[64:65], v[64:65], v[232:233]
	v_pk_fma_f32 v[234:235], v[66:67], v[66:67], v[234:235]
	v_pk_fma_f32 v[236:237], v[68:69], v[68:69], v[236:237]
	v_pk_fma_f32 v[238:239], v[70:71], v[70:71], v[238:239]
	v_pk_add_f32 v[232:233], v[232:233], v[234:235]
	v_pk_add_f32 v[236:237], v[236:237], v[238:239]
	v_pk_add_f32 v[232:233], v[232:233], v[236:237]
	v_add_f32_e32 v240, v232, v233
	s_nop 1
	v_add_f32_dpp v240, v240, v240 quad_perm:[1,0,3,2] row_mask:0xf bank_mask:0xf
	s_nop 1
	v_add_f32_dpp v240, v240, v240 quad_perm:[2,3,0,1] row_mask:0xf bank_mask:0xf
	s_nop 1
	v_add_f32_dpp v240, v240, v240 row_half_mirror row_mask:0xf bank_mask:0xf
	s_nop 1
	v_add_f32_dpp v240, v240, v240 row_mirror row_mask:0xf bank_mask:0xf
	s_nop 1
	v_readlane_b32 s0, v240, 0
	v_readlane_b32 s1, v240, 16
	v_readlane_b32 s4, v240, 32
	v_readlane_b32 s5, v240, 48
	v_mov_b32_e32 v249, 0x358637bd
	s_nop 1
	v_mov_b32_e32 v240, s0
	v_add_f32_e32 v240, s1, v240
	v_add_f32_e32 v240, s4, v240
	v_add_f32_e32 v240, s5, v240
	v_fmamk_f32 v240, v240, 0x3a000000, v249
	s_mov_b32 s0, 0xf800000
	v_mul_f32_e32 v241, 0x4f800000, v240
	v_cmp_gt_f32_e32 vcc, s0, v240
	s_nop 1
	v_cndmask_b32_e32 v240, v240, v241, vcc
	v_sqrt_f32_e32 v241, v240
	s_nop 0
	v_add_u32_e32 v242, -1, v241
	v_fma_f32 v243, -v242, v241, v240
	v_cmp_ge_f32_e64 s[0:1], 0, v243
	v_add_u32_e32 v243, 1, v241
	s_nop 0
	v_cndmask_b32_e64 v242, v241, v242, s[0:1]
	v_fma_f32 v241, -v243, v241, v240
	v_cmp_lt_f32_e64 s[0:1], 0, v241
	s_nop 1
	v_cndmask_b32_e64 v241, v242, v243, s[0:1]
	v_mul_f32_e32 v242, 0x37800000, v241
	v_cndmask_b32_e32 v241, v241, v242, vcc
	v_cmp_class_f32_e32 vcc, v240, v248
	s_nop 1
	v_cndmask_b32_e32 v240, v241, v240, vcc
	v_div_scale_f32 v241, s[0:1], v240, v240, 1.0
	v_rcp_f32_e32 v242, v241
	s_nop 0
	v_fma_f32 v243, -v241, v242, 1.0
	v_fmac_f32_e32 v242, v243, v242
	v_div_scale_f32 v243, vcc, 1.0, v240, 1.0
	v_mul_f32_e32 v244, v243, v242
	v_fma_f32 v247, -v241, v244, v243
	v_fmac_f32_e32 v244, v247, v242
	v_fma_f32 v241, -v241, v244, v243
	s_nop 1
	v_div_fmas_f32 v241, v241, v242, v244
	v_div_fixup_f32 v246, v241, v240, 1.0
	v_pk_mul_f32 v[40:41], v[40:41], v[246:247] op_sel_hi:[1,0]
	v_pk_mul_f32 v[42:43], v[42:43], v[246:247] op_sel_hi:[1,0]
	v_pk_mul_f32 v[44:45], v[44:45], v[246:247] op_sel_hi:[1,0]
	v_pk_mul_f32 v[46:47], v[46:47], v[246:247] op_sel_hi:[1,0]
	v_pk_mul_f32 v[48:49], v[48:49], v[246:247] op_sel_hi:[1,0]
	v_pk_mul_f32 v[50:51], v[50:51], v[246:247] op_sel_hi:[1,0]
	v_pk_mul_f32 v[52:53], v[52:53], v[246:247] op_sel_hi:[1,0]
	v_pk_mul_f32 v[54:55], v[54:55], v[246:247] op_sel_hi:[1,0]
	v_pk_mul_f32 v[56:57], v[56:57], v[246:247] op_sel_hi:[1,0]
	v_pk_mul_f32 v[58:59], v[58:59], v[246:247] op_sel_hi:[1,0]
	v_pk_mul_f32 v[60:61], v[60:61], v[246:247] op_sel_hi:[1,0]
	v_pk_mul_f32 v[62:63], v[62:63], v[246:247] op_sel_hi:[1,0]
	v_pk_mul_f32 v[64:65], v[64:65], v[246:247] op_sel_hi:[1,0]
	v_pk_mul_f32 v[66:67], v[66:67], v[246:247] op_sel_hi:[1,0]
	v_pk_mul_f32 v[68:69], v[68:69], v[246:247] op_sel_hi:[1,0]
	v_pk_mul_f32 v[70:71], v[70:71], v[246:247] op_sel_hi:[1,0]
	s_add_u32 s8, s10, 0xc0000
	s_addc_u32 s9, s11, 0
	v_pk_mul_f32 v[40:41], v[40:41], v[8:9]
	v_pk_mul_f32 v[42:43], v[42:43], v[10:11]
	global_store_dwordx4 v2, v[40:43], s[8:9] offset:0 nt
	v_pk_mul_f32 v[44:45], v[44:45], v[12:13]
	v_pk_mul_f32 v[46:47], v[46:47], v[14:15]
	global_store_dwordx4 v2, v[44:47], s[8:9] offset:16 nt
	v_pk_mul_f32 v[48:49], v[48:49], v[16:17]
	v_pk_mul_f32 v[50:51], v[50:51], v[18:19]
	global_store_dwordx4 v2, v[48:51], s[8:9] offset:2048 nt
	v_pk_mul_f32 v[52:53], v[52:53], v[20:21]
	v_pk_mul_f32 v[54:55], v[54:55], v[22:23]
	global_store_dwordx4 v2, v[52:55], s[8:9] offset:2064 nt
	v_pk_mul_f32 v[56:57], v[56:57], v[24:25]
	v_pk_mul_f32 v[58:59], v[58:59], v[26:27]
	global_store_dwordx4 v3, v[56:59], s[8:9] offset:0 nt
	v_pk_mul_f32 v[60:61], v[60:61], v[28:29]
	v_pk_mul_f32 v[62:63], v[62:63], v[30:31]
	global_store_dwordx4 v3, v[60:63], s[8:9] offset:16 nt
	v_pk_mul_f32 v[64:65], v[64:65], v[32:33]
	v_pk_mul_f32 v[66:67], v[66:67], v[34:35]
	global_store_dwordx4 v3, v[64:67], s[8:9] offset:2048 nt
	v_pk_mul_f32 v[68:69], v[68:69], v[36:37]
	v_pk_mul_f32 v[70:71], v[70:71], v[38:39]
	global_store_dwordx4 v3, v[68:71], s[8:9] offset:2064 nt
	s_waitcnt vmcnt(44)
	v_cvt_f32_f16_e32 v40, v136
	v_cvt_f32_f16_sdwa v41, v136 dst_sel:DWORD dst_unused:UNUSED_PAD src0_sel:WORD_1
	v_cvt_f32_f16_e32 v42, v137
	v_cvt_f32_f16_sdwa v43, v137 dst_sel:DWORD dst_unused:UNUSED_PAD src0_sel:WORD_1
	v_cvt_f32_f16_e32 v44, v138
	v_cvt_f32_f16_sdwa v45, v138 dst_sel:DWORD dst_unused:UNUSED_PAD src0_sel:WORD_1
	v_cvt_f32_f16_e32 v46, v139
	v_cvt_f32_f16_sdwa v47, v139 dst_sel:DWORD dst_unused:UNUSED_PAD src0_sel:WORD_1
	v_cvt_f32_f16_e32 v48, v140
	v_cvt_f32_f16_sdwa v49, v140 dst_sel:DWORD dst_unused:UNUSED_PAD src0_sel:WORD_1
	v_cvt_f32_f16_e32 v50, v141
	v_cvt_f32_f16_sdwa v51, v141 dst_sel:DWORD dst_unused:UNUSED_PAD src0_sel:WORD_1
	v_cvt_f32_f16_e32 v52, v142
	v_cvt_f32_f16_sdwa v53, v142 dst_sel:DWORD dst_unused:UNUSED_PAD src0_sel:WORD_1
	v_cvt_f32_f16_e32 v54, v143
	v_cvt_f32_f16_sdwa v55, v143 dst_sel:DWORD dst_unused:UNUSED_PAD src0_sel:WORD_1
	v_cvt_f32_f16_e32 v56, v144
	v_cvt_f32_f16_sdwa v57, v144 dst_sel:DWORD dst_unused:UNUSED_PAD src0_sel:WORD_1
	v_cvt_f32_f16_e32 v58, v145
	v_cvt_f32_f16_sdwa v59, v145 dst_sel:DWORD dst_unused:UNUSED_PAD src0_sel:WORD_1
	v_cvt_f32_f16_e32 v60, v146
	v_cvt_f32_f16_sdwa v61, v146 dst_sel:DWORD dst_unused:UNUSED_PAD src0_sel:WORD_1
	v_cvt_f32_f16_e32 v62, v147
	v_cvt_f32_f16_sdwa v63, v147 dst_sel:DWORD dst_unused:UNUSED_PAD src0_sel:WORD_1
	v_cvt_f32_f16_e32 v64, v148
	v_cvt_f32_f16_sdwa v65, v148 dst_sel:DWORD dst_unused:UNUSED_PAD src0_sel:WORD_1
	v_cvt_f32_f16_e32 v66, v149
	v_cvt_f32_f16_sdwa v67, v149 dst_sel:DWORD dst_unused:UNUSED_PAD src0_sel:WORD_1
	v_cvt_f32_f16_e32 v68, v150
	v_cvt_f32_f16_sdwa v69, v150 dst_sel:DWORD dst_unused:UNUSED_PAD src0_sel:WORD_1
	v_cvt_f32_f16_e32 v70, v151
	v_cvt_f32_f16_sdwa v71, v151 dst_sel:DWORD dst_unused:UNUSED_PAD src0_sel:WORD_1
	v_pk_mul_f32 v[232:233], v[40:41], v[40:41]
	v_pk_mul_f32 v[234:235], v[42:43], v[42:43]
	v_pk_mul_f32 v[236:237], v[44:45], v[44:45]
	v_pk_mul_f32 v[238:239], v[46:47], v[46:47]
	v_pk_fma_f32 v[232:233], v[48:49], v[48:49], v[232:233]
	v_pk_fma_f32 v[234:235], v[50:51], v[50:51], v[234:235]
	v_pk_fma_f32 v[236:237], v[52:53], v[52:53], v[236:237]
	v_pk_fma_f32 v[238:239], v[54:55], v[54:55], v[238:239]
	v_pk_fma_f32 v[232:233], v[56:57], v[56:57], v[232:233]
	v_pk_fma_f32 v[234:235], v[58:59], v[58:59], v[234:235]
	v_pk_fma_f32 v[236:237], v[60:61], v[60:61], v[236:237]
	v_pk_fma_f32 v[238:239], v[62:63], v[62:63], v[238:239]
	v_pk_fma_f32 v[232:233], v[64:65], v[64:65], v[232:233]
	v_pk_fma_f32 v[234:235], v[66:67], v[66:67], v[234:235]
	v_pk_fma_f32 v[236:237], v[68:69], v[68:69], v[236:237]
	v_pk_fma_f32 v[238:239], v[70:71], v[70:71], v[238:239]
	v_pk_add_f32 v[232:233], v[232:233], v[234:235]
	v_pk_add_f32 v[236:237], v[236:237], v[238:239]
	v_pk_add_f32 v[232:233], v[232:233], v[236:237]
	v_add_f32_e32 v240, v232, v233
	s_nop 1
	v_add_f32_dpp v240, v240, v240 quad_perm:[1,0,3,2] row_mask:0xf bank_mask:0xf
	s_nop 1
	v_add_f32_dpp v240, v240, v240 quad_perm:[2,3,0,1] row_mask:0xf bank_mask:0xf
	s_nop 1
	v_add_f32_dpp v240, v240, v240 row_half_mirror row_mask:0xf bank_mask:0xf
	s_nop 1
	v_add_f32_dpp v240, v240, v240 row_mirror row_mask:0xf bank_mask:0xf
	s_nop 1
	v_readlane_b32 s0, v240, 0
	v_readlane_b32 s1, v240, 16
	v_readlane_b32 s4, v240, 32
	v_readlane_b32 s5, v240, 48
	v_mov_b32_e32 v249, 0x358637bd
	s_nop 1
	v_mov_b32_e32 v240, s0
	v_add_f32_e32 v240, s1, v240
	v_add_f32_e32 v240, s4, v240
	v_add_f32_e32 v240, s5, v240
	v_fmamk_f32 v240, v240, 0x3a000000, v249
	s_mov_b32 s0, 0xf800000
	v_mul_f32_e32 v241, 0x4f800000, v240
	v_cmp_gt_f32_e32 vcc, s0, v240
	s_nop 1
	v_cndmask_b32_e32 v240, v240, v241, vcc
	v_sqrt_f32_e32 v241, v240
	s_nop 0
	v_add_u32_e32 v242, -1, v241
	v_fma_f32 v243, -v242, v241, v240
	v_cmp_ge_f32_e64 s[0:1], 0, v243
	v_add_u32_e32 v243, 1, v241
	s_nop 0
	v_cndmask_b32_e64 v242, v241, v242, s[0:1]
	v_fma_f32 v241, -v243, v241, v240
	v_cmp_lt_f32_e64 s[0:1], 0, v241
	s_nop 1
	v_cndmask_b32_e64 v241, v242, v243, s[0:1]
	v_mul_f32_e32 v242, 0x37800000, v241
	v_cndmask_b32_e32 v241, v241, v242, vcc
	v_cmp_class_f32_e32 vcc, v240, v248
	s_nop 1
	v_cndmask_b32_e32 v240, v241, v240, vcc
	v_div_scale_f32 v241, s[0:1], v240, v240, 1.0
	v_rcp_f32_e32 v242, v241
	s_nop 0
	v_fma_f32 v243, -v241, v242, 1.0
	v_fmac_f32_e32 v242, v243, v242
	v_div_scale_f32 v243, vcc, 1.0, v240, 1.0
	v_mul_f32_e32 v244, v243, v242
	v_fma_f32 v247, -v241, v244, v243
	v_fmac_f32_e32 v244, v247, v242
	v_fma_f32 v241, -v241, v244, v243
	s_nop 1
	v_div_fmas_f32 v241, v241, v242, v244
	v_div_fixup_f32 v246, v241, v240, 1.0
	v_pk_mul_f32 v[40:41], v[40:41], v[246:247] op_sel_hi:[1,0]
	v_pk_mul_f32 v[42:43], v[42:43], v[246:247] op_sel_hi:[1,0]
	v_pk_mul_f32 v[44:45], v[44:45], v[246:247] op_sel_hi:[1,0]
	v_pk_mul_f32 v[46:47], v[46:47], v[246:247] op_sel_hi:[1,0]
	v_pk_mul_f32 v[48:49], v[48:49], v[246:247] op_sel_hi:[1,0]
	v_pk_mul_f32 v[50:51], v[50:51], v[246:247] op_sel_hi:[1,0]
	v_pk_mul_f32 v[52:53], v[52:53], v[246:247] op_sel_hi:[1,0]
	v_pk_mul_f32 v[54:55], v[54:55], v[246:247] op_sel_hi:[1,0]
	v_pk_mul_f32 v[56:57], v[56:57], v[246:247] op_sel_hi:[1,0]
	v_pk_mul_f32 v[58:59], v[58:59], v[246:247] op_sel_hi:[1,0]
	v_pk_mul_f32 v[60:61], v[60:61], v[246:247] op_sel_hi:[1,0]
	v_pk_mul_f32 v[62:63], v[62:63], v[246:247] op_sel_hi:[1,0]
	v_pk_mul_f32 v[64:65], v[64:65], v[246:247] op_sel_hi:[1,0]
	v_pk_mul_f32 v[66:67], v[66:67], v[246:247] op_sel_hi:[1,0]
	v_pk_mul_f32 v[68:69], v[68:69], v[246:247] op_sel_hi:[1,0]
	v_pk_mul_f32 v[70:71], v[70:71], v[246:247] op_sel_hi:[1,0]
	s_add_u32 s8, s10, 0x100000
	s_addc_u32 s9, s11, 0
	v_pk_mul_f32 v[40:41], v[40:41], v[8:9]
	v_pk_mul_f32 v[42:43], v[42:43], v[10:11]
	global_store_dwordx4 v2, v[40:43], s[8:9] offset:0 nt
	v_pk_mul_f32 v[44:45], v[44:45], v[12:13]
	v_pk_mul_f32 v[46:47], v[46:47], v[14:15]
	global_store_dwordx4 v2, v[44:47], s[8:9] offset:16 nt
	v_pk_mul_f32 v[48:49], v[48:49], v[16:17]
	v_pk_mul_f32 v[50:51], v[50:51], v[18:19]
	global_store_dwordx4 v2, v[48:51], s[8:9] offset:2048 nt
	v_pk_mul_f32 v[52:53], v[52:53], v[20:21]
	v_pk_mul_f32 v[54:55], v[54:55], v[22:23]
	global_store_dwordx4 v2, v[52:55], s[8:9] offset:2064 nt
	v_pk_mul_f32 v[56:57], v[56:57], v[24:25]
	v_pk_mul_f32 v[58:59], v[58:59], v[26:27]
	global_store_dwordx4 v3, v[56:59], s[8:9] offset:0 nt
	v_pk_mul_f32 v[60:61], v[60:61], v[28:29]
	v_pk_mul_f32 v[62:63], v[62:63], v[30:31]
	global_store_dwordx4 v3, v[60:63], s[8:9] offset:16 nt
	v_pk_mul_f32 v[64:65], v[64:65], v[32:33]
	v_pk_mul_f32 v[66:67], v[66:67], v[34:35]
	global_store_dwordx4 v3, v[64:67], s[8:9] offset:2048 nt
	v_pk_mul_f32 v[68:69], v[68:69], v[36:37]
	v_pk_mul_f32 v[70:71], v[70:71], v[38:39]
	global_store_dwordx4 v3, v[68:71], s[8:9] offset:2064 nt
	s_waitcnt vmcnt(48)
	v_cvt_f32_f16_e32 v40, v152
	v_cvt_f32_f16_sdwa v41, v152 dst_sel:DWORD dst_unused:UNUSED_PAD src0_sel:WORD_1
	v_cvt_f32_f16_e32 v42, v153
	v_cvt_f32_f16_sdwa v43, v153 dst_sel:DWORD dst_unused:UNUSED_PAD src0_sel:WORD_1
	v_cvt_f32_f16_e32 v44, v154
	v_cvt_f32_f16_sdwa v45, v154 dst_sel:DWORD dst_unused:UNUSED_PAD src0_sel:WORD_1
	v_cvt_f32_f16_e32 v46, v155
	v_cvt_f32_f16_sdwa v47, v155 dst_sel:DWORD dst_unused:UNUSED_PAD src0_sel:WORD_1
	v_cvt_f32_f16_e32 v48, v156
	v_cvt_f32_f16_sdwa v49, v156 dst_sel:DWORD dst_unused:UNUSED_PAD src0_sel:WORD_1
	v_cvt_f32_f16_e32 v50, v157
	v_cvt_f32_f16_sdwa v51, v157 dst_sel:DWORD dst_unused:UNUSED_PAD src0_sel:WORD_1
	v_cvt_f32_f16_e32 v52, v158
	v_cvt_f32_f16_sdwa v53, v158 dst_sel:DWORD dst_unused:UNUSED_PAD src0_sel:WORD_1
	v_cvt_f32_f16_e32 v54, v159
	v_cvt_f32_f16_sdwa v55, v159 dst_sel:DWORD dst_unused:UNUSED_PAD src0_sel:WORD_1
	v_cvt_f32_f16_e32 v56, v160
	v_cvt_f32_f16_sdwa v57, v160 dst_sel:DWORD dst_unused:UNUSED_PAD src0_sel:WORD_1
	v_cvt_f32_f16_e32 v58, v161
	v_cvt_f32_f16_sdwa v59, v161 dst_sel:DWORD dst_unused:UNUSED_PAD src0_sel:WORD_1
	v_cvt_f32_f16_e32 v60, v162
	v_cvt_f32_f16_sdwa v61, v162 dst_sel:DWORD dst_unused:UNUSED_PAD src0_sel:WORD_1
	v_cvt_f32_f16_e32 v62, v163
	v_cvt_f32_f16_sdwa v63, v163 dst_sel:DWORD dst_unused:UNUSED_PAD src0_sel:WORD_1
	v_cvt_f32_f16_e32 v64, v164
	v_cvt_f32_f16_sdwa v65, v164 dst_sel:DWORD dst_unused:UNUSED_PAD src0_sel:WORD_1
	v_cvt_f32_f16_e32 v66, v165
	v_cvt_f32_f16_sdwa v67, v165 dst_sel:DWORD dst_unused:UNUSED_PAD src0_sel:WORD_1
	v_cvt_f32_f16_e32 v68, v166
	v_cvt_f32_f16_sdwa v69, v166 dst_sel:DWORD dst_unused:UNUSED_PAD src0_sel:WORD_1
	v_cvt_f32_f16_e32 v70, v167
	v_cvt_f32_f16_sdwa v71, v167 dst_sel:DWORD dst_unused:UNUSED_PAD src0_sel:WORD_1
	v_pk_mul_f32 v[232:233], v[40:41], v[40:41]
	v_pk_mul_f32 v[234:235], v[42:43], v[42:43]
	v_pk_mul_f32 v[236:237], v[44:45], v[44:45]
	v_pk_mul_f32 v[238:239], v[46:47], v[46:47]
	v_pk_fma_f32 v[232:233], v[48:49], v[48:49], v[232:233]
	v_pk_fma_f32 v[234:235], v[50:51], v[50:51], v[234:235]
	v_pk_fma_f32 v[236:237], v[52:53], v[52:53], v[236:237]
	v_pk_fma_f32 v[238:239], v[54:55], v[54:55], v[238:239]
	v_pk_fma_f32 v[232:233], v[56:57], v[56:57], v[232:233]
	v_pk_fma_f32 v[234:235], v[58:59], v[58:59], v[234:235]
	v_pk_fma_f32 v[236:237], v[60:61], v[60:61], v[236:237]
	v_pk_fma_f32 v[238:239], v[62:63], v[62:63], v[238:239]
	v_pk_fma_f32 v[232:233], v[64:65], v[64:65], v[232:233]
	v_pk_fma_f32 v[234:235], v[66:67], v[66:67], v[234:235]
	v_pk_fma_f32 v[236:237], v[68:69], v[68:69], v[236:237]
	v_pk_fma_f32 v[238:239], v[70:71], v[70:71], v[238:239]
	v_pk_add_f32 v[232:233], v[232:233], v[234:235]
	v_pk_add_f32 v[236:237], v[236:237], v[238:239]
	v_pk_add_f32 v[232:233], v[232:233], v[236:237]
	v_add_f32_e32 v240, v232, v233
	s_nop 1
	v_add_f32_dpp v240, v240, v240 quad_perm:[1,0,3,2] row_mask:0xf bank_mask:0xf
	s_nop 1
	v_add_f32_dpp v240, v240, v240 quad_perm:[2,3,0,1] row_mask:0xf bank_mask:0xf
	s_nop 1
	v_add_f32_dpp v240, v240, v240 row_half_mirror row_mask:0xf bank_mask:0xf
	s_nop 1
	v_add_f32_dpp v240, v240, v240 row_mirror row_mask:0xf bank_mask:0xf
	s_nop 1
	v_readlane_b32 s0, v240, 0
	v_readlane_b32 s1, v240, 16
	v_readlane_b32 s4, v240, 32
	v_readlane_b32 s5, v240, 48
	v_mov_b32_e32 v249, 0x358637bd
	s_nop 1
	v_mov_b32_e32 v240, s0
	v_add_f32_e32 v240, s1, v240
	v_add_f32_e32 v240, s4, v240
	v_add_f32_e32 v240, s5, v240
	v_fmamk_f32 v240, v240, 0x3a000000, v249
	s_mov_b32 s0, 0xf800000
	v_mul_f32_e32 v241, 0x4f800000, v240
	v_cmp_gt_f32_e32 vcc, s0, v240
	s_nop 1
	v_cndmask_b32_e32 v240, v240, v241, vcc
	v_sqrt_f32_e32 v241, v240
	s_nop 0
	v_add_u32_e32 v242, -1, v241
	v_fma_f32 v243, -v242, v241, v240
	v_cmp_ge_f32_e64 s[0:1], 0, v243
	v_add_u32_e32 v243, 1, v241
	s_nop 0
	v_cndmask_b32_e64 v242, v241, v242, s[0:1]
	v_fma_f32 v241, -v243, v241, v240
	v_cmp_lt_f32_e64 s[0:1], 0, v241
	s_nop 1
	v_cndmask_b32_e64 v241, v242, v243, s[0:1]
	v_mul_f32_e32 v242, 0x37800000, v241
	v_cndmask_b32_e32 v241, v241, v242, vcc
	v_cmp_class_f32_e32 vcc, v240, v248
	s_nop 1
	v_cndmask_b32_e32 v240, v241, v240, vcc
	v_div_scale_f32 v241, s[0:1], v240, v240, 1.0
	v_rcp_f32_e32 v242, v241
	s_nop 0
	v_fma_f32 v243, -v241, v242, 1.0
	v_fmac_f32_e32 v242, v243, v242
	v_div_scale_f32 v243, vcc, 1.0, v240, 1.0
	v_mul_f32_e32 v244, v243, v242
	v_fma_f32 v247, -v241, v244, v243
	v_fmac_f32_e32 v244, v247, v242
	v_fma_f32 v241, -v241, v244, v243
	s_nop 1
	v_div_fmas_f32 v241, v241, v242, v244
	v_div_fixup_f32 v246, v241, v240, 1.0
	v_pk_mul_f32 v[40:41], v[40:41], v[246:247] op_sel_hi:[1,0]
	v_pk_mul_f32 v[42:43], v[42:43], v[246:247] op_sel_hi:[1,0]
	v_pk_mul_f32 v[44:45], v[44:45], v[246:247] op_sel_hi:[1,0]
	v_pk_mul_f32 v[46:47], v[46:47], v[246:247] op_sel_hi:[1,0]
	v_pk_mul_f32 v[48:49], v[48:49], v[246:247] op_sel_hi:[1,0]
	v_pk_mul_f32 v[50:51], v[50:51], v[246:247] op_sel_hi:[1,0]
	v_pk_mul_f32 v[52:53], v[52:53], v[246:247] op_sel_hi:[1,0]
	v_pk_mul_f32 v[54:55], v[54:55], v[246:247] op_sel_hi:[1,0]
	v_pk_mul_f32 v[56:57], v[56:57], v[246:247] op_sel_hi:[1,0]
	v_pk_mul_f32 v[58:59], v[58:59], v[246:247] op_sel_hi:[1,0]
	v_pk_mul_f32 v[60:61], v[60:61], v[246:247] op_sel_hi:[1,0]
	v_pk_mul_f32 v[62:63], v[62:63], v[246:247] op_sel_hi:[1,0]
	v_pk_mul_f32 v[64:65], v[64:65], v[246:247] op_sel_hi:[1,0]
	v_pk_mul_f32 v[66:67], v[66:67], v[246:247] op_sel_hi:[1,0]
	v_pk_mul_f32 v[68:69], v[68:69], v[246:247] op_sel_hi:[1,0]
	v_pk_mul_f32 v[70:71], v[70:71], v[246:247] op_sel_hi:[1,0]
	s_add_u32 s8, s10, 0x140000
	s_addc_u32 s9, s11, 0
	v_pk_mul_f32 v[40:41], v[40:41], v[8:9]
	v_pk_mul_f32 v[42:43], v[42:43], v[10:11]
	global_store_dwordx4 v2, v[40:43], s[8:9] offset:0 nt
	v_pk_mul_f32 v[44:45], v[44:45], v[12:13]
	v_pk_mul_f32 v[46:47], v[46:47], v[14:15]
	global_store_dwordx4 v2, v[44:47], s[8:9] offset:16 nt
	v_pk_mul_f32 v[48:49], v[48:49], v[16:17]
	v_pk_mul_f32 v[50:51], v[50:51], v[18:19]
	global_store_dwordx4 v2, v[48:51], s[8:9] offset:2048 nt
	v_pk_mul_f32 v[52:53], v[52:53], v[20:21]
	v_pk_mul_f32 v[54:55], v[54:55], v[22:23]
	global_store_dwordx4 v2, v[52:55], s[8:9] offset:2064 nt
	v_pk_mul_f32 v[56:57], v[56:57], v[24:25]
	v_pk_mul_f32 v[58:59], v[58:59], v[26:27]
	global_store_dwordx4 v3, v[56:59], s[8:9] offset:0 nt
	v_pk_mul_f32 v[60:61], v[60:61], v[28:29]
	v_pk_mul_f32 v[62:63], v[62:63], v[30:31]
	global_store_dwordx4 v3, v[60:63], s[8:9] offset:16 nt
	v_pk_mul_f32 v[64:65], v[64:65], v[32:33]
	v_pk_mul_f32 v[66:67], v[66:67], v[34:35]
	global_store_dwordx4 v3, v[64:67], s[8:9] offset:2048 nt
	v_pk_mul_f32 v[68:69], v[68:69], v[36:37]
	v_pk_mul_f32 v[70:71], v[70:71], v[38:39]
	global_store_dwordx4 v3, v[68:71], s[8:9] offset:2064 nt
	s_waitcnt vmcnt(52)
	v_cvt_f32_f16_e32 v40, v168
	v_cvt_f32_f16_sdwa v41, v168 dst_sel:DWORD dst_unused:UNUSED_PAD src0_sel:WORD_1
	v_cvt_f32_f16_e32 v42, v169
	v_cvt_f32_f16_sdwa v43, v169 dst_sel:DWORD dst_unused:UNUSED_PAD src0_sel:WORD_1
	v_cvt_f32_f16_e32 v44, v170
	v_cvt_f32_f16_sdwa v45, v170 dst_sel:DWORD dst_unused:UNUSED_PAD src0_sel:WORD_1
	v_cvt_f32_f16_e32 v46, v171
	v_cvt_f32_f16_sdwa v47, v171 dst_sel:DWORD dst_unused:UNUSED_PAD src0_sel:WORD_1
	v_cvt_f32_f16_e32 v48, v172
	v_cvt_f32_f16_sdwa v49, v172 dst_sel:DWORD dst_unused:UNUSED_PAD src0_sel:WORD_1
	v_cvt_f32_f16_e32 v50, v173
	v_cvt_f32_f16_sdwa v51, v173 dst_sel:DWORD dst_unused:UNUSED_PAD src0_sel:WORD_1
	v_cvt_f32_f16_e32 v52, v174
	v_cvt_f32_f16_sdwa v53, v174 dst_sel:DWORD dst_unused:UNUSED_PAD src0_sel:WORD_1
	v_cvt_f32_f16_e32 v54, v175
	v_cvt_f32_f16_sdwa v55, v175 dst_sel:DWORD dst_unused:UNUSED_PAD src0_sel:WORD_1
	v_cvt_f32_f16_e32 v56, v176
	v_cvt_f32_f16_sdwa v57, v176 dst_sel:DWORD dst_unused:UNUSED_PAD src0_sel:WORD_1
	v_cvt_f32_f16_e32 v58, v177
	v_cvt_f32_f16_sdwa v59, v177 dst_sel:DWORD dst_unused:UNUSED_PAD src0_sel:WORD_1
	v_cvt_f32_f16_e32 v60, v178
	v_cvt_f32_f16_sdwa v61, v178 dst_sel:DWORD dst_unused:UNUSED_PAD src0_sel:WORD_1
	v_cvt_f32_f16_e32 v62, v179
	v_cvt_f32_f16_sdwa v63, v179 dst_sel:DWORD dst_unused:UNUSED_PAD src0_sel:WORD_1
	v_cvt_f32_f16_e32 v64, v180
	v_cvt_f32_f16_sdwa v65, v180 dst_sel:DWORD dst_unused:UNUSED_PAD src0_sel:WORD_1
	v_cvt_f32_f16_e32 v66, v181
	v_cvt_f32_f16_sdwa v67, v181 dst_sel:DWORD dst_unused:UNUSED_PAD src0_sel:WORD_1
	v_cvt_f32_f16_e32 v68, v182
	v_cvt_f32_f16_sdwa v69, v182 dst_sel:DWORD dst_unused:UNUSED_PAD src0_sel:WORD_1
	v_cvt_f32_f16_e32 v70, v183
	v_cvt_f32_f16_sdwa v71, v183 dst_sel:DWORD dst_unused:UNUSED_PAD src0_sel:WORD_1
	v_pk_mul_f32 v[232:233], v[40:41], v[40:41]
	v_pk_mul_f32 v[234:235], v[42:43], v[42:43]
	v_pk_mul_f32 v[236:237], v[44:45], v[44:45]
	v_pk_mul_f32 v[238:239], v[46:47], v[46:47]
	v_pk_fma_f32 v[232:233], v[48:49], v[48:49], v[232:233]
	v_pk_fma_f32 v[234:235], v[50:51], v[50:51], v[234:235]
	v_pk_fma_f32 v[236:237], v[52:53], v[52:53], v[236:237]
	v_pk_fma_f32 v[238:239], v[54:55], v[54:55], v[238:239]
	v_pk_fma_f32 v[232:233], v[56:57], v[56:57], v[232:233]
	v_pk_fma_f32 v[234:235], v[58:59], v[58:59], v[234:235]
	v_pk_fma_f32 v[236:237], v[60:61], v[60:61], v[236:237]
	v_pk_fma_f32 v[238:239], v[62:63], v[62:63], v[238:239]
	v_pk_fma_f32 v[232:233], v[64:65], v[64:65], v[232:233]
	v_pk_fma_f32 v[234:235], v[66:67], v[66:67], v[234:235]
	v_pk_fma_f32 v[236:237], v[68:69], v[68:69], v[236:237]
	v_pk_fma_f32 v[238:239], v[70:71], v[70:71], v[238:239]
	v_pk_add_f32 v[232:233], v[232:233], v[234:235]
	v_pk_add_f32 v[236:237], v[236:237], v[238:239]
	v_pk_add_f32 v[232:233], v[232:233], v[236:237]
	v_add_f32_e32 v240, v232, v233
	s_nop 1
	v_add_f32_dpp v240, v240, v240 quad_perm:[1,0,3,2] row_mask:0xf bank_mask:0xf
	s_nop 1
	v_add_f32_dpp v240, v240, v240 quad_perm:[2,3,0,1] row_mask:0xf bank_mask:0xf
	s_nop 1
	v_add_f32_dpp v240, v240, v240 row_half_mirror row_mask:0xf bank_mask:0xf
	s_nop 1
	v_add_f32_dpp v240, v240, v240 row_mirror row_mask:0xf bank_mask:0xf
	s_nop 1
	v_readlane_b32 s0, v240, 0
	v_readlane_b32 s1, v240, 16
	v_readlane_b32 s4, v240, 32
	v_readlane_b32 s5, v240, 48
	v_mov_b32_e32 v249, 0x358637bd
	s_nop 1
	v_mov_b32_e32 v240, s0
	v_add_f32_e32 v240, s1, v240
	v_add_f32_e32 v240, s4, v240
	v_add_f32_e32 v240, s5, v240
	v_fmamk_f32 v240, v240, 0x3a000000, v249
	s_mov_b32 s0, 0xf800000
	v_mul_f32_e32 v241, 0x4f800000, v240
	v_cmp_gt_f32_e32 vcc, s0, v240
	s_nop 1
	v_cndmask_b32_e32 v240, v240, v241, vcc
	v_sqrt_f32_e32 v241, v240
	s_nop 0
	v_add_u32_e32 v242, -1, v241
	v_fma_f32 v243, -v242, v241, v240
	v_cmp_ge_f32_e64 s[0:1], 0, v243
	v_add_u32_e32 v243, 1, v241
	s_nop 0
	v_cndmask_b32_e64 v242, v241, v242, s[0:1]
	v_fma_f32 v241, -v243, v241, v240
	v_cmp_lt_f32_e64 s[0:1], 0, v241
	s_nop 1
	v_cndmask_b32_e64 v241, v242, v243, s[0:1]
	v_mul_f32_e32 v242, 0x37800000, v241
	v_cndmask_b32_e32 v241, v241, v242, vcc
	v_cmp_class_f32_e32 vcc, v240, v248
	s_nop 1
	v_cndmask_b32_e32 v240, v241, v240, vcc
	v_div_scale_f32 v241, s[0:1], v240, v240, 1.0
	v_rcp_f32_e32 v242, v241
	s_nop 0
	v_fma_f32 v243, -v241, v242, 1.0
	v_fmac_f32_e32 v242, v243, v242
	v_div_scale_f32 v243, vcc, 1.0, v240, 1.0
	v_mul_f32_e32 v244, v243, v242
	v_fma_f32 v247, -v241, v244, v243
	v_fmac_f32_e32 v244, v247, v242
	v_fma_f32 v241, -v241, v244, v243
	s_nop 1
	v_div_fmas_f32 v241, v241, v242, v244
	v_div_fixup_f32 v246, v241, v240, 1.0
	v_pk_mul_f32 v[40:41], v[40:41], v[246:247] op_sel_hi:[1,0]
	v_pk_mul_f32 v[42:43], v[42:43], v[246:247] op_sel_hi:[1,0]
	v_pk_mul_f32 v[44:45], v[44:45], v[246:247] op_sel_hi:[1,0]
	v_pk_mul_f32 v[46:47], v[46:47], v[246:247] op_sel_hi:[1,0]
	v_pk_mul_f32 v[48:49], v[48:49], v[246:247] op_sel_hi:[1,0]
	v_pk_mul_f32 v[50:51], v[50:51], v[246:247] op_sel_hi:[1,0]
	v_pk_mul_f32 v[52:53], v[52:53], v[246:247] op_sel_hi:[1,0]
	v_pk_mul_f32 v[54:55], v[54:55], v[246:247] op_sel_hi:[1,0]
	v_pk_mul_f32 v[56:57], v[56:57], v[246:247] op_sel_hi:[1,0]
	v_pk_mul_f32 v[58:59], v[58:59], v[246:247] op_sel_hi:[1,0]
	v_pk_mul_f32 v[60:61], v[60:61], v[246:247] op_sel_hi:[1,0]
	v_pk_mul_f32 v[62:63], v[62:63], v[246:247] op_sel_hi:[1,0]
	v_pk_mul_f32 v[64:65], v[64:65], v[246:247] op_sel_hi:[1,0]
	v_pk_mul_f32 v[66:67], v[66:67], v[246:247] op_sel_hi:[1,0]
	v_pk_mul_f32 v[68:69], v[68:69], v[246:247] op_sel_hi:[1,0]
	v_pk_mul_f32 v[70:71], v[70:71], v[246:247] op_sel_hi:[1,0]
	s_add_u32 s8, s10, 0x180000
	s_addc_u32 s9, s11, 0
	v_pk_mul_f32 v[40:41], v[40:41], v[8:9]
	v_pk_mul_f32 v[42:43], v[42:43], v[10:11]
	global_store_dwordx4 v2, v[40:43], s[8:9] offset:0 nt
	v_pk_mul_f32 v[44:45], v[44:45], v[12:13]
	v_pk_mul_f32 v[46:47], v[46:47], v[14:15]
	global_store_dwordx4 v2, v[44:47], s[8:9] offset:16 nt
	v_pk_mul_f32 v[48:49], v[48:49], v[16:17]
	v_pk_mul_f32 v[50:51], v[50:51], v[18:19]
	global_store_dwordx4 v2, v[48:51], s[8:9] offset:2048 nt
	v_pk_mul_f32 v[52:53], v[52:53], v[20:21]
	v_pk_mul_f32 v[54:55], v[54:55], v[22:23]
	global_store_dwordx4 v2, v[52:55], s[8:9] offset:2064 nt
	v_pk_mul_f32 v[56:57], v[56:57], v[24:25]
	v_pk_mul_f32 v[58:59], v[58:59], v[26:27]
	global_store_dwordx4 v3, v[56:59], s[8:9] offset:0 nt
	v_pk_mul_f32 v[60:61], v[60:61], v[28:29]
	v_pk_mul_f32 v[62:63], v[62:63], v[30:31]
	global_store_dwordx4 v3, v[60:63], s[8:9] offset:16 nt
	v_pk_mul_f32 v[64:65], v[64:65], v[32:33]
	v_pk_mul_f32 v[66:67], v[66:67], v[34:35]
	s_waitcnt vmcnt(44)
	global_store_dwordx4 v3, v[64:67], s[8:9] offset:2048 nt
	v_pk_mul_f32 v[68:69], v[68:69], v[36:37]
	v_pk_mul_f32 v[70:71], v[70:71], v[38:39]
	global_store_dwordx4 v3, v[68:71], s[8:9] offset:2064 nt
	s_waitcnt vmcnt(56)
	v_cvt_f32_f16_e32 v40, v184
	v_cvt_f32_f16_sdwa v41, v184 dst_sel:DWORD dst_unused:UNUSED_PAD src0_sel:WORD_1
	v_cvt_f32_f16_e32 v42, v185
	v_cvt_f32_f16_sdwa v43, v185 dst_sel:DWORD dst_unused:UNUSED_PAD src0_sel:WORD_1
	v_cvt_f32_f16_e32 v44, v186
	v_cvt_f32_f16_sdwa v45, v186 dst_sel:DWORD dst_unused:UNUSED_PAD src0_sel:WORD_1
	v_cvt_f32_f16_e32 v46, v187
	v_cvt_f32_f16_sdwa v47, v187 dst_sel:DWORD dst_unused:UNUSED_PAD src0_sel:WORD_1
	v_cvt_f32_f16_e32 v48, v188
	v_cvt_f32_f16_sdwa v49, v188 dst_sel:DWORD dst_unused:UNUSED_PAD src0_sel:WORD_1
	v_cvt_f32_f16_e32 v50, v189
	v_cvt_f32_f16_sdwa v51, v189 dst_sel:DWORD dst_unused:UNUSED_PAD src0_sel:WORD_1
	v_cvt_f32_f16_e32 v52, v190
	v_cvt_f32_f16_sdwa v53, v190 dst_sel:DWORD dst_unused:UNUSED_PAD src0_sel:WORD_1
	v_cvt_f32_f16_e32 v54, v191
	v_cvt_f32_f16_sdwa v55, v191 dst_sel:DWORD dst_unused:UNUSED_PAD src0_sel:WORD_1
	v_cvt_f32_f16_e32 v56, v192
	v_cvt_f32_f16_sdwa v57, v192 dst_sel:DWORD dst_unused:UNUSED_PAD src0_sel:WORD_1
	v_cvt_f32_f16_e32 v58, v193
	v_cvt_f32_f16_sdwa v59, v193 dst_sel:DWORD dst_unused:UNUSED_PAD src0_sel:WORD_1
	v_cvt_f32_f16_e32 v60, v194
	v_cvt_f32_f16_sdwa v61, v194 dst_sel:DWORD dst_unused:UNUSED_PAD src0_sel:WORD_1
	v_cvt_f32_f16_e32 v62, v195
	v_cvt_f32_f16_sdwa v63, v195 dst_sel:DWORD dst_unused:UNUSED_PAD src0_sel:WORD_1
	v_cvt_f32_f16_e32 v64, v196
	v_cvt_f32_f16_sdwa v65, v196 dst_sel:DWORD dst_unused:UNUSED_PAD src0_sel:WORD_1
	v_cvt_f32_f16_e32 v66, v197
	v_cvt_f32_f16_sdwa v67, v197 dst_sel:DWORD dst_unused:UNUSED_PAD src0_sel:WORD_1
	v_cvt_f32_f16_e32 v68, v198
	v_cvt_f32_f16_sdwa v69, v198 dst_sel:DWORD dst_unused:UNUSED_PAD src0_sel:WORD_1
	v_cvt_f32_f16_e32 v70, v199
	v_cvt_f32_f16_sdwa v71, v199 dst_sel:DWORD dst_unused:UNUSED_PAD src0_sel:WORD_1
	v_pk_mul_f32 v[232:233], v[40:41], v[40:41]
	v_pk_mul_f32 v[234:235], v[42:43], v[42:43]
	v_pk_mul_f32 v[236:237], v[44:45], v[44:45]
	v_pk_mul_f32 v[238:239], v[46:47], v[46:47]
	v_pk_fma_f32 v[232:233], v[48:49], v[48:49], v[232:233]
	v_pk_fma_f32 v[234:235], v[50:51], v[50:51], v[234:235]
	v_pk_fma_f32 v[236:237], v[52:53], v[52:53], v[236:237]
	v_pk_fma_f32 v[238:239], v[54:55], v[54:55], v[238:239]
	v_pk_fma_f32 v[232:233], v[56:57], v[56:57], v[232:233]
	v_pk_fma_f32 v[234:235], v[58:59], v[58:59], v[234:235]
	v_pk_fma_f32 v[236:237], v[60:61], v[60:61], v[236:237]
	v_pk_fma_f32 v[238:239], v[62:63], v[62:63], v[238:239]
	v_pk_fma_f32 v[232:233], v[64:65], v[64:65], v[232:233]
	v_pk_fma_f32 v[234:235], v[66:67], v[66:67], v[234:235]
	v_pk_fma_f32 v[236:237], v[68:69], v[68:69], v[236:237]
	v_pk_fma_f32 v[238:239], v[70:71], v[70:71], v[238:239]
	v_pk_add_f32 v[232:233], v[232:233], v[234:235]
	v_pk_add_f32 v[236:237], v[236:237], v[238:239]
	v_pk_add_f32 v[232:233], v[232:233], v[236:237]
	v_add_f32_e32 v240, v232, v233
	s_nop 1
	v_add_f32_dpp v240, v240, v240 quad_perm:[1,0,3,2] row_mask:0xf bank_mask:0xf
	s_nop 1
	v_add_f32_dpp v240, v240, v240 quad_perm:[2,3,0,1] row_mask:0xf bank_mask:0xf
	s_nop 1
	v_add_f32_dpp v240, v240, v240 row_half_mirror row_mask:0xf bank_mask:0xf
	s_nop 1
	v_add_f32_dpp v240, v240, v240 row_mirror row_mask:0xf bank_mask:0xf
	s_nop 1
	v_readlane_b32 s0, v240, 0
	v_readlane_b32 s1, v240, 16
	v_readlane_b32 s4, v240, 32
	v_readlane_b32 s5, v240, 48
	v_mov_b32_e32 v249, 0x358637bd
	s_nop 1
	v_mov_b32_e32 v240, s0
	v_add_f32_e32 v240, s1, v240
	v_add_f32_e32 v240, s4, v240
	v_add_f32_e32 v240, s5, v240
	v_fmamk_f32 v240, v240, 0x3a000000, v249
	s_mov_b32 s0, 0xf800000
	v_mul_f32_e32 v241, 0x4f800000, v240
	v_cmp_gt_f32_e32 vcc, s0, v240
	s_nop 1
	v_cndmask_b32_e32 v240, v240, v241, vcc
	v_sqrt_f32_e32 v241, v240
	s_nop 0
	v_add_u32_e32 v242, -1, v241
	v_fma_f32 v243, -v242, v241, v240
	v_cmp_ge_f32_e64 s[0:1], 0, v243
	v_add_u32_e32 v243, 1, v241
	s_nop 0
	v_cndmask_b32_e64 v242, v241, v242, s[0:1]
	v_fma_f32 v241, -v243, v241, v240
	v_cmp_lt_f32_e64 s[0:1], 0, v241
	s_nop 1
	v_cndmask_b32_e64 v241, v242, v243, s[0:1]
	v_mul_f32_e32 v242, 0x37800000, v241
	v_cndmask_b32_e32 v241, v241, v242, vcc
	v_cmp_class_f32_e32 vcc, v240, v248
	s_nop 1
	v_cndmask_b32_e32 v240, v241, v240, vcc
	v_div_scale_f32 v241, s[0:1], v240, v240, 1.0
	v_rcp_f32_e32 v242, v241
	s_nop 0
	v_fma_f32 v243, -v241, v242, 1.0
	v_fmac_f32_e32 v242, v243, v242
	v_div_scale_f32 v243, vcc, 1.0, v240, 1.0
	v_mul_f32_e32 v244, v243, v242
	v_fma_f32 v247, -v241, v244, v243
	v_fmac_f32_e32 v244, v247, v242
	v_fma_f32 v241, -v241, v244, v243
	s_nop 1
	v_div_fmas_f32 v241, v241, v242, v244
	v_div_fixup_f32 v246, v241, v240, 1.0
	v_pk_mul_f32 v[40:41], v[40:41], v[246:247] op_sel_hi:[1,0]
	v_pk_mul_f32 v[42:43], v[42:43], v[246:247] op_sel_hi:[1,0]
	v_pk_mul_f32 v[44:45], v[44:45], v[246:247] op_sel_hi:[1,0]
	v_pk_mul_f32 v[46:47], v[46:47], v[246:247] op_sel_hi:[1,0]
	v_pk_mul_f32 v[48:49], v[48:49], v[246:247] op_sel_hi:[1,0]
	v_pk_mul_f32 v[50:51], v[50:51], v[246:247] op_sel_hi:[1,0]
	v_pk_mul_f32 v[52:53], v[52:53], v[246:247] op_sel_hi:[1,0]
	v_pk_mul_f32 v[54:55], v[54:55], v[246:247] op_sel_hi:[1,0]
	v_pk_mul_f32 v[56:57], v[56:57], v[246:247] op_sel_hi:[1,0]
	v_pk_mul_f32 v[58:59], v[58:59], v[246:247] op_sel_hi:[1,0]
	v_pk_mul_f32 v[60:61], v[60:61], v[246:247] op_sel_hi:[1,0]
	v_pk_mul_f32 v[62:63], v[62:63], v[246:247] op_sel_hi:[1,0]
	v_pk_mul_f32 v[64:65], v[64:65], v[246:247] op_sel_hi:[1,0]
	v_pk_mul_f32 v[66:67], v[66:67], v[246:247] op_sel_hi:[1,0]
	v_pk_mul_f32 v[68:69], v[68:69], v[246:247] op_sel_hi:[1,0]
	v_pk_mul_f32 v[70:71], v[70:71], v[246:247] op_sel_hi:[1,0]
	s_add_u32 s8, s10, 0x1c0000
	s_addc_u32 s9, s11, 0
	v_pk_mul_f32 v[40:41], v[40:41], v[8:9]
	v_pk_mul_f32 v[42:43], v[42:43], v[10:11]
	global_store_dwordx4 v2, v[40:43], s[8:9] offset:0 nt
	v_pk_mul_f32 v[44:45], v[44:45], v[12:13]
	v_pk_mul_f32 v[46:47], v[46:47], v[14:15]
	global_store_dwordx4 v2, v[44:47], s[8:9] offset:16 nt
	v_pk_mul_f32 v[48:49], v[48:49], v[16:17]
	v_pk_mul_f32 v[50:51], v[50:51], v[18:19]
	global_store_dwordx4 v2, v[48:51], s[8:9] offset:2048 nt
	v_pk_mul_f32 v[52:53], v[52:53], v[20:21]
	v_pk_mul_f32 v[54:55], v[54:55], v[22:23]
	global_store_dwordx4 v2, v[52:55], s[8:9] offset:2064 nt
	v_pk_mul_f32 v[56:57], v[56:57], v[24:25]
	v_pk_mul_f32 v[58:59], v[58:59], v[26:27]
	global_store_dwordx4 v3, v[56:59], s[8:9] offset:0 nt
	v_pk_mul_f32 v[60:61], v[60:61], v[28:29]
	v_pk_mul_f32 v[62:63], v[62:63], v[30:31]
	global_store_dwordx4 v3, v[60:63], s[8:9] offset:16 nt
	v_pk_mul_f32 v[64:65], v[64:65], v[32:33]
	v_pk_mul_f32 v[66:67], v[66:67], v[34:35]
	global_store_dwordx4 v3, v[64:67], s[8:9] offset:2048 nt
	v_pk_mul_f32 v[68:69], v[68:69], v[36:37]
	v_pk_mul_f32 v[70:71], v[70:71], v[38:39]
	global_store_dwordx4 v3, v[68:71], s[8:9] offset:2064 nt
	s_branch .LBB0_2880
.Lnorm_fb_fin:
	s_mov_b32 s0, s72
	s_add_i32 s0, 0, 0x2416c
	v_mov_b32_e32 v1, s0
	s_add_i32 s0, 0, 0x24170
	ds_read_b32 v1, v1
	s_waitcnt vmcnt(31)
	v_mov_b32_e32 v2, s0
	ds_read_b32 v2, v2
	v_readfirstlane_b32 s0, v0
	s_ashr_i32 s3, s0, 6
	s_waitcnt lgkmcnt(1)
	v_readfirstlane_b32 s5, v1
	s_cmp_lt_i32 s5, 1
	s_waitcnt lgkmcnt(0)
	v_readfirstlane_b32 s6, v2
	s_cbranch_scc0 .LBB0_2873
	s_lshl_b32 s0, s72, 3
	s_add_i32 s2, s3, s0
	s_lshl_b32 s4, s38, 3
	s_movk_i32 s14, 0x4000
	s_cbranch_execz .LBB0_2874
	s_branch .LBB0_2875
